# GEMM K-loops: removed the redundant back-to-back s_setprio 0 / s_setprio 1 pair in the middle of each 32-MFMA block (72 pairs)
# speedup vs baseline: 1.0004x; 1.0004x over previous
; #define PG8_STAGE(bufoff, gbase, voff) do { _Pragma("unroll") for (int _i = 0; _i < 2; ++_i) \
;         __builtin_amdgcn_global_load_lds((const unsigned*)((const char*)(gbase) + (voff)[_i]), (PG8_LAS unsigned*)(lds + (bufoff) + ldsw + _i * 8192), 16, 0, 0); } while (0)
; #define PG8_LDA(dst, b, h) do { _Pragma("unroll") for (int m = 0; m < 4; ++m) _Pragma("unroll") for (int k = 0; k < 2; ++k) dst[m][k] = *(const PG8_LAS bf16x8*)(lds + PG8_SA(b, h) + aoff + m * 2048 + k * 1024); } while (0)
; #define PG8_LDB(dst, b, h) do { _Pragma("unroll") for (int n = 0; n < 2; ++n) _Pragma("unroll") for (int k = 0; k < 2; ++k) dst[n][k] = *(const PG8_LAS bf16x8*)(lds + PG8_SB(b, h) + boff + n * 2048 + k * 1024); } while (0)
; #define PG8_WAIT_V(n) asm volatile("s_waitcnt vmcnt(" #n ")" ::: "memory")
; #define PG8_WAIT_L(n) asm volatile("s_waitcnt lgkmcnt(" #n ")" ::: "memory")
; #define PG8_BAR __builtin_amdgcn_s_barrier()
; template <class Epi, class Sched, bool ALIGN_EPI = false, bool SP2 = false>
; __device__ __forceinline__ void gemm_phase(PG8_LAS unsigned char* lds, const Gemm g, const Sched& S, const Epi& E) {
;     ...
;         const bool has_next = S.next(ui + 1, nxt);
;         const char* nA = has_next ? (const char*)g.A + (size_t)nxt.pm * tstepA + (size_t)nxt.pb * g.sA : cA; const char* nB = has_next ? (const char*)g.Bt + (size_t)nxt.pn * tstepB + (size_t)nxt.pb * g.sB : cB;
;         for (int t = 0; t < nt; t += 2) {
;             const bool last = (t == nt - 2);
;             const char* a1 = cA + (size_t)(t + 1) * kstep;
;             const char* a2 = last ? nA : cA + (size_t)(t + 2) * kstep; const char* b2 = last ? nB : cB + (size_t)(t + 2) * kstep;
;             const char* a3 = a2 + kstep; const char* b3 = b2 + kstep;
;             if (last && has_next) S.a_ready(nxt);
;             if constexpr (SP2) {
;             PG8_LDB(B0, 0, 0); PG8_LDB(B1, 0, 1); PG8_SCHED; PG8_LDA(At, 0, 0); PG8_STAGE(PG8_SA(1, 1), a1 + hstepA, voffA);
;             PG8_WAIT_V(8); PG8_WAIT_L(0); PG8_BAR; PG8_MMA(0, 0, At, B0); PG8_MMA(0, 1, At, B1); PG8_BAR; PG8_SCHED;
;             PG8_LDA(At, 0, 1); PG8_STAGE(PG8_SB(0, 0), b2, voffB); PG8_STAGE(PG8_SB(0, 1), b2 + hstepB, voffB); PG8_STAGE(PG8_SA(0, 0), a2, voffA);
;             PG8_WAIT_V(8); PG8_WAIT_L(0); PG8_BAR; PG8_MMA(1, 0, At, B0); PG8_MMA(1, 1, At, B1); PG8_BAR; PG8_SCHED;
.LBB0_285:
	s_ashr_i32 s15, s14, 31
	s_lshl_b64 s[16:17], s[14:15], 19
	s_add_u32 s16, s0, s16
	s_addc_u32 s17, s1, s17
	s_and_b64 s[18:19], s[44:45], exec
	s_cselect_b32 s15, s17, s31
	s_cselect_b32 s62, s16, s30
	s_ashr_i32 s9, s8, 31
	s_lshl_b64 s[18:19], s[8:9], 19
	s_add_u32 s18, s38, s18
	s_addc_u32 s19, s39, s19
	s_and_b64 s[36:37], s[44:45], exec
	s_cselect_b32 s9, s19, s35
	s_cselect_b32 s63, s18, s34
	s_add_u32 s30, s30, 0x40080
	s_addc_u32 s31, s31, 0
	s_add_u32 s70, s34, 0x100
	s_addc_u32 s71, s35, 0
	s_mov_b32 s78, -2
	s_add_u32 s20, s30, 0xfffc0080
	s_addc_u32 s21, s31, -1
	s_add_i32 s79, 0, 0x10000
	s_cmp_eq_u32 s78, 12
	s_cselect_b32 s37, s15, s21
	s_cselect_b32 s36, s62, s20
	v_add_u32_e32 v0, s79, v149
	s_cselect_b32 s35, s9, s71
	s_cselect_b32 s34, s63, s70
	s_add_i32 s20, 0, 0x14000
	ds_read_b128 v[144:147], v0
	ds_read_b128 v[152:155], v0 offset:1024
	ds_read_b128 v[156:159], v0 offset:2048
	ds_read_b128 v[160:163], v0 offset:3072
	v_add_u32_e32 v0, s20, v149
	ds_read_b128 v[164:167], v0
	ds_read_b128 v[168:171], v0 offset:1024
	ds_read_b128 v[172:175], v0 offset:2048
	ds_read_b128 v[176:179], v0 offset:3072
	v_lshl_add_u64 v[200:201], s[30:31], 0, v[138:139]
	s_add_i32 m0, s42, 0xc000
	ds_read_b128 v[180:183], v150
	ds_read_b128 v[184:187], v150 offset:1024
	ds_read_b128 v[188:191], v150 offset:2048
	ds_read_b128 v[192:195], v150 offset:3072
	ds_read_b128 v[196:199], v150 offset:4096
	ds_read_b128 v[208:211], v150 offset:5120
	ds_read_b128 v[212:215], v150 offset:6144
	ds_read_b128 v[216:219], v150 offset:7168
	global_load_lds_dwordx4 v[200:201], off
	v_lshl_add_u64 v[200:201], s[30:31], 0, v[140:141]
	s_add_i32 m0, s42, 0xe000
	s_nop 0
	global_load_lds_dwordx4 v[200:201], off
	s_waitcnt vmcnt(8)
	s_waitcnt lgkmcnt(0)
	s_barrier
	s_setprio 1
	s_waitcnt lgkmcnt(0)
	v_mfma_f32_16x16x32_bf16 v[126:129], v[144:147], v[180:183], 0
	v_mfma_f32_16x16x32_bf16 v[122:125], v[156:159], v[180:183], 0
	v_mfma_f32_16x16x32_bf16 v[110:113], v[144:147], v[188:191], 0
	v_mfma_f32_16x16x32_bf16 v[106:109], v[156:159], v[188:191], 0
	v_mfma_f32_16x16x32_bf16 v[98:101], v[144:147], v[196:199], 0
	v_mfma_f32_16x16x32_bf16 v[90:93], v[156:159], v[196:199], 0
	v_mfma_f32_16x16x32_bf16 v[82:85], v[144:147], v[212:215], 0
	v_mfma_f32_16x16x32_bf16 v[74:77], v[156:159], v[212:215], 0
	v_mfma_f32_16x16x32_bf16 v[126:129], v[152:155], v[184:187], v[126:129]
	v_mfma_f32_16x16x32_bf16 v[122:125], v[160:163], v[184:187], v[122:125]
	v_mfma_f32_16x16x32_bf16 v[110:113], v[152:155], v[192:195], v[110:113]
	v_mfma_f32_16x16x32_bf16 v[106:109], v[160:163], v[192:195], v[106:109]
	v_mfma_f32_16x16x32_bf16 v[98:101], v[152:155], v[208:211], v[98:101]
	v_mfma_f32_16x16x32_bf16 v[90:93], v[160:163], v[208:211], v[90:93]
	v_mfma_f32_16x16x32_bf16 v[82:85], v[152:155], v[216:219], v[82:85]
	v_mfma_f32_16x16x32_bf16 v[74:77], v[160:163], v[216:219], v[74:77]
	v_mfma_f32_16x16x32_bf16 v[118:121], v[164:167], v[180:183], 0
	v_mfma_f32_16x16x32_bf16 v[114:117], v[172:175], v[180:183], 0
	v_mfma_f32_16x16x32_bf16 v[102:105], v[164:167], v[188:191], 0
	v_mfma_f32_16x16x32_bf16 v[94:97], v[172:175], v[188:191], 0
	v_mfma_f32_16x16x32_bf16 v[86:89], v[164:167], v[196:199], 0
	v_mfma_f32_16x16x32_bf16 v[78:81], v[172:175], v[196:199], 0
	v_mfma_f32_16x16x32_bf16 v[70:73], v[164:167], v[212:215], 0
	v_mfma_f32_16x16x32_bf16 v[66:69], v[172:175], v[212:215], 0
	v_mfma_f32_16x16x32_bf16 v[118:121], v[168:171], v[184:187], v[118:121]
	v_mfma_f32_16x16x32_bf16 v[114:117], v[176:179], v[184:187], v[114:117]
	v_mfma_f32_16x16x32_bf16 v[102:105], v[168:171], v[192:195], v[102:105]
	v_mfma_f32_16x16x32_bf16 v[94:97], v[176:179], v[192:195], v[94:97]
	v_mfma_f32_16x16x32_bf16 v[86:89], v[168:171], v[208:211], v[86:89]
	v_mfma_f32_16x16x32_bf16 v[78:81], v[176:179], v[208:211], v[78:81]
	v_mfma_f32_16x16x32_bf16 v[70:73], v[168:171], v[216:219], v[70:73]
	v_mfma_f32_16x16x32_bf16 v[66:69], v[176:179], v[216:219], v[66:69]
	s_setprio 0
	s_barrier
	s_add_i32 s21, s79, s26
	v_lshl_add_u64 v[200:201], s[34:35], 0, v[134:135]
	s_mov_b32 m0, s21
	ds_read_b128 v[180:183], v150 offset:16384
	ds_read_b128 v[184:187], v150 offset:17408
	ds_read_b128 v[188:191], v150 offset:18432
	ds_read_b128 v[192:195], v150 offset:19456
	ds_read_b128 v[196:199], v150 offset:20480
	ds_read_b128 v[208:211], v150 offset:21504
	ds_read_b128 v[212:215], v150 offset:22528
	ds_read_b128 v[216:219], v150 offset:23552
	global_load_lds_dwordx4 v[200:201], off
	s_add_i32 m0, s21, 0x2000
	s_add_u32 s80, s34, 0x40000
	v_lshl_add_u64 v[204:205], s[34:35], 0, v[130:131]
	s_addc_u32 s81, s35, 0
	s_add_i32 s20, s20, s26
	global_load_lds_dwordx4 v[204:205], off
	v_lshl_add_u64 v[220:221], s[80:81], 0, v[134:135]
	s_mov_b32 m0, s20
	v_lshl_add_u64 v[222:223], s[36:37], 0, v[132:133]
	global_load_lds_dwordx4 v[220:221], off
	v_lshl_add_u64 v[220:221], s[80:81], 0, v[130:131]
	s_add_i32 m0, s20, 0x2000
	s_nop 0
	global_load_lds_dwordx4 v[220:221], off
	v_lshl_add_u64 v[220:221], s[36:37], 0, v[136:137]
	s_mov_b32 m0, s42
	s_nop 0
	global_load_lds_dwordx4 v[220:221], off
	s_mov_b32 m0, s43
	s_nop 0
	global_load_lds_dwordx4 v[222:223], off
	s_waitcnt vmcnt(8)
	s_waitcnt lgkmcnt(0)
	s_barrier
; #define PG8_STAGE(bufoff, gbase, voff) do { _Pragma("unroll") for (int _i = 0; _i < 2; ++_i) \
;         __builtin_amdgcn_global_load_lds((const unsigned*)((const char*)(gbase) + (voff)[_i]), (PG8_LAS unsigned*)(lds + (bufoff) + ldsw + _i * 8192), 16, 0, 0); } while (0)
; #define PG8_LDA(dst, b, h) do { _Pragma("unroll") for (int m = 0; m < 4; ++m) _Pragma("unroll") for (int k = 0; k < 2; ++k) dst[m][k] = *(const PG8_LAS bf16x8*)(lds + PG8_SA(b, h) + aoff + m * 2048 + k * 1024); } while (0)
; #define PG8_LDB(dst, b, h) do { _Pragma("unroll") for (int n = 0; n < 2; ++n) _Pragma("unroll") for (int k = 0; k < 2; ++k) dst[n][k] = *(const PG8_LAS bf16x8*)(lds + PG8_SB(b, h) + boff + n * 2048 + k * 1024); } while (0)
; #define PG8_MMA(ai, bj, At, Bt) do { __builtin_amdgcn_s_setprio(1); _Pragma("unroll") for (int m = 0; m < 4; ++m) _Pragma("unroll") for (int n = 0; n < 2; ++n) _Pragma("unroll") for (int k = 0; k < 2; ++k) \
;         acc[ai][bj][m][n] = __builtin_amdgcn_mfma_f32_16x16x32_bf16(Bt[n][k], At[m][k], acc[ai][bj][m][n], 0, 0, 0); __builtin_amdgcn_s_setprio(0); } while (0)
; #define PG8_WAIT_V(n) asm volatile("s_waitcnt vmcnt(" #n ")" ::: "memory")
; #define PG8_WAIT_L(n) asm volatile("s_waitcnt lgkmcnt(" #n ")" ::: "memory")
; #define PG8_BAR __builtin_amdgcn_s_barrier()
; #define PG8_SCHED __builtin_amdgcn_sched_barrier(0)
; template <class Epi, class Sched, bool ALIGN_EPI = false, bool SP2 = false>
; __device__ __forceinline__ void gemm_phase(PG8_LAS unsigned char* lds, const Gemm g, const Sched& S, const Epi& E) {
;     ...
;             PG8_WAIT_V(8); PG8_WAIT_L(0); PG8_BAR; PG8_MMA(1, 0, At, B0); PG8_MMA(1, 1, At, B1); PG8_BAR; PG8_SCHED;
;             PG8_LDB(B0, 1, 0); PG8_LDB(B1, 1, 1); PG8_SCHED; PG8_LDA(At, 1, 0); PG8_STAGE(PG8_SA(0, 1), a2 + hstepA, voffA);
;             PG8_WAIT_V(8); PG8_WAIT_L(0); PG8_BAR; PG8_MMA(0, 0, At, B0); PG8_MMA(0, 1, At, B1); PG8_BAR; PG8_SCHED;
	s_setprio 1
	s_waitcnt lgkmcnt(0)
	v_mfma_f32_16x16x32_bf16 v[62:65], v[144:147], v[180:183], 0
	v_mfma_f32_16x16x32_bf16 v[58:61], v[156:159], v[180:183], 0
	v_mfma_f32_16x16x32_bf16 v[46:49], v[144:147], v[188:191], 0
	v_mfma_f32_16x16x32_bf16 v[42:45], v[156:159], v[188:191], 0
	v_mfma_f32_16x16x32_bf16 v[34:37], v[144:147], v[196:199], 0
	v_mfma_f32_16x16x32_bf16 v[26:29], v[156:159], v[196:199], 0
	v_mfma_f32_16x16x32_bf16 v[18:21], v[144:147], v[212:215], 0
	v_mfma_f32_16x16x32_bf16 v[10:13], v[156:159], v[212:215], 0
	v_mfma_f32_16x16x32_bf16 v[62:65], v[152:155], v[184:187], v[62:65]
	v_mfma_f32_16x16x32_bf16 v[58:61], v[160:163], v[184:187], v[58:61]
	v_mfma_f32_16x16x32_bf16 v[46:49], v[152:155], v[192:195], v[46:49]
	v_mfma_f32_16x16x32_bf16 v[42:45], v[160:163], v[192:195], v[42:45]
	v_mfma_f32_16x16x32_bf16 v[34:37], v[152:155], v[208:211], v[34:37]
	v_mfma_f32_16x16x32_bf16 v[26:29], v[160:163], v[208:211], v[26:29]
	v_mfma_f32_16x16x32_bf16 v[18:21], v[152:155], v[216:219], v[18:21]
	v_mfma_f32_16x16x32_bf16 v[10:13], v[160:163], v[216:219], v[10:13]
	v_mfma_f32_16x16x32_bf16 v[54:57], v[164:167], v[180:183], 0
	v_mfma_f32_16x16x32_bf16 v[50:53], v[172:175], v[180:183], 0
	v_mfma_f32_16x16x32_bf16 v[38:41], v[164:167], v[188:191], 0
	v_mfma_f32_16x16x32_bf16 v[30:33], v[172:175], v[188:191], 0
	v_mfma_f32_16x16x32_bf16 v[22:25], v[164:167], v[196:199], 0
	v_mfma_f32_16x16x32_bf16 v[14:17], v[172:175], v[196:199], 0
	v_mfma_f32_16x16x32_bf16 v[6:9], v[164:167], v[212:215], 0
	v_mfma_f32_16x16x32_bf16 v[2:5], v[172:175], v[212:215], 0
	v_mfma_f32_16x16x32_bf16 v[54:57], v[168:171], v[184:187], v[54:57]
	v_mfma_f32_16x16x32_bf16 v[50:53], v[176:179], v[184:187], v[50:53]
	v_mfma_f32_16x16x32_bf16 v[38:41], v[168:171], v[192:195], v[38:41]
	v_mfma_f32_16x16x32_bf16 v[30:33], v[176:179], v[192:195], v[30:33]
	v_mfma_f32_16x16x32_bf16 v[22:25], v[168:171], v[208:211], v[22:25]
	v_mfma_f32_16x16x32_bf16 v[14:17], v[176:179], v[208:211], v[14:17]
	v_mfma_f32_16x16x32_bf16 v[6:9], v[168:171], v[216:219], v[6:9]
	v_mfma_f32_16x16x32_bf16 v[2:5], v[176:179], v[216:219], v[2:5]
	s_setprio 0
	s_barrier
	s_add_i32 s20, 0, 0x18000
	v_add_u32_e32 v0, s20, v149
	s_add_i32 s21, 0, 0x1c000
	ds_read_b128 v[144:147], v0
	ds_read_b128 v[152:155], v0 offset:1024
	ds_read_b128 v[156:159], v0 offset:2048
	ds_read_b128 v[160:163], v0 offset:3072
	v_add_u32_e32 v0, s21, v149
	ds_read_b128 v[164:167], v0
	ds_read_b128 v[168:171], v0 offset:1024
	ds_read_b128 v[172:175], v0 offset:2048
	ds_read_b128 v[176:179], v0 offset:3072
	s_add_u32 s36, s36, 0x40000
	s_addc_u32 s37, s37, 0
	s_mov_b32 m0, s46
	v_lshl_add_u64 v[224:225], s[36:37], 0, v[136:137]
	ds_read_b128 v[180:183], v150 offset:32768
	ds_read_b128 v[184:187], v150 offset:33792
	ds_read_b128 v[188:191], v150 offset:34816
	ds_read_b128 v[192:195], v150 offset:35840
	ds_read_b128 v[196:199], v150 offset:36864
	ds_read_b128 v[208:211], v150 offset:37888
	ds_read_b128 v[212:215], v150 offset:38912
	ds_read_b128 v[216:219], v150 offset:39936
	global_load_lds_dwordx4 v[224:225], off
	v_lshl_add_u64 v[224:225], s[36:37], 0, v[132:133]
	s_mov_b32 m0, s47
	s_nop 0
	global_load_lds_dwordx4 v[224:225], off
	s_waitcnt vmcnt(8)
	s_waitcnt lgkmcnt(0)
	s_barrier
	s_setprio 1
	s_waitcnt lgkmcnt(0)
	v_mfma_f32_16x16x32_bf16 v[126:129], v[144:147], v[180:183], v[126:129]
	v_mfma_f32_16x16x32_bf16 v[122:125], v[156:159], v[180:183], v[122:125]
	v_mfma_f32_16x16x32_bf16 v[110:113], v[144:147], v[188:191], v[110:113]
	v_mfma_f32_16x16x32_bf16 v[106:109], v[156:159], v[188:191], v[106:109]
	v_mfma_f32_16x16x32_bf16 v[98:101], v[144:147], v[196:199], v[98:101]
	v_mfma_f32_16x16x32_bf16 v[90:93], v[156:159], v[196:199], v[90:93]
	v_mfma_f32_16x16x32_bf16 v[82:85], v[144:147], v[212:215], v[82:85]
	v_mfma_f32_16x16x32_bf16 v[74:77], v[156:159], v[212:215], v[74:77]
	v_mfma_f32_16x16x32_bf16 v[126:129], v[152:155], v[184:187], v[126:129]
	v_mfma_f32_16x16x32_bf16 v[122:125], v[160:163], v[184:187], v[122:125]
	v_mfma_f32_16x16x32_bf16 v[110:113], v[152:155], v[192:195], v[110:113]
	v_mfma_f32_16x16x32_bf16 v[106:109], v[160:163], v[192:195], v[106:109]
	v_mfma_f32_16x16x32_bf16 v[98:101], v[152:155], v[208:211], v[98:101]
	v_mfma_f32_16x16x32_bf16 v[90:93], v[160:163], v[208:211], v[90:93]
	v_mfma_f32_16x16x32_bf16 v[82:85], v[152:155], v[216:219], v[82:85]
	v_mfma_f32_16x16x32_bf16 v[74:77], v[160:163], v[216:219], v[74:77]
	v_mfma_f32_16x16x32_bf16 v[118:121], v[164:167], v[180:183], v[118:121]
	v_mfma_f32_16x16x32_bf16 v[114:117], v[172:175], v[180:183], v[114:117]
	v_mfma_f32_16x16x32_bf16 v[102:105], v[164:167], v[188:191], v[102:105]
	v_mfma_f32_16x16x32_bf16 v[94:97], v[172:175], v[188:191], v[94:97]
	v_mfma_f32_16x16x32_bf16 v[86:89], v[164:167], v[196:199], v[86:89]
	v_mfma_f32_16x16x32_bf16 v[78:81], v[172:175], v[196:199], v[78:81]
	v_mfma_f32_16x16x32_bf16 v[70:73], v[164:167], v[212:215], v[70:73]
	v_mfma_f32_16x16x32_bf16 v[66:69], v[172:175], v[212:215], v[66:69]
	v_mfma_f32_16x16x32_bf16 v[118:121], v[168:171], v[184:187], v[118:121]
	v_mfma_f32_16x16x32_bf16 v[114:117], v[176:179], v[184:187], v[114:117]
	v_mfma_f32_16x16x32_bf16 v[102:105], v[168:171], v[192:195], v[102:105]
	v_mfma_f32_16x16x32_bf16 v[94:97], v[176:179], v[192:195], v[94:97]
	v_mfma_f32_16x16x32_bf16 v[86:89], v[168:171], v[208:211], v[86:89]
	v_mfma_f32_16x16x32_bf16 v[78:81], v[176:179], v[208:211], v[78:81]
	v_mfma_f32_16x16x32_bf16 v[70:73], v[168:171], v[216:219], v[70:73]
	v_mfma_f32_16x16x32_bf16 v[66:69], v[176:179], v[216:219], v[66:69]
	s_setprio 0
	s_barrier
; #define PG8_STAGE(bufoff, gbase, voff) do { _Pragma("unroll") for (int _i = 0; _i < 2; ++_i) \
;         __builtin_amdgcn_global_load_lds((const unsigned*)((const char*)(gbase) + (voff)[_i]), (PG8_LAS unsigned*)(lds + (bufoff) + ldsw + _i * 8192), 16, 0, 0); } while (0)
; #define PG8_LDA(dst, b, h) do { _Pragma("unroll") for (int m = 0; m < 4; ++m) _Pragma("unroll") for (int k = 0; k < 2; ++k) dst[m][k] = *(const PG8_LAS bf16x8*)(lds + PG8_SA(b, h) + aoff + m * 2048 + k * 1024); } while (0)
; #define PG8_LDB(dst, b, h) do { _Pragma("unroll") for (int n = 0; n < 2; ++n) _Pragma("unroll") for (int k = 0; k < 2; ++k) dst[n][k] = *(const PG8_LAS bf16x8*)(lds + PG8_SB(b, h) + boff + n * 2048 + k * 1024); } while (0)
; #define PG8_MMA(ai, bj, At, Bt) do { __builtin_amdgcn_s_setprio(1); _Pragma("unroll") for (int m = 0; m < 4; ++m) _Pragma("unroll") for (int n = 0; n < 2; ++n) _Pragma("unroll") for (int k = 0; k < 2; ++k) \
;         acc[ai][bj][m][n] = __builtin_amdgcn_mfma_f32_16x16x32_bf16(Bt[n][k], At[m][k], acc[ai][bj][m][n], 0, 0, 0); __builtin_amdgcn_s_setprio(0); } while (0)
; #define PG8_WAIT_V(n) asm volatile("s_waitcnt vmcnt(" #n ")" ::: "memory")
; #define PG8_BAR __builtin_amdgcn_s_barrier()
; template <class Epi, class Sched, bool ALIGN_EPI = false, bool SP2 = false>
; __device__ __forceinline__ void gemm_phase(PG8_LAS unsigned char* lds, const Gemm g, const Sched& S, const Epi& E) {
;     ...
;         for (int t = 0; t < nt; t += 2) {
;             const bool last = (t == nt - 2);
;             const char* a1 = cA + (size_t)(t + 1) * kstep;
;             const char* a2 = last ? nA : cA + (size_t)(t + 2) * kstep; const char* b2 = last ? nB : cB + (size_t)(t + 2) * kstep;
;             const char* a3 = a2 + kstep; const char* b3 = b2 + kstep;
;             if (last && has_next) S.a_ready(nxt);
;             if constexpr (SP2) {
;             PG8_LDB(B0, 0, 0); PG8_LDB(B1, 0, 1); PG8_SCHED; PG8_LDA(At, 0, 0); PG8_STAGE(PG8_SA(1, 1), a1 + hstepA, voffA);
;             PG8_WAIT_V(8); PG8_WAIT_L(0); PG8_BAR; PG8_MMA(0, 0, At, B0); PG8_MMA(0, 1, At, B1); PG8_BAR; PG8_SCHED;
;     ...
;             PG8_LDA(At, 1, 1); PG8_STAGE(PG8_SB(1, 0), b3, voffB); PG8_STAGE(PG8_SB(1, 1), b3 + hstepB, voffB); PG8_STAGE(PG8_SA(1, 0), a3, voffA);
;             PG8_WAIT_V(8); PG8_WAIT_L(0); PG8_BAR; PG8_MMA(1, 0, At, B0); PG8_MMA(1, 1, At, B1); PG8_BAR; PG8_SCHED;
	s_add_i32 s20, s20, s26
	v_lshl_add_u64 v[200:201], v[200:201], 0, s[22:23]
	s_mov_b32 m0, s20
	ds_read_b128 v[180:183], v150 offset:49152
	ds_read_b128 v[184:187], v150 offset:50176
	ds_read_b128 v[188:191], v150 offset:51200
	ds_read_b128 v[192:195], v150 offset:52224
	ds_read_b128 v[196:199], v150 offset:53248
	ds_read_b128 v[208:211], v150 offset:54272
	ds_read_b128 v[212:215], v150 offset:55296
	ds_read_b128 v[216:219], v150 offset:56320
	global_load_lds_dwordx4 v[200:201], off
	s_add_i32 m0, s20, 0x2000
	s_add_u32 s34, s34, 0x40080
	v_lshl_add_u64 v[200:201], v[204:205], 0, s[22:23]
	s_addc_u32 s35, s35, 0
	s_add_i32 s20, s21, s26
	global_load_lds_dwordx4 v[200:201], off
	v_lshl_add_u64 v[200:201], s[34:35], 0, v[134:135]
	s_mov_b32 m0, s20
	s_nop 0
	global_load_lds_dwordx4 v[200:201], off
	v_lshl_add_u64 v[200:201], s[34:35], 0, v[130:131]
	s_add_i32 m0, s20, 0x2000
	s_nop 0
	global_load_lds_dwordx4 v[200:201], off
	v_lshl_add_u64 v[200:201], v[220:221], 0, s[22:23]
	s_mov_b32 m0, s56
	s_nop 0
	global_load_lds_dwordx4 v[200:201], off
	v_lshl_add_u64 v[200:201], v[222:223], 0, s[22:23]
	s_mov_b32 m0, s57
	s_nop 0
	global_load_lds_dwordx4 v[200:201], off
	s_waitcnt vmcnt(8)
	s_waitcnt lgkmcnt(0)
	s_barrier
	s_setprio 1
	s_waitcnt lgkmcnt(0)
	v_mfma_f32_16x16x32_bf16 v[62:65], v[144:147], v[180:183], v[62:65]
	v_mfma_f32_16x16x32_bf16 v[58:61], v[156:159], v[180:183], v[58:61]
	v_mfma_f32_16x16x32_bf16 v[46:49], v[144:147], v[188:191], v[46:49]
	v_mfma_f32_16x16x32_bf16 v[42:45], v[156:159], v[188:191], v[42:45]
	v_mfma_f32_16x16x32_bf16 v[34:37], v[144:147], v[196:199], v[34:37]
	v_mfma_f32_16x16x32_bf16 v[26:29], v[156:159], v[196:199], v[26:29]
	v_mfma_f32_16x16x32_bf16 v[18:21], v[144:147], v[212:215], v[18:21]
	v_mfma_f32_16x16x32_bf16 v[10:13], v[156:159], v[212:215], v[10:13]
	v_mfma_f32_16x16x32_bf16 v[62:65], v[152:155], v[184:187], v[62:65]
	v_mfma_f32_16x16x32_bf16 v[58:61], v[160:163], v[184:187], v[58:61]
	v_mfma_f32_16x16x32_bf16 v[46:49], v[152:155], v[192:195], v[46:49]
	v_mfma_f32_16x16x32_bf16 v[42:45], v[160:163], v[192:195], v[42:45]
	v_mfma_f32_16x16x32_bf16 v[34:37], v[152:155], v[208:211], v[34:37]
	v_mfma_f32_16x16x32_bf16 v[26:29], v[160:163], v[208:211], v[26:29]
	v_mfma_f32_16x16x32_bf16 v[18:21], v[152:155], v[216:219], v[18:21]
	v_mfma_f32_16x16x32_bf16 v[10:13], v[160:163], v[216:219], v[10:13]
	v_mfma_f32_16x16x32_bf16 v[54:57], v[164:167], v[180:183], v[54:57]
	v_mfma_f32_16x16x32_bf16 v[50:53], v[172:175], v[180:183], v[50:53]
	v_mfma_f32_16x16x32_bf16 v[38:41], v[164:167], v[188:191], v[38:41]
	v_mfma_f32_16x16x32_bf16 v[30:33], v[172:175], v[188:191], v[30:33]
	v_mfma_f32_16x16x32_bf16 v[22:25], v[164:167], v[196:199], v[22:25]
	v_mfma_f32_16x16x32_bf16 v[14:17], v[172:175], v[196:199], v[14:17]
	v_mfma_f32_16x16x32_bf16 v[6:9], v[164:167], v[212:215], v[6:9]
	v_mfma_f32_16x16x32_bf16 v[2:5], v[172:175], v[212:215], v[2:5]
	v_mfma_f32_16x16x32_bf16 v[54:57], v[168:171], v[184:187], v[54:57]
	v_mfma_f32_16x16x32_bf16 v[50:53], v[176:179], v[184:187], v[50:53]
	v_mfma_f32_16x16x32_bf16 v[38:41], v[168:171], v[192:195], v[38:41]
	v_mfma_f32_16x16x32_bf16 v[30:33], v[176:179], v[192:195], v[30:33]
	v_mfma_f32_16x16x32_bf16 v[22:25], v[168:171], v[208:211], v[22:25]
	v_mfma_f32_16x16x32_bf16 v[14:17], v[176:179], v[208:211], v[14:17]
	v_mfma_f32_16x16x32_bf16 v[6:9], v[168:171], v[216:219], v[6:9]
	v_mfma_f32_16x16x32_bf16 v[2:5], v[176:179], v[216:219], v[2:5]
	s_setprio 0
	s_barrier
	s_add_i32 s78, s78, 2
	s_add_u32 s30, s30, 0x100
	s_addc_u32 s31, s31, 0
	s_add_u32 s70, s70, 0x100
	s_addc_u32 s71, s71, 0
	s_cmp_gt_u32 s78, 13
	s_cbranch_scc1 .Lpk_done_g286
.LBB0_286:
	s_add_u32 s20, s30, 0xfffc0080
	s_addc_u32 s21, s31, -1
	s_add_i32 s79, 0, 0x10000
	s_cmp_eq_u32 s78, 12
	s_cselect_b32 s37, s15, s21
	s_cselect_b32 s36, s62, s20
	v_add_u32_e32 v0, s79, v149
	s_cselect_b32 s35, s9, s71
	s_cselect_b32 s34, s63, s70
	s_add_i32 s20, 0, 0x14000
	ds_read_b128 v[144:147], v0
	ds_read_b128 v[152:155], v0 offset:1024
	ds_read_b128 v[156:159], v0 offset:2048
	ds_read_b128 v[160:163], v0 offset:3072
	v_add_u32_e32 v0, s20, v149
	ds_read_b128 v[164:167], v0
	ds_read_b128 v[168:171], v0 offset:1024
	ds_read_b128 v[172:175], v0 offset:2048
	ds_read_b128 v[176:179], v0 offset:3072
	v_lshl_add_u64 v[200:201], s[30:31], 0, v[138:139]
	s_add_i32 m0, s42, 0xc000
	ds_read_b128 v[180:183], v150
	ds_read_b128 v[184:187], v150 offset:1024
	ds_read_b128 v[188:191], v150 offset:2048
	ds_read_b128 v[192:195], v150 offset:3072
	ds_read_b128 v[196:199], v150 offset:4096
	ds_read_b128 v[208:211], v150 offset:5120
	ds_read_b128 v[212:215], v150 offset:6144
	ds_read_b128 v[216:219], v150 offset:7168
	global_load_lds_dwordx4 v[200:201], off
	v_lshl_add_u64 v[200:201], s[30:31], 0, v[140:141]
	s_add_i32 m0, s42, 0xe000
	s_nop 0
	global_load_lds_dwordx4 v[200:201], off
	s_waitcnt vmcnt(8)
	s_waitcnt lgkmcnt(0)
	s_barrier
; #define PG8_STAGE(bufoff, gbase, voff) do { _Pragma("unroll") for (int _i = 0; _i < 2; ++_i) \
;         __builtin_amdgcn_global_load_lds((const unsigned*)((const char*)(gbase) + (voff)[_i]), (PG8_LAS unsigned*)(lds + (bufoff) + ldsw + _i * 8192), 16, 0, 0); } while (0)
; #define PG8_LDA(dst, b, h) do { _Pragma("unroll") for (int m = 0; m < 4; ++m) _Pragma("unroll") for (int k = 0; k < 2; ++k) dst[m][k] = *(const PG8_LAS bf16x8*)(lds + PG8_SA(b, h) + aoff + m * 2048 + k * 1024); } while (0)
; #define PG8_MMA(ai, bj, At, Bt) do { __builtin_amdgcn_s_setprio(1); _Pragma("unroll") for (int m = 0; m < 4; ++m) _Pragma("unroll") for (int n = 0; n < 2; ++n) _Pragma("unroll") for (int k = 0; k < 2; ++k) \
;         acc[ai][bj][m][n] = __builtin_amdgcn_mfma_f32_16x16x32_bf16(Bt[n][k], At[m][k], acc[ai][bj][m][n], 0, 0, 0); __builtin_amdgcn_s_setprio(0); } while (0)
; #define PG8_WAIT_V(n) asm volatile("s_waitcnt vmcnt(" #n ")" ::: "memory")
; #define PG8_WAIT_L(n) asm volatile("s_waitcnt lgkmcnt(" #n ")" ::: "memory")
; #define PG8_BAR __builtin_amdgcn_s_barrier()
; #define PG8_SCHED __builtin_amdgcn_sched_barrier(0)
; template <class Epi, class Sched, bool ALIGN_EPI = false, bool SP2 = false>
; __device__ __forceinline__ void gemm_phase(PG8_LAS unsigned char* lds, const Gemm g, const Sched& S, const Epi& E) {
;     ...
;             PG8_WAIT_V(8); PG8_WAIT_L(0); PG8_BAR; PG8_MMA(0, 0, At, B0); PG8_MMA(0, 1, At, B1); PG8_BAR; PG8_SCHED;
;             PG8_LDA(At, 0, 1); PG8_STAGE(PG8_SB(0, 0), b2, voffB); PG8_STAGE(PG8_SB(0, 1), b2 + hstepB, voffB); PG8_STAGE(PG8_SA(0, 0), a2, voffA);
;             PG8_WAIT_V(8); PG8_WAIT_L(0); PG8_BAR; PG8_MMA(1, 0, At, B0); PG8_MMA(1, 1, At, B1); PG8_BAR; PG8_SCHED;
	s_setprio 1
	s_waitcnt lgkmcnt(0)
	v_mfma_f32_16x16x32_bf16 v[126:129], v[144:147], v[180:183], v[126:129]
	v_mfma_f32_16x16x32_bf16 v[122:125], v[156:159], v[180:183], v[122:125]
	v_mfma_f32_16x16x32_bf16 v[110:113], v[144:147], v[188:191], v[110:113]
	v_mfma_f32_16x16x32_bf16 v[106:109], v[156:159], v[188:191], v[106:109]
	v_mfma_f32_16x16x32_bf16 v[98:101], v[144:147], v[196:199], v[98:101]
	v_mfma_f32_16x16x32_bf16 v[90:93], v[156:159], v[196:199], v[90:93]
	v_mfma_f32_16x16x32_bf16 v[82:85], v[144:147], v[212:215], v[82:85]
	v_mfma_f32_16x16x32_bf16 v[74:77], v[156:159], v[212:215], v[74:77]
	v_mfma_f32_16x16x32_bf16 v[126:129], v[152:155], v[184:187], v[126:129]
	v_mfma_f32_16x16x32_bf16 v[122:125], v[160:163], v[184:187], v[122:125]
	v_mfma_f32_16x16x32_bf16 v[110:113], v[152:155], v[192:195], v[110:113]
	v_mfma_f32_16x16x32_bf16 v[106:109], v[160:163], v[192:195], v[106:109]
	v_mfma_f32_16x16x32_bf16 v[98:101], v[152:155], v[208:211], v[98:101]
	v_mfma_f32_16x16x32_bf16 v[90:93], v[160:163], v[208:211], v[90:93]
	v_mfma_f32_16x16x32_bf16 v[82:85], v[152:155], v[216:219], v[82:85]
	v_mfma_f32_16x16x32_bf16 v[74:77], v[160:163], v[216:219], v[74:77]
	v_mfma_f32_16x16x32_bf16 v[118:121], v[164:167], v[180:183], v[118:121]
	v_mfma_f32_16x16x32_bf16 v[114:117], v[172:175], v[180:183], v[114:117]
	v_mfma_f32_16x16x32_bf16 v[102:105], v[164:167], v[188:191], v[102:105]
	v_mfma_f32_16x16x32_bf16 v[94:97], v[172:175], v[188:191], v[94:97]
	v_mfma_f32_16x16x32_bf16 v[86:89], v[164:167], v[196:199], v[86:89]
	v_mfma_f32_16x16x32_bf16 v[78:81], v[172:175], v[196:199], v[78:81]
	v_mfma_f32_16x16x32_bf16 v[70:73], v[164:167], v[212:215], v[70:73]
	v_mfma_f32_16x16x32_bf16 v[66:69], v[172:175], v[212:215], v[66:69]
	v_mfma_f32_16x16x32_bf16 v[118:121], v[168:171], v[184:187], v[118:121]
	v_mfma_f32_16x16x32_bf16 v[114:117], v[176:179], v[184:187], v[114:117]
	v_mfma_f32_16x16x32_bf16 v[102:105], v[168:171], v[192:195], v[102:105]
	v_mfma_f32_16x16x32_bf16 v[94:97], v[176:179], v[192:195], v[94:97]
	v_mfma_f32_16x16x32_bf16 v[86:89], v[168:171], v[208:211], v[86:89]
	v_mfma_f32_16x16x32_bf16 v[78:81], v[176:179], v[208:211], v[78:81]
	v_mfma_f32_16x16x32_bf16 v[70:73], v[168:171], v[216:219], v[70:73]
	v_mfma_f32_16x16x32_bf16 v[66:69], v[176:179], v[216:219], v[66:69]
	s_setprio 0
	s_barrier
	s_add_i32 s21, s79, s26
	v_lshl_add_u64 v[200:201], s[34:35], 0, v[134:135]
	s_mov_b32 m0, s21
	ds_read_b128 v[180:183], v150 offset:16384
	ds_read_b128 v[184:187], v150 offset:17408
	ds_read_b128 v[188:191], v150 offset:18432
	ds_read_b128 v[192:195], v150 offset:19456
	ds_read_b128 v[196:199], v150 offset:20480
	ds_read_b128 v[208:211], v150 offset:21504
	ds_read_b128 v[212:215], v150 offset:22528
	ds_read_b128 v[216:219], v150 offset:23552
	global_load_lds_dwordx4 v[200:201], off
	s_add_i32 m0, s21, 0x2000
	s_add_u32 s80, s34, 0x40000
	v_lshl_add_u64 v[204:205], s[34:35], 0, v[130:131]
	s_addc_u32 s81, s35, 0
	s_add_i32 s20, s20, s26
	global_load_lds_dwordx4 v[204:205], off
	v_lshl_add_u64 v[220:221], s[80:81], 0, v[134:135]
	s_mov_b32 m0, s20
	v_lshl_add_u64 v[222:223], s[36:37], 0, v[132:133]
	global_load_lds_dwordx4 v[220:221], off
	v_lshl_add_u64 v[220:221], s[80:81], 0, v[130:131]
	s_add_i32 m0, s20, 0x2000
	s_nop 0
	global_load_lds_dwordx4 v[220:221], off
	v_lshl_add_u64 v[220:221], s[36:37], 0, v[136:137]
	s_mov_b32 m0, s42
	s_nop 0
	global_load_lds_dwordx4 v[220:221], off
	s_mov_b32 m0, s43
	s_nop 0
	global_load_lds_dwordx4 v[222:223], off
	s_waitcnt vmcnt(8)
	s_waitcnt lgkmcnt(0)
	s_barrier
	s_setprio 1
	s_waitcnt lgkmcnt(0)
	v_mfma_f32_16x16x32_bf16 v[62:65], v[144:147], v[180:183], v[62:65]
	v_mfma_f32_16x16x32_bf16 v[58:61], v[156:159], v[180:183], v[58:61]
	v_mfma_f32_16x16x32_bf16 v[46:49], v[144:147], v[188:191], v[46:49]
	v_mfma_f32_16x16x32_bf16 v[42:45], v[156:159], v[188:191], v[42:45]
	v_mfma_f32_16x16x32_bf16 v[34:37], v[144:147], v[196:199], v[34:37]
	v_mfma_f32_16x16x32_bf16 v[26:29], v[156:159], v[196:199], v[26:29]
	v_mfma_f32_16x16x32_bf16 v[18:21], v[144:147], v[212:215], v[18:21]
	v_mfma_f32_16x16x32_bf16 v[10:13], v[156:159], v[212:215], v[10:13]
	v_mfma_f32_16x16x32_bf16 v[62:65], v[152:155], v[184:187], v[62:65]
	v_mfma_f32_16x16x32_bf16 v[58:61], v[160:163], v[184:187], v[58:61]
	v_mfma_f32_16x16x32_bf16 v[46:49], v[152:155], v[192:195], v[46:49]
	v_mfma_f32_16x16x32_bf16 v[42:45], v[160:163], v[192:195], v[42:45]
	v_mfma_f32_16x16x32_bf16 v[34:37], v[152:155], v[208:211], v[34:37]
	v_mfma_f32_16x16x32_bf16 v[26:29], v[160:163], v[208:211], v[26:29]
	v_mfma_f32_16x16x32_bf16 v[18:21], v[152:155], v[216:219], v[18:21]
	v_mfma_f32_16x16x32_bf16 v[10:13], v[160:163], v[216:219], v[10:13]
	v_mfma_f32_16x16x32_bf16 v[54:57], v[164:167], v[180:183], v[54:57]
	v_mfma_f32_16x16x32_bf16 v[50:53], v[172:175], v[180:183], v[50:53]
	v_mfma_f32_16x16x32_bf16 v[38:41], v[164:167], v[188:191], v[38:41]
	v_mfma_f32_16x16x32_bf16 v[30:33], v[172:175], v[188:191], v[30:33]
	v_mfma_f32_16x16x32_bf16 v[22:25], v[164:167], v[196:199], v[22:25]
	v_mfma_f32_16x16x32_bf16 v[14:17], v[172:175], v[196:199], v[14:17]
	v_mfma_f32_16x16x32_bf16 v[6:9], v[164:167], v[212:215], v[6:9]
	v_mfma_f32_16x16x32_bf16 v[2:5], v[172:175], v[212:215], v[2:5]
	v_mfma_f32_16x16x32_bf16 v[54:57], v[168:171], v[184:187], v[54:57]
	v_mfma_f32_16x16x32_bf16 v[50:53], v[176:179], v[184:187], v[50:53]
	v_mfma_f32_16x16x32_bf16 v[38:41], v[168:171], v[192:195], v[38:41]
	v_mfma_f32_16x16x32_bf16 v[30:33], v[176:179], v[192:195], v[30:33]
	v_mfma_f32_16x16x32_bf16 v[22:25], v[168:171], v[208:211], v[22:25]
	v_mfma_f32_16x16x32_bf16 v[14:17], v[176:179], v[208:211], v[14:17]
	v_mfma_f32_16x16x32_bf16 v[6:9], v[168:171], v[216:219], v[6:9]
	v_mfma_f32_16x16x32_bf16 v[2:5], v[176:179], v[216:219], v[2:5]
	s_setprio 0
	s_barrier
; #define PG8_STAGE(bufoff, gbase, voff) do { _Pragma("unroll") for (int _i = 0; _i < 2; ++_i) \
;         __builtin_amdgcn_global_load_lds((const unsigned*)((const char*)(gbase) + (voff)[_i]), (PG8_LAS unsigned*)(lds + (bufoff) + ldsw + _i * 8192), 16, 0, 0); } while (0)
; #define PG8_LDA(dst, b, h) do { _Pragma("unroll") for (int m = 0; m < 4; ++m) _Pragma("unroll") for (int k = 0; k < 2; ++k) dst[m][k] = *(const PG8_LAS bf16x8*)(lds + PG8_SA(b, h) + aoff + m * 2048 + k * 1024); } while (0)
; #define PG8_LDB(dst, b, h) do { _Pragma("unroll") for (int n = 0; n < 2; ++n) _Pragma("unroll") for (int k = 0; k < 2; ++k) dst[n][k] = *(const PG8_LAS bf16x8*)(lds + PG8_SB(b, h) + boff + n * 2048 + k * 1024); } while (0)
; #define PG8_MMA(ai, bj, At, Bt) do { __builtin_amdgcn_s_setprio(1); _Pragma("unroll") for (int m = 0; m < 4; ++m) _Pragma("unroll") for (int n = 0; n < 2; ++n) _Pragma("unroll") for (int k = 0; k < 2; ++k) \
;         acc[ai][bj][m][n] = __builtin_amdgcn_mfma_f32_16x16x32_bf16(Bt[n][k], At[m][k], acc[ai][bj][m][n], 0, 0, 0); __builtin_amdgcn_s_setprio(0); } while (0)
; #define PG8_WAIT_V(n) asm volatile("s_waitcnt vmcnt(" #n ")" ::: "memory")
; #define PG8_WAIT_L(n) asm volatile("s_waitcnt lgkmcnt(" #n ")" ::: "memory")
; #define PG8_BAR __builtin_amdgcn_s_barrier()
; #define PG8_SCHED __builtin_amdgcn_sched_barrier(0)
; template <class Epi, class Sched, bool ALIGN_EPI = false, bool SP2 = false>
; __device__ __forceinline__ void gemm_phase(PG8_LAS unsigned char* lds, const Gemm g, const Sched& S, const Epi& E) {
;     ...
;             PG8_LDB(B0, 1, 0); PG8_LDB(B1, 1, 1); PG8_SCHED; PG8_LDA(At, 1, 0); PG8_STAGE(PG8_SA(0, 1), a2 + hstepA, voffA);
;             PG8_WAIT_V(8); PG8_WAIT_L(0); PG8_BAR; PG8_MMA(0, 0, At, B0); PG8_MMA(0, 1, At, B1); PG8_BAR; PG8_SCHED;
	s_add_i32 s20, 0, 0x18000
	v_add_u32_e32 v0, s20, v149
	s_add_i32 s21, 0, 0x1c000
	ds_read_b128 v[144:147], v0
	ds_read_b128 v[152:155], v0 offset:1024
	ds_read_b128 v[156:159], v0 offset:2048
	ds_read_b128 v[160:163], v0 offset:3072
	v_add_u32_e32 v0, s21, v149
	ds_read_b128 v[164:167], v0
	ds_read_b128 v[168:171], v0 offset:1024
	ds_read_b128 v[172:175], v0 offset:2048
	ds_read_b128 v[176:179], v0 offset:3072
	s_add_u32 s36, s36, 0x40000
	s_addc_u32 s37, s37, 0
	s_mov_b32 m0, s46
	v_lshl_add_u64 v[224:225], s[36:37], 0, v[136:137]
	ds_read_b128 v[180:183], v150 offset:32768
	ds_read_b128 v[184:187], v150 offset:33792
	ds_read_b128 v[188:191], v150 offset:34816
	ds_read_b128 v[192:195], v150 offset:35840
	ds_read_b128 v[196:199], v150 offset:36864
	ds_read_b128 v[208:211], v150 offset:37888
	ds_read_b128 v[212:215], v150 offset:38912
	ds_read_b128 v[216:219], v150 offset:39936
	global_load_lds_dwordx4 v[224:225], off
	v_lshl_add_u64 v[224:225], s[36:37], 0, v[132:133]
	s_mov_b32 m0, s47
	s_nop 0
	global_load_lds_dwordx4 v[224:225], off
	s_waitcnt vmcnt(8)
	s_waitcnt lgkmcnt(0)
	s_barrier
	s_setprio 1
	s_waitcnt lgkmcnt(0)
	v_mfma_f32_16x16x32_bf16 v[126:129], v[144:147], v[180:183], v[126:129]
	v_mfma_f32_16x16x32_bf16 v[122:125], v[156:159], v[180:183], v[122:125]
	v_mfma_f32_16x16x32_bf16 v[110:113], v[144:147], v[188:191], v[110:113]
	v_mfma_f32_16x16x32_bf16 v[106:109], v[156:159], v[188:191], v[106:109]
	v_mfma_f32_16x16x32_bf16 v[98:101], v[144:147], v[196:199], v[98:101]
	v_mfma_f32_16x16x32_bf16 v[90:93], v[156:159], v[196:199], v[90:93]
	v_mfma_f32_16x16x32_bf16 v[82:85], v[144:147], v[212:215], v[82:85]
	v_mfma_f32_16x16x32_bf16 v[74:77], v[156:159], v[212:215], v[74:77]
	v_mfma_f32_16x16x32_bf16 v[126:129], v[152:155], v[184:187], v[126:129]
	v_mfma_f32_16x16x32_bf16 v[122:125], v[160:163], v[184:187], v[122:125]
	v_mfma_f32_16x16x32_bf16 v[110:113], v[152:155], v[192:195], v[110:113]
	v_mfma_f32_16x16x32_bf16 v[106:109], v[160:163], v[192:195], v[106:109]
	v_mfma_f32_16x16x32_bf16 v[98:101], v[152:155], v[208:211], v[98:101]
	v_mfma_f32_16x16x32_bf16 v[90:93], v[160:163], v[208:211], v[90:93]
	v_mfma_f32_16x16x32_bf16 v[82:85], v[152:155], v[216:219], v[82:85]
	v_mfma_f32_16x16x32_bf16 v[74:77], v[160:163], v[216:219], v[74:77]
	v_mfma_f32_16x16x32_bf16 v[118:121], v[164:167], v[180:183], v[118:121]
	v_mfma_f32_16x16x32_bf16 v[114:117], v[172:175], v[180:183], v[114:117]
	v_mfma_f32_16x16x32_bf16 v[102:105], v[164:167], v[188:191], v[102:105]
	v_mfma_f32_16x16x32_bf16 v[94:97], v[172:175], v[188:191], v[94:97]
	v_mfma_f32_16x16x32_bf16 v[86:89], v[164:167], v[196:199], v[86:89]
	v_mfma_f32_16x16x32_bf16 v[78:81], v[172:175], v[196:199], v[78:81]
	v_mfma_f32_16x16x32_bf16 v[70:73], v[164:167], v[212:215], v[70:73]
	v_mfma_f32_16x16x32_bf16 v[66:69], v[172:175], v[212:215], v[66:69]
	v_mfma_f32_16x16x32_bf16 v[118:121], v[168:171], v[184:187], v[118:121]
	v_mfma_f32_16x16x32_bf16 v[114:117], v[176:179], v[184:187], v[114:117]
	v_mfma_f32_16x16x32_bf16 v[102:105], v[168:171], v[192:195], v[102:105]
	v_mfma_f32_16x16x32_bf16 v[94:97], v[176:179], v[192:195], v[94:97]
	v_mfma_f32_16x16x32_bf16 v[86:89], v[168:171], v[208:211], v[86:89]
	v_mfma_f32_16x16x32_bf16 v[78:81], v[176:179], v[208:211], v[78:81]
	v_mfma_f32_16x16x32_bf16 v[70:73], v[168:171], v[216:219], v[70:73]
	v_mfma_f32_16x16x32_bf16 v[66:69], v[176:179], v[216:219], v[66:69]
	s_setprio 0
	s_barrier
; #define PG8_STAGE(bufoff, gbase, voff) do { _Pragma("unroll") for (int _i = 0; _i < 2; ++_i) \
;         __builtin_amdgcn_global_load_lds((const unsigned*)((const char*)(gbase) + (voff)[_i]), (PG8_LAS unsigned*)(lds + (bufoff) + ldsw + _i * 8192), 16, 0, 0); } while (0)
; #define PG8_LDA(dst, b, h) do { _Pragma("unroll") for (int m = 0; m < 4; ++m) _Pragma("unroll") for (int k = 0; k < 2; ++k) dst[m][k] = *(const PG8_LAS bf16x8*)(lds + PG8_SA(b, h) + aoff + m * 2048 + k * 1024); } while (0)
; #define PG8_MMA(ai, bj, At, Bt) do { __builtin_amdgcn_s_setprio(1); _Pragma("unroll") for (int m = 0; m < 4; ++m) _Pragma("unroll") for (int n = 0; n < 2; ++n) _Pragma("unroll") for (int k = 0; k < 2; ++k) \
;         acc[ai][bj][m][n] = __builtin_amdgcn_mfma_f32_16x16x32_bf16(Bt[n][k], At[m][k], acc[ai][bj][m][n], 0, 0, 0); __builtin_amdgcn_s_setprio(0); } while (0)
; #define PG8_WAIT_V(n) asm volatile("s_waitcnt vmcnt(" #n ")" ::: "memory")
; #define PG8_WAIT_L(n) asm volatile("s_waitcnt lgkmcnt(" #n ")" ::: "memory")
; #define PG8_BAR __builtin_amdgcn_s_barrier()
; #define PG8_SCHED __builtin_amdgcn_sched_barrier(0)
; template <class Epi, class Sched, bool ALIGN_EPI = false, bool SP2 = false>
; __device__ __forceinline__ void gemm_phase(PG8_LAS unsigned char* lds, const Gemm g, const Sched& S, const Epi& E) {
;     ...
;         for (int t = 0; t < nt; t += 2) {
;             const bool last = (t == nt - 2);
;             const char* a1 = cA + (size_t)(t + 1) * kstep;
;             const char* a2 = last ? nA : cA + (size_t)(t + 2) * kstep; const char* b2 = last ? nB : cB + (size_t)(t + 2) * kstep;
;             const char* a3 = a2 + kstep; const char* b3 = b2 + kstep;
;     ...
;             PG8_LDA(At, 1, 1); PG8_STAGE(PG8_SB(1, 0), b3, voffB); PG8_STAGE(PG8_SB(1, 1), b3 + hstepB, voffB); PG8_STAGE(PG8_SA(1, 0), a3, voffA);
;             PG8_WAIT_V(8); PG8_WAIT_L(0); PG8_BAR; PG8_MMA(1, 0, At, B0); PG8_MMA(1, 1, At, B1); PG8_BAR; PG8_SCHED;
	s_add_i32 s20, s20, s26
	v_lshl_add_u64 v[200:201], v[200:201], 0, s[22:23]
	s_mov_b32 m0, s20
	ds_read_b128 v[180:183], v150 offset:49152
	ds_read_b128 v[184:187], v150 offset:50176
	ds_read_b128 v[188:191], v150 offset:51200
	ds_read_b128 v[192:195], v150 offset:52224
	ds_read_b128 v[196:199], v150 offset:53248
	ds_read_b128 v[208:211], v150 offset:54272
	ds_read_b128 v[212:215], v150 offset:55296
	ds_read_b128 v[216:219], v150 offset:56320
	global_load_lds_dwordx4 v[200:201], off
	s_add_i32 m0, s20, 0x2000
	s_add_u32 s34, s34, 0x40080
	v_lshl_add_u64 v[200:201], v[204:205], 0, s[22:23]
	s_addc_u32 s35, s35, 0
	s_add_i32 s20, s21, s26
	global_load_lds_dwordx4 v[200:201], off
	v_lshl_add_u64 v[200:201], s[34:35], 0, v[134:135]
	s_mov_b32 m0, s20
	s_nop 0
	global_load_lds_dwordx4 v[200:201], off
	v_lshl_add_u64 v[200:201], s[34:35], 0, v[130:131]
	s_add_i32 m0, s20, 0x2000
	s_nop 0
	global_load_lds_dwordx4 v[200:201], off
	v_lshl_add_u64 v[200:201], v[220:221], 0, s[22:23]
	s_mov_b32 m0, s56
	s_nop 0
	global_load_lds_dwordx4 v[200:201], off
	v_lshl_add_u64 v[200:201], v[222:223], 0, s[22:23]
	s_mov_b32 m0, s57
	s_nop 0
	global_load_lds_dwordx4 v[200:201], off
	s_waitcnt vmcnt(8)
	s_waitcnt lgkmcnt(0)
	s_barrier
	s_setprio 1
	s_waitcnt lgkmcnt(0)
	v_mfma_f32_16x16x32_bf16 v[62:65], v[144:147], v[180:183], v[62:65]
	v_mfma_f32_16x16x32_bf16 v[58:61], v[156:159], v[180:183], v[58:61]
	v_mfma_f32_16x16x32_bf16 v[46:49], v[144:147], v[188:191], v[46:49]
	v_mfma_f32_16x16x32_bf16 v[42:45], v[156:159], v[188:191], v[42:45]
	v_mfma_f32_16x16x32_bf16 v[34:37], v[144:147], v[196:199], v[34:37]
	v_mfma_f32_16x16x32_bf16 v[26:29], v[156:159], v[196:199], v[26:29]
	v_mfma_f32_16x16x32_bf16 v[18:21], v[144:147], v[212:215], v[18:21]
	v_mfma_f32_16x16x32_bf16 v[10:13], v[156:159], v[212:215], v[10:13]
	v_mfma_f32_16x16x32_bf16 v[62:65], v[152:155], v[184:187], v[62:65]
	v_mfma_f32_16x16x32_bf16 v[58:61], v[160:163], v[184:187], v[58:61]
	v_mfma_f32_16x16x32_bf16 v[46:49], v[152:155], v[192:195], v[46:49]
	v_mfma_f32_16x16x32_bf16 v[42:45], v[160:163], v[192:195], v[42:45]
	v_mfma_f32_16x16x32_bf16 v[34:37], v[152:155], v[208:211], v[34:37]
	v_mfma_f32_16x16x32_bf16 v[26:29], v[160:163], v[208:211], v[26:29]
	v_mfma_f32_16x16x32_bf16 v[18:21], v[152:155], v[216:219], v[18:21]
	v_mfma_f32_16x16x32_bf16 v[10:13], v[160:163], v[216:219], v[10:13]
	v_mfma_f32_16x16x32_bf16 v[54:57], v[164:167], v[180:183], v[54:57]
	v_mfma_f32_16x16x32_bf16 v[50:53], v[172:175], v[180:183], v[50:53]
	v_mfma_f32_16x16x32_bf16 v[38:41], v[164:167], v[188:191], v[38:41]
	v_mfma_f32_16x16x32_bf16 v[30:33], v[172:175], v[188:191], v[30:33]
	v_mfma_f32_16x16x32_bf16 v[22:25], v[164:167], v[196:199], v[22:25]
	v_mfma_f32_16x16x32_bf16 v[14:17], v[172:175], v[196:199], v[14:17]
	v_mfma_f32_16x16x32_bf16 v[6:9], v[164:167], v[212:215], v[6:9]
	v_mfma_f32_16x16x32_bf16 v[2:5], v[172:175], v[212:215], v[2:5]
	v_mfma_f32_16x16x32_bf16 v[54:57], v[168:171], v[184:187], v[54:57]
	v_mfma_f32_16x16x32_bf16 v[50:53], v[176:179], v[184:187], v[50:53]
	v_mfma_f32_16x16x32_bf16 v[38:41], v[168:171], v[192:195], v[38:41]
	v_mfma_f32_16x16x32_bf16 v[30:33], v[176:179], v[192:195], v[30:33]
	v_mfma_f32_16x16x32_bf16 v[22:25], v[168:171], v[208:211], v[22:25]
	v_mfma_f32_16x16x32_bf16 v[14:17], v[176:179], v[208:211], v[14:17]
	v_mfma_f32_16x16x32_bf16 v[6:9], v[168:171], v[216:219], v[6:9]
	v_mfma_f32_16x16x32_bf16 v[2:5], v[176:179], v[216:219], v[2:5]
	s_setprio 0
	s_barrier
	s_add_i32 s78, s78, 2
	s_add_u32 s30, s30, 0x100
	s_addc_u32 s31, s31, 0
	s_add_u32 s70, s70, 0x100
	s_addc_u32 s71, s71, 0
	s_cmp_gt_u32 s78, 13
	s_cbranch_scc0 .LBB0_286

; #define PG8_STAGE(bufoff, gbase, voff) do { _Pragma("unroll") for (int _i = 0; _i < 2; ++_i) \
;         __builtin_amdgcn_global_load_lds((const unsigned*)((const char*)(gbase) + (voff)[_i]), (PG8_LAS unsigned*)(lds + (bufoff) + ldsw + _i * 8192), 16, 0, 0); } while (0)
; #define PG8_LDA(dst, b, h) do { _Pragma("unroll") for (int m = 0; m < 4; ++m) _Pragma("unroll") for (int k = 0; k < 2; ++k) dst[m][k] = *(const PG8_LAS bf16x8*)(lds + PG8_SA(b, h) + aoff + m * 2048 + k * 1024); } while (0)
; #define PG8_LDB(dst, b, h) do { _Pragma("unroll") for (int n = 0; n < 2; ++n) _Pragma("unroll") for (int k = 0; k < 2; ++k) dst[n][k] = *(const PG8_LAS bf16x8*)(lds + PG8_SB(b, h) + boff + n * 2048 + k * 1024); } while (0)
; #define PG8_WAIT_V(n) asm volatile("s_waitcnt vmcnt(" #n ")" ::: "memory")
; #define PG8_WAIT_L(n) asm volatile("s_waitcnt lgkmcnt(" #n ")" ::: "memory")
; #define PG8_BAR __builtin_amdgcn_s_barrier()
; template <class Epi, class Sched, bool ALIGN_EPI = false, bool SP2 = false>
; __device__ __forceinline__ void gemm_phase(PG8_LAS unsigned char* lds, const Gemm g, const Sched& S, const Epi& E) {
;     ...
;         const bool has_next = S.next(ui + 1, nxt);
;         const char* nA = has_next ? (const char*)g.A + (size_t)nxt.pm * tstepA + (size_t)nxt.pb * g.sA : cA; const char* nB = has_next ? (const char*)g.Bt + (size_t)nxt.pn * tstepB + (size_t)nxt.pb * g.sB : cB;
;         for (int t = 0; t < nt; t += 2) {
;             const bool last = (t == nt - 2);
;             const char* a1 = cA + (size_t)(t + 1) * kstep;
;             const char* a2 = last ? nA : cA + (size_t)(t + 2) * kstep; const char* b2 = last ? nB : cB + (size_t)(t + 2) * kstep;
;             const char* a3 = a2 + kstep; const char* b3 = b2 + kstep;
;             if (last && has_next) S.a_ready(nxt);
;             if constexpr (SP2) {
;             PG8_LDB(B0, 0, 0); PG8_LDB(B1, 0, 1); PG8_SCHED; PG8_LDA(At, 0, 0); PG8_STAGE(PG8_SA(1, 1), a1 + hstepA, voffA);
;             PG8_WAIT_V(8); PG8_WAIT_L(0); PG8_BAR; PG8_MMA(0, 0, At, B0); PG8_MMA(0, 1, At, B1); PG8_BAR; PG8_SCHED;
;             PG8_LDA(At, 0, 1); PG8_STAGE(PG8_SB(0, 0), b2, voffB); PG8_STAGE(PG8_SB(0, 1), b2 + hstepB, voffB); PG8_STAGE(PG8_SA(0, 0), a2, voffA);
;             PG8_WAIT_V(8); PG8_WAIT_L(0); PG8_BAR; PG8_MMA(1, 0, At, B0); PG8_MMA(1, 1, At, B1); PG8_BAR; PG8_SCHED;
.LBB0_454:
	s_ashr_i32 s9, s8, 31
	s_lshl_b64 s[0:1], s[8:9], 19
	s_add_u32 s34, s56, s0
	s_addc_u32 s35, s57, s1
	s_and_b64 s[0:1], s[46:47], exec
	s_cselect_b32 s9, s35, s37
	s_cselect_b32 s39, s34, s36
	s_ashr_i32 s53, s52, 31
	s_lshl_b64 s[0:1], s[52:53], 19
	s_add_u32 s0, s26, s0
	s_addc_u32 s1, s78, s1
	s_and_b64 s[54:55], s[46:47], exec
	s_cselect_b32 s43, s1, s71
	s_cselect_b32 s53, s0, s70
	s_add_u32 s36, s36, 0x40080
	s_addc_u32 s37, s37, 0
	s_add_u32 s54, s70, 0x100
	s_addc_u32 s55, s71, 0
	s_mov_b32 s60, -2
	s_waitcnt lgkmcnt(0)
	s_add_u32 s20, s36, 0xfffc0080
	s_addc_u32 s21, s37, -1
	s_add_i32 s61, 0, 0x10000
	s_cmp_eq_u32 s60, 12
	s_cselect_b32 vcc_hi, s9, s21
	s_cselect_b32 vcc_lo, s39, s20
	s_cselect_b32 s71, s43, s55
	s_cselect_b32 s70, s53, s54
	s_add_i32 s63, 0, 0x14000
	v_add_u32_e32 v102, s61, v222
	v_add_u32_e32 v158, s63, v222
	ds_read_b128 v[90:93], v102
	ds_read_b128 v[94:97], v102 offset:1024
	ds_read_b128 v[98:101], v102 offset:2048
	ds_read_b128 v[102:105], v102 offset:3072
	ds_read_b128 v[146:149], v158
	ds_read_b128 v[150:153], v158 offset:1024
	ds_read_b128 v[154:157], v158 offset:2048
	ds_read_b128 v[158:161], v158 offset:3072
	v_lshl_add_u64 v[204:205], s[36:37], 0, v[214:215]
	s_add_i32 m0, s80, 0xc000
	ds_read_b128 v[162:165], v227
	ds_read_b128 v[166:169], v227 offset:1024
	ds_read_b128 v[170:173], v227 offset:2048
	ds_read_b128 v[174:177], v227 offset:3072
	ds_read_b128 v[178:181], v227 offset:4096
	ds_read_b128 v[182:185], v227 offset:5120
	ds_read_b128 v[218:221], v227 offset:6144
	ds_read_b128 v[240:243], v227 offset:7168
	global_load_lds_dwordx4 v[204:205], off
	v_lshl_add_u64 v[204:205], s[36:37], 0, v[216:217]
	s_add_i32 m0, s80, 0xe000
	s_nop 0
	global_load_lds_dwordx4 v[204:205], off
	s_waitcnt vmcnt(8)
	s_waitcnt lgkmcnt(0)
	s_barrier
	s_setprio 1
	s_waitcnt lgkmcnt(0)
	v_mfma_f32_16x16x32_bf16 v[142:145], v[90:93], v[162:165], 0
	v_mfma_f32_16x16x32_bf16 v[138:141], v[98:101], v[162:165], 0
	v_mfma_f32_16x16x32_bf16 v[126:129], v[90:93], v[170:173], 0
	v_mfma_f32_16x16x32_bf16 v[122:125], v[98:101], v[170:173], 0
	v_mfma_f32_16x16x32_bf16 v[110:113], v[90:93], v[178:181], 0
	v_mfma_f32_16x16x32_bf16 v[106:109], v[98:101], v[178:181], 0
	v_mfma_f32_16x16x32_bf16 v[78:81], v[90:93], v[218:221], 0
	v_mfma_f32_16x16x32_bf16 v[74:77], v[98:101], v[218:221], 0
	v_mfma_f32_16x16x32_bf16 v[142:145], v[94:97], v[166:169], v[142:145]
	v_mfma_f32_16x16x32_bf16 v[138:141], v[102:105], v[166:169], v[138:141]
	v_mfma_f32_16x16x32_bf16 v[126:129], v[94:97], v[174:177], v[126:129]
	v_mfma_f32_16x16x32_bf16 v[122:125], v[102:105], v[174:177], v[122:125]
	v_mfma_f32_16x16x32_bf16 v[110:113], v[94:97], v[182:185], v[110:113]
	v_mfma_f32_16x16x32_bf16 v[106:109], v[102:105], v[182:185], v[106:109]
	v_mfma_f32_16x16x32_bf16 v[78:81], v[94:97], v[240:243], v[78:81]
	v_mfma_f32_16x16x32_bf16 v[74:77], v[102:105], v[240:243], v[74:77]
	v_mfma_f32_16x16x32_bf16 v[134:137], v[146:149], v[162:165], 0
	v_mfma_f32_16x16x32_bf16 v[130:133], v[154:157], v[162:165], 0
	v_mfma_f32_16x16x32_bf16 v[118:121], v[146:149], v[170:173], 0
	v_mfma_f32_16x16x32_bf16 v[114:117], v[154:157], v[170:173], 0
	v_mfma_f32_16x16x32_bf16 v[86:89], v[146:149], v[178:181], 0
	v_mfma_f32_16x16x32_bf16 v[82:85], v[154:157], v[178:181], 0
	v_mfma_f32_16x16x32_bf16 v[70:73], v[146:149], v[218:221], 0
	v_mfma_f32_16x16x32_bf16 v[66:69], v[154:157], v[218:221], 0
	v_mfma_f32_16x16x32_bf16 v[134:137], v[150:153], v[166:169], v[134:137]
	v_mfma_f32_16x16x32_bf16 v[130:133], v[158:161], v[166:169], v[130:133]
	v_mfma_f32_16x16x32_bf16 v[118:121], v[150:153], v[174:177], v[118:121]
	v_mfma_f32_16x16x32_bf16 v[114:117], v[158:161], v[174:177], v[114:117]
	v_mfma_f32_16x16x32_bf16 v[86:89], v[150:153], v[182:185], v[86:89]
	v_mfma_f32_16x16x32_bf16 v[82:85], v[158:161], v[182:185], v[82:85]
	v_mfma_f32_16x16x32_bf16 v[70:73], v[150:153], v[240:243], v[70:73]
	v_mfma_f32_16x16x32_bf16 v[66:69], v[158:161], v[240:243], v[66:69]
	s_setprio 0
	s_barrier
	s_add_i32 s20, s61, s79
	v_lshl_add_u64 v[204:205], s[70:71], 0, v[0:1]
	s_mov_b32 m0, s20
	ds_read_b128 v[162:165], v227 offset:16384
	ds_read_b128 v[166:169], v227 offset:17408
	ds_read_b128 v[170:173], v227 offset:18432
	ds_read_b128 v[174:177], v227 offset:19456
	ds_read_b128 v[178:181], v227 offset:20480
	ds_read_b128 v[182:185], v227 offset:21504
	ds_read_b128 v[218:221], v227 offset:22528
	ds_read_b128 v[240:243], v227 offset:23552
	global_load_lds_dwordx4 v[204:205], off
	s_add_i32 m0, s20, 0x2000
	s_add_u32 s20, s70, 0x40000
	v_lshl_add_u64 v[234:235], s[70:71], 0, v[186:187]
	s_addc_u32 s21, s71, 0
	s_add_i32 s61, s63, s79
	global_load_lds_dwordx4 v[234:235], off
	v_lshl_add_u64 v[244:245], s[20:21], 0, v[0:1]
	s_mov_b32 m0, s61
	v_lshl_add_u64 v[246:247], vcc, 0, v[188:189]
	global_load_lds_dwordx4 v[244:245], off
	v_lshl_add_u64 v[244:245], s[20:21], 0, v[186:187]
	s_add_i32 m0, s61, 0x2000
	s_nop 0
	global_load_lds_dwordx4 v[244:245], off
	v_lshl_add_u64 v[244:245], vcc, 0, v[190:191]
	s_mov_b32 m0, s80
	s_nop 0
	global_load_lds_dwordx4 v[244:245], off
	s_mov_b32 m0, s81
	s_nop 0
	global_load_lds_dwordx4 v[246:247], off
	s_waitcnt vmcnt(8)
	s_waitcnt lgkmcnt(0)
	s_barrier
; #define PG8_STAGE(bufoff, gbase, voff) do { _Pragma("unroll") for (int _i = 0; _i < 2; ++_i) \
;         __builtin_amdgcn_global_load_lds((const unsigned*)((const char*)(gbase) + (voff)[_i]), (PG8_LAS unsigned*)(lds + (bufoff) + ldsw + _i * 8192), 16, 0, 0); } while (0)
; #define PG8_LDA(dst, b, h) do { _Pragma("unroll") for (int m = 0; m < 4; ++m) _Pragma("unroll") for (int k = 0; k < 2; ++k) dst[m][k] = *(const PG8_LAS bf16x8*)(lds + PG8_SA(b, h) + aoff + m * 2048 + k * 1024); } while (0)
; #define PG8_LDB(dst, b, h) do { _Pragma("unroll") for (int n = 0; n < 2; ++n) _Pragma("unroll") for (int k = 0; k < 2; ++k) dst[n][k] = *(const PG8_LAS bf16x8*)(lds + PG8_SB(b, h) + boff + n * 2048 + k * 1024); } while (0)
; #define PG8_MMA(ai, bj, At, Bt) do { __builtin_amdgcn_s_setprio(1); _Pragma("unroll") for (int m = 0; m < 4; ++m) _Pragma("unroll") for (int n = 0; n < 2; ++n) _Pragma("unroll") for (int k = 0; k < 2; ++k) \
;         acc[ai][bj][m][n] = __builtin_amdgcn_mfma_f32_16x16x32_bf16(Bt[n][k], At[m][k], acc[ai][bj][m][n], 0, 0, 0); __builtin_amdgcn_s_setprio(0); } while (0)
; #define PG8_WAIT_V(n) asm volatile("s_waitcnt vmcnt(" #n ")" ::: "memory")
; #define PG8_WAIT_L(n) asm volatile("s_waitcnt lgkmcnt(" #n ")" ::: "memory")
; #define PG8_BAR __builtin_amdgcn_s_barrier()
; #define PG8_SCHED __builtin_amdgcn_sched_barrier(0)
; template <class Epi, class Sched, bool ALIGN_EPI = false, bool SP2 = false>
; __device__ __forceinline__ void gemm_phase(PG8_LAS unsigned char* lds, const Gemm g, const Sched& S, const Epi& E) {
;     ...
;             PG8_WAIT_V(8); PG8_WAIT_L(0); PG8_BAR; PG8_MMA(1, 0, At, B0); PG8_MMA(1, 1, At, B1); PG8_BAR; PG8_SCHED;
;             PG8_LDB(B0, 1, 0); PG8_LDB(B1, 1, 1); PG8_SCHED; PG8_LDA(At, 1, 0); PG8_STAGE(PG8_SA(0, 1), a2 + hstepA, voffA);
;             PG8_WAIT_V(8); PG8_WAIT_L(0); PG8_BAR; PG8_MMA(0, 0, At, B0); PG8_MMA(0, 1, At, B1); PG8_BAR; PG8_SCHED;
	s_setprio 1
	s_waitcnt lgkmcnt(0)
	v_mfma_f32_16x16x32_bf16 v[62:65], v[90:93], v[162:165], 0
	v_mfma_f32_16x16x32_bf16 v[58:61], v[98:101], v[162:165], 0
	v_mfma_f32_16x16x32_bf16 v[46:49], v[90:93], v[170:173], 0
	v_mfma_f32_16x16x32_bf16 v[42:45], v[98:101], v[170:173], 0
	v_mfma_f32_16x16x32_bf16 v[30:33], v[90:93], v[178:181], 0
	v_mfma_f32_16x16x32_bf16 v[26:29], v[98:101], v[178:181], 0
	v_mfma_f32_16x16x32_bf16 v[14:17], v[90:93], v[218:221], 0
	v_mfma_f32_16x16x32_bf16 v[10:13], v[98:101], v[218:221], 0
	v_mfma_f32_16x16x32_bf16 v[62:65], v[94:97], v[166:169], v[62:65]
	v_mfma_f32_16x16x32_bf16 v[58:61], v[102:105], v[166:169], v[58:61]
	v_mfma_f32_16x16x32_bf16 v[46:49], v[94:97], v[174:177], v[46:49]
	v_mfma_f32_16x16x32_bf16 v[42:45], v[102:105], v[174:177], v[42:45]
	v_mfma_f32_16x16x32_bf16 v[30:33], v[94:97], v[182:185], v[30:33]
	v_mfma_f32_16x16x32_bf16 v[26:29], v[102:105], v[182:185], v[26:29]
	v_mfma_f32_16x16x32_bf16 v[14:17], v[94:97], v[240:243], v[14:17]
	v_mfma_f32_16x16x32_bf16 v[10:13], v[102:105], v[240:243], v[10:13]
	v_mfma_f32_16x16x32_bf16 v[54:57], v[146:149], v[162:165], 0
	v_mfma_f32_16x16x32_bf16 v[50:53], v[154:157], v[162:165], 0
	v_mfma_f32_16x16x32_bf16 v[38:41], v[146:149], v[170:173], 0
	v_mfma_f32_16x16x32_bf16 v[34:37], v[154:157], v[170:173], 0
	v_mfma_f32_16x16x32_bf16 v[22:25], v[146:149], v[178:181], 0
	v_mfma_f32_16x16x32_bf16 v[18:21], v[154:157], v[178:181], 0
	v_mfma_f32_16x16x32_bf16 v[6:9], v[146:149], v[218:221], 0
	v_mfma_f32_16x16x32_bf16 v[2:5], v[154:157], v[218:221], 0
	v_mfma_f32_16x16x32_bf16 v[54:57], v[150:153], v[166:169], v[54:57]
	v_mfma_f32_16x16x32_bf16 v[50:53], v[158:161], v[166:169], v[50:53]
	v_mfma_f32_16x16x32_bf16 v[38:41], v[150:153], v[174:177], v[38:41]
	v_mfma_f32_16x16x32_bf16 v[34:37], v[158:161], v[174:177], v[34:37]
	v_mfma_f32_16x16x32_bf16 v[22:25], v[150:153], v[182:185], v[22:25]
	v_mfma_f32_16x16x32_bf16 v[18:21], v[158:161], v[182:185], v[18:21]
	v_mfma_f32_16x16x32_bf16 v[6:9], v[150:153], v[240:243], v[6:9]
	v_mfma_f32_16x16x32_bf16 v[2:5], v[158:161], v[240:243], v[2:5]
	s_setprio 0
	s_barrier
	s_add_i32 s61, 0, 0x18000
	s_add_i32 s63, 0, 0x1c000
	v_add_u32_e32 v102, s61, v222
	v_add_u32_e32 v158, s63, v222
	ds_read_b128 v[90:93], v102
	ds_read_b128 v[94:97], v102 offset:1024
	ds_read_b128 v[98:101], v102 offset:2048
	ds_read_b128 v[102:105], v102 offset:3072
	ds_read_b128 v[146:149], v158
	ds_read_b128 v[150:153], v158 offset:1024
	ds_read_b128 v[154:157], v158 offset:2048
	ds_read_b128 v[158:161], v158 offset:3072
	s_add_u32 s20, vcc_lo, 0x40000
	s_addc_u32 s21, vcc_hi, 0
	s_mov_b32 m0, s82
	v_lshl_add_u64 v[248:249], s[20:21], 0, v[190:191]
	ds_read_b128 v[162:165], v227 offset:32768
	ds_read_b128 v[166:169], v227 offset:33792
	ds_read_b128 v[170:173], v227 offset:34816
	ds_read_b128 v[174:177], v227 offset:35840
	ds_read_b128 v[178:181], v227 offset:36864
	ds_read_b128 v[182:185], v227 offset:37888
	ds_read_b128 v[218:221], v227 offset:38912
	ds_read_b128 v[240:243], v227 offset:39936
	global_load_lds_dwordx4 v[248:249], off
	v_lshl_add_u64 v[248:249], s[20:21], 0, v[188:189]
	s_mov_b32 m0, s83
	s_nop 0
	global_load_lds_dwordx4 v[248:249], off
	s_waitcnt vmcnt(8)
	s_waitcnt lgkmcnt(0)
	s_barrier
	s_setprio 1
	s_waitcnt lgkmcnt(0)
	v_mfma_f32_16x16x32_bf16 v[142:145], v[90:93], v[162:165], v[142:145]
	v_mfma_f32_16x16x32_bf16 v[138:141], v[98:101], v[162:165], v[138:141]
	v_mfma_f32_16x16x32_bf16 v[126:129], v[90:93], v[170:173], v[126:129]
	v_mfma_f32_16x16x32_bf16 v[122:125], v[98:101], v[170:173], v[122:125]
	v_mfma_f32_16x16x32_bf16 v[110:113], v[90:93], v[178:181], v[110:113]
	v_mfma_f32_16x16x32_bf16 v[106:109], v[98:101], v[178:181], v[106:109]
	v_mfma_f32_16x16x32_bf16 v[78:81], v[90:93], v[218:221], v[78:81]
	v_mfma_f32_16x16x32_bf16 v[74:77], v[98:101], v[218:221], v[74:77]
	v_mfma_f32_16x16x32_bf16 v[142:145], v[94:97], v[166:169], v[142:145]
	v_mfma_f32_16x16x32_bf16 v[138:141], v[102:105], v[166:169], v[138:141]
	v_mfma_f32_16x16x32_bf16 v[126:129], v[94:97], v[174:177], v[126:129]
	v_mfma_f32_16x16x32_bf16 v[122:125], v[102:105], v[174:177], v[122:125]
	v_mfma_f32_16x16x32_bf16 v[110:113], v[94:97], v[182:185], v[110:113]
	v_mfma_f32_16x16x32_bf16 v[106:109], v[102:105], v[182:185], v[106:109]
	v_mfma_f32_16x16x32_bf16 v[78:81], v[94:97], v[240:243], v[78:81]
	v_mfma_f32_16x16x32_bf16 v[74:77], v[102:105], v[240:243], v[74:77]
	v_mfma_f32_16x16x32_bf16 v[134:137], v[146:149], v[162:165], v[134:137]
	v_mfma_f32_16x16x32_bf16 v[130:133], v[154:157], v[162:165], v[130:133]
	v_mfma_f32_16x16x32_bf16 v[118:121], v[146:149], v[170:173], v[118:121]
	v_mfma_f32_16x16x32_bf16 v[114:117], v[154:157], v[170:173], v[114:117]
	v_mfma_f32_16x16x32_bf16 v[86:89], v[146:149], v[178:181], v[86:89]
	v_mfma_f32_16x16x32_bf16 v[82:85], v[154:157], v[178:181], v[82:85]
	v_mfma_f32_16x16x32_bf16 v[70:73], v[146:149], v[218:221], v[70:73]
	v_mfma_f32_16x16x32_bf16 v[66:69], v[154:157], v[218:221], v[66:69]
	v_mfma_f32_16x16x32_bf16 v[134:137], v[150:153], v[166:169], v[134:137]
	v_mfma_f32_16x16x32_bf16 v[130:133], v[158:161], v[166:169], v[130:133]
	v_mfma_f32_16x16x32_bf16 v[118:121], v[150:153], v[174:177], v[118:121]
	v_mfma_f32_16x16x32_bf16 v[114:117], v[158:161], v[174:177], v[114:117]
	v_mfma_f32_16x16x32_bf16 v[86:89], v[150:153], v[182:185], v[86:89]
	v_mfma_f32_16x16x32_bf16 v[82:85], v[158:161], v[182:185], v[82:85]
	v_mfma_f32_16x16x32_bf16 v[70:73], v[150:153], v[240:243], v[70:73]
	v_mfma_f32_16x16x32_bf16 v[66:69], v[158:161], v[240:243], v[66:69]
	s_setprio 0
	s_barrier
; #define PG8_STAGE(bufoff, gbase, voff) do { _Pragma("unroll") for (int _i = 0; _i < 2; ++_i) \
;         __builtin_amdgcn_global_load_lds((const unsigned*)((const char*)(gbase) + (voff)[_i]), (PG8_LAS unsigned*)(lds + (bufoff) + ldsw + _i * 8192), 16, 0, 0); } while (0)
; #define PG8_LDA(dst, b, h) do { _Pragma("unroll") for (int m = 0; m < 4; ++m) _Pragma("unroll") for (int k = 0; k < 2; ++k) dst[m][k] = *(const PG8_LAS bf16x8*)(lds + PG8_SA(b, h) + aoff + m * 2048 + k * 1024); } while (0)
; #define PG8_LDB(dst, b, h) do { _Pragma("unroll") for (int n = 0; n < 2; ++n) _Pragma("unroll") for (int k = 0; k < 2; ++k) dst[n][k] = *(const PG8_LAS bf16x8*)(lds + PG8_SB(b, h) + boff + n * 2048 + k * 1024); } while (0)
; #define PG8_MMA(ai, bj, At, Bt) do { __builtin_amdgcn_s_setprio(1); _Pragma("unroll") for (int m = 0; m < 4; ++m) _Pragma("unroll") for (int n = 0; n < 2; ++n) _Pragma("unroll") for (int k = 0; k < 2; ++k) \
;         acc[ai][bj][m][n] = __builtin_amdgcn_mfma_f32_16x16x32_bf16(Bt[n][k], At[m][k], acc[ai][bj][m][n], 0, 0, 0); __builtin_amdgcn_s_setprio(0); } while (0)
; #define PG8_WAIT_V(n) asm volatile("s_waitcnt vmcnt(" #n ")" ::: "memory")
; template <class Epi, class Sched, bool ALIGN_EPI = false, bool SP2 = false>
; __device__ __forceinline__ void gemm_phase(PG8_LAS unsigned char* lds, const Gemm g, const Sched& S, const Epi& E) {
;     ...
;             PG8_LDB(B0, 0, 0); PG8_LDB(B1, 0, 1); PG8_SCHED; PG8_LDA(At, 0, 0); PG8_STAGE(PG8_SA(1, 1), a1 + hstepA, voffA);
;             PG8_WAIT_V(8); PG8_WAIT_L(0); PG8_BAR; PG8_MMA(0, 0, At, B0); PG8_MMA(0, 1, At, B1); PG8_BAR; PG8_SCHED;
;             PG8_LDA(At, 0, 1); PG8_STAGE(PG8_SB(0, 0), b2, voffB); PG8_STAGE(PG8_SB(0, 1), b2 + hstepB, voffB); PG8_STAGE(PG8_SA(0, 0), a2, voffA);
;             PG8_WAIT_V(8); PG8_WAIT_L(0); PG8_BAR; PG8_MMA(1, 0, At, B0); PG8_MMA(1, 1, At, B1); PG8_BAR; PG8_SCHED;
;             PG8_LDB(B0, 1, 0); PG8_LDB(B1, 1, 1); PG8_SCHED; PG8_LDA(At, 1, 0); PG8_STAGE(PG8_SA(0, 1), a2 + hstepA, voffA);
;             PG8_WAIT_V(8); PG8_WAIT_L(0); PG8_BAR; PG8_MMA(0, 0, At, B0); PG8_MMA(0, 1, At, B1); PG8_BAR; PG8_SCHED;
;             PG8_LDA(At, 1, 1); PG8_STAGE(PG8_SB(1, 0), b3, voffB); PG8_STAGE(PG8_SB(1, 1), b3 + hstepB, voffB); PG8_STAGE(PG8_SA(1, 0), a3, voffA);
;             PG8_WAIT_V(8); PG8_WAIT_L(0); PG8_BAR; PG8_MMA(1, 0, At, B0); PG8_MMA(1, 1, At, B1); PG8_BAR; PG8_SCHED;
	s_add_i32 s20, s61, s79
	v_lshl_add_u64 v[204:205], v[204:205], 0, s[22:23]
	s_mov_b32 m0, s20
	ds_read_b128 v[162:165], v227 offset:49152
	ds_read_b128 v[166:169], v227 offset:50176
	ds_read_b128 v[170:173], v227 offset:51200
	ds_read_b128 v[174:177], v227 offset:52224
	ds_read_b128 v[178:181], v227 offset:53248
	ds_read_b128 v[182:185], v227 offset:54272
	ds_read_b128 v[218:221], v227 offset:55296
	ds_read_b128 v[240:243], v227 offset:56320
	global_load_lds_dwordx4 v[204:205], off
	s_add_i32 m0, s20, 0x2000
	s_add_u32 s20, s70, 0x40080
	v_lshl_add_u64 v[204:205], v[234:235], 0, s[22:23]
	s_addc_u32 s21, s71, 0
	s_add_i32 s61, s63, s79
	global_load_lds_dwordx4 v[204:205], off
	v_lshl_add_u64 v[204:205], s[20:21], 0, v[0:1]
	s_mov_b32 m0, s61
	s_nop 0
	global_load_lds_dwordx4 v[204:205], off
	v_lshl_add_u64 v[204:205], s[20:21], 0, v[186:187]
	s_add_i32 m0, s61, 0x2000
	s_nop 0
	global_load_lds_dwordx4 v[204:205], off
	v_lshl_add_u64 v[204:205], v[244:245], 0, s[22:23]
	s_mov_b32 m0, s86
	s_nop 0
	global_load_lds_dwordx4 v[204:205], off
	v_lshl_add_u64 v[204:205], v[246:247], 0, s[22:23]
	s_mov_b32 m0, s87
	s_nop 0
	global_load_lds_dwordx4 v[204:205], off
	s_waitcnt vmcnt(8)
	s_waitcnt lgkmcnt(0)
	s_barrier
	s_setprio 1
	s_waitcnt lgkmcnt(0)
	v_mfma_f32_16x16x32_bf16 v[62:65], v[90:93], v[162:165], v[62:65]
	v_mfma_f32_16x16x32_bf16 v[58:61], v[98:101], v[162:165], v[58:61]
	v_mfma_f32_16x16x32_bf16 v[46:49], v[90:93], v[170:173], v[46:49]
	v_mfma_f32_16x16x32_bf16 v[42:45], v[98:101], v[170:173], v[42:45]
	v_mfma_f32_16x16x32_bf16 v[30:33], v[90:93], v[178:181], v[30:33]
	v_mfma_f32_16x16x32_bf16 v[26:29], v[98:101], v[178:181], v[26:29]
	v_mfma_f32_16x16x32_bf16 v[14:17], v[90:93], v[218:221], v[14:17]
	v_mfma_f32_16x16x32_bf16 v[10:13], v[98:101], v[218:221], v[10:13]
	v_mfma_f32_16x16x32_bf16 v[62:65], v[94:97], v[166:169], v[62:65]
	v_mfma_f32_16x16x32_bf16 v[58:61], v[102:105], v[166:169], v[58:61]
	v_mfma_f32_16x16x32_bf16 v[46:49], v[94:97], v[174:177], v[46:49]
	v_mfma_f32_16x16x32_bf16 v[42:45], v[102:105], v[174:177], v[42:45]
	v_mfma_f32_16x16x32_bf16 v[30:33], v[94:97], v[182:185], v[30:33]
	v_mfma_f32_16x16x32_bf16 v[26:29], v[102:105], v[182:185], v[26:29]
	v_mfma_f32_16x16x32_bf16 v[14:17], v[94:97], v[240:243], v[14:17]
	v_mfma_f32_16x16x32_bf16 v[10:13], v[102:105], v[240:243], v[10:13]
	v_mfma_f32_16x16x32_bf16 v[54:57], v[146:149], v[162:165], v[54:57]
	v_mfma_f32_16x16x32_bf16 v[50:53], v[154:157], v[162:165], v[50:53]
	v_mfma_f32_16x16x32_bf16 v[38:41], v[146:149], v[170:173], v[38:41]
	v_mfma_f32_16x16x32_bf16 v[34:37], v[154:157], v[170:173], v[34:37]
	v_mfma_f32_16x16x32_bf16 v[22:25], v[146:149], v[178:181], v[22:25]
	v_mfma_f32_16x16x32_bf16 v[18:21], v[154:157], v[178:181], v[18:21]
	v_mfma_f32_16x16x32_bf16 v[6:9], v[146:149], v[218:221], v[6:9]
	v_mfma_f32_16x16x32_bf16 v[2:5], v[154:157], v[218:221], v[2:5]
	v_mfma_f32_16x16x32_bf16 v[54:57], v[150:153], v[166:169], v[54:57]
	v_mfma_f32_16x16x32_bf16 v[50:53], v[158:161], v[166:169], v[50:53]
	v_mfma_f32_16x16x32_bf16 v[38:41], v[150:153], v[174:177], v[38:41]
	v_mfma_f32_16x16x32_bf16 v[34:37], v[158:161], v[174:177], v[34:37]
	v_mfma_f32_16x16x32_bf16 v[22:25], v[150:153], v[182:185], v[22:25]
	v_mfma_f32_16x16x32_bf16 v[18:21], v[158:161], v[182:185], v[18:21]
	v_mfma_f32_16x16x32_bf16 v[6:9], v[150:153], v[240:243], v[6:9]
	v_mfma_f32_16x16x32_bf16 v[2:5], v[158:161], v[240:243], v[2:5]
	s_setprio 0
	s_barrier
	s_add_i32 s60, s60, 2
	s_add_u32 s36, s36, 0x100
	s_addc_u32 s37, s37, 0
	s_add_u32 s54, s54, 0x100
	s_addc_u32 s55, s55, 0
	s_cmp_gt_u32 s60, 13
	s_cbranch_scc1 .Lpk_done_g455
.LBB0_455:
	s_add_u32 s20, s36, 0xfffc0080
	s_addc_u32 s21, s37, -1
	s_add_i32 s61, 0, 0x10000
	s_cmp_eq_u32 s60, 12
	s_cselect_b32 vcc_hi, s9, s21
	s_cselect_b32 vcc_lo, s39, s20
	s_cselect_b32 s71, s43, s55
	s_cselect_b32 s70, s53, s54
	s_add_i32 s63, 0, 0x14000
	v_add_u32_e32 v102, s61, v222
	v_add_u32_e32 v158, s63, v222
	ds_read_b128 v[90:93], v102
	ds_read_b128 v[94:97], v102 offset:1024
	ds_read_b128 v[98:101], v102 offset:2048
	ds_read_b128 v[102:105], v102 offset:3072
	ds_read_b128 v[146:149], v158
	ds_read_b128 v[150:153], v158 offset:1024
	ds_read_b128 v[154:157], v158 offset:2048
	ds_read_b128 v[158:161], v158 offset:3072
	v_lshl_add_u64 v[204:205], s[36:37], 0, v[214:215]
	s_add_i32 m0, s80, 0xc000
	ds_read_b128 v[162:165], v227
	ds_read_b128 v[166:169], v227 offset:1024
	ds_read_b128 v[170:173], v227 offset:2048
	ds_read_b128 v[174:177], v227 offset:3072
	ds_read_b128 v[178:181], v227 offset:4096
	ds_read_b128 v[182:185], v227 offset:5120
	ds_read_b128 v[218:221], v227 offset:6144
	ds_read_b128 v[240:243], v227 offset:7168
	global_load_lds_dwordx4 v[204:205], off
	v_lshl_add_u64 v[204:205], s[36:37], 0, v[216:217]
	s_add_i32 m0, s80, 0xe000
	s_nop 0
	global_load_lds_dwordx4 v[204:205], off
	s_waitcnt vmcnt(8)
	s_waitcnt lgkmcnt(0)
	s_barrier
; #define PG8_STAGE(bufoff, gbase, voff) do { _Pragma("unroll") for (int _i = 0; _i < 2; ++_i) \
;         __builtin_amdgcn_global_load_lds((const unsigned*)((const char*)(gbase) + (voff)[_i]), (PG8_LAS unsigned*)(lds + (bufoff) + ldsw + _i * 8192), 16, 0, 0); } while (0)
; #define PG8_LDA(dst, b, h) do { _Pragma("unroll") for (int m = 0; m < 4; ++m) _Pragma("unroll") for (int k = 0; k < 2; ++k) dst[m][k] = *(const PG8_LAS bf16x8*)(lds + PG8_SA(b, h) + aoff + m * 2048 + k * 1024); } while (0)
; #define PG8_MMA(ai, bj, At, Bt) do { __builtin_amdgcn_s_setprio(1); _Pragma("unroll") for (int m = 0; m < 4; ++m) _Pragma("unroll") for (int n = 0; n < 2; ++n) _Pragma("unroll") for (int k = 0; k < 2; ++k) \
;         acc[ai][bj][m][n] = __builtin_amdgcn_mfma_f32_16x16x32_bf16(Bt[n][k], At[m][k], acc[ai][bj][m][n], 0, 0, 0); __builtin_amdgcn_s_setprio(0); } while (0)
; #define PG8_WAIT_V(n) asm volatile("s_waitcnt vmcnt(" #n ")" ::: "memory")
; #define PG8_WAIT_L(n) asm volatile("s_waitcnt lgkmcnt(" #n ")" ::: "memory")
; #define PG8_BAR __builtin_amdgcn_s_barrier()
; #define PG8_SCHED __builtin_amdgcn_sched_barrier(0)
; template <class Epi, class Sched, bool ALIGN_EPI = false, bool SP2 = false>
; __device__ __forceinline__ void gemm_phase(PG8_LAS unsigned char* lds, const Gemm g, const Sched& S, const Epi& E) {
;     ...
;             PG8_WAIT_V(8); PG8_WAIT_L(0); PG8_BAR; PG8_MMA(0, 0, At, B0); PG8_MMA(0, 1, At, B1); PG8_BAR; PG8_SCHED;
;             PG8_LDA(At, 0, 1); PG8_STAGE(PG8_SB(0, 0), b2, voffB); PG8_STAGE(PG8_SB(0, 1), b2 + hstepB, voffB); PG8_STAGE(PG8_SA(0, 0), a2, voffA);
;             PG8_WAIT_V(8); PG8_WAIT_L(0); PG8_BAR; PG8_MMA(1, 0, At, B0); PG8_MMA(1, 1, At, B1); PG8_BAR; PG8_SCHED;
	s_setprio 1
	s_waitcnt lgkmcnt(0)
	v_mfma_f32_16x16x32_bf16 v[142:145], v[90:93], v[162:165], v[142:145]
	v_mfma_f32_16x16x32_bf16 v[138:141], v[98:101], v[162:165], v[138:141]
	v_mfma_f32_16x16x32_bf16 v[126:129], v[90:93], v[170:173], v[126:129]
	v_mfma_f32_16x16x32_bf16 v[122:125], v[98:101], v[170:173], v[122:125]
	v_mfma_f32_16x16x32_bf16 v[110:113], v[90:93], v[178:181], v[110:113]
	v_mfma_f32_16x16x32_bf16 v[106:109], v[98:101], v[178:181], v[106:109]
	v_mfma_f32_16x16x32_bf16 v[78:81], v[90:93], v[218:221], v[78:81]
	v_mfma_f32_16x16x32_bf16 v[74:77], v[98:101], v[218:221], v[74:77]
	v_mfma_f32_16x16x32_bf16 v[142:145], v[94:97], v[166:169], v[142:145]
	v_mfma_f32_16x16x32_bf16 v[138:141], v[102:105], v[166:169], v[138:141]
	v_mfma_f32_16x16x32_bf16 v[126:129], v[94:97], v[174:177], v[126:129]
	v_mfma_f32_16x16x32_bf16 v[122:125], v[102:105], v[174:177], v[122:125]
	v_mfma_f32_16x16x32_bf16 v[110:113], v[94:97], v[182:185], v[110:113]
	v_mfma_f32_16x16x32_bf16 v[106:109], v[102:105], v[182:185], v[106:109]
	v_mfma_f32_16x16x32_bf16 v[78:81], v[94:97], v[240:243], v[78:81]
	v_mfma_f32_16x16x32_bf16 v[74:77], v[102:105], v[240:243], v[74:77]
	v_mfma_f32_16x16x32_bf16 v[134:137], v[146:149], v[162:165], v[134:137]
	v_mfma_f32_16x16x32_bf16 v[130:133], v[154:157], v[162:165], v[130:133]
	v_mfma_f32_16x16x32_bf16 v[118:121], v[146:149], v[170:173], v[118:121]
	v_mfma_f32_16x16x32_bf16 v[114:117], v[154:157], v[170:173], v[114:117]
	v_mfma_f32_16x16x32_bf16 v[86:89], v[146:149], v[178:181], v[86:89]
	v_mfma_f32_16x16x32_bf16 v[82:85], v[154:157], v[178:181], v[82:85]
	v_mfma_f32_16x16x32_bf16 v[70:73], v[146:149], v[218:221], v[70:73]
	v_mfma_f32_16x16x32_bf16 v[66:69], v[154:157], v[218:221], v[66:69]
	v_mfma_f32_16x16x32_bf16 v[134:137], v[150:153], v[166:169], v[134:137]
	v_mfma_f32_16x16x32_bf16 v[130:133], v[158:161], v[166:169], v[130:133]
	v_mfma_f32_16x16x32_bf16 v[118:121], v[150:153], v[174:177], v[118:121]
	v_mfma_f32_16x16x32_bf16 v[114:117], v[158:161], v[174:177], v[114:117]
	v_mfma_f32_16x16x32_bf16 v[86:89], v[150:153], v[182:185], v[86:89]
	v_mfma_f32_16x16x32_bf16 v[82:85], v[158:161], v[182:185], v[82:85]
	v_mfma_f32_16x16x32_bf16 v[70:73], v[150:153], v[240:243], v[70:73]
	v_mfma_f32_16x16x32_bf16 v[66:69], v[158:161], v[240:243], v[66:69]
	s_setprio 0
	s_barrier
	s_add_i32 s20, s61, s79
	v_lshl_add_u64 v[204:205], s[70:71], 0, v[0:1]
	s_mov_b32 m0, s20
	ds_read_b128 v[162:165], v227 offset:16384
	ds_read_b128 v[166:169], v227 offset:17408
	ds_read_b128 v[170:173], v227 offset:18432
	ds_read_b128 v[174:177], v227 offset:19456
	ds_read_b128 v[178:181], v227 offset:20480
	ds_read_b128 v[182:185], v227 offset:21504
	ds_read_b128 v[218:221], v227 offset:22528
	ds_read_b128 v[240:243], v227 offset:23552
	global_load_lds_dwordx4 v[204:205], off
	s_add_i32 m0, s20, 0x2000
	s_add_u32 s20, s70, 0x40000
	v_lshl_add_u64 v[234:235], s[70:71], 0, v[186:187]
	s_addc_u32 s21, s71, 0
	s_add_i32 s61, s63, s79
	global_load_lds_dwordx4 v[234:235], off
	v_lshl_add_u64 v[244:245], s[20:21], 0, v[0:1]
	s_mov_b32 m0, s61
	v_lshl_add_u64 v[246:247], vcc, 0, v[188:189]
	global_load_lds_dwordx4 v[244:245], off
	v_lshl_add_u64 v[244:245], s[20:21], 0, v[186:187]
	s_add_i32 m0, s61, 0x2000
	s_nop 0
	global_load_lds_dwordx4 v[244:245], off
	v_lshl_add_u64 v[244:245], vcc, 0, v[190:191]
	s_mov_b32 m0, s80
	s_nop 0
	global_load_lds_dwordx4 v[244:245], off
	s_mov_b32 m0, s81
	s_nop 0
	global_load_lds_dwordx4 v[246:247], off
	s_waitcnt vmcnt(8)
	s_waitcnt lgkmcnt(0)
	s_barrier
	s_setprio 1
	s_waitcnt lgkmcnt(0)
	v_mfma_f32_16x16x32_bf16 v[62:65], v[90:93], v[162:165], v[62:65]
	v_mfma_f32_16x16x32_bf16 v[58:61], v[98:101], v[162:165], v[58:61]
	v_mfma_f32_16x16x32_bf16 v[46:49], v[90:93], v[170:173], v[46:49]
	v_mfma_f32_16x16x32_bf16 v[42:45], v[98:101], v[170:173], v[42:45]
	v_mfma_f32_16x16x32_bf16 v[30:33], v[90:93], v[178:181], v[30:33]
	v_mfma_f32_16x16x32_bf16 v[26:29], v[98:101], v[178:181], v[26:29]
	v_mfma_f32_16x16x32_bf16 v[14:17], v[90:93], v[218:221], v[14:17]
	v_mfma_f32_16x16x32_bf16 v[10:13], v[98:101], v[218:221], v[10:13]
	v_mfma_f32_16x16x32_bf16 v[62:65], v[94:97], v[166:169], v[62:65]
	v_mfma_f32_16x16x32_bf16 v[58:61], v[102:105], v[166:169], v[58:61]
	v_mfma_f32_16x16x32_bf16 v[46:49], v[94:97], v[174:177], v[46:49]
	v_mfma_f32_16x16x32_bf16 v[42:45], v[102:105], v[174:177], v[42:45]
	v_mfma_f32_16x16x32_bf16 v[30:33], v[94:97], v[182:185], v[30:33]
	v_mfma_f32_16x16x32_bf16 v[26:29], v[102:105], v[182:185], v[26:29]
	v_mfma_f32_16x16x32_bf16 v[14:17], v[94:97], v[240:243], v[14:17]
	v_mfma_f32_16x16x32_bf16 v[10:13], v[102:105], v[240:243], v[10:13]
	v_mfma_f32_16x16x32_bf16 v[54:57], v[146:149], v[162:165], v[54:57]
	v_mfma_f32_16x16x32_bf16 v[50:53], v[154:157], v[162:165], v[50:53]
	v_mfma_f32_16x16x32_bf16 v[38:41], v[146:149], v[170:173], v[38:41]
	v_mfma_f32_16x16x32_bf16 v[34:37], v[154:157], v[170:173], v[34:37]
	v_mfma_f32_16x16x32_bf16 v[22:25], v[146:149], v[178:181], v[22:25]
	v_mfma_f32_16x16x32_bf16 v[18:21], v[154:157], v[178:181], v[18:21]
	v_mfma_f32_16x16x32_bf16 v[6:9], v[146:149], v[218:221], v[6:9]
	v_mfma_f32_16x16x32_bf16 v[2:5], v[154:157], v[218:221], v[2:5]
	v_mfma_f32_16x16x32_bf16 v[54:57], v[150:153], v[166:169], v[54:57]
	v_mfma_f32_16x16x32_bf16 v[50:53], v[158:161], v[166:169], v[50:53]
	v_mfma_f32_16x16x32_bf16 v[38:41], v[150:153], v[174:177], v[38:41]
	v_mfma_f32_16x16x32_bf16 v[34:37], v[158:161], v[174:177], v[34:37]
	v_mfma_f32_16x16x32_bf16 v[22:25], v[150:153], v[182:185], v[22:25]
	v_mfma_f32_16x16x32_bf16 v[18:21], v[158:161], v[182:185], v[18:21]
	v_mfma_f32_16x16x32_bf16 v[6:9], v[150:153], v[240:243], v[6:9]
	v_mfma_f32_16x16x32_bf16 v[2:5], v[158:161], v[240:243], v[2:5]
	s_setprio 0
	s_barrier
; #define PG8_STAGE(bufoff, gbase, voff) do { _Pragma("unroll") for (int _i = 0; _i < 2; ++_i) \
;         __builtin_amdgcn_global_load_lds((const unsigned*)((const char*)(gbase) + (voff)[_i]), (PG8_LAS unsigned*)(lds + (bufoff) + ldsw + _i * 8192), 16, 0, 0); } while (0)
; #define PG8_LDA(dst, b, h) do { _Pragma("unroll") for (int m = 0; m < 4; ++m) _Pragma("unroll") for (int k = 0; k < 2; ++k) dst[m][k] = *(const PG8_LAS bf16x8*)(lds + PG8_SA(b, h) + aoff + m * 2048 + k * 1024); } while (0)
; #define PG8_LDB(dst, b, h) do { _Pragma("unroll") for (int n = 0; n < 2; ++n) _Pragma("unroll") for (int k = 0; k < 2; ++k) dst[n][k] = *(const PG8_LAS bf16x8*)(lds + PG8_SB(b, h) + boff + n * 2048 + k * 1024); } while (0)
; #define PG8_MMA(ai, bj, At, Bt) do { __builtin_amdgcn_s_setprio(1); _Pragma("unroll") for (int m = 0; m < 4; ++m) _Pragma("unroll") for (int n = 0; n < 2; ++n) _Pragma("unroll") for (int k = 0; k < 2; ++k) \
;         acc[ai][bj][m][n] = __builtin_amdgcn_mfma_f32_16x16x32_bf16(Bt[n][k], At[m][k], acc[ai][bj][m][n], 0, 0, 0); __builtin_amdgcn_s_setprio(0); } while (0)
; #define PG8_WAIT_V(n) asm volatile("s_waitcnt vmcnt(" #n ")" ::: "memory")
; #define PG8_WAIT_L(n) asm volatile("s_waitcnt lgkmcnt(" #n ")" ::: "memory")
; #define PG8_BAR __builtin_amdgcn_s_barrier()
; #define PG8_SCHED __builtin_amdgcn_sched_barrier(0)
; template <class Epi, class Sched, bool ALIGN_EPI = false, bool SP2 = false>
; __device__ __forceinline__ void gemm_phase(PG8_LAS unsigned char* lds, const Gemm g, const Sched& S, const Epi& E) {
;     ...
;             PG8_LDB(B0, 1, 0); PG8_LDB(B1, 1, 1); PG8_SCHED; PG8_LDA(At, 1, 0); PG8_STAGE(PG8_SA(0, 1), a2 + hstepA, voffA);
;             PG8_WAIT_V(8); PG8_WAIT_L(0); PG8_BAR; PG8_MMA(0, 0, At, B0); PG8_MMA(0, 1, At, B1); PG8_BAR; PG8_SCHED;
	s_add_i32 s61, 0, 0x18000
	s_add_i32 s63, 0, 0x1c000
	v_add_u32_e32 v102, s61, v222
	v_add_u32_e32 v158, s63, v222
	ds_read_b128 v[90:93], v102
	ds_read_b128 v[94:97], v102 offset:1024
	ds_read_b128 v[98:101], v102 offset:2048
	ds_read_b128 v[102:105], v102 offset:3072
	ds_read_b128 v[146:149], v158
	ds_read_b128 v[150:153], v158 offset:1024
	ds_read_b128 v[154:157], v158 offset:2048
	ds_read_b128 v[158:161], v158 offset:3072
	s_add_u32 s20, vcc_lo, 0x40000
	s_addc_u32 s21, vcc_hi, 0
	s_mov_b32 m0, s82
	v_lshl_add_u64 v[248:249], s[20:21], 0, v[190:191]
	ds_read_b128 v[162:165], v227 offset:32768
	ds_read_b128 v[166:169], v227 offset:33792
	ds_read_b128 v[170:173], v227 offset:34816
	ds_read_b128 v[174:177], v227 offset:35840
	ds_read_b128 v[178:181], v227 offset:36864
	ds_read_b128 v[182:185], v227 offset:37888
	ds_read_b128 v[218:221], v227 offset:38912
	ds_read_b128 v[240:243], v227 offset:39936
	global_load_lds_dwordx4 v[248:249], off
	v_lshl_add_u64 v[248:249], s[20:21], 0, v[188:189]
	s_mov_b32 m0, s83
	s_nop 0
	global_load_lds_dwordx4 v[248:249], off
	s_waitcnt vmcnt(8)
	s_waitcnt lgkmcnt(0)
	s_barrier
	s_setprio 1
	s_waitcnt lgkmcnt(0)
	v_mfma_f32_16x16x32_bf16 v[142:145], v[90:93], v[162:165], v[142:145]
	v_mfma_f32_16x16x32_bf16 v[138:141], v[98:101], v[162:165], v[138:141]
	v_mfma_f32_16x16x32_bf16 v[126:129], v[90:93], v[170:173], v[126:129]
	v_mfma_f32_16x16x32_bf16 v[122:125], v[98:101], v[170:173], v[122:125]
	v_mfma_f32_16x16x32_bf16 v[110:113], v[90:93], v[178:181], v[110:113]
	v_mfma_f32_16x16x32_bf16 v[106:109], v[98:101], v[178:181], v[106:109]
	v_mfma_f32_16x16x32_bf16 v[78:81], v[90:93], v[218:221], v[78:81]
	v_mfma_f32_16x16x32_bf16 v[74:77], v[98:101], v[218:221], v[74:77]
	v_mfma_f32_16x16x32_bf16 v[142:145], v[94:97], v[166:169], v[142:145]
	v_mfma_f32_16x16x32_bf16 v[138:141], v[102:105], v[166:169], v[138:141]
	v_mfma_f32_16x16x32_bf16 v[126:129], v[94:97], v[174:177], v[126:129]
	v_mfma_f32_16x16x32_bf16 v[122:125], v[102:105], v[174:177], v[122:125]
	v_mfma_f32_16x16x32_bf16 v[110:113], v[94:97], v[182:185], v[110:113]
	v_mfma_f32_16x16x32_bf16 v[106:109], v[102:105], v[182:185], v[106:109]
	v_mfma_f32_16x16x32_bf16 v[78:81], v[94:97], v[240:243], v[78:81]
	v_mfma_f32_16x16x32_bf16 v[74:77], v[102:105], v[240:243], v[74:77]
	v_mfma_f32_16x16x32_bf16 v[134:137], v[146:149], v[162:165], v[134:137]
	v_mfma_f32_16x16x32_bf16 v[130:133], v[154:157], v[162:165], v[130:133]
	v_mfma_f32_16x16x32_bf16 v[118:121], v[146:149], v[170:173], v[118:121]
	v_mfma_f32_16x16x32_bf16 v[114:117], v[154:157], v[170:173], v[114:117]
	v_mfma_f32_16x16x32_bf16 v[86:89], v[146:149], v[178:181], v[86:89]
	v_mfma_f32_16x16x32_bf16 v[82:85], v[154:157], v[178:181], v[82:85]
	v_mfma_f32_16x16x32_bf16 v[70:73], v[146:149], v[218:221], v[70:73]
	v_mfma_f32_16x16x32_bf16 v[66:69], v[154:157], v[218:221], v[66:69]
	v_mfma_f32_16x16x32_bf16 v[134:137], v[150:153], v[166:169], v[134:137]
	v_mfma_f32_16x16x32_bf16 v[130:133], v[158:161], v[166:169], v[130:133]
	v_mfma_f32_16x16x32_bf16 v[118:121], v[150:153], v[174:177], v[118:121]
	v_mfma_f32_16x16x32_bf16 v[114:117], v[158:161], v[174:177], v[114:117]
	v_mfma_f32_16x16x32_bf16 v[86:89], v[150:153], v[182:185], v[86:89]
	v_mfma_f32_16x16x32_bf16 v[82:85], v[158:161], v[182:185], v[82:85]
	v_mfma_f32_16x16x32_bf16 v[70:73], v[150:153], v[240:243], v[70:73]
	v_mfma_f32_16x16x32_bf16 v[66:69], v[158:161], v[240:243], v[66:69]
	s_setprio 0
	s_barrier
; #define PG8_STAGE(bufoff, gbase, voff) do { _Pragma("unroll") for (int _i = 0; _i < 2; ++_i) \
;         __builtin_amdgcn_global_load_lds((const unsigned*)((const char*)(gbase) + (voff)[_i]), (PG8_LAS unsigned*)(lds + (bufoff) + ldsw + _i * 8192), 16, 0, 0); } while (0)
; #define PG8_LDA(dst, b, h) do { _Pragma("unroll") for (int m = 0; m < 4; ++m) _Pragma("unroll") for (int k = 0; k < 2; ++k) dst[m][k] = *(const PG8_LAS bf16x8*)(lds + PG8_SA(b, h) + aoff + m * 2048 + k * 1024); } while (0)
; #define PG8_MMA(ai, bj, At, Bt) do { __builtin_amdgcn_s_setprio(1); _Pragma("unroll") for (int m = 0; m < 4; ++m) _Pragma("unroll") for (int n = 0; n < 2; ++n) _Pragma("unroll") for (int k = 0; k < 2; ++k) \
;         acc[ai][bj][m][n] = __builtin_amdgcn_mfma_f32_16x16x32_bf16(Bt[n][k], At[m][k], acc[ai][bj][m][n], 0, 0, 0); __builtin_amdgcn_s_setprio(0); } while (0)
; #define PG8_WAIT_V(n) asm volatile("s_waitcnt vmcnt(" #n ")" ::: "memory")
; #define PG8_WAIT_L(n) asm volatile("s_waitcnt lgkmcnt(" #n ")" ::: "memory")
; #define PG8_BAR __builtin_amdgcn_s_barrier()
; #define PG8_SCHED __builtin_amdgcn_sched_barrier(0)
; template <class Epi, class Sched, bool ALIGN_EPI = false, bool SP2 = false>
; __device__ __forceinline__ void gemm_phase(PG8_LAS unsigned char* lds, const Gemm g, const Sched& S, const Epi& E) {
;     ...
;         for (int t = 0; t < nt; t += 2) {
;             const bool last = (t == nt - 2);
;             const char* a1 = cA + (size_t)(t + 1) * kstep;
;             const char* a2 = last ? nA : cA + (size_t)(t + 2) * kstep; const char* b2 = last ? nB : cB + (size_t)(t + 2) * kstep;
;             const char* a3 = a2 + kstep; const char* b3 = b2 + kstep;
;     ...
;             PG8_LDA(At, 1, 1); PG8_STAGE(PG8_SB(1, 0), b3, voffB); PG8_STAGE(PG8_SB(1, 1), b3 + hstepB, voffB); PG8_STAGE(PG8_SA(1, 0), a3, voffA);
;             PG8_WAIT_V(8); PG8_WAIT_L(0); PG8_BAR; PG8_MMA(1, 0, At, B0); PG8_MMA(1, 1, At, B1); PG8_BAR; PG8_SCHED;
	s_add_i32 s20, s61, s79
	v_lshl_add_u64 v[204:205], v[204:205], 0, s[22:23]
	s_mov_b32 m0, s20
	ds_read_b128 v[162:165], v227 offset:49152
	ds_read_b128 v[166:169], v227 offset:50176
	ds_read_b128 v[170:173], v227 offset:51200
	ds_read_b128 v[174:177], v227 offset:52224
	ds_read_b128 v[178:181], v227 offset:53248
	ds_read_b128 v[182:185], v227 offset:54272
	ds_read_b128 v[218:221], v227 offset:55296
	ds_read_b128 v[240:243], v227 offset:56320
	global_load_lds_dwordx4 v[204:205], off
	s_add_i32 m0, s20, 0x2000
	s_add_u32 s20, s70, 0x40080
	v_lshl_add_u64 v[204:205], v[234:235], 0, s[22:23]
	s_addc_u32 s21, s71, 0
	s_add_i32 s61, s63, s79
	global_load_lds_dwordx4 v[204:205], off
	v_lshl_add_u64 v[204:205], s[20:21], 0, v[0:1]
	s_mov_b32 m0, s61
	s_nop 0
	global_load_lds_dwordx4 v[204:205], off
	v_lshl_add_u64 v[204:205], s[20:21], 0, v[186:187]
	s_add_i32 m0, s61, 0x2000
	s_nop 0
	global_load_lds_dwordx4 v[204:205], off
	v_lshl_add_u64 v[204:205], v[244:245], 0, s[22:23]
	s_mov_b32 m0, s86
	s_nop 0
	global_load_lds_dwordx4 v[204:205], off
	v_lshl_add_u64 v[204:205], v[246:247], 0, s[22:23]
	s_mov_b32 m0, s87
	s_nop 0
	global_load_lds_dwordx4 v[204:205], off
	s_waitcnt vmcnt(8)
	s_waitcnt lgkmcnt(0)
	s_barrier
	s_setprio 1
	s_waitcnt lgkmcnt(0)
	v_mfma_f32_16x16x32_bf16 v[62:65], v[90:93], v[162:165], v[62:65]
	v_mfma_f32_16x16x32_bf16 v[58:61], v[98:101], v[162:165], v[58:61]
	v_mfma_f32_16x16x32_bf16 v[46:49], v[90:93], v[170:173], v[46:49]
	v_mfma_f32_16x16x32_bf16 v[42:45], v[98:101], v[170:173], v[42:45]
	v_mfma_f32_16x16x32_bf16 v[30:33], v[90:93], v[178:181], v[30:33]
	v_mfma_f32_16x16x32_bf16 v[26:29], v[98:101], v[178:181], v[26:29]
	v_mfma_f32_16x16x32_bf16 v[14:17], v[90:93], v[218:221], v[14:17]
	v_mfma_f32_16x16x32_bf16 v[10:13], v[98:101], v[218:221], v[10:13]
	v_mfma_f32_16x16x32_bf16 v[62:65], v[94:97], v[166:169], v[62:65]
	v_mfma_f32_16x16x32_bf16 v[58:61], v[102:105], v[166:169], v[58:61]
	v_mfma_f32_16x16x32_bf16 v[46:49], v[94:97], v[174:177], v[46:49]
	v_mfma_f32_16x16x32_bf16 v[42:45], v[102:105], v[174:177], v[42:45]
	v_mfma_f32_16x16x32_bf16 v[30:33], v[94:97], v[182:185], v[30:33]
	v_mfma_f32_16x16x32_bf16 v[26:29], v[102:105], v[182:185], v[26:29]
	v_mfma_f32_16x16x32_bf16 v[14:17], v[94:97], v[240:243], v[14:17]
	v_mfma_f32_16x16x32_bf16 v[10:13], v[102:105], v[240:243], v[10:13]
	v_mfma_f32_16x16x32_bf16 v[54:57], v[146:149], v[162:165], v[54:57]
	v_mfma_f32_16x16x32_bf16 v[50:53], v[154:157], v[162:165], v[50:53]
	v_mfma_f32_16x16x32_bf16 v[38:41], v[146:149], v[170:173], v[38:41]
	v_mfma_f32_16x16x32_bf16 v[34:37], v[154:157], v[170:173], v[34:37]
	v_mfma_f32_16x16x32_bf16 v[22:25], v[146:149], v[178:181], v[22:25]
	v_mfma_f32_16x16x32_bf16 v[18:21], v[154:157], v[178:181], v[18:21]
	v_mfma_f32_16x16x32_bf16 v[6:9], v[146:149], v[218:221], v[6:9]
	v_mfma_f32_16x16x32_bf16 v[2:5], v[154:157], v[218:221], v[2:5]
	v_mfma_f32_16x16x32_bf16 v[54:57], v[150:153], v[166:169], v[54:57]
	v_mfma_f32_16x16x32_bf16 v[50:53], v[158:161], v[166:169], v[50:53]
	v_mfma_f32_16x16x32_bf16 v[38:41], v[150:153], v[174:177], v[38:41]
	v_mfma_f32_16x16x32_bf16 v[34:37], v[158:161], v[174:177], v[34:37]
	v_mfma_f32_16x16x32_bf16 v[22:25], v[150:153], v[182:185], v[22:25]
	v_mfma_f32_16x16x32_bf16 v[18:21], v[158:161], v[182:185], v[18:21]
	v_mfma_f32_16x16x32_bf16 v[6:9], v[150:153], v[240:243], v[6:9]
	v_mfma_f32_16x16x32_bf16 v[2:5], v[158:161], v[240:243], v[2:5]
	s_setprio 0
	s_barrier
	s_add_i32 s60, s60, 2
	s_add_u32 s36, s36, 0x100
	s_addc_u32 s37, s37, 0
	s_add_u32 s54, s54, 0x100
	s_addc_u32 s55, s55, 0
	s_cmp_gt_u32 s60, 13
	s_cbranch_scc0 .LBB0_455

; #define PG8_STAGE(bufoff, gbase, voff) do { _Pragma("unroll") for (int _i = 0; _i < 2; ++_i) \
;         __builtin_amdgcn_global_load_lds((const unsigned*)((const char*)(gbase) + (voff)[_i]), (PG8_LAS unsigned*)(lds + (bufoff) + ldsw + _i * 8192), 16, 0, 0); } while (0)
; #define PG8_LDA(dst, b, h) do { _Pragma("unroll") for (int m = 0; m < 4; ++m) _Pragma("unroll") for (int k = 0; k < 2; ++k) dst[m][k] = *(const PG8_LAS bf16x8*)(lds + PG8_SA(b, h) + aoff + m * 2048 + k * 1024); } while (0)
; #define PG8_LDB(dst, b, h) do { _Pragma("unroll") for (int n = 0; n < 2; ++n) _Pragma("unroll") for (int k = 0; k < 2; ++k) dst[n][k] = *(const PG8_LAS bf16x8*)(lds + PG8_SB(b, h) + boff + n * 2048 + k * 1024); } while (0)
; #define PG8_WAIT_V(n) asm volatile("s_waitcnt vmcnt(" #n ")" ::: "memory")
; #define PG8_WAIT_L(n) asm volatile("s_waitcnt lgkmcnt(" #n ")" ::: "memory")
; #define PG8_BAR __builtin_amdgcn_s_barrier()
; template <class Epi, class Sched, bool ALIGN_EPI = false, bool SP2 = false>
; __device__ __forceinline__ void gemm_phase(PG8_LAS unsigned char* lds, const Gemm g, const Sched& S, const Epi& E) {
;     ...
;         const bool has_next = S.next(ui + 1, nxt);
;         const char* nA = has_next ? (const char*)g.A + (size_t)nxt.pm * tstepA + (size_t)nxt.pb * g.sA : cA; const char* nB = has_next ? (const char*)g.Bt + (size_t)nxt.pn * tstepB + (size_t)nxt.pb * g.sB : cB;
;         for (int t = 0; t < nt; t += 2) {
;             const bool last = (t == nt - 2);
;             const char* a1 = cA + (size_t)(t + 1) * kstep;
;             const char* a2 = last ? nA : cA + (size_t)(t + 2) * kstep; const char* b2 = last ? nB : cB + (size_t)(t + 2) * kstep;
;             const char* a3 = a2 + kstep; const char* b3 = b2 + kstep;
;             if (last && has_next) S.a_ready(nxt);
;             if constexpr (SP2) {
;             PG8_LDB(B0, 0, 0); PG8_LDB(B1, 0, 1); PG8_SCHED; PG8_LDA(At, 0, 0); PG8_STAGE(PG8_SA(1, 1), a1 + hstepA, voffA);
;             PG8_WAIT_V(8); PG8_WAIT_L(0); PG8_BAR; PG8_MMA(0, 0, At, B0); PG8_MMA(0, 1, At, B1); PG8_BAR; PG8_SCHED;
;             PG8_LDA(At, 0, 1); PG8_STAGE(PG8_SB(0, 0), b2, voffB); PG8_STAGE(PG8_SB(0, 1), b2 + hstepB, voffB); PG8_STAGE(PG8_SA(0, 0), a2, voffA);
;             PG8_WAIT_V(8); PG8_WAIT_L(0); PG8_BAR; PG8_MMA(1, 0, At, B0); PG8_MMA(1, 1, At, B1); PG8_BAR; PG8_SCHED;
.LBB0_596:
	s_ashr_i32 s35, s34, 31
	s_lshl_b64 s[36:37], s[34:35], 19
	s_add_u32 s38, s0, s36
	s_addc_u32 s39, s1, s37
	s_and_b64 s[36:37], s[42:43], exec
	s_cselect_b32 s35, s39, s9
	s_cselect_b32 s62, s38, s8
	s_ashr_i32 s31, s30, 31
	s_lshl_b64 s[36:37], s[30:31], 19
	s_add_u32 s46, s52, s36
	s_addc_u32 s47, s53, s37
	s_and_b64 s[36:37], s[42:43], exec
	s_cselect_b32 s31, s47, s15
	s_cselect_b32 s63, s46, s14
	s_add_u32 s8, s8, 0x40080
	s_addc_u32 s9, s9, 0
	s_add_u32 s70, s14, 0x100
	s_addc_u32 s71, s15, 0
	s_mov_b32 s78, -2
	s_add_u32 s14, s8, 0xfffc0080
	s_addc_u32 s15, s9, -1
	s_add_i32 s20, 0, 0x10000
	s_cmp_eq_u32 s78, 12
	s_cselect_b32 s37, s35, s15
	s_cselect_b32 s36, s62, s14
	v_add_u32_e32 v0, s20, v161
	s_cselect_b32 s15, s31, s71
	s_cselect_b32 s14, s63, s70
	s_add_i32 s21, 0, 0x14000
	ds_read_b128 v[146:149], v0
	ds_read_b128 v[150:153], v0 offset:1024
	ds_read_b128 v[154:157], v0 offset:2048
	ds_read_b128 v[164:167], v0 offset:3072
	v_add_u32_e32 v0, s21, v161
	ds_read_b128 v[168:171], v0
	ds_read_b128 v[172:175], v0 offset:1024
	ds_read_b128 v[176:179], v0 offset:2048
	ds_read_b128 v[180:183], v0 offset:3072
	v_lshl_add_u64 v[158:159], s[8:9], 0, v[142:143]
	s_add_i32 m0, s54, 0xc000
	ds_read_b128 v[184:187], v163
	ds_read_b128 v[188:191], v163 offset:1024
	ds_read_b128 v[192:195], v163 offset:2048
	ds_read_b128 v[196:199], v163 offset:3072
	ds_read_b128 v[208:211], v163 offset:4096
	ds_read_b128 v[212:215], v163 offset:5120
	ds_read_b128 v[216:219], v163 offset:6144
	ds_read_b128 v[220:223], v163 offset:7168
	global_load_lds_dwordx4 v[158:159], off
	v_lshl_add_u64 v[158:159], s[8:9], 0, v[144:145]
	s_add_i32 m0, s54, 0xe000
	s_nop 0
	global_load_lds_dwordx4 v[158:159], off
	s_waitcnt vmcnt(8)
	s_waitcnt lgkmcnt(0)
	s_barrier
	s_setprio 1
	s_waitcnt lgkmcnt(0)
	v_mfma_f32_16x16x32_bf16 v[126:129], v[146:149], v[184:187], 0
	v_mfma_f32_16x16x32_bf16 v[122:125], v[154:157], v[184:187], 0
	v_mfma_f32_16x16x32_bf16 v[110:113], v[146:149], v[192:195], 0
	v_mfma_f32_16x16x32_bf16 v[106:109], v[154:157], v[192:195], 0
	v_mfma_f32_16x16x32_bf16 v[94:97], v[146:149], v[208:211], 0
	v_mfma_f32_16x16x32_bf16 v[90:93], v[154:157], v[208:211], 0
	v_mfma_f32_16x16x32_bf16 v[78:81], v[146:149], v[216:219], 0
	v_mfma_f32_16x16x32_bf16 v[74:77], v[154:157], v[216:219], 0
	v_mfma_f32_16x16x32_bf16 v[126:129], v[150:153], v[188:191], v[126:129]
	v_mfma_f32_16x16x32_bf16 v[122:125], v[164:167], v[188:191], v[122:125]
	v_mfma_f32_16x16x32_bf16 v[110:113], v[150:153], v[196:199], v[110:113]
	v_mfma_f32_16x16x32_bf16 v[106:109], v[164:167], v[196:199], v[106:109]
	v_mfma_f32_16x16x32_bf16 v[94:97], v[150:153], v[212:215], v[94:97]
	v_mfma_f32_16x16x32_bf16 v[90:93], v[164:167], v[212:215], v[90:93]
	v_mfma_f32_16x16x32_bf16 v[78:81], v[150:153], v[220:223], v[78:81]
	v_mfma_f32_16x16x32_bf16 v[74:77], v[164:167], v[220:223], v[74:77]
	v_mfma_f32_16x16x32_bf16 v[118:121], v[168:171], v[184:187], 0
	v_mfma_f32_16x16x32_bf16 v[114:117], v[176:179], v[184:187], 0
	v_mfma_f32_16x16x32_bf16 v[102:105], v[168:171], v[192:195], 0
	v_mfma_f32_16x16x32_bf16 v[98:101], v[176:179], v[192:195], 0
	v_mfma_f32_16x16x32_bf16 v[86:89], v[168:171], v[208:211], 0
	v_mfma_f32_16x16x32_bf16 v[82:85], v[176:179], v[208:211], 0
	v_mfma_f32_16x16x32_bf16 v[70:73], v[168:171], v[216:219], 0
	v_mfma_f32_16x16x32_bf16 v[66:69], v[176:179], v[216:219], 0
	v_mfma_f32_16x16x32_bf16 v[118:121], v[172:175], v[188:191], v[118:121]
	v_mfma_f32_16x16x32_bf16 v[114:117], v[180:183], v[188:191], v[114:117]
	v_mfma_f32_16x16x32_bf16 v[102:105], v[172:175], v[196:199], v[102:105]
	v_mfma_f32_16x16x32_bf16 v[98:101], v[180:183], v[196:199], v[98:101]
	v_mfma_f32_16x16x32_bf16 v[86:89], v[172:175], v[212:215], v[86:89]
	v_mfma_f32_16x16x32_bf16 v[82:85], v[180:183], v[212:215], v[82:85]
	v_mfma_f32_16x16x32_bf16 v[70:73], v[172:175], v[220:223], v[70:73]
	v_mfma_f32_16x16x32_bf16 v[66:69], v[180:183], v[220:223], v[66:69]
	s_setprio 0
	s_barrier
	s_add_i32 s20, s20, s26
	v_lshl_add_u64 v[158:159], s[14:15], 0, v[134:135]
	s_mov_b32 m0, s20
	ds_read_b128 v[184:187], v163 offset:16384
	ds_read_b128 v[188:191], v163 offset:17408
	ds_read_b128 v[192:195], v163 offset:18432
	ds_read_b128 v[196:199], v163 offset:19456
	ds_read_b128 v[208:211], v163 offset:20480
	ds_read_b128 v[212:215], v163 offset:21504
	ds_read_b128 v[216:219], v163 offset:22528
	ds_read_b128 v[220:223], v163 offset:23552
	global_load_lds_dwordx4 v[158:159], off
	s_add_i32 m0, s20, 0x2000
	s_add_u32 s80, s14, 0x40000
	v_lshl_add_u64 v[200:201], s[14:15], 0, v[130:131]
	s_addc_u32 s81, s15, 0
	s_add_i32 s20, s21, s26
	global_load_lds_dwordx4 v[200:201], off
	v_lshl_add_u64 v[224:225], s[80:81], 0, v[134:135]
	s_mov_b32 m0, s20
	v_lshl_add_u64 v[226:227], s[36:37], 0, v[132:133]
	global_load_lds_dwordx4 v[224:225], off
	v_lshl_add_u64 v[224:225], s[80:81], 0, v[130:131]
	s_add_i32 m0, s20, 0x2000
	s_nop 0
	global_load_lds_dwordx4 v[224:225], off
	v_lshl_add_u64 v[224:225], s[36:37], 0, v[136:137]
	s_mov_b32 m0, s54
	s_nop 0
	global_load_lds_dwordx4 v[224:225], off
	s_mov_b32 m0, s55
	s_nop 0
	global_load_lds_dwordx4 v[226:227], off
	s_waitcnt vmcnt(8)
	s_waitcnt lgkmcnt(0)
	s_barrier
; #define PG8_STAGE(bufoff, gbase, voff) do { _Pragma("unroll") for (int _i = 0; _i < 2; ++_i) \
;         __builtin_amdgcn_global_load_lds((const unsigned*)((const char*)(gbase) + (voff)[_i]), (PG8_LAS unsigned*)(lds + (bufoff) + ldsw + _i * 8192), 16, 0, 0); } while (0)
; #define PG8_LDA(dst, b, h) do { _Pragma("unroll") for (int m = 0; m < 4; ++m) _Pragma("unroll") for (int k = 0; k < 2; ++k) dst[m][k] = *(const PG8_LAS bf16x8*)(lds + PG8_SA(b, h) + aoff + m * 2048 + k * 1024); } while (0)
; #define PG8_LDB(dst, b, h) do { _Pragma("unroll") for (int n = 0; n < 2; ++n) _Pragma("unroll") for (int k = 0; k < 2; ++k) dst[n][k] = *(const PG8_LAS bf16x8*)(lds + PG8_SB(b, h) + boff + n * 2048 + k * 1024); } while (0)
; #define PG8_MMA(ai, bj, At, Bt) do { __builtin_amdgcn_s_setprio(1); _Pragma("unroll") for (int m = 0; m < 4; ++m) _Pragma("unroll") for (int n = 0; n < 2; ++n) _Pragma("unroll") for (int k = 0; k < 2; ++k) \
;         acc[ai][bj][m][n] = __builtin_amdgcn_mfma_f32_16x16x32_bf16(Bt[n][k], At[m][k], acc[ai][bj][m][n], 0, 0, 0); __builtin_amdgcn_s_setprio(0); } while (0)
; #define PG8_WAIT_V(n) asm volatile("s_waitcnt vmcnt(" #n ")" ::: "memory")
; #define PG8_WAIT_L(n) asm volatile("s_waitcnt lgkmcnt(" #n ")" ::: "memory")
; #define PG8_BAR __builtin_amdgcn_s_barrier()
; #define PG8_SCHED __builtin_amdgcn_sched_barrier(0)
; template <class Epi, class Sched, bool ALIGN_EPI = false, bool SP2 = false>
; __device__ __forceinline__ void gemm_phase(PG8_LAS unsigned char* lds, const Gemm g, const Sched& S, const Epi& E) {
;     ...
;             PG8_WAIT_V(8); PG8_WAIT_L(0); PG8_BAR; PG8_MMA(1, 0, At, B0); PG8_MMA(1, 1, At, B1); PG8_BAR; PG8_SCHED;
;             PG8_LDB(B0, 1, 0); PG8_LDB(B1, 1, 1); PG8_SCHED; PG8_LDA(At, 1, 0); PG8_STAGE(PG8_SA(0, 1), a2 + hstepA, voffA);
;             PG8_WAIT_V(8); PG8_WAIT_L(0); PG8_BAR; PG8_MMA(0, 0, At, B0); PG8_MMA(0, 1, At, B1); PG8_BAR; PG8_SCHED;
	s_setprio 1
	s_waitcnt lgkmcnt(0)
	v_mfma_f32_16x16x32_bf16 v[62:65], v[146:149], v[184:187], 0
	v_mfma_f32_16x16x32_bf16 v[58:61], v[154:157], v[184:187], 0
	v_mfma_f32_16x16x32_bf16 v[46:49], v[146:149], v[192:195], 0
	v_mfma_f32_16x16x32_bf16 v[42:45], v[154:157], v[192:195], 0
	v_mfma_f32_16x16x32_bf16 v[30:33], v[146:149], v[208:211], 0
	v_mfma_f32_16x16x32_bf16 v[26:29], v[154:157], v[208:211], 0
	v_mfma_f32_16x16x32_bf16 v[14:17], v[146:149], v[216:219], 0
	v_mfma_f32_16x16x32_bf16 v[10:13], v[154:157], v[216:219], 0
	v_mfma_f32_16x16x32_bf16 v[62:65], v[150:153], v[188:191], v[62:65]
	v_mfma_f32_16x16x32_bf16 v[58:61], v[164:167], v[188:191], v[58:61]
	v_mfma_f32_16x16x32_bf16 v[46:49], v[150:153], v[196:199], v[46:49]
	v_mfma_f32_16x16x32_bf16 v[42:45], v[164:167], v[196:199], v[42:45]
	v_mfma_f32_16x16x32_bf16 v[30:33], v[150:153], v[212:215], v[30:33]
	v_mfma_f32_16x16x32_bf16 v[26:29], v[164:167], v[212:215], v[26:29]
	v_mfma_f32_16x16x32_bf16 v[14:17], v[150:153], v[220:223], v[14:17]
	v_mfma_f32_16x16x32_bf16 v[10:13], v[164:167], v[220:223], v[10:13]
	v_mfma_f32_16x16x32_bf16 v[54:57], v[168:171], v[184:187], 0
	v_mfma_f32_16x16x32_bf16 v[50:53], v[176:179], v[184:187], 0
	v_mfma_f32_16x16x32_bf16 v[38:41], v[168:171], v[192:195], 0
	v_mfma_f32_16x16x32_bf16 v[34:37], v[176:179], v[192:195], 0
	v_mfma_f32_16x16x32_bf16 v[22:25], v[168:171], v[208:211], 0
	v_mfma_f32_16x16x32_bf16 v[18:21], v[176:179], v[208:211], 0
	v_mfma_f32_16x16x32_bf16 v[6:9], v[168:171], v[216:219], 0
	v_mfma_f32_16x16x32_bf16 v[2:5], v[176:179], v[216:219], 0
	v_mfma_f32_16x16x32_bf16 v[54:57], v[172:175], v[188:191], v[54:57]
	v_mfma_f32_16x16x32_bf16 v[50:53], v[180:183], v[188:191], v[50:53]
	v_mfma_f32_16x16x32_bf16 v[38:41], v[172:175], v[196:199], v[38:41]
	v_mfma_f32_16x16x32_bf16 v[34:37], v[180:183], v[196:199], v[34:37]
	v_mfma_f32_16x16x32_bf16 v[22:25], v[172:175], v[212:215], v[22:25]
	v_mfma_f32_16x16x32_bf16 v[18:21], v[180:183], v[212:215], v[18:21]
	v_mfma_f32_16x16x32_bf16 v[6:9], v[172:175], v[220:223], v[6:9]
	v_mfma_f32_16x16x32_bf16 v[2:5], v[180:183], v[220:223], v[2:5]
	s_setprio 0
	s_barrier
	s_add_i32 s20, 0, 0x18000
	v_add_u32_e32 v0, s20, v161
	s_add_i32 s21, 0, 0x1c000
	ds_read_b128 v[146:149], v0
	ds_read_b128 v[150:153], v0 offset:1024
	ds_read_b128 v[154:157], v0 offset:2048
	ds_read_b128 v[164:167], v0 offset:3072
	v_add_u32_e32 v0, s21, v161
	ds_read_b128 v[168:171], v0
	ds_read_b128 v[172:175], v0 offset:1024
	ds_read_b128 v[176:179], v0 offset:2048
	ds_read_b128 v[180:183], v0 offset:3072
	s_add_u32 s36, s36, 0x40000
	s_addc_u32 s37, s37, 0
	s_mov_b32 m0, s56
	v_lshl_add_u64 v[228:229], s[36:37], 0, v[136:137]
	ds_read_b128 v[184:187], v163 offset:32768
	ds_read_b128 v[188:191], v163 offset:33792
	ds_read_b128 v[192:195], v163 offset:34816
	ds_read_b128 v[196:199], v163 offset:35840
	ds_read_b128 v[208:211], v163 offset:36864
	ds_read_b128 v[212:215], v163 offset:37888
	ds_read_b128 v[216:219], v163 offset:38912
	ds_read_b128 v[220:223], v163 offset:39936
	global_load_lds_dwordx4 v[228:229], off
	v_lshl_add_u64 v[228:229], s[36:37], 0, v[132:133]
	s_mov_b32 m0, s57
	s_nop 0
	global_load_lds_dwordx4 v[228:229], off
	s_waitcnt vmcnt(8)
	s_waitcnt lgkmcnt(0)
	s_barrier
	s_setprio 1
	s_waitcnt lgkmcnt(0)
	v_mfma_f32_16x16x32_bf16 v[126:129], v[146:149], v[184:187], v[126:129]
	v_mfma_f32_16x16x32_bf16 v[122:125], v[154:157], v[184:187], v[122:125]
	v_mfma_f32_16x16x32_bf16 v[110:113], v[146:149], v[192:195], v[110:113]
	v_mfma_f32_16x16x32_bf16 v[106:109], v[154:157], v[192:195], v[106:109]
	v_mfma_f32_16x16x32_bf16 v[94:97], v[146:149], v[208:211], v[94:97]
	v_mfma_f32_16x16x32_bf16 v[90:93], v[154:157], v[208:211], v[90:93]
	v_mfma_f32_16x16x32_bf16 v[78:81], v[146:149], v[216:219], v[78:81]
	v_mfma_f32_16x16x32_bf16 v[74:77], v[154:157], v[216:219], v[74:77]
	v_mfma_f32_16x16x32_bf16 v[126:129], v[150:153], v[188:191], v[126:129]
	v_mfma_f32_16x16x32_bf16 v[122:125], v[164:167], v[188:191], v[122:125]
	v_mfma_f32_16x16x32_bf16 v[110:113], v[150:153], v[196:199], v[110:113]
	v_mfma_f32_16x16x32_bf16 v[106:109], v[164:167], v[196:199], v[106:109]
	v_mfma_f32_16x16x32_bf16 v[94:97], v[150:153], v[212:215], v[94:97]
	v_mfma_f32_16x16x32_bf16 v[90:93], v[164:167], v[212:215], v[90:93]
	v_mfma_f32_16x16x32_bf16 v[78:81], v[150:153], v[220:223], v[78:81]
	v_mfma_f32_16x16x32_bf16 v[74:77], v[164:167], v[220:223], v[74:77]
	v_mfma_f32_16x16x32_bf16 v[118:121], v[168:171], v[184:187], v[118:121]
	v_mfma_f32_16x16x32_bf16 v[114:117], v[176:179], v[184:187], v[114:117]
	v_mfma_f32_16x16x32_bf16 v[102:105], v[168:171], v[192:195], v[102:105]
	v_mfma_f32_16x16x32_bf16 v[98:101], v[176:179], v[192:195], v[98:101]
	v_mfma_f32_16x16x32_bf16 v[86:89], v[168:171], v[208:211], v[86:89]
	v_mfma_f32_16x16x32_bf16 v[82:85], v[176:179], v[208:211], v[82:85]
	v_mfma_f32_16x16x32_bf16 v[70:73], v[168:171], v[216:219], v[70:73]
	v_mfma_f32_16x16x32_bf16 v[66:69], v[176:179], v[216:219], v[66:69]
	v_mfma_f32_16x16x32_bf16 v[118:121], v[172:175], v[188:191], v[118:121]
	v_mfma_f32_16x16x32_bf16 v[114:117], v[180:183], v[188:191], v[114:117]
	v_mfma_f32_16x16x32_bf16 v[102:105], v[172:175], v[196:199], v[102:105]
	v_mfma_f32_16x16x32_bf16 v[98:101], v[180:183], v[196:199], v[98:101]
	v_mfma_f32_16x16x32_bf16 v[86:89], v[172:175], v[212:215], v[86:89]
	v_mfma_f32_16x16x32_bf16 v[82:85], v[180:183], v[212:215], v[82:85]
	v_mfma_f32_16x16x32_bf16 v[70:73], v[172:175], v[220:223], v[70:73]
	v_mfma_f32_16x16x32_bf16 v[66:69], v[180:183], v[220:223], v[66:69]
	s_setprio 0
	s_barrier
; #define PG8_STAGE(bufoff, gbase, voff) do { _Pragma("unroll") for (int _i = 0; _i < 2; ++_i) \
;         __builtin_amdgcn_global_load_lds((const unsigned*)((const char*)(gbase) + (voff)[_i]), (PG8_LAS unsigned*)(lds + (bufoff) + ldsw + _i * 8192), 16, 0, 0); } while (0)
; #define PG8_LDA(dst, b, h) do { _Pragma("unroll") for (int m = 0; m < 4; ++m) _Pragma("unroll") for (int k = 0; k < 2; ++k) dst[m][k] = *(const PG8_LAS bf16x8*)(lds + PG8_SA(b, h) + aoff + m * 2048 + k * 1024); } while (0)
; #define PG8_LDB(dst, b, h) do { _Pragma("unroll") for (int n = 0; n < 2; ++n) _Pragma("unroll") for (int k = 0; k < 2; ++k) dst[n][k] = *(const PG8_LAS bf16x8*)(lds + PG8_SB(b, h) + boff + n * 2048 + k * 1024); } while (0)
; #define PG8_MMA(ai, bj, At, Bt) do { __builtin_amdgcn_s_setprio(1); _Pragma("unroll") for (int m = 0; m < 4; ++m) _Pragma("unroll") for (int n = 0; n < 2; ++n) _Pragma("unroll") for (int k = 0; k < 2; ++k) \
;         acc[ai][bj][m][n] = __builtin_amdgcn_mfma_f32_16x16x32_bf16(Bt[n][k], At[m][k], acc[ai][bj][m][n], 0, 0, 0); __builtin_amdgcn_s_setprio(0); } while (0)
; #define PG8_WAIT_V(n) asm volatile("s_waitcnt vmcnt(" #n ")" ::: "memory")
; template <class Epi, class Sched, bool ALIGN_EPI = false, bool SP2 = false>
; __device__ __forceinline__ void gemm_phase(PG8_LAS unsigned char* lds, const Gemm g, const Sched& S, const Epi& E) {
;     ...
;             PG8_LDB(B0, 0, 0); PG8_LDB(B1, 0, 1); PG8_SCHED; PG8_LDA(At, 0, 0); PG8_STAGE(PG8_SA(1, 1), a1 + hstepA, voffA);
;             PG8_WAIT_V(8); PG8_WAIT_L(0); PG8_BAR; PG8_MMA(0, 0, At, B0); PG8_MMA(0, 1, At, B1); PG8_BAR; PG8_SCHED;
;             PG8_LDA(At, 0, 1); PG8_STAGE(PG8_SB(0, 0), b2, voffB); PG8_STAGE(PG8_SB(0, 1), b2 + hstepB, voffB); PG8_STAGE(PG8_SA(0, 0), a2, voffA);
;             PG8_WAIT_V(8); PG8_WAIT_L(0); PG8_BAR; PG8_MMA(1, 0, At, B0); PG8_MMA(1, 1, At, B1); PG8_BAR; PG8_SCHED;
;             PG8_LDB(B0, 1, 0); PG8_LDB(B1, 1, 1); PG8_SCHED; PG8_LDA(At, 1, 0); PG8_STAGE(PG8_SA(0, 1), a2 + hstepA, voffA);
;             PG8_WAIT_V(8); PG8_WAIT_L(0); PG8_BAR; PG8_MMA(0, 0, At, B0); PG8_MMA(0, 1, At, B1); PG8_BAR; PG8_SCHED;
;             PG8_LDA(At, 1, 1); PG8_STAGE(PG8_SB(1, 0), b3, voffB); PG8_STAGE(PG8_SB(1, 1), b3 + hstepB, voffB); PG8_STAGE(PG8_SA(1, 0), a3, voffA);
;             PG8_WAIT_V(8); PG8_WAIT_L(0); PG8_BAR; PG8_MMA(1, 0, At, B0); PG8_MMA(1, 1, At, B1); PG8_BAR; PG8_SCHED;
	s_add_i32 s20, s20, s26
	v_lshl_add_u64 v[158:159], v[158:159], 0, s[22:23]
	s_mov_b32 m0, s20
	ds_read_b128 v[184:187], v163 offset:49152
	ds_read_b128 v[188:191], v163 offset:50176
	ds_read_b128 v[192:195], v163 offset:51200
	ds_read_b128 v[196:199], v163 offset:52224
	ds_read_b128 v[208:211], v163 offset:53248
	ds_read_b128 v[212:215], v163 offset:54272
	ds_read_b128 v[216:219], v163 offset:55296
	ds_read_b128 v[220:223], v163 offset:56320
	global_load_lds_dwordx4 v[158:159], off
	s_add_i32 m0, s20, 0x2000
	s_add_u32 s14, s14, 0x40080
	v_lshl_add_u64 v[158:159], v[200:201], 0, s[22:23]
	s_addc_u32 s15, s15, 0
	s_add_i32 s20, s21, s26
	global_load_lds_dwordx4 v[158:159], off
	v_lshl_add_u64 v[158:159], s[14:15], 0, v[134:135]
	s_mov_b32 m0, s20
	s_nop 0
	global_load_lds_dwordx4 v[158:159], off
	v_lshl_add_u64 v[158:159], s[14:15], 0, v[130:131]
	s_add_i32 m0, s20, 0x2000
	s_nop 0
	global_load_lds_dwordx4 v[158:159], off
	v_lshl_add_u64 v[158:159], v[224:225], 0, s[22:23]
	s_mov_b32 m0, s58
	s_nop 0
	global_load_lds_dwordx4 v[158:159], off
	v_lshl_add_u64 v[158:159], v[226:227], 0, s[22:23]
	s_mov_b32 m0, s59
	s_nop 0
	global_load_lds_dwordx4 v[158:159], off
	s_waitcnt vmcnt(8)
	s_waitcnt lgkmcnt(0)
	s_barrier
	s_setprio 1
	s_waitcnt lgkmcnt(0)
	v_mfma_f32_16x16x32_bf16 v[62:65], v[146:149], v[184:187], v[62:65]
	v_mfma_f32_16x16x32_bf16 v[58:61], v[154:157], v[184:187], v[58:61]
	v_mfma_f32_16x16x32_bf16 v[46:49], v[146:149], v[192:195], v[46:49]
	v_mfma_f32_16x16x32_bf16 v[42:45], v[154:157], v[192:195], v[42:45]
	v_mfma_f32_16x16x32_bf16 v[30:33], v[146:149], v[208:211], v[30:33]
	v_mfma_f32_16x16x32_bf16 v[26:29], v[154:157], v[208:211], v[26:29]
	v_mfma_f32_16x16x32_bf16 v[14:17], v[146:149], v[216:219], v[14:17]
	v_mfma_f32_16x16x32_bf16 v[10:13], v[154:157], v[216:219], v[10:13]
	v_mfma_f32_16x16x32_bf16 v[62:65], v[150:153], v[188:191], v[62:65]
	v_mfma_f32_16x16x32_bf16 v[58:61], v[164:167], v[188:191], v[58:61]
	v_mfma_f32_16x16x32_bf16 v[46:49], v[150:153], v[196:199], v[46:49]
	v_mfma_f32_16x16x32_bf16 v[42:45], v[164:167], v[196:199], v[42:45]
	v_mfma_f32_16x16x32_bf16 v[30:33], v[150:153], v[212:215], v[30:33]
	v_mfma_f32_16x16x32_bf16 v[26:29], v[164:167], v[212:215], v[26:29]
	v_mfma_f32_16x16x32_bf16 v[14:17], v[150:153], v[220:223], v[14:17]
	v_mfma_f32_16x16x32_bf16 v[10:13], v[164:167], v[220:223], v[10:13]
	v_mfma_f32_16x16x32_bf16 v[54:57], v[168:171], v[184:187], v[54:57]
	v_mfma_f32_16x16x32_bf16 v[50:53], v[176:179], v[184:187], v[50:53]
	v_mfma_f32_16x16x32_bf16 v[38:41], v[168:171], v[192:195], v[38:41]
	v_mfma_f32_16x16x32_bf16 v[34:37], v[176:179], v[192:195], v[34:37]
	v_mfma_f32_16x16x32_bf16 v[22:25], v[168:171], v[208:211], v[22:25]
	v_mfma_f32_16x16x32_bf16 v[18:21], v[176:179], v[208:211], v[18:21]
	v_mfma_f32_16x16x32_bf16 v[6:9], v[168:171], v[216:219], v[6:9]
	v_mfma_f32_16x16x32_bf16 v[2:5], v[176:179], v[216:219], v[2:5]
	v_mfma_f32_16x16x32_bf16 v[54:57], v[172:175], v[188:191], v[54:57]
	v_mfma_f32_16x16x32_bf16 v[50:53], v[180:183], v[188:191], v[50:53]
	v_mfma_f32_16x16x32_bf16 v[38:41], v[172:175], v[196:199], v[38:41]
	v_mfma_f32_16x16x32_bf16 v[34:37], v[180:183], v[196:199], v[34:37]
	v_mfma_f32_16x16x32_bf16 v[22:25], v[172:175], v[212:215], v[22:25]
	v_mfma_f32_16x16x32_bf16 v[18:21], v[180:183], v[212:215], v[18:21]
	v_mfma_f32_16x16x32_bf16 v[6:9], v[172:175], v[220:223], v[6:9]
	v_mfma_f32_16x16x32_bf16 v[2:5], v[180:183], v[220:223], v[2:5]
	s_setprio 0
	s_barrier
	s_add_i32 s78, s78, 2
	s_add_u32 s8, s8, 0x100
	s_addc_u32 s9, s9, 0
	s_add_u32 s70, s70, 0x100
	s_addc_u32 s71, s71, 0
	s_cmp_gt_u32 s78, 13
	s_cbranch_scc1 .Lpk_done_g597
.LBB0_597:
	s_add_u32 s14, s8, 0xfffc0080
	s_addc_u32 s15, s9, -1
	s_add_i32 s20, 0, 0x10000
	s_cmp_eq_u32 s78, 12
	s_cselect_b32 s37, s35, s15
	s_cselect_b32 s36, s62, s14
	v_add_u32_e32 v0, s20, v161
	s_cselect_b32 s15, s31, s71
	s_cselect_b32 s14, s63, s70
	s_add_i32 s21, 0, 0x14000
	ds_read_b128 v[146:149], v0
	ds_read_b128 v[150:153], v0 offset:1024
	ds_read_b128 v[154:157], v0 offset:2048
	ds_read_b128 v[164:167], v0 offset:3072
	v_add_u32_e32 v0, s21, v161
	ds_read_b128 v[168:171], v0
	ds_read_b128 v[172:175], v0 offset:1024
	ds_read_b128 v[176:179], v0 offset:2048
	ds_read_b128 v[180:183], v0 offset:3072
	v_lshl_add_u64 v[158:159], s[8:9], 0, v[142:143]
	s_add_i32 m0, s54, 0xc000
	ds_read_b128 v[184:187], v163
	ds_read_b128 v[188:191], v163 offset:1024
	ds_read_b128 v[192:195], v163 offset:2048
	ds_read_b128 v[196:199], v163 offset:3072
	ds_read_b128 v[208:211], v163 offset:4096
	ds_read_b128 v[212:215], v163 offset:5120
	ds_read_b128 v[216:219], v163 offset:6144
	ds_read_b128 v[220:223], v163 offset:7168
	global_load_lds_dwordx4 v[158:159], off
	v_lshl_add_u64 v[158:159], s[8:9], 0, v[144:145]
	s_add_i32 m0, s54, 0xe000
	s_nop 0
	global_load_lds_dwordx4 v[158:159], off
	s_waitcnt vmcnt(8)
	s_waitcnt lgkmcnt(0)
	s_barrier
; #define PG8_STAGE(bufoff, gbase, voff) do { _Pragma("unroll") for (int _i = 0; _i < 2; ++_i) \
;         __builtin_amdgcn_global_load_lds((const unsigned*)((const char*)(gbase) + (voff)[_i]), (PG8_LAS unsigned*)(lds + (bufoff) + ldsw + _i * 8192), 16, 0, 0); } while (0)
; #define PG8_LDA(dst, b, h) do { _Pragma("unroll") for (int m = 0; m < 4; ++m) _Pragma("unroll") for (int k = 0; k < 2; ++k) dst[m][k] = *(const PG8_LAS bf16x8*)(lds + PG8_SA(b, h) + aoff + m * 2048 + k * 1024); } while (0)
; #define PG8_MMA(ai, bj, At, Bt) do { __builtin_amdgcn_s_setprio(1); _Pragma("unroll") for (int m = 0; m < 4; ++m) _Pragma("unroll") for (int n = 0; n < 2; ++n) _Pragma("unroll") for (int k = 0; k < 2; ++k) \
;         acc[ai][bj][m][n] = __builtin_amdgcn_mfma_f32_16x16x32_bf16(Bt[n][k], At[m][k], acc[ai][bj][m][n], 0, 0, 0); __builtin_amdgcn_s_setprio(0); } while (0)
; #define PG8_WAIT_V(n) asm volatile("s_waitcnt vmcnt(" #n ")" ::: "memory")
; #define PG8_WAIT_L(n) asm volatile("s_waitcnt lgkmcnt(" #n ")" ::: "memory")
; #define PG8_BAR __builtin_amdgcn_s_barrier()
; #define PG8_SCHED __builtin_amdgcn_sched_barrier(0)
; template <class Epi, class Sched, bool ALIGN_EPI = false, bool SP2 = false>
; __device__ __forceinline__ void gemm_phase(PG8_LAS unsigned char* lds, const Gemm g, const Sched& S, const Epi& E) {
;     ...
;             PG8_WAIT_V(8); PG8_WAIT_L(0); PG8_BAR; PG8_MMA(0, 0, At, B0); PG8_MMA(0, 1, At, B1); PG8_BAR; PG8_SCHED;
;             PG8_LDA(At, 0, 1); PG8_STAGE(PG8_SB(0, 0), b2, voffB); PG8_STAGE(PG8_SB(0, 1), b2 + hstepB, voffB); PG8_STAGE(PG8_SA(0, 0), a2, voffA);
;             PG8_WAIT_V(8); PG8_WAIT_L(0); PG8_BAR; PG8_MMA(1, 0, At, B0); PG8_MMA(1, 1, At, B1); PG8_BAR; PG8_SCHED;
	s_setprio 1
	s_waitcnt lgkmcnt(0)
	v_mfma_f32_16x16x32_bf16 v[126:129], v[146:149], v[184:187], v[126:129]
	v_mfma_f32_16x16x32_bf16 v[122:125], v[154:157], v[184:187], v[122:125]
	v_mfma_f32_16x16x32_bf16 v[110:113], v[146:149], v[192:195], v[110:113]
	v_mfma_f32_16x16x32_bf16 v[106:109], v[154:157], v[192:195], v[106:109]
	v_mfma_f32_16x16x32_bf16 v[94:97], v[146:149], v[208:211], v[94:97]
	v_mfma_f32_16x16x32_bf16 v[90:93], v[154:157], v[208:211], v[90:93]
	v_mfma_f32_16x16x32_bf16 v[78:81], v[146:149], v[216:219], v[78:81]
	v_mfma_f32_16x16x32_bf16 v[74:77], v[154:157], v[216:219], v[74:77]
	v_mfma_f32_16x16x32_bf16 v[126:129], v[150:153], v[188:191], v[126:129]
	v_mfma_f32_16x16x32_bf16 v[122:125], v[164:167], v[188:191], v[122:125]
	v_mfma_f32_16x16x32_bf16 v[110:113], v[150:153], v[196:199], v[110:113]
	v_mfma_f32_16x16x32_bf16 v[106:109], v[164:167], v[196:199], v[106:109]
	v_mfma_f32_16x16x32_bf16 v[94:97], v[150:153], v[212:215], v[94:97]
	v_mfma_f32_16x16x32_bf16 v[90:93], v[164:167], v[212:215], v[90:93]
	v_mfma_f32_16x16x32_bf16 v[78:81], v[150:153], v[220:223], v[78:81]
	v_mfma_f32_16x16x32_bf16 v[74:77], v[164:167], v[220:223], v[74:77]
	v_mfma_f32_16x16x32_bf16 v[118:121], v[168:171], v[184:187], v[118:121]
	v_mfma_f32_16x16x32_bf16 v[114:117], v[176:179], v[184:187], v[114:117]
	v_mfma_f32_16x16x32_bf16 v[102:105], v[168:171], v[192:195], v[102:105]
	v_mfma_f32_16x16x32_bf16 v[98:101], v[176:179], v[192:195], v[98:101]
	v_mfma_f32_16x16x32_bf16 v[86:89], v[168:171], v[208:211], v[86:89]
	v_mfma_f32_16x16x32_bf16 v[82:85], v[176:179], v[208:211], v[82:85]
	v_mfma_f32_16x16x32_bf16 v[70:73], v[168:171], v[216:219], v[70:73]
	v_mfma_f32_16x16x32_bf16 v[66:69], v[176:179], v[216:219], v[66:69]
	v_mfma_f32_16x16x32_bf16 v[118:121], v[172:175], v[188:191], v[118:121]
	v_mfma_f32_16x16x32_bf16 v[114:117], v[180:183], v[188:191], v[114:117]
	v_mfma_f32_16x16x32_bf16 v[102:105], v[172:175], v[196:199], v[102:105]
	v_mfma_f32_16x16x32_bf16 v[98:101], v[180:183], v[196:199], v[98:101]
	v_mfma_f32_16x16x32_bf16 v[86:89], v[172:175], v[212:215], v[86:89]
	v_mfma_f32_16x16x32_bf16 v[82:85], v[180:183], v[212:215], v[82:85]
	v_mfma_f32_16x16x32_bf16 v[70:73], v[172:175], v[220:223], v[70:73]
	v_mfma_f32_16x16x32_bf16 v[66:69], v[180:183], v[220:223], v[66:69]
	s_setprio 0
	s_barrier
	s_add_i32 s20, s20, s26
	v_lshl_add_u64 v[158:159], s[14:15], 0, v[134:135]
	s_mov_b32 m0, s20
	ds_read_b128 v[184:187], v163 offset:16384
	ds_read_b128 v[188:191], v163 offset:17408
	ds_read_b128 v[192:195], v163 offset:18432
	ds_read_b128 v[196:199], v163 offset:19456
	ds_read_b128 v[208:211], v163 offset:20480
	ds_read_b128 v[212:215], v163 offset:21504
	ds_read_b128 v[216:219], v163 offset:22528
	ds_read_b128 v[220:223], v163 offset:23552
	global_load_lds_dwordx4 v[158:159], off
	s_add_i32 m0, s20, 0x2000
	s_add_u32 s80, s14, 0x40000
	v_lshl_add_u64 v[200:201], s[14:15], 0, v[130:131]
	s_addc_u32 s81, s15, 0
	s_add_i32 s20, s21, s26
	global_load_lds_dwordx4 v[200:201], off
	v_lshl_add_u64 v[224:225], s[80:81], 0, v[134:135]
	s_mov_b32 m0, s20
	v_lshl_add_u64 v[226:227], s[36:37], 0, v[132:133]
	global_load_lds_dwordx4 v[224:225], off
	v_lshl_add_u64 v[224:225], s[80:81], 0, v[130:131]
	s_add_i32 m0, s20, 0x2000
	s_nop 0
	global_load_lds_dwordx4 v[224:225], off
	v_lshl_add_u64 v[224:225], s[36:37], 0, v[136:137]
	s_mov_b32 m0, s54
	s_nop 0
	global_load_lds_dwordx4 v[224:225], off
	s_mov_b32 m0, s55
	s_nop 0
	global_load_lds_dwordx4 v[226:227], off
	s_waitcnt vmcnt(8)
	s_waitcnt lgkmcnt(0)
	s_barrier
	s_setprio 1
	s_waitcnt lgkmcnt(0)
	v_mfma_f32_16x16x32_bf16 v[62:65], v[146:149], v[184:187], v[62:65]
	v_mfma_f32_16x16x32_bf16 v[58:61], v[154:157], v[184:187], v[58:61]
	v_mfma_f32_16x16x32_bf16 v[46:49], v[146:149], v[192:195], v[46:49]
	v_mfma_f32_16x16x32_bf16 v[42:45], v[154:157], v[192:195], v[42:45]
	v_mfma_f32_16x16x32_bf16 v[30:33], v[146:149], v[208:211], v[30:33]
	v_mfma_f32_16x16x32_bf16 v[26:29], v[154:157], v[208:211], v[26:29]
	v_mfma_f32_16x16x32_bf16 v[14:17], v[146:149], v[216:219], v[14:17]
	v_mfma_f32_16x16x32_bf16 v[10:13], v[154:157], v[216:219], v[10:13]
	v_mfma_f32_16x16x32_bf16 v[62:65], v[150:153], v[188:191], v[62:65]
	v_mfma_f32_16x16x32_bf16 v[58:61], v[164:167], v[188:191], v[58:61]
	v_mfma_f32_16x16x32_bf16 v[46:49], v[150:153], v[196:199], v[46:49]
	v_mfma_f32_16x16x32_bf16 v[42:45], v[164:167], v[196:199], v[42:45]
	v_mfma_f32_16x16x32_bf16 v[30:33], v[150:153], v[212:215], v[30:33]
	v_mfma_f32_16x16x32_bf16 v[26:29], v[164:167], v[212:215], v[26:29]
	v_mfma_f32_16x16x32_bf16 v[14:17], v[150:153], v[220:223], v[14:17]
	v_mfma_f32_16x16x32_bf16 v[10:13], v[164:167], v[220:223], v[10:13]
	v_mfma_f32_16x16x32_bf16 v[54:57], v[168:171], v[184:187], v[54:57]
	v_mfma_f32_16x16x32_bf16 v[50:53], v[176:179], v[184:187], v[50:53]
	v_mfma_f32_16x16x32_bf16 v[38:41], v[168:171], v[192:195], v[38:41]
	v_mfma_f32_16x16x32_bf16 v[34:37], v[176:179], v[192:195], v[34:37]
	v_mfma_f32_16x16x32_bf16 v[22:25], v[168:171], v[208:211], v[22:25]
	v_mfma_f32_16x16x32_bf16 v[18:21], v[176:179], v[208:211], v[18:21]
	v_mfma_f32_16x16x32_bf16 v[6:9], v[168:171], v[216:219], v[6:9]
	v_mfma_f32_16x16x32_bf16 v[2:5], v[176:179], v[216:219], v[2:5]
	v_mfma_f32_16x16x32_bf16 v[54:57], v[172:175], v[188:191], v[54:57]
	v_mfma_f32_16x16x32_bf16 v[50:53], v[180:183], v[188:191], v[50:53]
	v_mfma_f32_16x16x32_bf16 v[38:41], v[172:175], v[196:199], v[38:41]
	v_mfma_f32_16x16x32_bf16 v[34:37], v[180:183], v[196:199], v[34:37]
	v_mfma_f32_16x16x32_bf16 v[22:25], v[172:175], v[212:215], v[22:25]
	v_mfma_f32_16x16x32_bf16 v[18:21], v[180:183], v[212:215], v[18:21]
	v_mfma_f32_16x16x32_bf16 v[6:9], v[172:175], v[220:223], v[6:9]
	v_mfma_f32_16x16x32_bf16 v[2:5], v[180:183], v[220:223], v[2:5]
	s_setprio 0
	s_barrier
; #define PG8_STAGE(bufoff, gbase, voff) do { _Pragma("unroll") for (int _i = 0; _i < 2; ++_i) \
;         __builtin_amdgcn_global_load_lds((const unsigned*)((const char*)(gbase) + (voff)[_i]), (PG8_LAS unsigned*)(lds + (bufoff) + ldsw + _i * 8192), 16, 0, 0); } while (0)
; #define PG8_LDA(dst, b, h) do { _Pragma("unroll") for (int m = 0; m < 4; ++m) _Pragma("unroll") for (int k = 0; k < 2; ++k) dst[m][k] = *(const PG8_LAS bf16x8*)(lds + PG8_SA(b, h) + aoff + m * 2048 + k * 1024); } while (0)
; #define PG8_LDB(dst, b, h) do { _Pragma("unroll") for (int n = 0; n < 2; ++n) _Pragma("unroll") for (int k = 0; k < 2; ++k) dst[n][k] = *(const PG8_LAS bf16x8*)(lds + PG8_SB(b, h) + boff + n * 2048 + k * 1024); } while (0)
; #define PG8_MMA(ai, bj, At, Bt) do { __builtin_amdgcn_s_setprio(1); _Pragma("unroll") for (int m = 0; m < 4; ++m) _Pragma("unroll") for (int n = 0; n < 2; ++n) _Pragma("unroll") for (int k = 0; k < 2; ++k) \
;         acc[ai][bj][m][n] = __builtin_amdgcn_mfma_f32_16x16x32_bf16(Bt[n][k], At[m][k], acc[ai][bj][m][n], 0, 0, 0); __builtin_amdgcn_s_setprio(0); } while (0)
; #define PG8_WAIT_V(n) asm volatile("s_waitcnt vmcnt(" #n ")" ::: "memory")
; #define PG8_WAIT_L(n) asm volatile("s_waitcnt lgkmcnt(" #n ")" ::: "memory")
; #define PG8_BAR __builtin_amdgcn_s_barrier()
; #define PG8_SCHED __builtin_amdgcn_sched_barrier(0)
; template <class Epi, class Sched, bool ALIGN_EPI = false, bool SP2 = false>
; __device__ __forceinline__ void gemm_phase(PG8_LAS unsigned char* lds, const Gemm g, const Sched& S, const Epi& E) {
;     ...
;             PG8_LDB(B0, 1, 0); PG8_LDB(B1, 1, 1); PG8_SCHED; PG8_LDA(At, 1, 0); PG8_STAGE(PG8_SA(0, 1), a2 + hstepA, voffA);
;             PG8_WAIT_V(8); PG8_WAIT_L(0); PG8_BAR; PG8_MMA(0, 0, At, B0); PG8_MMA(0, 1, At, B1); PG8_BAR; PG8_SCHED;
	s_add_i32 s20, 0, 0x18000
	v_add_u32_e32 v0, s20, v161
	s_add_i32 s21, 0, 0x1c000
	ds_read_b128 v[146:149], v0
	ds_read_b128 v[150:153], v0 offset:1024
	ds_read_b128 v[154:157], v0 offset:2048
	ds_read_b128 v[164:167], v0 offset:3072
	v_add_u32_e32 v0, s21, v161
	ds_read_b128 v[168:171], v0
	ds_read_b128 v[172:175], v0 offset:1024
	ds_read_b128 v[176:179], v0 offset:2048
	ds_read_b128 v[180:183], v0 offset:3072
	s_add_u32 s36, s36, 0x40000
	s_addc_u32 s37, s37, 0
	s_mov_b32 m0, s56
	v_lshl_add_u64 v[228:229], s[36:37], 0, v[136:137]
	ds_read_b128 v[184:187], v163 offset:32768
	ds_read_b128 v[188:191], v163 offset:33792
	ds_read_b128 v[192:195], v163 offset:34816
	ds_read_b128 v[196:199], v163 offset:35840
	ds_read_b128 v[208:211], v163 offset:36864
	ds_read_b128 v[212:215], v163 offset:37888
	ds_read_b128 v[216:219], v163 offset:38912
	ds_read_b128 v[220:223], v163 offset:39936
	global_load_lds_dwordx4 v[228:229], off
	v_lshl_add_u64 v[228:229], s[36:37], 0, v[132:133]
	s_mov_b32 m0, s57
	s_nop 0
	global_load_lds_dwordx4 v[228:229], off
	s_waitcnt vmcnt(8)
	s_waitcnt lgkmcnt(0)
	s_barrier
	s_setprio 1
	s_waitcnt lgkmcnt(0)
	v_mfma_f32_16x16x32_bf16 v[126:129], v[146:149], v[184:187], v[126:129]
	v_mfma_f32_16x16x32_bf16 v[122:125], v[154:157], v[184:187], v[122:125]
	v_mfma_f32_16x16x32_bf16 v[110:113], v[146:149], v[192:195], v[110:113]
	v_mfma_f32_16x16x32_bf16 v[106:109], v[154:157], v[192:195], v[106:109]
	v_mfma_f32_16x16x32_bf16 v[94:97], v[146:149], v[208:211], v[94:97]
	v_mfma_f32_16x16x32_bf16 v[90:93], v[154:157], v[208:211], v[90:93]
	v_mfma_f32_16x16x32_bf16 v[78:81], v[146:149], v[216:219], v[78:81]
	v_mfma_f32_16x16x32_bf16 v[74:77], v[154:157], v[216:219], v[74:77]
	v_mfma_f32_16x16x32_bf16 v[126:129], v[150:153], v[188:191], v[126:129]
	v_mfma_f32_16x16x32_bf16 v[122:125], v[164:167], v[188:191], v[122:125]
	v_mfma_f32_16x16x32_bf16 v[110:113], v[150:153], v[196:199], v[110:113]
	v_mfma_f32_16x16x32_bf16 v[106:109], v[164:167], v[196:199], v[106:109]
	v_mfma_f32_16x16x32_bf16 v[94:97], v[150:153], v[212:215], v[94:97]
	v_mfma_f32_16x16x32_bf16 v[90:93], v[164:167], v[212:215], v[90:93]
	v_mfma_f32_16x16x32_bf16 v[78:81], v[150:153], v[220:223], v[78:81]
	v_mfma_f32_16x16x32_bf16 v[74:77], v[164:167], v[220:223], v[74:77]
	v_mfma_f32_16x16x32_bf16 v[118:121], v[168:171], v[184:187], v[118:121]
	v_mfma_f32_16x16x32_bf16 v[114:117], v[176:179], v[184:187], v[114:117]
	v_mfma_f32_16x16x32_bf16 v[102:105], v[168:171], v[192:195], v[102:105]
	v_mfma_f32_16x16x32_bf16 v[98:101], v[176:179], v[192:195], v[98:101]
	v_mfma_f32_16x16x32_bf16 v[86:89], v[168:171], v[208:211], v[86:89]
	v_mfma_f32_16x16x32_bf16 v[82:85], v[176:179], v[208:211], v[82:85]
	v_mfma_f32_16x16x32_bf16 v[70:73], v[168:171], v[216:219], v[70:73]
	v_mfma_f32_16x16x32_bf16 v[66:69], v[176:179], v[216:219], v[66:69]
	v_mfma_f32_16x16x32_bf16 v[118:121], v[172:175], v[188:191], v[118:121]
	v_mfma_f32_16x16x32_bf16 v[114:117], v[180:183], v[188:191], v[114:117]
	v_mfma_f32_16x16x32_bf16 v[102:105], v[172:175], v[196:199], v[102:105]
	v_mfma_f32_16x16x32_bf16 v[98:101], v[180:183], v[196:199], v[98:101]
	v_mfma_f32_16x16x32_bf16 v[86:89], v[172:175], v[212:215], v[86:89]
	v_mfma_f32_16x16x32_bf16 v[82:85], v[180:183], v[212:215], v[82:85]
	v_mfma_f32_16x16x32_bf16 v[70:73], v[172:175], v[220:223], v[70:73]
	v_mfma_f32_16x16x32_bf16 v[66:69], v[180:183], v[220:223], v[66:69]
	s_setprio 0
	s_barrier
; #define PG8_STAGE(bufoff, gbase, voff) do { _Pragma("unroll") for (int _i = 0; _i < 2; ++_i) \
;         __builtin_amdgcn_global_load_lds((const unsigned*)((const char*)(gbase) + (voff)[_i]), (PG8_LAS unsigned*)(lds + (bufoff) + ldsw + _i * 8192), 16, 0, 0); } while (0)
; #define PG8_LDA(dst, b, h) do { _Pragma("unroll") for (int m = 0; m < 4; ++m) _Pragma("unroll") for (int k = 0; k < 2; ++k) dst[m][k] = *(const PG8_LAS bf16x8*)(lds + PG8_SA(b, h) + aoff + m * 2048 + k * 1024); } while (0)
; #define PG8_MMA(ai, bj, At, Bt) do { __builtin_amdgcn_s_setprio(1); _Pragma("unroll") for (int m = 0; m < 4; ++m) _Pragma("unroll") for (int n = 0; n < 2; ++n) _Pragma("unroll") for (int k = 0; k < 2; ++k) \
;         acc[ai][bj][m][n] = __builtin_amdgcn_mfma_f32_16x16x32_bf16(Bt[n][k], At[m][k], acc[ai][bj][m][n], 0, 0, 0); __builtin_amdgcn_s_setprio(0); } while (0)
; #define PG8_WAIT_V(n) asm volatile("s_waitcnt vmcnt(" #n ")" ::: "memory")
; #define PG8_WAIT_L(n) asm volatile("s_waitcnt lgkmcnt(" #n ")" ::: "memory")
; #define PG8_BAR __builtin_amdgcn_s_barrier()
; #define PG8_SCHED __builtin_amdgcn_sched_barrier(0)
; template <class Epi, class Sched, bool ALIGN_EPI = false, bool SP2 = false>
; __device__ __forceinline__ void gemm_phase(PG8_LAS unsigned char* lds, const Gemm g, const Sched& S, const Epi& E) {
;     ...
;         for (int t = 0; t < nt; t += 2) {
;             const bool last = (t == nt - 2);
;             const char* a1 = cA + (size_t)(t + 1) * kstep;
;             const char* a2 = last ? nA : cA + (size_t)(t + 2) * kstep; const char* b2 = last ? nB : cB + (size_t)(t + 2) * kstep;
;             const char* a3 = a2 + kstep; const char* b3 = b2 + kstep;
;     ...
;             PG8_LDA(At, 1, 1); PG8_STAGE(PG8_SB(1, 0), b3, voffB); PG8_STAGE(PG8_SB(1, 1), b3 + hstepB, voffB); PG8_STAGE(PG8_SA(1, 0), a3, voffA);
;             PG8_WAIT_V(8); PG8_WAIT_L(0); PG8_BAR; PG8_MMA(1, 0, At, B0); PG8_MMA(1, 1, At, B1); PG8_BAR; PG8_SCHED;
	s_add_i32 s20, s20, s26
	v_lshl_add_u64 v[158:159], v[158:159], 0, s[22:23]
	s_mov_b32 m0, s20
	ds_read_b128 v[184:187], v163 offset:49152
	ds_read_b128 v[188:191], v163 offset:50176
	ds_read_b128 v[192:195], v163 offset:51200
	ds_read_b128 v[196:199], v163 offset:52224
	ds_read_b128 v[208:211], v163 offset:53248
	ds_read_b128 v[212:215], v163 offset:54272
	ds_read_b128 v[216:219], v163 offset:55296
	ds_read_b128 v[220:223], v163 offset:56320
	global_load_lds_dwordx4 v[158:159], off
	s_add_i32 m0, s20, 0x2000
	s_add_u32 s14, s14, 0x40080
	v_lshl_add_u64 v[158:159], v[200:201], 0, s[22:23]
	s_addc_u32 s15, s15, 0
	s_add_i32 s20, s21, s26
	global_load_lds_dwordx4 v[158:159], off
	v_lshl_add_u64 v[158:159], s[14:15], 0, v[134:135]
	s_mov_b32 m0, s20
	s_nop 0
	global_load_lds_dwordx4 v[158:159], off
	v_lshl_add_u64 v[158:159], s[14:15], 0, v[130:131]
	s_add_i32 m0, s20, 0x2000
	s_nop 0
	global_load_lds_dwordx4 v[158:159], off
	v_lshl_add_u64 v[158:159], v[224:225], 0, s[22:23]
	s_mov_b32 m0, s58
	s_nop 0
	global_load_lds_dwordx4 v[158:159], off
	v_lshl_add_u64 v[158:159], v[226:227], 0, s[22:23]
	s_mov_b32 m0, s59
	s_nop 0
	global_load_lds_dwordx4 v[158:159], off
	s_waitcnt vmcnt(8)
	s_waitcnt lgkmcnt(0)
	s_barrier
	s_setprio 1
	s_waitcnt lgkmcnt(0)
	v_mfma_f32_16x16x32_bf16 v[62:65], v[146:149], v[184:187], v[62:65]
	v_mfma_f32_16x16x32_bf16 v[58:61], v[154:157], v[184:187], v[58:61]
	v_mfma_f32_16x16x32_bf16 v[46:49], v[146:149], v[192:195], v[46:49]
	v_mfma_f32_16x16x32_bf16 v[42:45], v[154:157], v[192:195], v[42:45]
	v_mfma_f32_16x16x32_bf16 v[30:33], v[146:149], v[208:211], v[30:33]
	v_mfma_f32_16x16x32_bf16 v[26:29], v[154:157], v[208:211], v[26:29]
	v_mfma_f32_16x16x32_bf16 v[14:17], v[146:149], v[216:219], v[14:17]
	v_mfma_f32_16x16x32_bf16 v[10:13], v[154:157], v[216:219], v[10:13]
	v_mfma_f32_16x16x32_bf16 v[62:65], v[150:153], v[188:191], v[62:65]
	v_mfma_f32_16x16x32_bf16 v[58:61], v[164:167], v[188:191], v[58:61]
	v_mfma_f32_16x16x32_bf16 v[46:49], v[150:153], v[196:199], v[46:49]
	v_mfma_f32_16x16x32_bf16 v[42:45], v[164:167], v[196:199], v[42:45]
	v_mfma_f32_16x16x32_bf16 v[30:33], v[150:153], v[212:215], v[30:33]
	v_mfma_f32_16x16x32_bf16 v[26:29], v[164:167], v[212:215], v[26:29]
	v_mfma_f32_16x16x32_bf16 v[14:17], v[150:153], v[220:223], v[14:17]
	v_mfma_f32_16x16x32_bf16 v[10:13], v[164:167], v[220:223], v[10:13]
	v_mfma_f32_16x16x32_bf16 v[54:57], v[168:171], v[184:187], v[54:57]
	v_mfma_f32_16x16x32_bf16 v[50:53], v[176:179], v[184:187], v[50:53]
	v_mfma_f32_16x16x32_bf16 v[38:41], v[168:171], v[192:195], v[38:41]
	v_mfma_f32_16x16x32_bf16 v[34:37], v[176:179], v[192:195], v[34:37]
	v_mfma_f32_16x16x32_bf16 v[22:25], v[168:171], v[208:211], v[22:25]
	v_mfma_f32_16x16x32_bf16 v[18:21], v[176:179], v[208:211], v[18:21]
	v_mfma_f32_16x16x32_bf16 v[6:9], v[168:171], v[216:219], v[6:9]
	v_mfma_f32_16x16x32_bf16 v[2:5], v[176:179], v[216:219], v[2:5]
	v_mfma_f32_16x16x32_bf16 v[54:57], v[172:175], v[188:191], v[54:57]
	v_mfma_f32_16x16x32_bf16 v[50:53], v[180:183], v[188:191], v[50:53]
	v_mfma_f32_16x16x32_bf16 v[38:41], v[172:175], v[196:199], v[38:41]
	v_mfma_f32_16x16x32_bf16 v[34:37], v[180:183], v[196:199], v[34:37]
	v_mfma_f32_16x16x32_bf16 v[22:25], v[172:175], v[212:215], v[22:25]
	v_mfma_f32_16x16x32_bf16 v[18:21], v[180:183], v[212:215], v[18:21]
	v_mfma_f32_16x16x32_bf16 v[6:9], v[172:175], v[220:223], v[6:9]
	v_mfma_f32_16x16x32_bf16 v[2:5], v[180:183], v[220:223], v[2:5]
	s_setprio 0
	s_barrier
	s_add_i32 s78, s78, 2
	s_add_u32 s8, s8, 0x100
	s_addc_u32 s9, s9, 0
	s_add_u32 s70, s70, 0x100
	s_addc_u32 s71, s71, 0
	s_cmp_gt_u32 s78, 13
	s_cbranch_scc0 .LBB0_597

; #define PG8_STAGE(bufoff, gbase, voff) do { _Pragma("unroll") for (int _i = 0; _i < 2; ++_i) \
;         __builtin_amdgcn_global_load_lds((const unsigned*)((const char*)(gbase) + (voff)[_i]), (PG8_LAS unsigned*)(lds + (bufoff) + ldsw + _i * 8192), 16, 0, 0); } while (0)
; #define PG8_LDA(dst, b, h) do { _Pragma("unroll") for (int m = 0; m < 4; ++m) _Pragma("unroll") for (int k = 0; k < 2; ++k) dst[m][k] = *(const PG8_LAS bf16x8*)(lds + PG8_SA(b, h) + aoff + m * 2048 + k * 1024); } while (0)
; #define PG8_LDB(dst, b, h) do { _Pragma("unroll") for (int n = 0; n < 2; ++n) _Pragma("unroll") for (int k = 0; k < 2; ++k) dst[n][k] = *(const PG8_LAS bf16x8*)(lds + PG8_SB(b, h) + boff + n * 2048 + k * 1024); } while (0)
; #define PG8_WAIT_V(n) asm volatile("s_waitcnt vmcnt(" #n ")" ::: "memory")
; #define PG8_WAIT_L(n) asm volatile("s_waitcnt lgkmcnt(" #n ")" ::: "memory")
; #define PG8_BAR __builtin_amdgcn_s_barrier()
; template <class Epi, class Sched, bool ALIGN_EPI = false, bool SP2 = false>
; __device__ __forceinline__ void gemm_phase(PG8_LAS unsigned char* lds, const Gemm g, const Sched& S, const Epi& E) {
;     ...
;         const bool has_next = S.next(ui + 1, nxt);
;         const char* nA = has_next ? (const char*)g.A + (size_t)nxt.pm * tstepA + (size_t)nxt.pb * g.sA : cA; const char* nB = has_next ? (const char*)g.Bt + (size_t)nxt.pn * tstepB + (size_t)nxt.pb * g.sB : cB;
;         for (int t = 0; t < nt; t += 2) {
;             const bool last = (t == nt - 2);
;             const char* a1 = cA + (size_t)(t + 1) * kstep;
;             const char* a2 = last ? nA : cA + (size_t)(t + 2) * kstep; const char* b2 = last ? nB : cB + (size_t)(t + 2) * kstep;
;             const char* a3 = a2 + kstep; const char* b3 = b2 + kstep;
;             if (last && has_next) S.a_ready(nxt);
;             if constexpr (SP2) {
;             PG8_LDB(B0, 0, 0); PG8_LDB(B1, 0, 1); PG8_SCHED; PG8_LDA(At, 0, 0); PG8_STAGE(PG8_SA(1, 1), a1 + hstepA, voffA);
;             PG8_WAIT_V(8); PG8_WAIT_L(0); PG8_BAR; PG8_MMA(0, 0, At, B0); PG8_MMA(0, 1, At, B1); PG8_BAR; PG8_SCHED;
;             PG8_LDA(At, 0, 1); PG8_STAGE(PG8_SB(0, 0), b2, voffB); PG8_STAGE(PG8_SB(0, 1), b2 + hstepB, voffB); PG8_STAGE(PG8_SA(0, 0), a2, voffA);
;             PG8_WAIT_V(8); PG8_WAIT_L(0); PG8_BAR; PG8_MMA(1, 0, At, B0); PG8_MMA(1, 1, At, B1); PG8_BAR; PG8_SCHED;
.LBB0_782:
	s_lshl_b64 s[28:29], s[12:13], 18
	s_add_u32 s28, s43, s28
	s_addc_u32 s29, s44, s29
	s_and_b64 s[36:37], s[16:17], exec
	s_cselect_b32 s13, s29, s35
	s_cselect_b32 s60, s28, s34
	s_add_u32 s61, s34, 0x100
	s_addc_u32 s62, s35, 0
	s_mov_b32 s63, -2
	s_add_u32 s34, s30, 0x100
	s_addc_u32 s35, s31, 0
	s_add_i32 s20, 0, 0x10000
	s_cmp_eq_u32 s63, 4
	s_cselect_b32 s39, s19, s35
	s_cselect_b32 s38, s18, s34
	v_add_u32_e32 v145, s20, v143
	s_cselect_b32 s37, s13, s62
	s_cselect_b32 s36, s60, s61
	s_add_i32 s21, 0, 0x14000
	ds_read_b128 v[146:149], v145
	ds_read_b128 v[150:153], v145 offset:1024
	ds_read_b128 v[154:157], v145 offset:2048
	ds_read_b128 v[158:161], v145 offset:3072
	v_add_u32_e32 v145, s21, v143
	ds_read_b128 v[162:165], v145
	ds_read_b128 v[166:169], v145 offset:1024
	ds_read_b128 v[170:173], v145 offset:2048
	ds_read_b128 v[174:177], v145 offset:3072
	v_lshl_add_u64 v[216:217], s[30:31], 0, v[138:139]
	s_add_i32 m0, s52, 0xc000
	ds_read_b128 v[178:181], v144
	ds_read_b128 v[182:185], v144 offset:1024
	ds_read_b128 v[186:189], v144 offset:2048
	ds_read_b128 v[190:193], v144 offset:3072
	ds_read_b128 v[194:197], v144 offset:4096
	ds_read_b128 v[198:201], v144 offset:5120
	ds_read_b128 v[208:211], v144 offset:6144
	ds_read_b128 v[212:215], v144 offset:7168
	global_load_lds_dwordx4 v[216:217], off
	v_lshl_add_u64 v[216:217], s[30:31], 0, v[140:141]
	s_add_i32 m0, s52, 0xe000
	s_nop 0
	global_load_lds_dwordx4 v[216:217], off
	s_waitcnt vmcnt(8)
	s_waitcnt lgkmcnt(0)
	s_barrier
	s_setprio 1
	s_waitcnt lgkmcnt(0)
	v_mfma_f32_16x16x32_bf16 v[126:129], v[146:149], v[178:181], 0
	v_mfma_f32_16x16x32_bf16 v[122:125], v[154:157], v[178:181], 0
	v_mfma_f32_16x16x32_bf16 v[118:121], v[146:149], v[186:189], 0
	v_mfma_f32_16x16x32_bf16 v[114:117], v[154:157], v[186:189], 0
	v_mfma_f32_16x16x32_bf16 v[106:109], v[146:149], v[194:197], 0
	v_mfma_f32_16x16x32_bf16 v[98:101], v[154:157], v[194:197], 0
	v_mfma_f32_16x16x32_bf16 v[90:93], v[146:149], v[208:211], 0
	v_mfma_f32_16x16x32_bf16 v[82:85], v[154:157], v[208:211], 0
	v_mfma_f32_16x16x32_bf16 v[126:129], v[150:153], v[182:185], v[126:129]
	v_mfma_f32_16x16x32_bf16 v[122:125], v[158:161], v[182:185], v[122:125]
	v_mfma_f32_16x16x32_bf16 v[118:121], v[150:153], v[190:193], v[118:121]
	v_mfma_f32_16x16x32_bf16 v[114:117], v[158:161], v[190:193], v[114:117]
	v_mfma_f32_16x16x32_bf16 v[106:109], v[150:153], v[198:201], v[106:109]
	v_mfma_f32_16x16x32_bf16 v[98:101], v[158:161], v[198:201], v[98:101]
	v_mfma_f32_16x16x32_bf16 v[90:93], v[150:153], v[212:215], v[90:93]
	v_mfma_f32_16x16x32_bf16 v[82:85], v[158:161], v[212:215], v[82:85]
	v_mfma_f32_16x16x32_bf16 v[110:113], v[162:165], v[178:181], 0
	v_mfma_f32_16x16x32_bf16 v[102:105], v[170:173], v[178:181], 0
	v_mfma_f32_16x16x32_bf16 v[94:97], v[162:165], v[186:189], 0
	v_mfma_f32_16x16x32_bf16 v[86:89], v[170:173], v[186:189], 0
	v_mfma_f32_16x16x32_bf16 v[78:81], v[162:165], v[194:197], 0
	v_mfma_f32_16x16x32_bf16 v[74:77], v[170:173], v[194:197], 0
	v_mfma_f32_16x16x32_bf16 v[70:73], v[162:165], v[208:211], 0
	v_mfma_f32_16x16x32_bf16 v[66:69], v[170:173], v[208:211], 0
	v_mfma_f32_16x16x32_bf16 v[110:113], v[166:169], v[182:185], v[110:113]
	v_mfma_f32_16x16x32_bf16 v[102:105], v[174:177], v[182:185], v[102:105]
	v_mfma_f32_16x16x32_bf16 v[94:97], v[166:169], v[190:193], v[94:97]
	v_mfma_f32_16x16x32_bf16 v[86:89], v[174:177], v[190:193], v[86:89]
	v_mfma_f32_16x16x32_bf16 v[78:81], v[166:169], v[198:201], v[78:81]
	v_mfma_f32_16x16x32_bf16 v[74:77], v[174:177], v[198:201], v[74:77]
	v_mfma_f32_16x16x32_bf16 v[70:73], v[166:169], v[212:215], v[70:73]
	v_mfma_f32_16x16x32_bf16 v[66:69], v[174:177], v[212:215], v[66:69]
	s_setprio 0
	s_barrier
	s_add_i32 s20, s20, s45
	v_lshl_add_u64 v[216:217], s[36:37], 0, v[134:135]
	s_mov_b32 m0, s20
	ds_read_b128 v[178:181], v144 offset:16384
	ds_read_b128 v[182:185], v144 offset:17408
	ds_read_b128 v[186:189], v144 offset:18432
	ds_read_b128 v[190:193], v144 offset:19456
	ds_read_b128 v[194:197], v144 offset:20480
	ds_read_b128 v[198:201], v144 offset:21504
	ds_read_b128 v[208:211], v144 offset:22528
	ds_read_b128 v[212:215], v144 offset:23552
	global_load_lds_dwordx4 v[216:217], off
	s_add_i32 m0, s20, 0x2000
	s_add_u32 s30, s36, 0x20000
	v_lshl_add_u64 v[218:219], s[36:37], 0, v[130:131]
	s_addc_u32 s31, s37, 0
	s_add_i32 s20, s21, s45
	global_load_lds_dwordx4 v[218:219], off
	v_lshl_add_u64 v[220:221], s[30:31], 0, v[134:135]
	s_mov_b32 m0, s20
	v_lshl_add_u64 v[222:223], s[38:39], 0, v[132:133]
	global_load_lds_dwordx4 v[220:221], off
	v_lshl_add_u64 v[220:221], s[30:31], 0, v[130:131]
	s_add_i32 m0, s20, 0x2000
	s_nop 0
	global_load_lds_dwordx4 v[220:221], off
	v_lshl_add_u64 v[220:221], s[38:39], 0, v[136:137]
	s_mov_b32 m0, s52
	s_nop 0
	global_load_lds_dwordx4 v[220:221], off
	s_mov_b32 m0, s53
	s_nop 0
	global_load_lds_dwordx4 v[222:223], off
	s_waitcnt vmcnt(8)
	s_waitcnt lgkmcnt(0)
	s_barrier
; #define PG8_STAGE(bufoff, gbase, voff) do { _Pragma("unroll") for (int _i = 0; _i < 2; ++_i) \
;         __builtin_amdgcn_global_load_lds((const unsigned*)((const char*)(gbase) + (voff)[_i]), (PG8_LAS unsigned*)(lds + (bufoff) + ldsw + _i * 8192), 16, 0, 0); } while (0)
; #define PG8_LDA(dst, b, h) do { _Pragma("unroll") for (int m = 0; m < 4; ++m) _Pragma("unroll") for (int k = 0; k < 2; ++k) dst[m][k] = *(const PG8_LAS bf16x8*)(lds + PG8_SA(b, h) + aoff + m * 2048 + k * 1024); } while (0)
; #define PG8_LDB(dst, b, h) do { _Pragma("unroll") for (int n = 0; n < 2; ++n) _Pragma("unroll") for (int k = 0; k < 2; ++k) dst[n][k] = *(const PG8_LAS bf16x8*)(lds + PG8_SB(b, h) + boff + n * 2048 + k * 1024); } while (0)
; #define PG8_MMA(ai, bj, At, Bt) do { __builtin_amdgcn_s_setprio(1); _Pragma("unroll") for (int m = 0; m < 4; ++m) _Pragma("unroll") for (int n = 0; n < 2; ++n) _Pragma("unroll") for (int k = 0; k < 2; ++k) \
;         acc[ai][bj][m][n] = __builtin_amdgcn_mfma_f32_16x16x32_bf16(Bt[n][k], At[m][k], acc[ai][bj][m][n], 0, 0, 0); __builtin_amdgcn_s_setprio(0); } while (0)
; #define PG8_WAIT_V(n) asm volatile("s_waitcnt vmcnt(" #n ")" ::: "memory")
; #define PG8_WAIT_L(n) asm volatile("s_waitcnt lgkmcnt(" #n ")" ::: "memory")
; #define PG8_BAR __builtin_amdgcn_s_barrier()
; #define PG8_SCHED __builtin_amdgcn_sched_barrier(0)
; template <class Epi, class Sched, bool ALIGN_EPI = false, bool SP2 = false>
; __device__ __forceinline__ void gemm_phase(PG8_LAS unsigned char* lds, const Gemm g, const Sched& S, const Epi& E) {
;     ...
;             PG8_WAIT_V(8); PG8_WAIT_L(0); PG8_BAR; PG8_MMA(1, 0, At, B0); PG8_MMA(1, 1, At, B1); PG8_BAR; PG8_SCHED;
;             PG8_LDB(B0, 1, 0); PG8_LDB(B1, 1, 1); PG8_SCHED; PG8_LDA(At, 1, 0); PG8_STAGE(PG8_SA(0, 1), a2 + hstepA, voffA);
;             PG8_WAIT_V(8); PG8_WAIT_L(0); PG8_BAR; PG8_MMA(0, 0, At, B0); PG8_MMA(0, 1, At, B1); PG8_BAR; PG8_SCHED;
	s_setprio 1
	s_waitcnt lgkmcnt(0)
	v_mfma_f32_16x16x32_bf16 v[62:65], v[146:149], v[178:181], 0
	v_mfma_f32_16x16x32_bf16 v[58:61], v[154:157], v[178:181], 0
	v_mfma_f32_16x16x32_bf16 v[54:57], v[146:149], v[186:189], 0
	v_mfma_f32_16x16x32_bf16 v[50:53], v[154:157], v[186:189], 0
	v_mfma_f32_16x16x32_bf16 v[38:41], v[146:149], v[194:197], 0
	v_mfma_f32_16x16x32_bf16 v[34:37], v[154:157], v[194:197], 0
	v_mfma_f32_16x16x32_bf16 v[22:25], v[146:149], v[208:211], 0
	v_mfma_f32_16x16x32_bf16 v[18:21], v[154:157], v[208:211], 0
	v_mfma_f32_16x16x32_bf16 v[62:65], v[150:153], v[182:185], v[62:65]
	v_mfma_f32_16x16x32_bf16 v[58:61], v[158:161], v[182:185], v[58:61]
	v_mfma_f32_16x16x32_bf16 v[54:57], v[150:153], v[190:193], v[54:57]
	v_mfma_f32_16x16x32_bf16 v[50:53], v[158:161], v[190:193], v[50:53]
	v_mfma_f32_16x16x32_bf16 v[38:41], v[150:153], v[198:201], v[38:41]
	v_mfma_f32_16x16x32_bf16 v[34:37], v[158:161], v[198:201], v[34:37]
	v_mfma_f32_16x16x32_bf16 v[22:25], v[150:153], v[212:215], v[22:25]
	v_mfma_f32_16x16x32_bf16 v[18:21], v[158:161], v[212:215], v[18:21]
	v_mfma_f32_16x16x32_bf16 v[46:49], v[162:165], v[178:181], 0
	v_mfma_f32_16x16x32_bf16 v[42:45], v[170:173], v[178:181], 0
	v_mfma_f32_16x16x32_bf16 v[30:33], v[162:165], v[186:189], 0
	v_mfma_f32_16x16x32_bf16 v[26:29], v[170:173], v[186:189], 0
	v_mfma_f32_16x16x32_bf16 v[14:17], v[162:165], v[194:197], 0
	v_mfma_f32_16x16x32_bf16 v[10:13], v[170:173], v[194:197], 0
	v_mfma_f32_16x16x32_bf16 v[6:9], v[162:165], v[208:211], 0
	v_mfma_f32_16x16x32_bf16 v[2:5], v[170:173], v[208:211], 0
	v_mfma_f32_16x16x32_bf16 v[46:49], v[166:169], v[182:185], v[46:49]
	v_mfma_f32_16x16x32_bf16 v[42:45], v[174:177], v[182:185], v[42:45]
	v_mfma_f32_16x16x32_bf16 v[30:33], v[166:169], v[190:193], v[30:33]
	v_mfma_f32_16x16x32_bf16 v[26:29], v[174:177], v[190:193], v[26:29]
	v_mfma_f32_16x16x32_bf16 v[14:17], v[166:169], v[198:201], v[14:17]
	v_mfma_f32_16x16x32_bf16 v[10:13], v[174:177], v[198:201], v[10:13]
	v_mfma_f32_16x16x32_bf16 v[6:9], v[166:169], v[212:215], v[6:9]
	v_mfma_f32_16x16x32_bf16 v[2:5], v[174:177], v[212:215], v[2:5]
	s_setprio 0
	s_barrier
	s_add_i32 s20, 0, 0x18000
	v_add_u32_e32 v145, s20, v143
	s_add_i32 s21, 0, 0x1c000
	ds_read_b128 v[146:149], v145
	ds_read_b128 v[150:153], v145 offset:1024
	ds_read_b128 v[154:157], v145 offset:2048
	ds_read_b128 v[158:161], v145 offset:3072
	v_add_u32_e32 v145, s21, v143
	ds_read_b128 v[162:165], v145
	ds_read_b128 v[166:169], v145 offset:1024
	ds_read_b128 v[170:173], v145 offset:2048
	ds_read_b128 v[174:177], v145 offset:3072
	s_add_u32 s30, s38, 0x30000
	s_addc_u32 s31, s39, 0
	s_mov_b32 m0, s54
	v_lshl_add_u64 v[224:225], s[30:31], 0, v[136:137]
	ds_read_b128 v[178:181], v144 offset:32768
	ds_read_b128 v[182:185], v144 offset:33792
	ds_read_b128 v[186:189], v144 offset:34816
	ds_read_b128 v[190:193], v144 offset:35840
	ds_read_b128 v[194:197], v144 offset:36864
	ds_read_b128 v[198:201], v144 offset:37888
	ds_read_b128 v[208:211], v144 offset:38912
	ds_read_b128 v[212:215], v144 offset:39936
	global_load_lds_dwordx4 v[224:225], off
	v_lshl_add_u64 v[224:225], s[30:31], 0, v[132:133]
	s_mov_b32 m0, s55
	s_nop 0
	global_load_lds_dwordx4 v[224:225], off
	s_waitcnt vmcnt(8)
	s_waitcnt lgkmcnt(0)
	s_barrier
	s_setprio 1
	s_waitcnt lgkmcnt(0)
	v_mfma_f32_16x16x32_bf16 v[126:129], v[146:149], v[178:181], v[126:129]
	v_mfma_f32_16x16x32_bf16 v[122:125], v[154:157], v[178:181], v[122:125]
	v_mfma_f32_16x16x32_bf16 v[118:121], v[146:149], v[186:189], v[118:121]
	v_mfma_f32_16x16x32_bf16 v[114:117], v[154:157], v[186:189], v[114:117]
	v_mfma_f32_16x16x32_bf16 v[106:109], v[146:149], v[194:197], v[106:109]
	v_mfma_f32_16x16x32_bf16 v[98:101], v[154:157], v[194:197], v[98:101]
	v_mfma_f32_16x16x32_bf16 v[90:93], v[146:149], v[208:211], v[90:93]
	v_mfma_f32_16x16x32_bf16 v[82:85], v[154:157], v[208:211], v[82:85]
	v_mfma_f32_16x16x32_bf16 v[126:129], v[150:153], v[182:185], v[126:129]
	v_mfma_f32_16x16x32_bf16 v[122:125], v[158:161], v[182:185], v[122:125]
	v_mfma_f32_16x16x32_bf16 v[118:121], v[150:153], v[190:193], v[118:121]
	v_mfma_f32_16x16x32_bf16 v[114:117], v[158:161], v[190:193], v[114:117]
	v_mfma_f32_16x16x32_bf16 v[106:109], v[150:153], v[198:201], v[106:109]
	v_mfma_f32_16x16x32_bf16 v[98:101], v[158:161], v[198:201], v[98:101]
	v_mfma_f32_16x16x32_bf16 v[90:93], v[150:153], v[212:215], v[90:93]
	v_mfma_f32_16x16x32_bf16 v[82:85], v[158:161], v[212:215], v[82:85]
	v_mfma_f32_16x16x32_bf16 v[110:113], v[162:165], v[178:181], v[110:113]
	v_mfma_f32_16x16x32_bf16 v[102:105], v[170:173], v[178:181], v[102:105]
	v_mfma_f32_16x16x32_bf16 v[94:97], v[162:165], v[186:189], v[94:97]
	v_mfma_f32_16x16x32_bf16 v[86:89], v[170:173], v[186:189], v[86:89]
	v_mfma_f32_16x16x32_bf16 v[78:81], v[162:165], v[194:197], v[78:81]
	v_mfma_f32_16x16x32_bf16 v[74:77], v[170:173], v[194:197], v[74:77]
	v_mfma_f32_16x16x32_bf16 v[70:73], v[162:165], v[208:211], v[70:73]
	v_mfma_f32_16x16x32_bf16 v[66:69], v[170:173], v[208:211], v[66:69]
	v_mfma_f32_16x16x32_bf16 v[110:113], v[166:169], v[182:185], v[110:113]
	v_mfma_f32_16x16x32_bf16 v[102:105], v[174:177], v[182:185], v[102:105]
	v_mfma_f32_16x16x32_bf16 v[94:97], v[166:169], v[190:193], v[94:97]
	v_mfma_f32_16x16x32_bf16 v[86:89], v[174:177], v[190:193], v[86:89]
	v_mfma_f32_16x16x32_bf16 v[78:81], v[166:169], v[198:201], v[78:81]
	v_mfma_f32_16x16x32_bf16 v[74:77], v[174:177], v[198:201], v[74:77]
	v_mfma_f32_16x16x32_bf16 v[70:73], v[166:169], v[212:215], v[70:73]
	v_mfma_f32_16x16x32_bf16 v[66:69], v[174:177], v[212:215], v[66:69]
	s_setprio 0
	s_barrier
; #define PG8_STAGE(bufoff, gbase, voff) do { _Pragma("unroll") for (int _i = 0; _i < 2; ++_i) \
;         __builtin_amdgcn_global_load_lds((const unsigned*)((const char*)(gbase) + (voff)[_i]), (PG8_LAS unsigned*)(lds + (bufoff) + ldsw + _i * 8192), 16, 0, 0); } while (0)
; #define PG8_LDA(dst, b, h) do { _Pragma("unroll") for (int m = 0; m < 4; ++m) _Pragma("unroll") for (int k = 0; k < 2; ++k) dst[m][k] = *(const PG8_LAS bf16x8*)(lds + PG8_SA(b, h) + aoff + m * 2048 + k * 1024); } while (0)
; #define PG8_LDB(dst, b, h) do { _Pragma("unroll") for (int n = 0; n < 2; ++n) _Pragma("unroll") for (int k = 0; k < 2; ++k) dst[n][k] = *(const PG8_LAS bf16x8*)(lds + PG8_SB(b, h) + boff + n * 2048 + k * 1024); } while (0)
; #define PG8_MMA(ai, bj, At, Bt) do { __builtin_amdgcn_s_setprio(1); _Pragma("unroll") for (int m = 0; m < 4; ++m) _Pragma("unroll") for (int n = 0; n < 2; ++n) _Pragma("unroll") for (int k = 0; k < 2; ++k) \
;         acc[ai][bj][m][n] = __builtin_amdgcn_mfma_f32_16x16x32_bf16(Bt[n][k], At[m][k], acc[ai][bj][m][n], 0, 0, 0); __builtin_amdgcn_s_setprio(0); } while (0)
; #define PG8_WAIT_V(n) asm volatile("s_waitcnt vmcnt(" #n ")" ::: "memory")
; template <class Epi, class Sched, bool ALIGN_EPI = false, bool SP2 = false>
; __device__ __forceinline__ void gemm_phase(PG8_LAS unsigned char* lds, const Gemm g, const Sched& S, const Epi& E) {
;     ...
;             PG8_LDB(B0, 0, 0); PG8_LDB(B1, 0, 1); PG8_SCHED; PG8_LDA(At, 0, 0); PG8_STAGE(PG8_SA(1, 1), a1 + hstepA, voffA);
;             PG8_WAIT_V(8); PG8_WAIT_L(0); PG8_BAR; PG8_MMA(0, 0, At, B0); PG8_MMA(0, 1, At, B1); PG8_BAR; PG8_SCHED;
;             PG8_LDA(At, 0, 1); PG8_STAGE(PG8_SB(0, 0), b2, voffB); PG8_STAGE(PG8_SB(0, 1), b2 + hstepB, voffB); PG8_STAGE(PG8_SA(0, 0), a2, voffA);
;             PG8_WAIT_V(8); PG8_WAIT_L(0); PG8_BAR; PG8_MMA(1, 0, At, B0); PG8_MMA(1, 1, At, B1); PG8_BAR; PG8_SCHED;
;             PG8_LDB(B0, 1, 0); PG8_LDB(B1, 1, 1); PG8_SCHED; PG8_LDA(At, 1, 0); PG8_STAGE(PG8_SA(0, 1), a2 + hstepA, voffA);
;             PG8_WAIT_V(8); PG8_WAIT_L(0); PG8_BAR; PG8_MMA(0, 0, At, B0); PG8_MMA(0, 1, At, B1); PG8_BAR; PG8_SCHED;
;             PG8_LDA(At, 1, 1); PG8_STAGE(PG8_SB(1, 0), b3, voffB); PG8_STAGE(PG8_SB(1, 1), b3 + hstepB, voffB); PG8_STAGE(PG8_SA(1, 0), a3, voffA);
;             PG8_WAIT_V(8); PG8_WAIT_L(0); PG8_BAR; PG8_MMA(1, 0, At, B0); PG8_MMA(1, 1, At, B1); PG8_BAR; PG8_SCHED;
	s_add_i32 s20, s20, s45
	v_lshl_add_u64 v[216:217], v[216:217], 0, s[22:23]
	s_mov_b32 m0, s20
	ds_read_b128 v[178:181], v144 offset:49152
	ds_read_b128 v[182:185], v144 offset:50176
	ds_read_b128 v[186:189], v144 offset:51200
	ds_read_b128 v[190:193], v144 offset:52224
	ds_read_b128 v[194:197], v144 offset:53248
	ds_read_b128 v[198:201], v144 offset:54272
	ds_read_b128 v[208:211], v144 offset:55296
	ds_read_b128 v[212:215], v144 offset:56320
	global_load_lds_dwordx4 v[216:217], off
	s_add_i32 m0, s20, 0x2000
	s_add_u32 s30, s36, 0x20080
	v_lshl_add_u64 v[216:217], v[218:219], 0, s[22:23]
	s_addc_u32 s31, s37, 0
	s_add_i32 s20, s21, s45
	global_load_lds_dwordx4 v[216:217], off
	v_lshl_add_u64 v[216:217], s[30:31], 0, v[134:135]
	s_mov_b32 m0, s20
	s_nop 0
	global_load_lds_dwordx4 v[216:217], off
	v_lshl_add_u64 v[216:217], s[30:31], 0, v[130:131]
	s_add_i32 m0, s20, 0x2000
	s_nop 0
	global_load_lds_dwordx4 v[216:217], off
	v_lshl_add_u64 v[216:217], v[220:221], 0, s[22:23]
	s_mov_b32 m0, s56
	s_nop 0
	global_load_lds_dwordx4 v[216:217], off
	v_lshl_add_u64 v[216:217], v[222:223], 0, s[22:23]
	s_mov_b32 m0, s57
	s_nop 0
	global_load_lds_dwordx4 v[216:217], off
	s_waitcnt vmcnt(8)
	s_waitcnt lgkmcnt(0)
	s_barrier
	s_setprio 1
	s_waitcnt lgkmcnt(0)
	v_mfma_f32_16x16x32_bf16 v[62:65], v[146:149], v[178:181], v[62:65]
	v_mfma_f32_16x16x32_bf16 v[58:61], v[154:157], v[178:181], v[58:61]
	v_mfma_f32_16x16x32_bf16 v[54:57], v[146:149], v[186:189], v[54:57]
	v_mfma_f32_16x16x32_bf16 v[50:53], v[154:157], v[186:189], v[50:53]
	v_mfma_f32_16x16x32_bf16 v[38:41], v[146:149], v[194:197], v[38:41]
	v_mfma_f32_16x16x32_bf16 v[34:37], v[154:157], v[194:197], v[34:37]
	v_mfma_f32_16x16x32_bf16 v[22:25], v[146:149], v[208:211], v[22:25]
	v_mfma_f32_16x16x32_bf16 v[18:21], v[154:157], v[208:211], v[18:21]
	v_mfma_f32_16x16x32_bf16 v[62:65], v[150:153], v[182:185], v[62:65]
	v_mfma_f32_16x16x32_bf16 v[58:61], v[158:161], v[182:185], v[58:61]
	v_mfma_f32_16x16x32_bf16 v[54:57], v[150:153], v[190:193], v[54:57]
	v_mfma_f32_16x16x32_bf16 v[50:53], v[158:161], v[190:193], v[50:53]
	v_mfma_f32_16x16x32_bf16 v[38:41], v[150:153], v[198:201], v[38:41]
	v_mfma_f32_16x16x32_bf16 v[34:37], v[158:161], v[198:201], v[34:37]
	v_mfma_f32_16x16x32_bf16 v[22:25], v[150:153], v[212:215], v[22:25]
	v_mfma_f32_16x16x32_bf16 v[18:21], v[158:161], v[212:215], v[18:21]
	v_mfma_f32_16x16x32_bf16 v[46:49], v[162:165], v[178:181], v[46:49]
	v_mfma_f32_16x16x32_bf16 v[42:45], v[170:173], v[178:181], v[42:45]
	v_mfma_f32_16x16x32_bf16 v[30:33], v[162:165], v[186:189], v[30:33]
	v_mfma_f32_16x16x32_bf16 v[26:29], v[170:173], v[186:189], v[26:29]
	v_mfma_f32_16x16x32_bf16 v[14:17], v[162:165], v[194:197], v[14:17]
	v_mfma_f32_16x16x32_bf16 v[10:13], v[170:173], v[194:197], v[10:13]
	v_mfma_f32_16x16x32_bf16 v[6:9], v[162:165], v[208:211], v[6:9]
	v_mfma_f32_16x16x32_bf16 v[2:5], v[170:173], v[208:211], v[2:5]
	v_mfma_f32_16x16x32_bf16 v[46:49], v[166:169], v[182:185], v[46:49]
	v_mfma_f32_16x16x32_bf16 v[42:45], v[174:177], v[182:185], v[42:45]
	v_mfma_f32_16x16x32_bf16 v[30:33], v[166:169], v[190:193], v[30:33]
	v_mfma_f32_16x16x32_bf16 v[26:29], v[174:177], v[190:193], v[26:29]
	v_mfma_f32_16x16x32_bf16 v[14:17], v[166:169], v[198:201], v[14:17]
	v_mfma_f32_16x16x32_bf16 v[10:13], v[174:177], v[198:201], v[10:13]
	v_mfma_f32_16x16x32_bf16 v[6:9], v[166:169], v[212:215], v[6:9]
	v_mfma_f32_16x16x32_bf16 v[2:5], v[174:177], v[212:215], v[2:5]
	s_setprio 0
	s_barrier
	s_add_i32 s63, s63, 2
	s_add_u32 s61, s61, 0x100
	s_addc_u32 s62, s62, 0
	s_cmp_gt_u32 s63, 5
	s_mov_b64 s[30:31], s[34:35]
	s_cbranch_scc1 .Lpk_done_g783
.LBB0_783:
	s_add_u32 s34, s30, 0x100
	s_addc_u32 s35, s31, 0
	s_add_i32 s20, 0, 0x10000
	s_cmp_eq_u32 s63, 4
	s_cselect_b32 s39, s19, s35
	s_cselect_b32 s38, s18, s34
	v_add_u32_e32 v145, s20, v143
	s_cselect_b32 s37, s13, s62
	s_cselect_b32 s36, s60, s61
	s_add_i32 s21, 0, 0x14000
	ds_read_b128 v[146:149], v145
	ds_read_b128 v[150:153], v145 offset:1024
	ds_read_b128 v[154:157], v145 offset:2048
	ds_read_b128 v[158:161], v145 offset:3072
	v_add_u32_e32 v145, s21, v143
	ds_read_b128 v[162:165], v145
	ds_read_b128 v[166:169], v145 offset:1024
	ds_read_b128 v[170:173], v145 offset:2048
	ds_read_b128 v[174:177], v145 offset:3072
	v_lshl_add_u64 v[216:217], s[30:31], 0, v[138:139]
	s_add_i32 m0, s52, 0xc000
	ds_read_b128 v[178:181], v144
	ds_read_b128 v[182:185], v144 offset:1024
	ds_read_b128 v[186:189], v144 offset:2048
	ds_read_b128 v[190:193], v144 offset:3072
	ds_read_b128 v[194:197], v144 offset:4096
	ds_read_b128 v[198:201], v144 offset:5120
	ds_read_b128 v[208:211], v144 offset:6144
	ds_read_b128 v[212:215], v144 offset:7168
	global_load_lds_dwordx4 v[216:217], off
	v_lshl_add_u64 v[216:217], s[30:31], 0, v[140:141]
	s_add_i32 m0, s52, 0xe000
	s_nop 0
	global_load_lds_dwordx4 v[216:217], off
	s_waitcnt vmcnt(8)
	s_waitcnt lgkmcnt(0)
	s_barrier
; #define PG8_STAGE(bufoff, gbase, voff) do { _Pragma("unroll") for (int _i = 0; _i < 2; ++_i) \
;         __builtin_amdgcn_global_load_lds((const unsigned*)((const char*)(gbase) + (voff)[_i]), (PG8_LAS unsigned*)(lds + (bufoff) + ldsw + _i * 8192), 16, 0, 0); } while (0)
; #define PG8_LDA(dst, b, h) do { _Pragma("unroll") for (int m = 0; m < 4; ++m) _Pragma("unroll") for (int k = 0; k < 2; ++k) dst[m][k] = *(const PG8_LAS bf16x8*)(lds + PG8_SA(b, h) + aoff + m * 2048 + k * 1024); } while (0)
; #define PG8_MMA(ai, bj, At, Bt) do { __builtin_amdgcn_s_setprio(1); _Pragma("unroll") for (int m = 0; m < 4; ++m) _Pragma("unroll") for (int n = 0; n < 2; ++n) _Pragma("unroll") for (int k = 0; k < 2; ++k) \
;         acc[ai][bj][m][n] = __builtin_amdgcn_mfma_f32_16x16x32_bf16(Bt[n][k], At[m][k], acc[ai][bj][m][n], 0, 0, 0); __builtin_amdgcn_s_setprio(0); } while (0)
; #define PG8_WAIT_V(n) asm volatile("s_waitcnt vmcnt(" #n ")" ::: "memory")
; #define PG8_WAIT_L(n) asm volatile("s_waitcnt lgkmcnt(" #n ")" ::: "memory")
; #define PG8_BAR __builtin_amdgcn_s_barrier()
; #define PG8_SCHED __builtin_amdgcn_sched_barrier(0)
; template <class Epi, class Sched, bool ALIGN_EPI = false, bool SP2 = false>
; __device__ __forceinline__ void gemm_phase(PG8_LAS unsigned char* lds, const Gemm g, const Sched& S, const Epi& E) {
;     ...
;             PG8_WAIT_V(8); PG8_WAIT_L(0); PG8_BAR; PG8_MMA(0, 0, At, B0); PG8_MMA(0, 1, At, B1); PG8_BAR; PG8_SCHED;
;             PG8_LDA(At, 0, 1); PG8_STAGE(PG8_SB(0, 0), b2, voffB); PG8_STAGE(PG8_SB(0, 1), b2 + hstepB, voffB); PG8_STAGE(PG8_SA(0, 0), a2, voffA);
;             PG8_WAIT_V(8); PG8_WAIT_L(0); PG8_BAR; PG8_MMA(1, 0, At, B0); PG8_MMA(1, 1, At, B1); PG8_BAR; PG8_SCHED;
	s_setprio 1
	s_waitcnt lgkmcnt(0)
	v_mfma_f32_16x16x32_bf16 v[126:129], v[146:149], v[178:181], v[126:129]
	v_mfma_f32_16x16x32_bf16 v[122:125], v[154:157], v[178:181], v[122:125]
	v_mfma_f32_16x16x32_bf16 v[118:121], v[146:149], v[186:189], v[118:121]
	v_mfma_f32_16x16x32_bf16 v[114:117], v[154:157], v[186:189], v[114:117]
	v_mfma_f32_16x16x32_bf16 v[106:109], v[146:149], v[194:197], v[106:109]
	v_mfma_f32_16x16x32_bf16 v[98:101], v[154:157], v[194:197], v[98:101]
	v_mfma_f32_16x16x32_bf16 v[90:93], v[146:149], v[208:211], v[90:93]
	v_mfma_f32_16x16x32_bf16 v[82:85], v[154:157], v[208:211], v[82:85]
	v_mfma_f32_16x16x32_bf16 v[126:129], v[150:153], v[182:185], v[126:129]
	v_mfma_f32_16x16x32_bf16 v[122:125], v[158:161], v[182:185], v[122:125]
	v_mfma_f32_16x16x32_bf16 v[118:121], v[150:153], v[190:193], v[118:121]
	v_mfma_f32_16x16x32_bf16 v[114:117], v[158:161], v[190:193], v[114:117]
	v_mfma_f32_16x16x32_bf16 v[106:109], v[150:153], v[198:201], v[106:109]
	v_mfma_f32_16x16x32_bf16 v[98:101], v[158:161], v[198:201], v[98:101]
	v_mfma_f32_16x16x32_bf16 v[90:93], v[150:153], v[212:215], v[90:93]
	v_mfma_f32_16x16x32_bf16 v[82:85], v[158:161], v[212:215], v[82:85]
	v_mfma_f32_16x16x32_bf16 v[110:113], v[162:165], v[178:181], v[110:113]
	v_mfma_f32_16x16x32_bf16 v[102:105], v[170:173], v[178:181], v[102:105]
	v_mfma_f32_16x16x32_bf16 v[94:97], v[162:165], v[186:189], v[94:97]
	v_mfma_f32_16x16x32_bf16 v[86:89], v[170:173], v[186:189], v[86:89]
	v_mfma_f32_16x16x32_bf16 v[78:81], v[162:165], v[194:197], v[78:81]
	v_mfma_f32_16x16x32_bf16 v[74:77], v[170:173], v[194:197], v[74:77]
	v_mfma_f32_16x16x32_bf16 v[70:73], v[162:165], v[208:211], v[70:73]
	v_mfma_f32_16x16x32_bf16 v[66:69], v[170:173], v[208:211], v[66:69]
	v_mfma_f32_16x16x32_bf16 v[110:113], v[166:169], v[182:185], v[110:113]
	v_mfma_f32_16x16x32_bf16 v[102:105], v[174:177], v[182:185], v[102:105]
	v_mfma_f32_16x16x32_bf16 v[94:97], v[166:169], v[190:193], v[94:97]
	v_mfma_f32_16x16x32_bf16 v[86:89], v[174:177], v[190:193], v[86:89]
	v_mfma_f32_16x16x32_bf16 v[78:81], v[166:169], v[198:201], v[78:81]
	v_mfma_f32_16x16x32_bf16 v[74:77], v[174:177], v[198:201], v[74:77]
	v_mfma_f32_16x16x32_bf16 v[70:73], v[166:169], v[212:215], v[70:73]
	v_mfma_f32_16x16x32_bf16 v[66:69], v[174:177], v[212:215], v[66:69]
	s_setprio 0
	s_barrier
	s_add_i32 s20, s20, s45
	v_lshl_add_u64 v[216:217], s[36:37], 0, v[134:135]
	s_mov_b32 m0, s20
	ds_read_b128 v[178:181], v144 offset:16384
	ds_read_b128 v[182:185], v144 offset:17408
	ds_read_b128 v[186:189], v144 offset:18432
	ds_read_b128 v[190:193], v144 offset:19456
	ds_read_b128 v[194:197], v144 offset:20480
	ds_read_b128 v[198:201], v144 offset:21504
	ds_read_b128 v[208:211], v144 offset:22528
	ds_read_b128 v[212:215], v144 offset:23552
	global_load_lds_dwordx4 v[216:217], off
	s_add_i32 m0, s20, 0x2000
	s_add_u32 s30, s36, 0x20000
	v_lshl_add_u64 v[218:219], s[36:37], 0, v[130:131]
	s_addc_u32 s31, s37, 0
	s_add_i32 s20, s21, s45
	global_load_lds_dwordx4 v[218:219], off
	v_lshl_add_u64 v[220:221], s[30:31], 0, v[134:135]
	s_mov_b32 m0, s20
	v_lshl_add_u64 v[222:223], s[38:39], 0, v[132:133]
	global_load_lds_dwordx4 v[220:221], off
	v_lshl_add_u64 v[220:221], s[30:31], 0, v[130:131]
	s_add_i32 m0, s20, 0x2000
	s_nop 0
	global_load_lds_dwordx4 v[220:221], off
	v_lshl_add_u64 v[220:221], s[38:39], 0, v[136:137]
	s_mov_b32 m0, s52
	s_nop 0
	global_load_lds_dwordx4 v[220:221], off
	s_mov_b32 m0, s53
	s_nop 0
	global_load_lds_dwordx4 v[222:223], off
	s_waitcnt vmcnt(8)
	s_waitcnt lgkmcnt(0)
	s_barrier
	s_setprio 1
	s_waitcnt lgkmcnt(0)
	v_mfma_f32_16x16x32_bf16 v[62:65], v[146:149], v[178:181], v[62:65]
	v_mfma_f32_16x16x32_bf16 v[58:61], v[154:157], v[178:181], v[58:61]
	v_mfma_f32_16x16x32_bf16 v[54:57], v[146:149], v[186:189], v[54:57]
	v_mfma_f32_16x16x32_bf16 v[50:53], v[154:157], v[186:189], v[50:53]
	v_mfma_f32_16x16x32_bf16 v[38:41], v[146:149], v[194:197], v[38:41]
	v_mfma_f32_16x16x32_bf16 v[34:37], v[154:157], v[194:197], v[34:37]
	v_mfma_f32_16x16x32_bf16 v[22:25], v[146:149], v[208:211], v[22:25]
	v_mfma_f32_16x16x32_bf16 v[18:21], v[154:157], v[208:211], v[18:21]
	v_mfma_f32_16x16x32_bf16 v[62:65], v[150:153], v[182:185], v[62:65]
	v_mfma_f32_16x16x32_bf16 v[58:61], v[158:161], v[182:185], v[58:61]
	v_mfma_f32_16x16x32_bf16 v[54:57], v[150:153], v[190:193], v[54:57]
	v_mfma_f32_16x16x32_bf16 v[50:53], v[158:161], v[190:193], v[50:53]
	v_mfma_f32_16x16x32_bf16 v[38:41], v[150:153], v[198:201], v[38:41]
	v_mfma_f32_16x16x32_bf16 v[34:37], v[158:161], v[198:201], v[34:37]
	v_mfma_f32_16x16x32_bf16 v[22:25], v[150:153], v[212:215], v[22:25]
	v_mfma_f32_16x16x32_bf16 v[18:21], v[158:161], v[212:215], v[18:21]
	v_mfma_f32_16x16x32_bf16 v[46:49], v[162:165], v[178:181], v[46:49]
	v_mfma_f32_16x16x32_bf16 v[42:45], v[170:173], v[178:181], v[42:45]
	v_mfma_f32_16x16x32_bf16 v[30:33], v[162:165], v[186:189], v[30:33]
	v_mfma_f32_16x16x32_bf16 v[26:29], v[170:173], v[186:189], v[26:29]
	v_mfma_f32_16x16x32_bf16 v[14:17], v[162:165], v[194:197], v[14:17]
	v_mfma_f32_16x16x32_bf16 v[10:13], v[170:173], v[194:197], v[10:13]
	v_mfma_f32_16x16x32_bf16 v[6:9], v[162:165], v[208:211], v[6:9]
	v_mfma_f32_16x16x32_bf16 v[2:5], v[170:173], v[208:211], v[2:5]
	v_mfma_f32_16x16x32_bf16 v[46:49], v[166:169], v[182:185], v[46:49]
	v_mfma_f32_16x16x32_bf16 v[42:45], v[174:177], v[182:185], v[42:45]
	v_mfma_f32_16x16x32_bf16 v[30:33], v[166:169], v[190:193], v[30:33]
	v_mfma_f32_16x16x32_bf16 v[26:29], v[174:177], v[190:193], v[26:29]
	v_mfma_f32_16x16x32_bf16 v[14:17], v[166:169], v[198:201], v[14:17]
	v_mfma_f32_16x16x32_bf16 v[10:13], v[174:177], v[198:201], v[10:13]
	v_mfma_f32_16x16x32_bf16 v[6:9], v[166:169], v[212:215], v[6:9]
	v_mfma_f32_16x16x32_bf16 v[2:5], v[174:177], v[212:215], v[2:5]
	s_setprio 0
	s_barrier
; #define PG8_STAGE(bufoff, gbase, voff) do { _Pragma("unroll") for (int _i = 0; _i < 2; ++_i) \
;         __builtin_amdgcn_global_load_lds((const unsigned*)((const char*)(gbase) + (voff)[_i]), (PG8_LAS unsigned*)(lds + (bufoff) + ldsw + _i * 8192), 16, 0, 0); } while (0)
; #define PG8_LDA(dst, b, h) do { _Pragma("unroll") for (int m = 0; m < 4; ++m) _Pragma("unroll") for (int k = 0; k < 2; ++k) dst[m][k] = *(const PG8_LAS bf16x8*)(lds + PG8_SA(b, h) + aoff + m * 2048 + k * 1024); } while (0)
; #define PG8_LDB(dst, b, h) do { _Pragma("unroll") for (int n = 0; n < 2; ++n) _Pragma("unroll") for (int k = 0; k < 2; ++k) dst[n][k] = *(const PG8_LAS bf16x8*)(lds + PG8_SB(b, h) + boff + n * 2048 + k * 1024); } while (0)
; #define PG8_MMA(ai, bj, At, Bt) do { __builtin_amdgcn_s_setprio(1); _Pragma("unroll") for (int m = 0; m < 4; ++m) _Pragma("unroll") for (int n = 0; n < 2; ++n) _Pragma("unroll") for (int k = 0; k < 2; ++k) \
;         acc[ai][bj][m][n] = __builtin_amdgcn_mfma_f32_16x16x32_bf16(Bt[n][k], At[m][k], acc[ai][bj][m][n], 0, 0, 0); __builtin_amdgcn_s_setprio(0); } while (0)
; #define PG8_WAIT_V(n) asm volatile("s_waitcnt vmcnt(" #n ")" ::: "memory")
; #define PG8_WAIT_L(n) asm volatile("s_waitcnt lgkmcnt(" #n ")" ::: "memory")
; #define PG8_BAR __builtin_amdgcn_s_barrier()
; #define PG8_SCHED __builtin_amdgcn_sched_barrier(0)
; template <class Epi, class Sched, bool ALIGN_EPI = false, bool SP2 = false>
; __device__ __forceinline__ void gemm_phase(PG8_LAS unsigned char* lds, const Gemm g, const Sched& S, const Epi& E) {
;     ...
;             PG8_LDB(B0, 1, 0); PG8_LDB(B1, 1, 1); PG8_SCHED; PG8_LDA(At, 1, 0); PG8_STAGE(PG8_SA(0, 1), a2 + hstepA, voffA);
;             PG8_WAIT_V(8); PG8_WAIT_L(0); PG8_BAR; PG8_MMA(0, 0, At, B0); PG8_MMA(0, 1, At, B1); PG8_BAR; PG8_SCHED;
	s_add_i32 s20, 0, 0x18000
	v_add_u32_e32 v145, s20, v143
	s_add_i32 s21, 0, 0x1c000
	ds_read_b128 v[146:149], v145
	ds_read_b128 v[150:153], v145 offset:1024
	ds_read_b128 v[154:157], v145 offset:2048
	ds_read_b128 v[158:161], v145 offset:3072
	v_add_u32_e32 v145, s21, v143
	ds_read_b128 v[162:165], v145
	ds_read_b128 v[166:169], v145 offset:1024
	ds_read_b128 v[170:173], v145 offset:2048
	ds_read_b128 v[174:177], v145 offset:3072
	s_add_u32 s30, s38, 0x30000
	s_addc_u32 s31, s39, 0
	s_mov_b32 m0, s54
	v_lshl_add_u64 v[224:225], s[30:31], 0, v[136:137]
	ds_read_b128 v[178:181], v144 offset:32768
	ds_read_b128 v[182:185], v144 offset:33792
	ds_read_b128 v[186:189], v144 offset:34816
	ds_read_b128 v[190:193], v144 offset:35840
	ds_read_b128 v[194:197], v144 offset:36864
	ds_read_b128 v[198:201], v144 offset:37888
	ds_read_b128 v[208:211], v144 offset:38912
	ds_read_b128 v[212:215], v144 offset:39936
	global_load_lds_dwordx4 v[224:225], off
	v_lshl_add_u64 v[224:225], s[30:31], 0, v[132:133]
	s_mov_b32 m0, s55
	s_nop 0
	global_load_lds_dwordx4 v[224:225], off
	s_waitcnt vmcnt(8)
	s_waitcnt lgkmcnt(0)
	s_barrier
	s_setprio 1
	s_waitcnt lgkmcnt(0)
	v_mfma_f32_16x16x32_bf16 v[126:129], v[146:149], v[178:181], v[126:129]
	v_mfma_f32_16x16x32_bf16 v[122:125], v[154:157], v[178:181], v[122:125]
	v_mfma_f32_16x16x32_bf16 v[118:121], v[146:149], v[186:189], v[118:121]
	v_mfma_f32_16x16x32_bf16 v[114:117], v[154:157], v[186:189], v[114:117]
	v_mfma_f32_16x16x32_bf16 v[106:109], v[146:149], v[194:197], v[106:109]
	v_mfma_f32_16x16x32_bf16 v[98:101], v[154:157], v[194:197], v[98:101]
	v_mfma_f32_16x16x32_bf16 v[90:93], v[146:149], v[208:211], v[90:93]
	v_mfma_f32_16x16x32_bf16 v[82:85], v[154:157], v[208:211], v[82:85]
	v_mfma_f32_16x16x32_bf16 v[126:129], v[150:153], v[182:185], v[126:129]
	v_mfma_f32_16x16x32_bf16 v[122:125], v[158:161], v[182:185], v[122:125]
	v_mfma_f32_16x16x32_bf16 v[118:121], v[150:153], v[190:193], v[118:121]
	v_mfma_f32_16x16x32_bf16 v[114:117], v[158:161], v[190:193], v[114:117]
	v_mfma_f32_16x16x32_bf16 v[106:109], v[150:153], v[198:201], v[106:109]
	v_mfma_f32_16x16x32_bf16 v[98:101], v[158:161], v[198:201], v[98:101]
	v_mfma_f32_16x16x32_bf16 v[90:93], v[150:153], v[212:215], v[90:93]
	v_mfma_f32_16x16x32_bf16 v[82:85], v[158:161], v[212:215], v[82:85]
	v_mfma_f32_16x16x32_bf16 v[110:113], v[162:165], v[178:181], v[110:113]
	v_mfma_f32_16x16x32_bf16 v[102:105], v[170:173], v[178:181], v[102:105]
	v_mfma_f32_16x16x32_bf16 v[94:97], v[162:165], v[186:189], v[94:97]
	v_mfma_f32_16x16x32_bf16 v[86:89], v[170:173], v[186:189], v[86:89]
	v_mfma_f32_16x16x32_bf16 v[78:81], v[162:165], v[194:197], v[78:81]
	v_mfma_f32_16x16x32_bf16 v[74:77], v[170:173], v[194:197], v[74:77]
	v_mfma_f32_16x16x32_bf16 v[70:73], v[162:165], v[208:211], v[70:73]
	v_mfma_f32_16x16x32_bf16 v[66:69], v[170:173], v[208:211], v[66:69]
	v_mfma_f32_16x16x32_bf16 v[110:113], v[166:169], v[182:185], v[110:113]
	v_mfma_f32_16x16x32_bf16 v[102:105], v[174:177], v[182:185], v[102:105]
	v_mfma_f32_16x16x32_bf16 v[94:97], v[166:169], v[190:193], v[94:97]
	v_mfma_f32_16x16x32_bf16 v[86:89], v[174:177], v[190:193], v[86:89]
	v_mfma_f32_16x16x32_bf16 v[78:81], v[166:169], v[198:201], v[78:81]
	v_mfma_f32_16x16x32_bf16 v[74:77], v[174:177], v[198:201], v[74:77]
	v_mfma_f32_16x16x32_bf16 v[70:73], v[166:169], v[212:215], v[70:73]
	v_mfma_f32_16x16x32_bf16 v[66:69], v[174:177], v[212:215], v[66:69]
	s_setprio 0
	s_barrier
; #define PG8_STAGE(bufoff, gbase, voff) do { _Pragma("unroll") for (int _i = 0; _i < 2; ++_i) \
;         __builtin_amdgcn_global_load_lds((const unsigned*)((const char*)(gbase) + (voff)[_i]), (PG8_LAS unsigned*)(lds + (bufoff) + ldsw + _i * 8192), 16, 0, 0); } while (0)
; #define PG8_LDA(dst, b, h) do { _Pragma("unroll") for (int m = 0; m < 4; ++m) _Pragma("unroll") for (int k = 0; k < 2; ++k) dst[m][k] = *(const PG8_LAS bf16x8*)(lds + PG8_SA(b, h) + aoff + m * 2048 + k * 1024); } while (0)
; #define PG8_MMA(ai, bj, At, Bt) do { __builtin_amdgcn_s_setprio(1); _Pragma("unroll") for (int m = 0; m < 4; ++m) _Pragma("unroll") for (int n = 0; n < 2; ++n) _Pragma("unroll") for (int k = 0; k < 2; ++k) \
;         acc[ai][bj][m][n] = __builtin_amdgcn_mfma_f32_16x16x32_bf16(Bt[n][k], At[m][k], acc[ai][bj][m][n], 0, 0, 0); __builtin_amdgcn_s_setprio(0); } while (0)
; #define PG8_WAIT_V(n) asm volatile("s_waitcnt vmcnt(" #n ")" ::: "memory")
; #define PG8_WAIT_L(n) asm volatile("s_waitcnt lgkmcnt(" #n ")" ::: "memory")
; #define PG8_BAR __builtin_amdgcn_s_barrier()
; #define PG8_SCHED __builtin_amdgcn_sched_barrier(0)
; template <class Epi, class Sched, bool ALIGN_EPI = false, bool SP2 = false>
; __device__ __forceinline__ void gemm_phase(PG8_LAS unsigned char* lds, const Gemm g, const Sched& S, const Epi& E) {
;     ...
;         for (int t = 0; t < nt; t += 2) {
;             const bool last = (t == nt - 2);
;             const char* a1 = cA + (size_t)(t + 1) * kstep;
;             const char* a2 = last ? nA : cA + (size_t)(t + 2) * kstep; const char* b2 = last ? nB : cB + (size_t)(t + 2) * kstep;
;             const char* a3 = a2 + kstep; const char* b3 = b2 + kstep;
;     ...
;             PG8_LDA(At, 1, 1); PG8_STAGE(PG8_SB(1, 0), b3, voffB); PG8_STAGE(PG8_SB(1, 1), b3 + hstepB, voffB); PG8_STAGE(PG8_SA(1, 0), a3, voffA);
;             PG8_WAIT_V(8); PG8_WAIT_L(0); PG8_BAR; PG8_MMA(1, 0, At, B0); PG8_MMA(1, 1, At, B1); PG8_BAR; PG8_SCHED;
	s_add_i32 s20, s20, s45
	v_lshl_add_u64 v[216:217], v[216:217], 0, s[22:23]
	s_mov_b32 m0, s20
	ds_read_b128 v[178:181], v144 offset:49152
	ds_read_b128 v[182:185], v144 offset:50176
	ds_read_b128 v[186:189], v144 offset:51200
	ds_read_b128 v[190:193], v144 offset:52224
	ds_read_b128 v[194:197], v144 offset:53248
	ds_read_b128 v[198:201], v144 offset:54272
	ds_read_b128 v[208:211], v144 offset:55296
	ds_read_b128 v[212:215], v144 offset:56320
	global_load_lds_dwordx4 v[216:217], off
	s_add_i32 m0, s20, 0x2000
	s_add_u32 s30, s36, 0x20080
	v_lshl_add_u64 v[216:217], v[218:219], 0, s[22:23]
	s_addc_u32 s31, s37, 0
	s_add_i32 s20, s21, s45
	global_load_lds_dwordx4 v[216:217], off
	v_lshl_add_u64 v[216:217], s[30:31], 0, v[134:135]
	s_mov_b32 m0, s20
	s_nop 0
	global_load_lds_dwordx4 v[216:217], off
	v_lshl_add_u64 v[216:217], s[30:31], 0, v[130:131]
	s_add_i32 m0, s20, 0x2000
	s_nop 0
	global_load_lds_dwordx4 v[216:217], off
	v_lshl_add_u64 v[216:217], v[220:221], 0, s[22:23]
	s_mov_b32 m0, s56
	s_nop 0
	global_load_lds_dwordx4 v[216:217], off
	v_lshl_add_u64 v[216:217], v[222:223], 0, s[22:23]
	s_mov_b32 m0, s57
	s_nop 0
	global_load_lds_dwordx4 v[216:217], off
	s_waitcnt vmcnt(8)
	s_waitcnt lgkmcnt(0)
	s_barrier
	s_setprio 1
	s_waitcnt lgkmcnt(0)
	v_mfma_f32_16x16x32_bf16 v[62:65], v[146:149], v[178:181], v[62:65]
	v_mfma_f32_16x16x32_bf16 v[58:61], v[154:157], v[178:181], v[58:61]
	v_mfma_f32_16x16x32_bf16 v[54:57], v[146:149], v[186:189], v[54:57]
	v_mfma_f32_16x16x32_bf16 v[50:53], v[154:157], v[186:189], v[50:53]
	v_mfma_f32_16x16x32_bf16 v[38:41], v[146:149], v[194:197], v[38:41]
	v_mfma_f32_16x16x32_bf16 v[34:37], v[154:157], v[194:197], v[34:37]
	v_mfma_f32_16x16x32_bf16 v[22:25], v[146:149], v[208:211], v[22:25]
	v_mfma_f32_16x16x32_bf16 v[18:21], v[154:157], v[208:211], v[18:21]
	v_mfma_f32_16x16x32_bf16 v[62:65], v[150:153], v[182:185], v[62:65]
	v_mfma_f32_16x16x32_bf16 v[58:61], v[158:161], v[182:185], v[58:61]
	v_mfma_f32_16x16x32_bf16 v[54:57], v[150:153], v[190:193], v[54:57]
	v_mfma_f32_16x16x32_bf16 v[50:53], v[158:161], v[190:193], v[50:53]
	v_mfma_f32_16x16x32_bf16 v[38:41], v[150:153], v[198:201], v[38:41]
	v_mfma_f32_16x16x32_bf16 v[34:37], v[158:161], v[198:201], v[34:37]
	v_mfma_f32_16x16x32_bf16 v[22:25], v[150:153], v[212:215], v[22:25]
	v_mfma_f32_16x16x32_bf16 v[18:21], v[158:161], v[212:215], v[18:21]
	v_mfma_f32_16x16x32_bf16 v[46:49], v[162:165], v[178:181], v[46:49]
	v_mfma_f32_16x16x32_bf16 v[42:45], v[170:173], v[178:181], v[42:45]
	v_mfma_f32_16x16x32_bf16 v[30:33], v[162:165], v[186:189], v[30:33]
	v_mfma_f32_16x16x32_bf16 v[26:29], v[170:173], v[186:189], v[26:29]
	v_mfma_f32_16x16x32_bf16 v[14:17], v[162:165], v[194:197], v[14:17]
	v_mfma_f32_16x16x32_bf16 v[10:13], v[170:173], v[194:197], v[10:13]
	v_mfma_f32_16x16x32_bf16 v[6:9], v[162:165], v[208:211], v[6:9]
	v_mfma_f32_16x16x32_bf16 v[2:5], v[170:173], v[208:211], v[2:5]
	v_mfma_f32_16x16x32_bf16 v[46:49], v[166:169], v[182:185], v[46:49]
	v_mfma_f32_16x16x32_bf16 v[42:45], v[174:177], v[182:185], v[42:45]
	v_mfma_f32_16x16x32_bf16 v[30:33], v[166:169], v[190:193], v[30:33]
	v_mfma_f32_16x16x32_bf16 v[26:29], v[174:177], v[190:193], v[26:29]
	v_mfma_f32_16x16x32_bf16 v[14:17], v[166:169], v[198:201], v[14:17]
	v_mfma_f32_16x16x32_bf16 v[10:13], v[174:177], v[198:201], v[10:13]
	v_mfma_f32_16x16x32_bf16 v[6:9], v[166:169], v[212:215], v[6:9]
	v_mfma_f32_16x16x32_bf16 v[2:5], v[174:177], v[212:215], v[2:5]
	s_setprio 0
	s_barrier
	s_add_i32 s63, s63, 2
	s_add_u32 s61, s61, 0x100
	s_addc_u32 s62, s62, 0
	s_cmp_gt_u32 s63, 5
	s_mov_b64 s[30:31], s[34:35]
	s_cbranch_scc0 .LBB0_783

; #define PG8_STAGE(bufoff, gbase, voff) do { _Pragma("unroll") for (int _i = 0; _i < 2; ++_i) \
;         __builtin_amdgcn_global_load_lds((const unsigned*)((const char*)(gbase) + (voff)[_i]), (PG8_LAS unsigned*)(lds + (bufoff) + ldsw + _i * 8192), 16, 0, 0); } while (0)
; #define PG8_LDA(dst, b, h) do { _Pragma("unroll") for (int m = 0; m < 4; ++m) _Pragma("unroll") for (int k = 0; k < 2; ++k) dst[m][k] = *(const PG8_LAS bf16x8*)(lds + PG8_SA(b, h) + aoff + m * 2048 + k * 1024); } while (0)
; #define PG8_LDB(dst, b, h) do { _Pragma("unroll") for (int n = 0; n < 2; ++n) _Pragma("unroll") for (int k = 0; k < 2; ++k) dst[n][k] = *(const PG8_LAS bf16x8*)(lds + PG8_SB(b, h) + boff + n * 2048 + k * 1024); } while (0)
; #define PG8_WAIT_V(n) asm volatile("s_waitcnt vmcnt(" #n ")" ::: "memory")
; #define PG8_WAIT_L(n) asm volatile("s_waitcnt lgkmcnt(" #n ")" ::: "memory")
; #define PG8_BAR __builtin_amdgcn_s_barrier()
; template <class Epi, class Sched, bool ALIGN_EPI = false, bool SP2 = false>
; __device__ __forceinline__ void gemm_phase(PG8_LAS unsigned char* lds, const Gemm g, const Sched& S, const Epi& E) {
;     ...
;         const bool has_next = S.next(ui + 1, nxt);
;         const char* nA = has_next ? (const char*)g.A + (size_t)nxt.pm * tstepA + (size_t)nxt.pb * g.sA : cA; const char* nB = has_next ? (const char*)g.Bt + (size_t)nxt.pn * tstepB + (size_t)nxt.pb * g.sB : cB;
;         for (int t = 0; t < nt; t += 2) {
;             const bool last = (t == nt - 2);
;             const char* a1 = cA + (size_t)(t + 1) * kstep;
;             const char* a2 = last ? nA : cA + (size_t)(t + 2) * kstep; const char* b2 = last ? nB : cB + (size_t)(t + 2) * kstep;
;             const char* a3 = a2 + kstep; const char* b3 = b2 + kstep;
;             if (last && has_next) S.a_ready(nxt);
;             if constexpr (SP2) {
;             PG8_LDB(B0, 0, 0); PG8_LDB(B1, 0, 1); PG8_SCHED; PG8_LDA(At, 0, 0); PG8_STAGE(PG8_SA(1, 1), a1 + hstepA, voffA);
;             PG8_WAIT_V(8); PG8_WAIT_L(0); PG8_BAR; PG8_MMA(0, 0, At, B0); PG8_MMA(0, 1, At, B1); PG8_BAR; PG8_SCHED;
;             PG8_LDA(At, 0, 1); PG8_STAGE(PG8_SB(0, 0), b2, voffB); PG8_STAGE(PG8_SB(0, 1), b2 + hstepB, voffB); PG8_STAGE(PG8_SA(0, 0), a2, voffA);
;             PG8_WAIT_V(8); PG8_WAIT_L(0); PG8_BAR; PG8_MMA(1, 0, At, B0); PG8_MMA(1, 1, At, B1); PG8_BAR; PG8_SCHED;
.LBB0_958:
	s_add_u32 s63, s8, 0x100
	s_addc_u32 s70, s9, 0
	s_mov_b32 s71, -2
	s_add_u32 s8, s0, 0x100
	s_addc_u32 s9, s1, 0
	s_add_i32 s20, 0, 0x10000
	s_cmp_eq_u32 s71, 8
	s_cselect_b32 s13, s31, s9
	s_cselect_b32 s12, s30, s8
	v_add_u32_e32 v142, s20, v145
	s_cselect_b32 s11, s19, s70
	s_cselect_b32 s10, s18, s63
	s_add_i32 s21, 0, 0x14000
	ds_read_b128 v[148:151], v142
	ds_read_b128 v[152:155], v142 offset:1024
	ds_read_b128 v[156:159], v142 offset:2048
	ds_read_b128 v[160:163], v142 offset:3072
	v_add_u32_e32 v142, s21, v145
	ds_read_b128 v[164:167], v142
	ds_read_b128 v[168:171], v142 offset:1024
	ds_read_b128 v[172:175], v142 offset:2048
	ds_read_b128 v[176:179], v142 offset:3072
	v_lshl_add_u64 v[142:143], s[0:1], 0, v[138:139]
	s_add_i32 m0, s34, 0xc000
	ds_read_b128 v[180:183], v147
	ds_read_b128 v[184:187], v147 offset:1024
	ds_read_b128 v[188:191], v147 offset:2048
	ds_read_b128 v[192:195], v147 offset:3072
	ds_read_b128 v[196:199], v147 offset:4096
	ds_read_b128 v[208:211], v147 offset:5120
	ds_read_b128 v[212:215], v147 offset:6144
	ds_read_b128 v[216:219], v147 offset:7168
	global_load_lds_dwordx4 v[142:143], off
	v_lshl_add_u64 v[142:143], s[0:1], 0, v[140:141]
	s_add_i32 m0, s34, 0xe000
	s_nop 0
	global_load_lds_dwordx4 v[142:143], off
	s_waitcnt vmcnt(8)
	s_waitcnt lgkmcnt(0)
	s_barrier
	s_setprio 1
	s_waitcnt lgkmcnt(0)
	v_mfma_f32_16x16x32_bf16 v[126:129], v[148:151], v[180:183], 0
	v_mfma_f32_16x16x32_bf16 v[122:125], v[156:159], v[180:183], 0
	v_mfma_f32_16x16x32_bf16 v[110:113], v[148:151], v[188:191], 0
	v_mfma_f32_16x16x32_bf16 v[106:109], v[156:159], v[188:191], 0
	v_mfma_f32_16x16x32_bf16 v[94:97], v[148:151], v[196:199], 0
	v_mfma_f32_16x16x32_bf16 v[90:93], v[156:159], v[196:199], 0
	v_mfma_f32_16x16x32_bf16 v[78:81], v[148:151], v[212:215], 0
	v_mfma_f32_16x16x32_bf16 v[74:77], v[156:159], v[212:215], 0
	v_mfma_f32_16x16x32_bf16 v[126:129], v[152:155], v[184:187], v[126:129]
	v_mfma_f32_16x16x32_bf16 v[122:125], v[160:163], v[184:187], v[122:125]
	v_mfma_f32_16x16x32_bf16 v[110:113], v[152:155], v[192:195], v[110:113]
	v_mfma_f32_16x16x32_bf16 v[106:109], v[160:163], v[192:195], v[106:109]
	v_mfma_f32_16x16x32_bf16 v[94:97], v[152:155], v[208:211], v[94:97]
	v_mfma_f32_16x16x32_bf16 v[90:93], v[160:163], v[208:211], v[90:93]
	v_mfma_f32_16x16x32_bf16 v[78:81], v[152:155], v[216:219], v[78:81]
	v_mfma_f32_16x16x32_bf16 v[74:77], v[160:163], v[216:219], v[74:77]
	v_mfma_f32_16x16x32_bf16 v[118:121], v[164:167], v[180:183], 0
	v_mfma_f32_16x16x32_bf16 v[114:117], v[172:175], v[180:183], 0
	v_mfma_f32_16x16x32_bf16 v[102:105], v[164:167], v[188:191], 0
	v_mfma_f32_16x16x32_bf16 v[98:101], v[172:175], v[188:191], 0
	v_mfma_f32_16x16x32_bf16 v[86:89], v[164:167], v[196:199], 0
	v_mfma_f32_16x16x32_bf16 v[82:85], v[172:175], v[196:199], 0
	v_mfma_f32_16x16x32_bf16 v[70:73], v[164:167], v[212:215], 0
	v_mfma_f32_16x16x32_bf16 v[66:69], v[172:175], v[212:215], 0
	v_mfma_f32_16x16x32_bf16 v[118:121], v[168:171], v[184:187], v[118:121]
	v_mfma_f32_16x16x32_bf16 v[114:117], v[176:179], v[184:187], v[114:117]
	v_mfma_f32_16x16x32_bf16 v[102:105], v[168:171], v[192:195], v[102:105]
	v_mfma_f32_16x16x32_bf16 v[98:101], v[176:179], v[192:195], v[98:101]
	v_mfma_f32_16x16x32_bf16 v[86:89], v[168:171], v[208:211], v[86:89]
	v_mfma_f32_16x16x32_bf16 v[82:85], v[176:179], v[208:211], v[82:85]
	v_mfma_f32_16x16x32_bf16 v[70:73], v[168:171], v[216:219], v[70:73]
	v_mfma_f32_16x16x32_bf16 v[66:69], v[176:179], v[216:219], v[66:69]
	s_setprio 0
	s_barrier
	s_add_i32 s0, s20, s26
	v_lshl_add_u64 v[142:143], s[10:11], 0, v[134:135]
	s_mov_b32 m0, s0
	ds_read_b128 v[180:183], v147 offset:16384
	ds_read_b128 v[184:187], v147 offset:17408
	ds_read_b128 v[188:191], v147 offset:18432
	ds_read_b128 v[192:195], v147 offset:19456
	ds_read_b128 v[196:199], v147 offset:20480
	ds_read_b128 v[208:211], v147 offset:21504
	ds_read_b128 v[212:215], v147 offset:22528
	ds_read_b128 v[216:219], v147 offset:23552
	global_load_lds_dwordx4 v[142:143], off
	s_add_i32 m0, s0, 0x2000
	s_add_u32 s0, s10, 0x30000
	v_lshl_add_u64 v[200:201], s[10:11], 0, v[130:131]
	s_addc_u32 s1, s11, 0
	s_add_i32 s20, s21, s26
	global_load_lds_dwordx4 v[200:201], off
	v_lshl_add_u64 v[220:221], s[0:1], 0, v[134:135]
	s_mov_b32 m0, s20
	v_lshl_add_u64 v[222:223], s[12:13], 0, v[132:133]
	global_load_lds_dwordx4 v[220:221], off
	v_lshl_add_u64 v[220:221], s[0:1], 0, v[130:131]
	s_add_i32 m0, s20, 0x2000
	s_nop 0
	global_load_lds_dwordx4 v[220:221], off
	v_lshl_add_u64 v[220:221], s[12:13], 0, v[136:137]
	s_mov_b32 m0, s34
	s_nop 0
	global_load_lds_dwordx4 v[220:221], off
	s_mov_b32 m0, s35
	s_nop 0
	global_load_lds_dwordx4 v[222:223], off
	s_waitcnt vmcnt(8)
	s_waitcnt lgkmcnt(0)
	s_barrier
; #define PG8_STAGE(bufoff, gbase, voff) do { _Pragma("unroll") for (int _i = 0; _i < 2; ++_i) \
;         __builtin_amdgcn_global_load_lds((const unsigned*)((const char*)(gbase) + (voff)[_i]), (PG8_LAS unsigned*)(lds + (bufoff) + ldsw + _i * 8192), 16, 0, 0); } while (0)
; #define PG8_LDA(dst, b, h) do { _Pragma("unroll") for (int m = 0; m < 4; ++m) _Pragma("unroll") for (int k = 0; k < 2; ++k) dst[m][k] = *(const PG8_LAS bf16x8*)(lds + PG8_SA(b, h) + aoff + m * 2048 + k * 1024); } while (0)
; #define PG8_LDB(dst, b, h) do { _Pragma("unroll") for (int n = 0; n < 2; ++n) _Pragma("unroll") for (int k = 0; k < 2; ++k) dst[n][k] = *(const PG8_LAS bf16x8*)(lds + PG8_SB(b, h) + boff + n * 2048 + k * 1024); } while (0)
; #define PG8_MMA(ai, bj, At, Bt) do { __builtin_amdgcn_s_setprio(1); _Pragma("unroll") for (int m = 0; m < 4; ++m) _Pragma("unroll") for (int n = 0; n < 2; ++n) _Pragma("unroll") for (int k = 0; k < 2; ++k) \
;         acc[ai][bj][m][n] = __builtin_amdgcn_mfma_f32_16x16x32_bf16(Bt[n][k], At[m][k], acc[ai][bj][m][n], 0, 0, 0); __builtin_amdgcn_s_setprio(0); } while (0)
; #define PG8_WAIT_V(n) asm volatile("s_waitcnt vmcnt(" #n ")" ::: "memory")
; #define PG8_WAIT_L(n) asm volatile("s_waitcnt lgkmcnt(" #n ")" ::: "memory")
; #define PG8_BAR __builtin_amdgcn_s_barrier()
; #define PG8_SCHED __builtin_amdgcn_sched_barrier(0)
; template <class Epi, class Sched, bool ALIGN_EPI = false, bool SP2 = false>
; __device__ __forceinline__ void gemm_phase(PG8_LAS unsigned char* lds, const Gemm g, const Sched& S, const Epi& E) {
;     ...
;             PG8_WAIT_V(8); PG8_WAIT_L(0); PG8_BAR; PG8_MMA(1, 0, At, B0); PG8_MMA(1, 1, At, B1); PG8_BAR; PG8_SCHED;
;             PG8_LDB(B0, 1, 0); PG8_LDB(B1, 1, 1); PG8_SCHED; PG8_LDA(At, 1, 0); PG8_STAGE(PG8_SA(0, 1), a2 + hstepA, voffA);
;             PG8_WAIT_V(8); PG8_WAIT_L(0); PG8_BAR; PG8_MMA(0, 0, At, B0); PG8_MMA(0, 1, At, B1); PG8_BAR; PG8_SCHED;
	s_setprio 1
	s_waitcnt lgkmcnt(0)
	v_mfma_f32_16x16x32_bf16 v[62:65], v[148:151], v[180:183], 0
	v_mfma_f32_16x16x32_bf16 v[58:61], v[156:159], v[180:183], 0
	v_mfma_f32_16x16x32_bf16 v[46:49], v[148:151], v[188:191], 0
	v_mfma_f32_16x16x32_bf16 v[42:45], v[156:159], v[188:191], 0
	v_mfma_f32_16x16x32_bf16 v[30:33], v[148:151], v[196:199], 0
	v_mfma_f32_16x16x32_bf16 v[26:29], v[156:159], v[196:199], 0
	v_mfma_f32_16x16x32_bf16 v[14:17], v[148:151], v[212:215], 0
	v_mfma_f32_16x16x32_bf16 v[10:13], v[156:159], v[212:215], 0
	v_mfma_f32_16x16x32_bf16 v[62:65], v[152:155], v[184:187], v[62:65]
	v_mfma_f32_16x16x32_bf16 v[58:61], v[160:163], v[184:187], v[58:61]
	v_mfma_f32_16x16x32_bf16 v[46:49], v[152:155], v[192:195], v[46:49]
	v_mfma_f32_16x16x32_bf16 v[42:45], v[160:163], v[192:195], v[42:45]
	v_mfma_f32_16x16x32_bf16 v[30:33], v[152:155], v[208:211], v[30:33]
	v_mfma_f32_16x16x32_bf16 v[26:29], v[160:163], v[208:211], v[26:29]
	v_mfma_f32_16x16x32_bf16 v[14:17], v[152:155], v[216:219], v[14:17]
	v_mfma_f32_16x16x32_bf16 v[10:13], v[160:163], v[216:219], v[10:13]
	v_mfma_f32_16x16x32_bf16 v[54:57], v[164:167], v[180:183], 0
	v_mfma_f32_16x16x32_bf16 v[50:53], v[172:175], v[180:183], 0
	v_mfma_f32_16x16x32_bf16 v[38:41], v[164:167], v[188:191], 0
	v_mfma_f32_16x16x32_bf16 v[34:37], v[172:175], v[188:191], 0
	v_mfma_f32_16x16x32_bf16 v[22:25], v[164:167], v[196:199], 0
	v_mfma_f32_16x16x32_bf16 v[18:21], v[172:175], v[196:199], 0
	v_mfma_f32_16x16x32_bf16 v[6:9], v[164:167], v[212:215], 0
	v_mfma_f32_16x16x32_bf16 v[2:5], v[172:175], v[212:215], 0
	v_mfma_f32_16x16x32_bf16 v[54:57], v[168:171], v[184:187], v[54:57]
	v_mfma_f32_16x16x32_bf16 v[50:53], v[176:179], v[184:187], v[50:53]
	v_mfma_f32_16x16x32_bf16 v[38:41], v[168:171], v[192:195], v[38:41]
	v_mfma_f32_16x16x32_bf16 v[34:37], v[176:179], v[192:195], v[34:37]
	v_mfma_f32_16x16x32_bf16 v[22:25], v[168:171], v[208:211], v[22:25]
	v_mfma_f32_16x16x32_bf16 v[18:21], v[176:179], v[208:211], v[18:21]
	v_mfma_f32_16x16x32_bf16 v[6:9], v[168:171], v[216:219], v[6:9]
	v_mfma_f32_16x16x32_bf16 v[2:5], v[176:179], v[216:219], v[2:5]
	s_setprio 0
	s_barrier
	s_add_i32 s20, 0, 0x18000
	s_add_i32 s21, 0, 0x1c000
	v_add_u32_e32 v160, s20, v145
	v_add_u32_e32 v176, s21, v145
	ds_read_b128 v[148:151], v160
	ds_read_b128 v[152:155], v160 offset:1024
	ds_read_b128 v[156:159], v160 offset:2048
	ds_read_b128 v[160:163], v160 offset:3072
	ds_read_b128 v[164:167], v176
	ds_read_b128 v[168:171], v176 offset:1024
	ds_read_b128 v[172:175], v176 offset:2048
	ds_read_b128 v[176:179], v176 offset:3072
	s_add_u32 s0, s12, 0x30000
	s_addc_u32 s1, s13, 0
	s_mov_b32 m0, s36
	v_lshl_add_u64 v[224:225], s[0:1], 0, v[136:137]
	ds_read_b128 v[180:183], v147 offset:32768
	ds_read_b128 v[184:187], v147 offset:33792
	ds_read_b128 v[188:191], v147 offset:34816
	ds_read_b128 v[192:195], v147 offset:35840
	ds_read_b128 v[196:199], v147 offset:36864
	ds_read_b128 v[208:211], v147 offset:37888
	ds_read_b128 v[212:215], v147 offset:38912
	ds_read_b128 v[216:219], v147 offset:39936
	global_load_lds_dwordx4 v[224:225], off
	v_lshl_add_u64 v[224:225], s[0:1], 0, v[132:133]
	s_mov_b32 m0, s37
	s_nop 0
	global_load_lds_dwordx4 v[224:225], off
	s_waitcnt vmcnt(8)
	s_waitcnt lgkmcnt(0)
	s_barrier
	s_setprio 1
	s_waitcnt lgkmcnt(0)
	v_mfma_f32_16x16x32_bf16 v[126:129], v[148:151], v[180:183], v[126:129]
	v_mfma_f32_16x16x32_bf16 v[122:125], v[156:159], v[180:183], v[122:125]
	v_mfma_f32_16x16x32_bf16 v[110:113], v[148:151], v[188:191], v[110:113]
	v_mfma_f32_16x16x32_bf16 v[106:109], v[156:159], v[188:191], v[106:109]
	v_mfma_f32_16x16x32_bf16 v[94:97], v[148:151], v[196:199], v[94:97]
	v_mfma_f32_16x16x32_bf16 v[90:93], v[156:159], v[196:199], v[90:93]
	v_mfma_f32_16x16x32_bf16 v[78:81], v[148:151], v[212:215], v[78:81]
	v_mfma_f32_16x16x32_bf16 v[74:77], v[156:159], v[212:215], v[74:77]
	v_mfma_f32_16x16x32_bf16 v[126:129], v[152:155], v[184:187], v[126:129]
	v_mfma_f32_16x16x32_bf16 v[122:125], v[160:163], v[184:187], v[122:125]
	v_mfma_f32_16x16x32_bf16 v[110:113], v[152:155], v[192:195], v[110:113]
	v_mfma_f32_16x16x32_bf16 v[106:109], v[160:163], v[192:195], v[106:109]
	v_mfma_f32_16x16x32_bf16 v[94:97], v[152:155], v[208:211], v[94:97]
	v_mfma_f32_16x16x32_bf16 v[90:93], v[160:163], v[208:211], v[90:93]
	v_mfma_f32_16x16x32_bf16 v[78:81], v[152:155], v[216:219], v[78:81]
	v_mfma_f32_16x16x32_bf16 v[74:77], v[160:163], v[216:219], v[74:77]
	v_mfma_f32_16x16x32_bf16 v[118:121], v[164:167], v[180:183], v[118:121]
	v_mfma_f32_16x16x32_bf16 v[114:117], v[172:175], v[180:183], v[114:117]
	v_mfma_f32_16x16x32_bf16 v[102:105], v[164:167], v[188:191], v[102:105]
	v_mfma_f32_16x16x32_bf16 v[98:101], v[172:175], v[188:191], v[98:101]
	v_mfma_f32_16x16x32_bf16 v[86:89], v[164:167], v[196:199], v[86:89]
	v_mfma_f32_16x16x32_bf16 v[82:85], v[172:175], v[196:199], v[82:85]
	v_mfma_f32_16x16x32_bf16 v[70:73], v[164:167], v[212:215], v[70:73]
	v_mfma_f32_16x16x32_bf16 v[66:69], v[172:175], v[212:215], v[66:69]
	v_mfma_f32_16x16x32_bf16 v[118:121], v[168:171], v[184:187], v[118:121]
	v_mfma_f32_16x16x32_bf16 v[114:117], v[176:179], v[184:187], v[114:117]
	v_mfma_f32_16x16x32_bf16 v[102:105], v[168:171], v[192:195], v[102:105]
	v_mfma_f32_16x16x32_bf16 v[98:101], v[176:179], v[192:195], v[98:101]
	v_mfma_f32_16x16x32_bf16 v[86:89], v[168:171], v[208:211], v[86:89]
	v_mfma_f32_16x16x32_bf16 v[82:85], v[176:179], v[208:211], v[82:85]
	v_mfma_f32_16x16x32_bf16 v[70:73], v[168:171], v[216:219], v[70:73]
	v_mfma_f32_16x16x32_bf16 v[66:69], v[176:179], v[216:219], v[66:69]
	s_setprio 0
	s_barrier
; #define PG8_STAGE(bufoff, gbase, voff) do { _Pragma("unroll") for (int _i = 0; _i < 2; ++_i) \
;         __builtin_amdgcn_global_load_lds((const unsigned*)((const char*)(gbase) + (voff)[_i]), (PG8_LAS unsigned*)(lds + (bufoff) + ldsw + _i * 8192), 16, 0, 0); } while (0)
; #define PG8_LDA(dst, b, h) do { _Pragma("unroll") for (int m = 0; m < 4; ++m) _Pragma("unroll") for (int k = 0; k < 2; ++k) dst[m][k] = *(const PG8_LAS bf16x8*)(lds + PG8_SA(b, h) + aoff + m * 2048 + k * 1024); } while (0)
; #define PG8_LDB(dst, b, h) do { _Pragma("unroll") for (int n = 0; n < 2; ++n) _Pragma("unroll") for (int k = 0; k < 2; ++k) dst[n][k] = *(const PG8_LAS bf16x8*)(lds + PG8_SB(b, h) + boff + n * 2048 + k * 1024); } while (0)
; #define PG8_MMA(ai, bj, At, Bt) do { __builtin_amdgcn_s_setprio(1); _Pragma("unroll") for (int m = 0; m < 4; ++m) _Pragma("unroll") for (int n = 0; n < 2; ++n) _Pragma("unroll") for (int k = 0; k < 2; ++k) \
;         acc[ai][bj][m][n] = __builtin_amdgcn_mfma_f32_16x16x32_bf16(Bt[n][k], At[m][k], acc[ai][bj][m][n], 0, 0, 0); __builtin_amdgcn_s_setprio(0); } while (0)
; #define PG8_WAIT_V(n) asm volatile("s_waitcnt vmcnt(" #n ")" ::: "memory")
; template <class Epi, class Sched, bool ALIGN_EPI = false, bool SP2 = false>
; __device__ __forceinline__ void gemm_phase(PG8_LAS unsigned char* lds, const Gemm g, const Sched& S, const Epi& E) {
;     ...
;             PG8_LDB(B0, 0, 0); PG8_LDB(B1, 0, 1); PG8_SCHED; PG8_LDA(At, 0, 0); PG8_STAGE(PG8_SA(1, 1), a1 + hstepA, voffA);
;             PG8_WAIT_V(8); PG8_WAIT_L(0); PG8_BAR; PG8_MMA(0, 0, At, B0); PG8_MMA(0, 1, At, B1); PG8_BAR; PG8_SCHED;
;             PG8_LDA(At, 0, 1); PG8_STAGE(PG8_SB(0, 0), b2, voffB); PG8_STAGE(PG8_SB(0, 1), b2 + hstepB, voffB); PG8_STAGE(PG8_SA(0, 0), a2, voffA);
;             PG8_WAIT_V(8); PG8_WAIT_L(0); PG8_BAR; PG8_MMA(1, 0, At, B0); PG8_MMA(1, 1, At, B1); PG8_BAR; PG8_SCHED;
;             PG8_LDB(B0, 1, 0); PG8_LDB(B1, 1, 1); PG8_SCHED; PG8_LDA(At, 1, 0); PG8_STAGE(PG8_SA(0, 1), a2 + hstepA, voffA);
;             PG8_WAIT_V(8); PG8_WAIT_L(0); PG8_BAR; PG8_MMA(0, 0, At, B0); PG8_MMA(0, 1, At, B1); PG8_BAR; PG8_SCHED;
;             PG8_LDA(At, 1, 1); PG8_STAGE(PG8_SB(1, 0), b3, voffB); PG8_STAGE(PG8_SB(1, 1), b3 + hstepB, voffB); PG8_STAGE(PG8_SA(1, 0), a3, voffA);
;             PG8_WAIT_V(8); PG8_WAIT_L(0); PG8_BAR; PG8_MMA(1, 0, At, B0); PG8_MMA(1, 1, At, B1); PG8_BAR; PG8_SCHED;
	s_add_i32 s0, s20, s26
	v_lshl_add_u64 v[142:143], v[142:143], 0, s[22:23]
	s_mov_b32 m0, s0
	ds_read_b128 v[180:183], v147 offset:49152
	ds_read_b128 v[184:187], v147 offset:50176
	ds_read_b128 v[188:191], v147 offset:51200
	ds_read_b128 v[192:195], v147 offset:52224
	ds_read_b128 v[196:199], v147 offset:53248
	ds_read_b128 v[208:211], v147 offset:54272
	ds_read_b128 v[212:215], v147 offset:55296
	ds_read_b128 v[216:219], v147 offset:56320
	global_load_lds_dwordx4 v[142:143], off
	s_add_i32 m0, s0, 0x2000
	s_add_u32 s0, s10, 0x30080
	v_lshl_add_u64 v[142:143], v[200:201], 0, s[22:23]
	s_addc_u32 s1, s11, 0
	s_add_i32 s10, s21, s26
	global_load_lds_dwordx4 v[142:143], off
	v_lshl_add_u64 v[142:143], s[0:1], 0, v[134:135]
	s_mov_b32 m0, s10
	s_nop 0
	global_load_lds_dwordx4 v[142:143], off
	v_lshl_add_u64 v[142:143], s[0:1], 0, v[130:131]
	s_add_i32 m0, s10, 0x2000
	s_nop 0
	global_load_lds_dwordx4 v[142:143], off
	v_lshl_add_u64 v[142:143], v[220:221], 0, s[22:23]
	s_mov_b32 m0, s38
	s_nop 0
	global_load_lds_dwordx4 v[142:143], off
	v_lshl_add_u64 v[142:143], v[222:223], 0, s[22:23]
	s_mov_b32 m0, s39
	s_nop 0
	global_load_lds_dwordx4 v[142:143], off
	s_waitcnt vmcnt(8)
	s_waitcnt lgkmcnt(0)
	s_barrier
	s_setprio 1
	s_waitcnt lgkmcnt(0)
	v_mfma_f32_16x16x32_bf16 v[62:65], v[148:151], v[180:183], v[62:65]
	v_mfma_f32_16x16x32_bf16 v[58:61], v[156:159], v[180:183], v[58:61]
	v_mfma_f32_16x16x32_bf16 v[46:49], v[148:151], v[188:191], v[46:49]
	v_mfma_f32_16x16x32_bf16 v[42:45], v[156:159], v[188:191], v[42:45]
	v_mfma_f32_16x16x32_bf16 v[30:33], v[148:151], v[196:199], v[30:33]
	v_mfma_f32_16x16x32_bf16 v[26:29], v[156:159], v[196:199], v[26:29]
	v_mfma_f32_16x16x32_bf16 v[14:17], v[148:151], v[212:215], v[14:17]
	v_mfma_f32_16x16x32_bf16 v[10:13], v[156:159], v[212:215], v[10:13]
	v_mfma_f32_16x16x32_bf16 v[62:65], v[152:155], v[184:187], v[62:65]
	v_mfma_f32_16x16x32_bf16 v[58:61], v[160:163], v[184:187], v[58:61]
	v_mfma_f32_16x16x32_bf16 v[46:49], v[152:155], v[192:195], v[46:49]
	v_mfma_f32_16x16x32_bf16 v[42:45], v[160:163], v[192:195], v[42:45]
	v_mfma_f32_16x16x32_bf16 v[30:33], v[152:155], v[208:211], v[30:33]
	v_mfma_f32_16x16x32_bf16 v[26:29], v[160:163], v[208:211], v[26:29]
	v_mfma_f32_16x16x32_bf16 v[14:17], v[152:155], v[216:219], v[14:17]
	v_mfma_f32_16x16x32_bf16 v[10:13], v[160:163], v[216:219], v[10:13]
	v_mfma_f32_16x16x32_bf16 v[54:57], v[164:167], v[180:183], v[54:57]
	v_mfma_f32_16x16x32_bf16 v[50:53], v[172:175], v[180:183], v[50:53]
	v_mfma_f32_16x16x32_bf16 v[38:41], v[164:167], v[188:191], v[38:41]
	v_mfma_f32_16x16x32_bf16 v[34:37], v[172:175], v[188:191], v[34:37]
	v_mfma_f32_16x16x32_bf16 v[22:25], v[164:167], v[196:199], v[22:25]
	v_mfma_f32_16x16x32_bf16 v[18:21], v[172:175], v[196:199], v[18:21]
	v_mfma_f32_16x16x32_bf16 v[6:9], v[164:167], v[212:215], v[6:9]
	v_mfma_f32_16x16x32_bf16 v[2:5], v[172:175], v[212:215], v[2:5]
	v_mfma_f32_16x16x32_bf16 v[54:57], v[168:171], v[184:187], v[54:57]
	v_mfma_f32_16x16x32_bf16 v[50:53], v[176:179], v[184:187], v[50:53]
	v_mfma_f32_16x16x32_bf16 v[38:41], v[168:171], v[192:195], v[38:41]
	v_mfma_f32_16x16x32_bf16 v[34:37], v[176:179], v[192:195], v[34:37]
	v_mfma_f32_16x16x32_bf16 v[22:25], v[168:171], v[208:211], v[22:25]
	v_mfma_f32_16x16x32_bf16 v[18:21], v[176:179], v[208:211], v[18:21]
	v_mfma_f32_16x16x32_bf16 v[6:9], v[168:171], v[216:219], v[6:9]
	v_mfma_f32_16x16x32_bf16 v[2:5], v[176:179], v[216:219], v[2:5]
	s_setprio 0
	s_barrier
	s_add_i32 s71, s71, 2
	s_add_u32 s63, s63, 0x100
	s_addc_u32 s70, s70, 0
	s_cmp_gt_u32 s71, 9
	s_mov_b64 s[0:1], s[8:9]
	s_cbranch_scc1 .Lpk_done_g959
.LBB0_959:
	s_add_u32 s8, s0, 0x100
	s_addc_u32 s9, s1, 0
	s_add_i32 s20, 0, 0x10000
	s_cmp_eq_u32 s71, 8
	s_cselect_b32 s13, s31, s9
	s_cselect_b32 s12, s30, s8
	v_add_u32_e32 v142, s20, v145
	s_cselect_b32 s11, s19, s70
	s_cselect_b32 s10, s18, s63
	s_add_i32 s21, 0, 0x14000
	ds_read_b128 v[148:151], v142
	ds_read_b128 v[152:155], v142 offset:1024
	ds_read_b128 v[156:159], v142 offset:2048
	ds_read_b128 v[160:163], v142 offset:3072
	v_add_u32_e32 v142, s21, v145
	ds_read_b128 v[164:167], v142
	ds_read_b128 v[168:171], v142 offset:1024
	ds_read_b128 v[172:175], v142 offset:2048
	ds_read_b128 v[176:179], v142 offset:3072
	v_lshl_add_u64 v[142:143], s[0:1], 0, v[138:139]
	s_add_i32 m0, s34, 0xc000
	ds_read_b128 v[180:183], v147
	ds_read_b128 v[184:187], v147 offset:1024
	ds_read_b128 v[188:191], v147 offset:2048
	ds_read_b128 v[192:195], v147 offset:3072
	ds_read_b128 v[196:199], v147 offset:4096
	ds_read_b128 v[208:211], v147 offset:5120
	ds_read_b128 v[212:215], v147 offset:6144
	ds_read_b128 v[216:219], v147 offset:7168
	global_load_lds_dwordx4 v[142:143], off
	v_lshl_add_u64 v[142:143], s[0:1], 0, v[140:141]
	s_add_i32 m0, s34, 0xe000
	s_nop 0
	global_load_lds_dwordx4 v[142:143], off
	s_waitcnt vmcnt(8)
	s_waitcnt lgkmcnt(0)
	s_barrier
; #define PG8_STAGE(bufoff, gbase, voff) do { _Pragma("unroll") for (int _i = 0; _i < 2; ++_i) \
;         __builtin_amdgcn_global_load_lds((const unsigned*)((const char*)(gbase) + (voff)[_i]), (PG8_LAS unsigned*)(lds + (bufoff) + ldsw + _i * 8192), 16, 0, 0); } while (0)
; #define PG8_LDA(dst, b, h) do { _Pragma("unroll") for (int m = 0; m < 4; ++m) _Pragma("unroll") for (int k = 0; k < 2; ++k) dst[m][k] = *(const PG8_LAS bf16x8*)(lds + PG8_SA(b, h) + aoff + m * 2048 + k * 1024); } while (0)
; #define PG8_MMA(ai, bj, At, Bt) do { __builtin_amdgcn_s_setprio(1); _Pragma("unroll") for (int m = 0; m < 4; ++m) _Pragma("unroll") for (int n = 0; n < 2; ++n) _Pragma("unroll") for (int k = 0; k < 2; ++k) \
;         acc[ai][bj][m][n] = __builtin_amdgcn_mfma_f32_16x16x32_bf16(Bt[n][k], At[m][k], acc[ai][bj][m][n], 0, 0, 0); __builtin_amdgcn_s_setprio(0); } while (0)
; #define PG8_WAIT_V(n) asm volatile("s_waitcnt vmcnt(" #n ")" ::: "memory")
; #define PG8_WAIT_L(n) asm volatile("s_waitcnt lgkmcnt(" #n ")" ::: "memory")
; #define PG8_BAR __builtin_amdgcn_s_barrier()
; #define PG8_SCHED __builtin_amdgcn_sched_barrier(0)
; template <class Epi, class Sched, bool ALIGN_EPI = false, bool SP2 = false>
; __device__ __forceinline__ void gemm_phase(PG8_LAS unsigned char* lds, const Gemm g, const Sched& S, const Epi& E) {
;     ...
;             PG8_WAIT_V(8); PG8_WAIT_L(0); PG8_BAR; PG8_MMA(0, 0, At, B0); PG8_MMA(0, 1, At, B1); PG8_BAR; PG8_SCHED;
;             PG8_LDA(At, 0, 1); PG8_STAGE(PG8_SB(0, 0), b2, voffB); PG8_STAGE(PG8_SB(0, 1), b2 + hstepB, voffB); PG8_STAGE(PG8_SA(0, 0), a2, voffA);
;             PG8_WAIT_V(8); PG8_WAIT_L(0); PG8_BAR; PG8_MMA(1, 0, At, B0); PG8_MMA(1, 1, At, B1); PG8_BAR; PG8_SCHED;
	s_setprio 1
	s_waitcnt lgkmcnt(0)
	v_mfma_f32_16x16x32_bf16 v[126:129], v[148:151], v[180:183], v[126:129]
	v_mfma_f32_16x16x32_bf16 v[122:125], v[156:159], v[180:183], v[122:125]
	v_mfma_f32_16x16x32_bf16 v[110:113], v[148:151], v[188:191], v[110:113]
	v_mfma_f32_16x16x32_bf16 v[106:109], v[156:159], v[188:191], v[106:109]
	v_mfma_f32_16x16x32_bf16 v[94:97], v[148:151], v[196:199], v[94:97]
	v_mfma_f32_16x16x32_bf16 v[90:93], v[156:159], v[196:199], v[90:93]
	v_mfma_f32_16x16x32_bf16 v[78:81], v[148:151], v[212:215], v[78:81]
	v_mfma_f32_16x16x32_bf16 v[74:77], v[156:159], v[212:215], v[74:77]
	v_mfma_f32_16x16x32_bf16 v[126:129], v[152:155], v[184:187], v[126:129]
	v_mfma_f32_16x16x32_bf16 v[122:125], v[160:163], v[184:187], v[122:125]
	v_mfma_f32_16x16x32_bf16 v[110:113], v[152:155], v[192:195], v[110:113]
	v_mfma_f32_16x16x32_bf16 v[106:109], v[160:163], v[192:195], v[106:109]
	v_mfma_f32_16x16x32_bf16 v[94:97], v[152:155], v[208:211], v[94:97]
	v_mfma_f32_16x16x32_bf16 v[90:93], v[160:163], v[208:211], v[90:93]
	v_mfma_f32_16x16x32_bf16 v[78:81], v[152:155], v[216:219], v[78:81]
	v_mfma_f32_16x16x32_bf16 v[74:77], v[160:163], v[216:219], v[74:77]
	v_mfma_f32_16x16x32_bf16 v[118:121], v[164:167], v[180:183], v[118:121]
	v_mfma_f32_16x16x32_bf16 v[114:117], v[172:175], v[180:183], v[114:117]
	v_mfma_f32_16x16x32_bf16 v[102:105], v[164:167], v[188:191], v[102:105]
	v_mfma_f32_16x16x32_bf16 v[98:101], v[172:175], v[188:191], v[98:101]
	v_mfma_f32_16x16x32_bf16 v[86:89], v[164:167], v[196:199], v[86:89]
	v_mfma_f32_16x16x32_bf16 v[82:85], v[172:175], v[196:199], v[82:85]
	v_mfma_f32_16x16x32_bf16 v[70:73], v[164:167], v[212:215], v[70:73]
	v_mfma_f32_16x16x32_bf16 v[66:69], v[172:175], v[212:215], v[66:69]
	v_mfma_f32_16x16x32_bf16 v[118:121], v[168:171], v[184:187], v[118:121]
	v_mfma_f32_16x16x32_bf16 v[114:117], v[176:179], v[184:187], v[114:117]
	v_mfma_f32_16x16x32_bf16 v[102:105], v[168:171], v[192:195], v[102:105]
	v_mfma_f32_16x16x32_bf16 v[98:101], v[176:179], v[192:195], v[98:101]
	v_mfma_f32_16x16x32_bf16 v[86:89], v[168:171], v[208:211], v[86:89]
	v_mfma_f32_16x16x32_bf16 v[82:85], v[176:179], v[208:211], v[82:85]
	v_mfma_f32_16x16x32_bf16 v[70:73], v[168:171], v[216:219], v[70:73]
	v_mfma_f32_16x16x32_bf16 v[66:69], v[176:179], v[216:219], v[66:69]
	s_setprio 0
	s_barrier
	s_add_i32 s0, s20, s26
	v_lshl_add_u64 v[142:143], s[10:11], 0, v[134:135]
	s_mov_b32 m0, s0
	ds_read_b128 v[180:183], v147 offset:16384
	ds_read_b128 v[184:187], v147 offset:17408
	ds_read_b128 v[188:191], v147 offset:18432
	ds_read_b128 v[192:195], v147 offset:19456
	ds_read_b128 v[196:199], v147 offset:20480
	ds_read_b128 v[208:211], v147 offset:21504
	ds_read_b128 v[212:215], v147 offset:22528
	ds_read_b128 v[216:219], v147 offset:23552
	global_load_lds_dwordx4 v[142:143], off
	s_add_i32 m0, s0, 0x2000
	s_add_u32 s0, s10, 0x30000
	v_lshl_add_u64 v[200:201], s[10:11], 0, v[130:131]
	s_addc_u32 s1, s11, 0
	s_add_i32 s20, s21, s26
	global_load_lds_dwordx4 v[200:201], off
	v_lshl_add_u64 v[220:221], s[0:1], 0, v[134:135]
	s_mov_b32 m0, s20
	v_lshl_add_u64 v[222:223], s[12:13], 0, v[132:133]
	global_load_lds_dwordx4 v[220:221], off
	v_lshl_add_u64 v[220:221], s[0:1], 0, v[130:131]
	s_add_i32 m0, s20, 0x2000
	s_nop 0
	global_load_lds_dwordx4 v[220:221], off
	v_lshl_add_u64 v[220:221], s[12:13], 0, v[136:137]
	s_mov_b32 m0, s34
	s_nop 0
	global_load_lds_dwordx4 v[220:221], off
	s_mov_b32 m0, s35
	s_nop 0
	global_load_lds_dwordx4 v[222:223], off
	s_waitcnt vmcnt(8)
	s_waitcnt lgkmcnt(0)
	s_barrier
	s_setprio 1
	s_waitcnt lgkmcnt(0)
	v_mfma_f32_16x16x32_bf16 v[62:65], v[148:151], v[180:183], v[62:65]
	v_mfma_f32_16x16x32_bf16 v[58:61], v[156:159], v[180:183], v[58:61]
	v_mfma_f32_16x16x32_bf16 v[46:49], v[148:151], v[188:191], v[46:49]
	v_mfma_f32_16x16x32_bf16 v[42:45], v[156:159], v[188:191], v[42:45]
	v_mfma_f32_16x16x32_bf16 v[30:33], v[148:151], v[196:199], v[30:33]
	v_mfma_f32_16x16x32_bf16 v[26:29], v[156:159], v[196:199], v[26:29]
	v_mfma_f32_16x16x32_bf16 v[14:17], v[148:151], v[212:215], v[14:17]
	v_mfma_f32_16x16x32_bf16 v[10:13], v[156:159], v[212:215], v[10:13]
	v_mfma_f32_16x16x32_bf16 v[62:65], v[152:155], v[184:187], v[62:65]
	v_mfma_f32_16x16x32_bf16 v[58:61], v[160:163], v[184:187], v[58:61]
	v_mfma_f32_16x16x32_bf16 v[46:49], v[152:155], v[192:195], v[46:49]
	v_mfma_f32_16x16x32_bf16 v[42:45], v[160:163], v[192:195], v[42:45]
	v_mfma_f32_16x16x32_bf16 v[30:33], v[152:155], v[208:211], v[30:33]
	v_mfma_f32_16x16x32_bf16 v[26:29], v[160:163], v[208:211], v[26:29]
	v_mfma_f32_16x16x32_bf16 v[14:17], v[152:155], v[216:219], v[14:17]
	v_mfma_f32_16x16x32_bf16 v[10:13], v[160:163], v[216:219], v[10:13]
	v_mfma_f32_16x16x32_bf16 v[54:57], v[164:167], v[180:183], v[54:57]
	v_mfma_f32_16x16x32_bf16 v[50:53], v[172:175], v[180:183], v[50:53]
	v_mfma_f32_16x16x32_bf16 v[38:41], v[164:167], v[188:191], v[38:41]
	v_mfma_f32_16x16x32_bf16 v[34:37], v[172:175], v[188:191], v[34:37]
	v_mfma_f32_16x16x32_bf16 v[22:25], v[164:167], v[196:199], v[22:25]
	v_mfma_f32_16x16x32_bf16 v[18:21], v[172:175], v[196:199], v[18:21]
	v_mfma_f32_16x16x32_bf16 v[6:9], v[164:167], v[212:215], v[6:9]
	v_mfma_f32_16x16x32_bf16 v[2:5], v[172:175], v[212:215], v[2:5]
	v_mfma_f32_16x16x32_bf16 v[54:57], v[168:171], v[184:187], v[54:57]
	v_mfma_f32_16x16x32_bf16 v[50:53], v[176:179], v[184:187], v[50:53]
	v_mfma_f32_16x16x32_bf16 v[38:41], v[168:171], v[192:195], v[38:41]
	v_mfma_f32_16x16x32_bf16 v[34:37], v[176:179], v[192:195], v[34:37]
	v_mfma_f32_16x16x32_bf16 v[22:25], v[168:171], v[208:211], v[22:25]
	v_mfma_f32_16x16x32_bf16 v[18:21], v[176:179], v[208:211], v[18:21]
	v_mfma_f32_16x16x32_bf16 v[6:9], v[168:171], v[216:219], v[6:9]
	v_mfma_f32_16x16x32_bf16 v[2:5], v[176:179], v[216:219], v[2:5]
	s_setprio 0
	s_barrier
; #define PG8_STAGE(bufoff, gbase, voff) do { _Pragma("unroll") for (int _i = 0; _i < 2; ++_i) \
;         __builtin_amdgcn_global_load_lds((const unsigned*)((const char*)(gbase) + (voff)[_i]), (PG8_LAS unsigned*)(lds + (bufoff) + ldsw + _i * 8192), 16, 0, 0); } while (0)
; #define PG8_LDA(dst, b, h) do { _Pragma("unroll") for (int m = 0; m < 4; ++m) _Pragma("unroll") for (int k = 0; k < 2; ++k) dst[m][k] = *(const PG8_LAS bf16x8*)(lds + PG8_SA(b, h) + aoff + m * 2048 + k * 1024); } while (0)
; #define PG8_LDB(dst, b, h) do { _Pragma("unroll") for (int n = 0; n < 2; ++n) _Pragma("unroll") for (int k = 0; k < 2; ++k) dst[n][k] = *(const PG8_LAS bf16x8*)(lds + PG8_SB(b, h) + boff + n * 2048 + k * 1024); } while (0)
; #define PG8_MMA(ai, bj, At, Bt) do { __builtin_amdgcn_s_setprio(1); _Pragma("unroll") for (int m = 0; m < 4; ++m) _Pragma("unroll") for (int n = 0; n < 2; ++n) _Pragma("unroll") for (int k = 0; k < 2; ++k) \
;         acc[ai][bj][m][n] = __builtin_amdgcn_mfma_f32_16x16x32_bf16(Bt[n][k], At[m][k], acc[ai][bj][m][n], 0, 0, 0); __builtin_amdgcn_s_setprio(0); } while (0)
; #define PG8_WAIT_V(n) asm volatile("s_waitcnt vmcnt(" #n ")" ::: "memory")
; #define PG8_WAIT_L(n) asm volatile("s_waitcnt lgkmcnt(" #n ")" ::: "memory")
; #define PG8_BAR __builtin_amdgcn_s_barrier()
; #define PG8_SCHED __builtin_amdgcn_sched_barrier(0)
; template <class Epi, class Sched, bool ALIGN_EPI = false, bool SP2 = false>
; __device__ __forceinline__ void gemm_phase(PG8_LAS unsigned char* lds, const Gemm g, const Sched& S, const Epi& E) {
;     ...
;             PG8_LDB(B0, 1, 0); PG8_LDB(B1, 1, 1); PG8_SCHED; PG8_LDA(At, 1, 0); PG8_STAGE(PG8_SA(0, 1), a2 + hstepA, voffA);
;             PG8_WAIT_V(8); PG8_WAIT_L(0); PG8_BAR; PG8_MMA(0, 0, At, B0); PG8_MMA(0, 1, At, B1); PG8_BAR; PG8_SCHED;
	s_add_i32 s20, 0, 0x18000
	s_add_i32 s21, 0, 0x1c000
	v_add_u32_e32 v160, s20, v145
	v_add_u32_e32 v176, s21, v145
	ds_read_b128 v[148:151], v160
	ds_read_b128 v[152:155], v160 offset:1024
	ds_read_b128 v[156:159], v160 offset:2048
	ds_read_b128 v[160:163], v160 offset:3072
	ds_read_b128 v[164:167], v176
	ds_read_b128 v[168:171], v176 offset:1024
	ds_read_b128 v[172:175], v176 offset:2048
	ds_read_b128 v[176:179], v176 offset:3072
	s_add_u32 s0, s12, 0x30000
	s_addc_u32 s1, s13, 0
	s_mov_b32 m0, s36
	v_lshl_add_u64 v[224:225], s[0:1], 0, v[136:137]
	ds_read_b128 v[180:183], v147 offset:32768
	ds_read_b128 v[184:187], v147 offset:33792
	ds_read_b128 v[188:191], v147 offset:34816
	ds_read_b128 v[192:195], v147 offset:35840
	ds_read_b128 v[196:199], v147 offset:36864
	ds_read_b128 v[208:211], v147 offset:37888
	ds_read_b128 v[212:215], v147 offset:38912
	ds_read_b128 v[216:219], v147 offset:39936
	global_load_lds_dwordx4 v[224:225], off
	v_lshl_add_u64 v[224:225], s[0:1], 0, v[132:133]
	s_mov_b32 m0, s37
	s_nop 0
	global_load_lds_dwordx4 v[224:225], off
	s_waitcnt vmcnt(8)
	s_waitcnt lgkmcnt(0)
	s_barrier
	s_setprio 1
	s_waitcnt lgkmcnt(0)
	v_mfma_f32_16x16x32_bf16 v[126:129], v[148:151], v[180:183], v[126:129]
	v_mfma_f32_16x16x32_bf16 v[122:125], v[156:159], v[180:183], v[122:125]
	v_mfma_f32_16x16x32_bf16 v[110:113], v[148:151], v[188:191], v[110:113]
	v_mfma_f32_16x16x32_bf16 v[106:109], v[156:159], v[188:191], v[106:109]
	v_mfma_f32_16x16x32_bf16 v[94:97], v[148:151], v[196:199], v[94:97]
	v_mfma_f32_16x16x32_bf16 v[90:93], v[156:159], v[196:199], v[90:93]
	v_mfma_f32_16x16x32_bf16 v[78:81], v[148:151], v[212:215], v[78:81]
	v_mfma_f32_16x16x32_bf16 v[74:77], v[156:159], v[212:215], v[74:77]
	v_mfma_f32_16x16x32_bf16 v[126:129], v[152:155], v[184:187], v[126:129]
	v_mfma_f32_16x16x32_bf16 v[122:125], v[160:163], v[184:187], v[122:125]
	v_mfma_f32_16x16x32_bf16 v[110:113], v[152:155], v[192:195], v[110:113]
	v_mfma_f32_16x16x32_bf16 v[106:109], v[160:163], v[192:195], v[106:109]
	v_mfma_f32_16x16x32_bf16 v[94:97], v[152:155], v[208:211], v[94:97]
	v_mfma_f32_16x16x32_bf16 v[90:93], v[160:163], v[208:211], v[90:93]
	v_mfma_f32_16x16x32_bf16 v[78:81], v[152:155], v[216:219], v[78:81]
	v_mfma_f32_16x16x32_bf16 v[74:77], v[160:163], v[216:219], v[74:77]
	v_mfma_f32_16x16x32_bf16 v[118:121], v[164:167], v[180:183], v[118:121]
	v_mfma_f32_16x16x32_bf16 v[114:117], v[172:175], v[180:183], v[114:117]
	v_mfma_f32_16x16x32_bf16 v[102:105], v[164:167], v[188:191], v[102:105]
	v_mfma_f32_16x16x32_bf16 v[98:101], v[172:175], v[188:191], v[98:101]
	v_mfma_f32_16x16x32_bf16 v[86:89], v[164:167], v[196:199], v[86:89]
	v_mfma_f32_16x16x32_bf16 v[82:85], v[172:175], v[196:199], v[82:85]
	v_mfma_f32_16x16x32_bf16 v[70:73], v[164:167], v[212:215], v[70:73]
	v_mfma_f32_16x16x32_bf16 v[66:69], v[172:175], v[212:215], v[66:69]
	v_mfma_f32_16x16x32_bf16 v[118:121], v[168:171], v[184:187], v[118:121]
	v_mfma_f32_16x16x32_bf16 v[114:117], v[176:179], v[184:187], v[114:117]
	v_mfma_f32_16x16x32_bf16 v[102:105], v[168:171], v[192:195], v[102:105]
	v_mfma_f32_16x16x32_bf16 v[98:101], v[176:179], v[192:195], v[98:101]
	v_mfma_f32_16x16x32_bf16 v[86:89], v[168:171], v[208:211], v[86:89]
	v_mfma_f32_16x16x32_bf16 v[82:85], v[176:179], v[208:211], v[82:85]
	v_mfma_f32_16x16x32_bf16 v[70:73], v[168:171], v[216:219], v[70:73]
	v_mfma_f32_16x16x32_bf16 v[66:69], v[176:179], v[216:219], v[66:69]
	s_setprio 0
	s_barrier
; #define PG8_STAGE(bufoff, gbase, voff) do { _Pragma("unroll") for (int _i = 0; _i < 2; ++_i) \
;         __builtin_amdgcn_global_load_lds((const unsigned*)((const char*)(gbase) + (voff)[_i]), (PG8_LAS unsigned*)(lds + (bufoff) + ldsw + _i * 8192), 16, 0, 0); } while (0)
; #define PG8_LDA(dst, b, h) do { _Pragma("unroll") for (int m = 0; m < 4; ++m) _Pragma("unroll") for (int k = 0; k < 2; ++k) dst[m][k] = *(const PG8_LAS bf16x8*)(lds + PG8_SA(b, h) + aoff + m * 2048 + k * 1024); } while (0)
; #define PG8_MMA(ai, bj, At, Bt) do { __builtin_amdgcn_s_setprio(1); _Pragma("unroll") for (int m = 0; m < 4; ++m) _Pragma("unroll") for (int n = 0; n < 2; ++n) _Pragma("unroll") for (int k = 0; k < 2; ++k) \
;         acc[ai][bj][m][n] = __builtin_amdgcn_mfma_f32_16x16x32_bf16(Bt[n][k], At[m][k], acc[ai][bj][m][n], 0, 0, 0); __builtin_amdgcn_s_setprio(0); } while (0)
; #define PG8_WAIT_V(n) asm volatile("s_waitcnt vmcnt(" #n ")" ::: "memory")
; #define PG8_WAIT_L(n) asm volatile("s_waitcnt lgkmcnt(" #n ")" ::: "memory")
; #define PG8_BAR __builtin_amdgcn_s_barrier()
; #define PG8_SCHED __builtin_amdgcn_sched_barrier(0)
; template <class Epi, class Sched, bool ALIGN_EPI = false, bool SP2 = false>
; __device__ __forceinline__ void gemm_phase(PG8_LAS unsigned char* lds, const Gemm g, const Sched& S, const Epi& E) {
;     ...
;         for (int t = 0; t < nt; t += 2) {
;             const bool last = (t == nt - 2);
;             const char* a1 = cA + (size_t)(t + 1) * kstep;
;             const char* a2 = last ? nA : cA + (size_t)(t + 2) * kstep; const char* b2 = last ? nB : cB + (size_t)(t + 2) * kstep;
;             const char* a3 = a2 + kstep; const char* b3 = b2 + kstep;
;     ...
;             PG8_LDA(At, 1, 1); PG8_STAGE(PG8_SB(1, 0), b3, voffB); PG8_STAGE(PG8_SB(1, 1), b3 + hstepB, voffB); PG8_STAGE(PG8_SA(1, 0), a3, voffA);
;             PG8_WAIT_V(8); PG8_WAIT_L(0); PG8_BAR; PG8_MMA(1, 0, At, B0); PG8_MMA(1, 1, At, B1); PG8_BAR; PG8_SCHED;
	s_add_i32 s0, s20, s26
	v_lshl_add_u64 v[142:143], v[142:143], 0, s[22:23]
	s_mov_b32 m0, s0
	ds_read_b128 v[180:183], v147 offset:49152
	ds_read_b128 v[184:187], v147 offset:50176
	ds_read_b128 v[188:191], v147 offset:51200
	ds_read_b128 v[192:195], v147 offset:52224
	ds_read_b128 v[196:199], v147 offset:53248
	ds_read_b128 v[208:211], v147 offset:54272
	ds_read_b128 v[212:215], v147 offset:55296
	ds_read_b128 v[216:219], v147 offset:56320
	global_load_lds_dwordx4 v[142:143], off
	s_add_i32 m0, s0, 0x2000
	s_add_u32 s0, s10, 0x30080
	v_lshl_add_u64 v[142:143], v[200:201], 0, s[22:23]
	s_addc_u32 s1, s11, 0
	s_add_i32 s10, s21, s26
	global_load_lds_dwordx4 v[142:143], off
	v_lshl_add_u64 v[142:143], s[0:1], 0, v[134:135]
	s_mov_b32 m0, s10
	s_nop 0
	global_load_lds_dwordx4 v[142:143], off
	v_lshl_add_u64 v[142:143], s[0:1], 0, v[130:131]
	s_add_i32 m0, s10, 0x2000
	s_nop 0
	global_load_lds_dwordx4 v[142:143], off
	v_lshl_add_u64 v[142:143], v[220:221], 0, s[22:23]
	s_mov_b32 m0, s38
	s_nop 0
	global_load_lds_dwordx4 v[142:143], off
	v_lshl_add_u64 v[142:143], v[222:223], 0, s[22:23]
	s_mov_b32 m0, s39
	s_nop 0
	global_load_lds_dwordx4 v[142:143], off
	s_waitcnt vmcnt(8)
	s_waitcnt lgkmcnt(0)
	s_barrier
	s_setprio 1
	s_waitcnt lgkmcnt(0)
	v_mfma_f32_16x16x32_bf16 v[62:65], v[148:151], v[180:183], v[62:65]
	v_mfma_f32_16x16x32_bf16 v[58:61], v[156:159], v[180:183], v[58:61]
	v_mfma_f32_16x16x32_bf16 v[46:49], v[148:151], v[188:191], v[46:49]
	v_mfma_f32_16x16x32_bf16 v[42:45], v[156:159], v[188:191], v[42:45]
	v_mfma_f32_16x16x32_bf16 v[30:33], v[148:151], v[196:199], v[30:33]
	v_mfma_f32_16x16x32_bf16 v[26:29], v[156:159], v[196:199], v[26:29]
	v_mfma_f32_16x16x32_bf16 v[14:17], v[148:151], v[212:215], v[14:17]
	v_mfma_f32_16x16x32_bf16 v[10:13], v[156:159], v[212:215], v[10:13]
	v_mfma_f32_16x16x32_bf16 v[62:65], v[152:155], v[184:187], v[62:65]
	v_mfma_f32_16x16x32_bf16 v[58:61], v[160:163], v[184:187], v[58:61]
	v_mfma_f32_16x16x32_bf16 v[46:49], v[152:155], v[192:195], v[46:49]
	v_mfma_f32_16x16x32_bf16 v[42:45], v[160:163], v[192:195], v[42:45]
	v_mfma_f32_16x16x32_bf16 v[30:33], v[152:155], v[208:211], v[30:33]
	v_mfma_f32_16x16x32_bf16 v[26:29], v[160:163], v[208:211], v[26:29]
	v_mfma_f32_16x16x32_bf16 v[14:17], v[152:155], v[216:219], v[14:17]
	v_mfma_f32_16x16x32_bf16 v[10:13], v[160:163], v[216:219], v[10:13]
	v_mfma_f32_16x16x32_bf16 v[54:57], v[164:167], v[180:183], v[54:57]
	v_mfma_f32_16x16x32_bf16 v[50:53], v[172:175], v[180:183], v[50:53]
	v_mfma_f32_16x16x32_bf16 v[38:41], v[164:167], v[188:191], v[38:41]
	v_mfma_f32_16x16x32_bf16 v[34:37], v[172:175], v[188:191], v[34:37]
	v_mfma_f32_16x16x32_bf16 v[22:25], v[164:167], v[196:199], v[22:25]
	v_mfma_f32_16x16x32_bf16 v[18:21], v[172:175], v[196:199], v[18:21]
	v_mfma_f32_16x16x32_bf16 v[6:9], v[164:167], v[212:215], v[6:9]
	v_mfma_f32_16x16x32_bf16 v[2:5], v[172:175], v[212:215], v[2:5]
	v_mfma_f32_16x16x32_bf16 v[54:57], v[168:171], v[184:187], v[54:57]
	v_mfma_f32_16x16x32_bf16 v[50:53], v[176:179], v[184:187], v[50:53]
	v_mfma_f32_16x16x32_bf16 v[38:41], v[168:171], v[192:195], v[38:41]
	v_mfma_f32_16x16x32_bf16 v[34:37], v[176:179], v[192:195], v[34:37]
	v_mfma_f32_16x16x32_bf16 v[22:25], v[168:171], v[208:211], v[22:25]
	v_mfma_f32_16x16x32_bf16 v[18:21], v[176:179], v[208:211], v[18:21]
	v_mfma_f32_16x16x32_bf16 v[6:9], v[168:171], v[216:219], v[6:9]
	v_mfma_f32_16x16x32_bf16 v[2:5], v[176:179], v[216:219], v[2:5]
	s_setprio 0
	s_barrier
	s_add_i32 s71, s71, 2
	s_add_u32 s63, s63, 0x100
	s_addc_u32 s70, s70, 0
	s_cmp_gt_u32 s71, 9
	s_mov_b64 s[0:1], s[8:9]
	s_cbranch_scc0 .LBB0_959

; #define PG8_STAGE(bufoff, gbase, voff) do { _Pragma("unroll") for (int _i = 0; _i < 2; ++_i) \
;         __builtin_amdgcn_global_load_lds((const unsigned*)((const char*)(gbase) + (voff)[_i]), (PG8_LAS unsigned*)(lds + (bufoff) + ldsw + _i * 8192), 16, 0, 0); } while (0)
; #define PG8_LDA(dst, b, h) do { _Pragma("unroll") for (int m = 0; m < 4; ++m) _Pragma("unroll") for (int k = 0; k < 2; ++k) dst[m][k] = *(const PG8_LAS bf16x8*)(lds + PG8_SA(b, h) + aoff + m * 2048 + k * 1024); } while (0)
; #define PG8_LDB(dst, b, h) do { _Pragma("unroll") for (int n = 0; n < 2; ++n) _Pragma("unroll") for (int k = 0; k < 2; ++k) dst[n][k] = *(const PG8_LAS bf16x8*)(lds + PG8_SB(b, h) + boff + n * 2048 + k * 1024); } while (0)
; #define PG8_WAIT_V(n) asm volatile("s_waitcnt vmcnt(" #n ")" ::: "memory")
; #define PG8_WAIT_L(n) asm volatile("s_waitcnt lgkmcnt(" #n ")" ::: "memory")
; #define PG8_BAR __builtin_amdgcn_s_barrier()
; template <class Epi, class Sched, bool ALIGN_EPI = false, bool SP2 = false>
; __device__ __forceinline__ void gemm_phase(PG8_LAS unsigned char* lds, const Gemm g, const Sched& S, const Epi& E) {
;     ...
;         const bool has_next = S.next(ui + 1, nxt);
;         const char* nA = has_next ? (const char*)g.A + (size_t)nxt.pm * tstepA + (size_t)nxt.pb * g.sA : cA; const char* nB = has_next ? (const char*)g.Bt + (size_t)nxt.pn * tstepB + (size_t)nxt.pb * g.sB : cB;
;         for (int t = 0; t < nt; t += 2) {
;             const bool last = (t == nt - 2);
;             const char* a1 = cA + (size_t)(t + 1) * kstep;
;             const char* a2 = last ? nA : cA + (size_t)(t + 2) * kstep; const char* b2 = last ? nB : cB + (size_t)(t + 2) * kstep;
;             const char* a3 = a2 + kstep; const char* b3 = b2 + kstep;
;             if (last && has_next) S.a_ready(nxt);
;             if constexpr (SP2) {
;             PG8_LDB(B0, 0, 0); PG8_LDB(B1, 0, 1); PG8_SCHED; PG8_LDA(At, 0, 0); PG8_STAGE(PG8_SA(1, 1), a1 + hstepA, voffA);
;             PG8_WAIT_V(8); PG8_WAIT_L(0); PG8_BAR; PG8_MMA(0, 0, At, B0); PG8_MMA(0, 1, At, B1); PG8_BAR; PG8_SCHED;
;             PG8_LDA(At, 0, 1); PG8_STAGE(PG8_SB(0, 0), b2, voffB); PG8_STAGE(PG8_SB(0, 1), b2 + hstepB, voffB); PG8_STAGE(PG8_SA(0, 0), a2, voffA);
;             PG8_WAIT_V(8); PG8_WAIT_L(0); PG8_BAR; PG8_MMA(1, 0, At, B0); PG8_MMA(1, 1, At, B1); PG8_BAR; PG8_SCHED;
.LBB0_1047:
	s_ashr_i32 s31, s30, 31
	s_lshl_b64 s[34:35], s[30:31], 18
	s_add_u32 s34, s12, s34
	s_addc_u32 s35, s13, s35
	s_and_b64 s[36:37], s[42:43], exec
	s_cselect_b32 s31, s35, s9
	s_cselect_b32 s61, s34, s8
	s_ashr_i32 s29, s28, 31
	s_lshl_b64 s[36:37], s[28:29], 18
	s_add_u32 s38, s26, s36
	s_addc_u32 s39, s46, s37
	s_and_b64 s[36:37], s[42:43], exec
	s_cselect_b32 s29, s39, s15
	s_cselect_b32 s62, s38, s14
	s_add_u32 s8, s8, 0x20080
	s_addc_u32 s9, s9, 0
	s_add_u32 s63, s14, 0x100
	s_addc_u32 s70, s15, 0
	s_mov_b32 s71, -2
	s_add_u32 s14, s8, 0xfffe0080
	s_addc_u32 s15, s9, -1
	s_add_i32 s20, 0, 0x10000
	s_cmp_eq_u32 s71, 4
	s_cselect_b32 s37, s31, s15
	s_cselect_b32 s36, s61, s14
	s_cselect_b32 s15, s29, s70
	s_cselect_b32 s14, s62, s63
	s_add_i32 s21, 0, 0x14000
	v_add_u32_e32 v102, s20, v239
	v_add_u32_e32 v142, s21, v239
	ds_read_b128 v[82:85], v102
	ds_read_b128 v[86:89], v102 offset:1024
	ds_read_b128 v[94:97], v102 offset:2048
	ds_read_b128 v[102:105], v102 offset:3072
	ds_read_b128 v[114:117], v142
	ds_read_b128 v[122:125], v142 offset:1024
	ds_read_b128 v[134:137], v142 offset:2048
	ds_read_b128 v[142:145], v142 offset:3072
	v_lshl_add_u64 v[194:195], s[8:9], 0, v[214:215]
	s_add_i32 m0, s52, 0xc000
	ds_read_b128 v[154:157], v241
	ds_read_b128 v[166:169], v241 offset:1024
	ds_read_b128 v[170:173], v241 offset:2048
	ds_read_b128 v[174:177], v241 offset:3072
	ds_read_b128 v[178:181], v241 offset:4096
	ds_read_b128 v[182:185], v241 offset:5120
	ds_read_b128 v[186:189], v241 offset:6144
	ds_read_b128 v[190:193], v241 offset:7168
	global_load_lds_dwordx4 v[194:195], off
	v_lshl_add_u64 v[194:195], s[8:9], 0, v[216:217]
	s_add_i32 m0, s52, 0xe000
	s_nop 0
	global_load_lds_dwordx4 v[194:195], off
	s_waitcnt vmcnt(8)
	s_waitcnt lgkmcnt(0)
	s_barrier
	s_setprio 1
	s_waitcnt lgkmcnt(0)
	v_mfma_f32_16x16x32_bf16 v[162:165], v[82:85], v[154:157], 0
	v_mfma_f32_16x16x32_bf16 v[158:161], v[94:97], v[154:157], 0
	v_mfma_f32_16x16x32_bf16 v[150:153], v[82:85], v[170:173], 0
	v_mfma_f32_16x16x32_bf16 v[146:149], v[94:97], v[170:173], 0
	v_mfma_f32_16x16x32_bf16 v[138:141], v[82:85], v[178:181], 0
	v_mfma_f32_16x16x32_bf16 v[130:133], v[94:97], v[178:181], 0
	v_mfma_f32_16x16x32_bf16 v[126:129], v[82:85], v[186:189], 0
	v_mfma_f32_16x16x32_bf16 v[118:121], v[94:97], v[186:189], 0
	v_mfma_f32_16x16x32_bf16 v[162:165], v[86:89], v[166:169], v[162:165]
	v_mfma_f32_16x16x32_bf16 v[158:161], v[102:105], v[166:169], v[158:161]
	v_mfma_f32_16x16x32_bf16 v[150:153], v[86:89], v[174:177], v[150:153]
	v_mfma_f32_16x16x32_bf16 v[146:149], v[102:105], v[174:177], v[146:149]
	v_mfma_f32_16x16x32_bf16 v[138:141], v[86:89], v[182:185], v[138:141]
	v_mfma_f32_16x16x32_bf16 v[130:133], v[102:105], v[182:185], v[130:133]
	v_mfma_f32_16x16x32_bf16 v[126:129], v[86:89], v[190:193], v[126:129]
	v_mfma_f32_16x16x32_bf16 v[118:121], v[102:105], v[190:193], v[118:121]
	v_mfma_f32_16x16x32_bf16 v[62:65], v[114:117], v[154:157], 0
	v_mfma_f32_16x16x32_bf16 v[58:61], v[134:137], v[154:157], 0
	v_mfma_f32_16x16x32_bf16 v[54:57], v[114:117], v[170:173], 0
	v_mfma_f32_16x16x32_bf16 v[50:53], v[134:137], v[170:173], 0
	v_mfma_f32_16x16x32_bf16 v[46:49], v[114:117], v[178:181], 0
	v_mfma_f32_16x16x32_bf16 v[42:45], v[134:137], v[178:181], 0
	v_mfma_f32_16x16x32_bf16 v[38:41], v[114:117], v[186:189], 0
	v_mfma_f32_16x16x32_bf16 v[34:37], v[134:137], v[186:189], 0
	v_mfma_f32_16x16x32_bf16 v[62:65], v[122:125], v[166:169], v[62:65]
	v_mfma_f32_16x16x32_bf16 v[58:61], v[142:145], v[166:169], v[58:61]
	v_mfma_f32_16x16x32_bf16 v[54:57], v[122:125], v[174:177], v[54:57]
	v_mfma_f32_16x16x32_bf16 v[50:53], v[142:145], v[174:177], v[50:53]
	v_mfma_f32_16x16x32_bf16 v[46:49], v[122:125], v[182:185], v[46:49]
	v_mfma_f32_16x16x32_bf16 v[42:45], v[142:145], v[182:185], v[42:45]
	v_mfma_f32_16x16x32_bf16 v[38:41], v[122:125], v[190:193], v[38:41]
	v_mfma_f32_16x16x32_bf16 v[34:37], v[142:145], v[190:193], v[34:37]
	s_setprio 0
	s_barrier
	s_add_i32 s20, s20, s47
	v_lshl_add_u64 v[194:195], s[14:15], 0, v[0:1]
	s_mov_b32 m0, s20
	ds_read_b128 v[154:157], v241 offset:16384
	ds_read_b128 v[166:169], v241 offset:17408
	ds_read_b128 v[170:173], v241 offset:18432
	ds_read_b128 v[174:177], v241 offset:19456
	ds_read_b128 v[178:181], v241 offset:20480
	ds_read_b128 v[182:185], v241 offset:21504
	ds_read_b128 v[186:189], v241 offset:22528
	ds_read_b128 v[190:193], v241 offset:23552
	global_load_lds_dwordx4 v[194:195], off
	s_add_i32 m0, s20, 0x2000
	s_add_u32 s78, s14, 0x20000
	v_lshl_add_u64 v[196:197], s[14:15], 0, v[208:209]
	s_addc_u32 s79, s15, 0
	s_add_i32 s20, s21, s47
	global_load_lds_dwordx4 v[196:197], off
	v_lshl_add_u64 v[198:199], s[78:79], 0, v[0:1]
	s_mov_b32 m0, s20
	v_lshl_add_u64 v[200:201], s[36:37], 0, v[210:211]
	global_load_lds_dwordx4 v[198:199], off
	v_lshl_add_u64 v[198:199], s[78:79], 0, v[208:209]
	s_add_i32 m0, s20, 0x2000
	s_nop 0
	global_load_lds_dwordx4 v[198:199], off
	v_lshl_add_u64 v[198:199], s[36:37], 0, v[212:213]
	s_mov_b32 m0, s52
	s_nop 0
	global_load_lds_dwordx4 v[198:199], off
	s_mov_b32 m0, s53
	s_nop 0
	global_load_lds_dwordx4 v[200:201], off
	s_waitcnt vmcnt(8)
	s_waitcnt lgkmcnt(0)
	s_barrier
; #define PG8_STAGE(bufoff, gbase, voff) do { _Pragma("unroll") for (int _i = 0; _i < 2; ++_i) \
;         __builtin_amdgcn_global_load_lds((const unsigned*)((const char*)(gbase) + (voff)[_i]), (PG8_LAS unsigned*)(lds + (bufoff) + ldsw + _i * 8192), 16, 0, 0); } while (0)
; #define PG8_LDA(dst, b, h) do { _Pragma("unroll") for (int m = 0; m < 4; ++m) _Pragma("unroll") for (int k = 0; k < 2; ++k) dst[m][k] = *(const PG8_LAS bf16x8*)(lds + PG8_SA(b, h) + aoff + m * 2048 + k * 1024); } while (0)
; #define PG8_LDB(dst, b, h) do { _Pragma("unroll") for (int n = 0; n < 2; ++n) _Pragma("unroll") for (int k = 0; k < 2; ++k) dst[n][k] = *(const PG8_LAS bf16x8*)(lds + PG8_SB(b, h) + boff + n * 2048 + k * 1024); } while (0)
; #define PG8_MMA(ai, bj, At, Bt) do { __builtin_amdgcn_s_setprio(1); _Pragma("unroll") for (int m = 0; m < 4; ++m) _Pragma("unroll") for (int n = 0; n < 2; ++n) _Pragma("unroll") for (int k = 0; k < 2; ++k) \
;         acc[ai][bj][m][n] = __builtin_amdgcn_mfma_f32_16x16x32_bf16(Bt[n][k], At[m][k], acc[ai][bj][m][n], 0, 0, 0); __builtin_amdgcn_s_setprio(0); } while (0)
; #define PG8_WAIT_V(n) asm volatile("s_waitcnt vmcnt(" #n ")" ::: "memory")
; template <class Epi, class Sched, bool ALIGN_EPI = false, bool SP2 = false>
; __device__ __forceinline__ void gemm_phase(PG8_LAS unsigned char* lds, const Gemm g, const Sched& S, const Epi& E) {
;     ...
;             PG8_LDB(B0, 0, 0); PG8_LDB(B1, 0, 1); PG8_SCHED; PG8_LDA(At, 0, 0); PG8_STAGE(PG8_SA(1, 1), a1 + hstepA, voffA);
;             PG8_WAIT_V(8); PG8_WAIT_L(0); PG8_BAR; PG8_MMA(0, 0, At, B0); PG8_MMA(0, 1, At, B1); PG8_BAR; PG8_SCHED;
;             PG8_LDA(At, 0, 1); PG8_STAGE(PG8_SB(0, 0), b2, voffB); PG8_STAGE(PG8_SB(0, 1), b2 + hstepB, voffB); PG8_STAGE(PG8_SA(0, 0), a2, voffA);
;             PG8_WAIT_V(8); PG8_WAIT_L(0); PG8_BAR; PG8_MMA(1, 0, At, B0); PG8_MMA(1, 1, At, B1); PG8_BAR; PG8_SCHED;
;             PG8_LDB(B0, 1, 0); PG8_LDB(B1, 1, 1); PG8_SCHED; PG8_LDA(At, 1, 0); PG8_STAGE(PG8_SA(0, 1), a2 + hstepA, voffA);
;             PG8_WAIT_V(8); PG8_WAIT_L(0); PG8_BAR; PG8_MMA(0, 0, At, B0); PG8_MMA(0, 1, At, B1); PG8_BAR; PG8_SCHED;
;             PG8_LDA(At, 1, 1); PG8_STAGE(PG8_SB(1, 0), b3, voffB); PG8_STAGE(PG8_SB(1, 1), b3 + hstepB, voffB); PG8_STAGE(PG8_SA(1, 0), a3, voffA);
;             PG8_WAIT_V(8); PG8_WAIT_L(0); PG8_BAR; PG8_MMA(1, 0, At, B0); PG8_MMA(1, 1, At, B1); PG8_BAR; PG8_SCHED;
	s_setprio 1
	s_waitcnt lgkmcnt(0)
	v_mfma_f32_16x16x32_bf16 v[110:113], v[82:85], v[154:157], 0
	v_mfma_f32_16x16x32_bf16 v[106:109], v[94:97], v[154:157], 0
	v_mfma_f32_16x16x32_bf16 v[98:101], v[82:85], v[170:173], 0
	v_mfma_f32_16x16x32_bf16 v[90:93], v[94:97], v[170:173], 0
	v_mfma_f32_16x16x32_bf16 v[78:81], v[82:85], v[178:181], 0
	v_mfma_f32_16x16x32_bf16 v[74:77], v[94:97], v[178:181], 0
	v_mfma_f32_16x16x32_bf16 v[70:73], v[82:85], v[186:189], 0
	v_mfma_f32_16x16x32_bf16 v[66:69], v[94:97], v[186:189], 0
	v_mfma_f32_16x16x32_bf16 v[110:113], v[86:89], v[166:169], v[110:113]
	v_mfma_f32_16x16x32_bf16 v[106:109], v[102:105], v[166:169], v[106:109]
	v_mfma_f32_16x16x32_bf16 v[98:101], v[86:89], v[174:177], v[98:101]
	v_mfma_f32_16x16x32_bf16 v[90:93], v[102:105], v[174:177], v[90:93]
	v_mfma_f32_16x16x32_bf16 v[78:81], v[86:89], v[182:185], v[78:81]
	v_mfma_f32_16x16x32_bf16 v[74:77], v[102:105], v[182:185], v[74:77]
	v_mfma_f32_16x16x32_bf16 v[70:73], v[86:89], v[190:193], v[70:73]
	v_mfma_f32_16x16x32_bf16 v[66:69], v[102:105], v[190:193], v[66:69]
	v_mfma_f32_16x16x32_bf16 v[30:33], v[114:117], v[154:157], 0
	v_mfma_f32_16x16x32_bf16 v[26:29], v[134:137], v[154:157], 0
	v_mfma_f32_16x16x32_bf16 v[22:25], v[114:117], v[170:173], 0
	v_mfma_f32_16x16x32_bf16 v[18:21], v[134:137], v[170:173], 0
	v_mfma_f32_16x16x32_bf16 v[14:17], v[114:117], v[178:181], 0
	v_mfma_f32_16x16x32_bf16 v[10:13], v[134:137], v[178:181], 0
	v_mfma_f32_16x16x32_bf16 v[6:9], v[114:117], v[186:189], 0
	v_mfma_f32_16x16x32_bf16 v[2:5], v[134:137], v[186:189], 0
	v_mfma_f32_16x16x32_bf16 v[30:33], v[122:125], v[166:169], v[30:33]
	v_mfma_f32_16x16x32_bf16 v[26:29], v[142:145], v[166:169], v[26:29]
	v_mfma_f32_16x16x32_bf16 v[22:25], v[122:125], v[174:177], v[22:25]
	v_mfma_f32_16x16x32_bf16 v[18:21], v[142:145], v[174:177], v[18:21]
	v_mfma_f32_16x16x32_bf16 v[14:17], v[122:125], v[182:185], v[14:17]
	v_mfma_f32_16x16x32_bf16 v[10:13], v[142:145], v[182:185], v[10:13]
	v_mfma_f32_16x16x32_bf16 v[6:9], v[122:125], v[190:193], v[6:9]
	v_mfma_f32_16x16x32_bf16 v[2:5], v[142:145], v[190:193], v[2:5]
	s_setprio 0
	s_barrier
	s_add_i32 s20, 0, 0x18000
	s_add_i32 s21, 0, 0x1c000
	v_add_u32_e32 v102, s20, v239
	v_add_u32_e32 v142, s21, v239
	ds_read_b128 v[82:85], v102
	ds_read_b128 v[86:89], v102 offset:1024
	ds_read_b128 v[94:97], v102 offset:2048
	ds_read_b128 v[102:105], v102 offset:3072
	ds_read_b128 v[114:117], v142
	ds_read_b128 v[122:125], v142 offset:1024
	ds_read_b128 v[134:137], v142 offset:2048
	ds_read_b128 v[142:145], v142 offset:3072
	s_add_u32 s36, s36, 0x20000
	s_addc_u32 s37, s37, 0
	s_mov_b32 m0, s54
	v_lshl_add_u64 v[218:219], s[36:37], 0, v[212:213]
	ds_read_b128 v[154:157], v241 offset:32768
	ds_read_b128 v[166:169], v241 offset:33792
	ds_read_b128 v[170:173], v241 offset:34816
	ds_read_b128 v[174:177], v241 offset:35840
	ds_read_b128 v[178:181], v241 offset:36864
	ds_read_b128 v[182:185], v241 offset:37888
	ds_read_b128 v[186:189], v241 offset:38912
	ds_read_b128 v[190:193], v241 offset:39936
	global_load_lds_dwordx4 v[218:219], off
	v_lshl_add_u64 v[218:219], s[36:37], 0, v[210:211]
	s_mov_b32 m0, s55
	s_nop 0
	global_load_lds_dwordx4 v[218:219], off
	s_waitcnt vmcnt(8)
	s_waitcnt lgkmcnt(0)
	s_barrier
	s_setprio 1
	s_waitcnt lgkmcnt(0)
	v_mfma_f32_16x16x32_bf16 v[162:165], v[82:85], v[154:157], v[162:165]
	v_mfma_f32_16x16x32_bf16 v[158:161], v[94:97], v[154:157], v[158:161]
	v_mfma_f32_16x16x32_bf16 v[150:153], v[82:85], v[170:173], v[150:153]
	v_mfma_f32_16x16x32_bf16 v[146:149], v[94:97], v[170:173], v[146:149]
	v_mfma_f32_16x16x32_bf16 v[138:141], v[82:85], v[178:181], v[138:141]
	v_mfma_f32_16x16x32_bf16 v[130:133], v[94:97], v[178:181], v[130:133]
	v_mfma_f32_16x16x32_bf16 v[126:129], v[82:85], v[186:189], v[126:129]
	v_mfma_f32_16x16x32_bf16 v[118:121], v[94:97], v[186:189], v[118:121]
	v_mfma_f32_16x16x32_bf16 v[162:165], v[86:89], v[166:169], v[162:165]
	v_mfma_f32_16x16x32_bf16 v[158:161], v[102:105], v[166:169], v[158:161]
	v_mfma_f32_16x16x32_bf16 v[150:153], v[86:89], v[174:177], v[150:153]
	v_mfma_f32_16x16x32_bf16 v[146:149], v[102:105], v[174:177], v[146:149]
	v_mfma_f32_16x16x32_bf16 v[138:141], v[86:89], v[182:185], v[138:141]
	v_mfma_f32_16x16x32_bf16 v[130:133], v[102:105], v[182:185], v[130:133]
	v_mfma_f32_16x16x32_bf16 v[126:129], v[86:89], v[190:193], v[126:129]
	v_mfma_f32_16x16x32_bf16 v[118:121], v[102:105], v[190:193], v[118:121]
	v_mfma_f32_16x16x32_bf16 v[62:65], v[114:117], v[154:157], v[62:65]
	v_mfma_f32_16x16x32_bf16 v[58:61], v[134:137], v[154:157], v[58:61]
	v_mfma_f32_16x16x32_bf16 v[54:57], v[114:117], v[170:173], v[54:57]
	v_mfma_f32_16x16x32_bf16 v[50:53], v[134:137], v[170:173], v[50:53]
	v_mfma_f32_16x16x32_bf16 v[46:49], v[114:117], v[178:181], v[46:49]
	v_mfma_f32_16x16x32_bf16 v[42:45], v[134:137], v[178:181], v[42:45]
	v_mfma_f32_16x16x32_bf16 v[38:41], v[114:117], v[186:189], v[38:41]
	v_mfma_f32_16x16x32_bf16 v[34:37], v[134:137], v[186:189], v[34:37]
	v_mfma_f32_16x16x32_bf16 v[62:65], v[122:125], v[166:169], v[62:65]
	v_mfma_f32_16x16x32_bf16 v[58:61], v[142:145], v[166:169], v[58:61]
	v_mfma_f32_16x16x32_bf16 v[54:57], v[122:125], v[174:177], v[54:57]
	v_mfma_f32_16x16x32_bf16 v[50:53], v[142:145], v[174:177], v[50:53]
	v_mfma_f32_16x16x32_bf16 v[46:49], v[122:125], v[182:185], v[46:49]
	v_mfma_f32_16x16x32_bf16 v[42:45], v[142:145], v[182:185], v[42:45]
	v_mfma_f32_16x16x32_bf16 v[38:41], v[122:125], v[190:193], v[38:41]
	v_mfma_f32_16x16x32_bf16 v[34:37], v[142:145], v[190:193], v[34:37]
	s_setprio 0
	s_barrier
; #define PG8_STAGE(bufoff, gbase, voff) do { _Pragma("unroll") for (int _i = 0; _i < 2; ++_i) \
;         __builtin_amdgcn_global_load_lds((const unsigned*)((const char*)(gbase) + (voff)[_i]), (PG8_LAS unsigned*)(lds + (bufoff) + ldsw + _i * 8192), 16, 0, 0); } while (0)
; #define PG8_LDA(dst, b, h) do { _Pragma("unroll") for (int m = 0; m < 4; ++m) _Pragma("unroll") for (int k = 0; k < 2; ++k) dst[m][k] = *(const PG8_LAS bf16x8*)(lds + PG8_SA(b, h) + aoff + m * 2048 + k * 1024); } while (0)
; #define PG8_WAIT_V(n) asm volatile("s_waitcnt vmcnt(" #n ")" ::: "memory")
; template <class Epi, class Sched, bool ALIGN_EPI = false, bool SP2 = false>
; __device__ __forceinline__ void gemm_phase(PG8_LAS unsigned char* lds, const Gemm g, const Sched& S, const Epi& E) {
;     ...
;         for (int t = 0; t < nt; t += 2) {
;             const bool last = (t == nt - 2);
;             const char* a1 = cA + (size_t)(t + 1) * kstep;
;             const char* a2 = last ? nA : cA + (size_t)(t + 2) * kstep; const char* b2 = last ? nB : cB + (size_t)(t + 2) * kstep;
;             const char* a3 = a2 + kstep; const char* b3 = b2 + kstep;
;             if (last && has_next) S.a_ready(nxt);
;             if constexpr (SP2) {
;             PG8_LDB(B0, 0, 0); PG8_LDB(B1, 0, 1); PG8_SCHED; PG8_LDA(At, 0, 0); PG8_STAGE(PG8_SA(1, 1), a1 + hstepA, voffA);
;             PG8_WAIT_V(8); PG8_WAIT_L(0); PG8_BAR; PG8_MMA(0, 0, At, B0); PG8_MMA(0, 1, At, B1); PG8_BAR; PG8_SCHED;
;             PG8_LDA(At, 0, 1); PG8_STAGE(PG8_SB(0, 0), b2, voffB); PG8_STAGE(PG8_SB(0, 1), b2 + hstepB, voffB); PG8_STAGE(PG8_SA(0, 0), a2, voffA);
;             PG8_WAIT_V(8); PG8_WAIT_L(0); PG8_BAR; PG8_MMA(1, 0, At, B0); PG8_MMA(1, 1, At, B1); PG8_BAR; PG8_SCHED;
;             PG8_LDB(B0, 1, 0); PG8_LDB(B1, 1, 1); PG8_SCHED; PG8_LDA(At, 1, 0); PG8_STAGE(PG8_SA(0, 1), a2 + hstepA, voffA);
;             PG8_WAIT_V(8); PG8_WAIT_L(0); PG8_BAR; PG8_MMA(0, 0, At, B0); PG8_MMA(0, 1, At, B1); PG8_BAR; PG8_SCHED;
;             PG8_LDA(At, 1, 1); PG8_STAGE(PG8_SB(1, 0), b3, voffB); PG8_STAGE(PG8_SB(1, 1), b3 + hstepB, voffB); PG8_STAGE(PG8_SA(1, 0), a3, voffA);
;             PG8_WAIT_V(8); PG8_WAIT_L(0); PG8_BAR; PG8_MMA(1, 0, At, B0); PG8_MMA(1, 1, At, B1); PG8_BAR; PG8_SCHED;
;             } else {
;             PG8_LDB(B0, 0, 0); PG8_SCHED; PG8_LDA(At, 0, 0); PG8_STAGE(PG8_SA(1, 1), a1 + hstepA, voffA);
	s_add_i32 s20, s20, s47
	v_lshl_add_u64 v[194:195], v[194:195], 0, s[22:23]
	s_mov_b32 m0, s20
	ds_read_b128 v[154:157], v241 offset:49152
	ds_read_b128 v[166:169], v241 offset:50176
	ds_read_b128 v[170:173], v241 offset:51200
	ds_read_b128 v[174:177], v241 offset:52224
	ds_read_b128 v[178:181], v241 offset:53248
	ds_read_b128 v[182:185], v241 offset:54272
	ds_read_b128 v[186:189], v241 offset:55296
	ds_read_b128 v[190:193], v241 offset:56320
	global_load_lds_dwordx4 v[194:195], off
	s_add_i32 m0, s20, 0x2000
	s_add_u32 s14, s14, 0x20080
	v_lshl_add_u64 v[194:195], v[196:197], 0, s[22:23]
	s_addc_u32 s15, s15, 0
	s_add_i32 s20, s21, s47
	global_load_lds_dwordx4 v[194:195], off
	v_lshl_add_u64 v[194:195], s[14:15], 0, v[0:1]
	s_mov_b32 m0, s20
	s_nop 0
	global_load_lds_dwordx4 v[194:195], off
	v_lshl_add_u64 v[194:195], s[14:15], 0, v[208:209]
	s_add_i32 m0, s20, 0x2000
	s_nop 0
	global_load_lds_dwordx4 v[194:195], off
	v_lshl_add_u64 v[194:195], v[198:199], 0, s[22:23]
	s_mov_b32 m0, s56
	s_nop 0
	global_load_lds_dwordx4 v[194:195], off
	v_lshl_add_u64 v[194:195], v[200:201], 0, s[22:23]
	s_mov_b32 m0, s57
	s_nop 0
	global_load_lds_dwordx4 v[194:195], off
	s_waitcnt vmcnt(8)
	s_waitcnt lgkmcnt(0)
	s_barrier
	s_setprio 1
	s_waitcnt lgkmcnt(0)
	v_mfma_f32_16x16x32_bf16 v[110:113], v[82:85], v[154:157], v[110:113]
	v_mfma_f32_16x16x32_bf16 v[106:109], v[94:97], v[154:157], v[106:109]
	v_mfma_f32_16x16x32_bf16 v[98:101], v[82:85], v[170:173], v[98:101]
	v_mfma_f32_16x16x32_bf16 v[90:93], v[94:97], v[170:173], v[90:93]
	v_mfma_f32_16x16x32_bf16 v[78:81], v[82:85], v[178:181], v[78:81]
	v_mfma_f32_16x16x32_bf16 v[74:77], v[94:97], v[178:181], v[74:77]
	v_mfma_f32_16x16x32_bf16 v[70:73], v[82:85], v[186:189], v[70:73]
	v_mfma_f32_16x16x32_bf16 v[66:69], v[94:97], v[186:189], v[66:69]
	v_mfma_f32_16x16x32_bf16 v[110:113], v[86:89], v[166:169], v[110:113]
	v_mfma_f32_16x16x32_bf16 v[106:109], v[102:105], v[166:169], v[106:109]
	v_mfma_f32_16x16x32_bf16 v[98:101], v[86:89], v[174:177], v[98:101]
	v_mfma_f32_16x16x32_bf16 v[90:93], v[102:105], v[174:177], v[90:93]
	v_mfma_f32_16x16x32_bf16 v[78:81], v[86:89], v[182:185], v[78:81]
	v_mfma_f32_16x16x32_bf16 v[74:77], v[102:105], v[182:185], v[74:77]
	v_mfma_f32_16x16x32_bf16 v[70:73], v[86:89], v[190:193], v[70:73]
	v_mfma_f32_16x16x32_bf16 v[66:69], v[102:105], v[190:193], v[66:69]
	v_mfma_f32_16x16x32_bf16 v[30:33], v[114:117], v[154:157], v[30:33]
	v_mfma_f32_16x16x32_bf16 v[26:29], v[134:137], v[154:157], v[26:29]
	v_mfma_f32_16x16x32_bf16 v[22:25], v[114:117], v[170:173], v[22:25]
	v_mfma_f32_16x16x32_bf16 v[18:21], v[134:137], v[170:173], v[18:21]
	v_mfma_f32_16x16x32_bf16 v[14:17], v[114:117], v[178:181], v[14:17]
	v_mfma_f32_16x16x32_bf16 v[10:13], v[134:137], v[178:181], v[10:13]
	v_mfma_f32_16x16x32_bf16 v[6:9], v[114:117], v[186:189], v[6:9]
	v_mfma_f32_16x16x32_bf16 v[2:5], v[134:137], v[186:189], v[2:5]
	v_mfma_f32_16x16x32_bf16 v[30:33], v[122:125], v[166:169], v[30:33]
	v_mfma_f32_16x16x32_bf16 v[26:29], v[142:145], v[166:169], v[26:29]
	v_mfma_f32_16x16x32_bf16 v[22:25], v[122:125], v[174:177], v[22:25]
	v_mfma_f32_16x16x32_bf16 v[18:21], v[142:145], v[174:177], v[18:21]
	v_mfma_f32_16x16x32_bf16 v[14:17], v[122:125], v[182:185], v[14:17]
	v_mfma_f32_16x16x32_bf16 v[10:13], v[142:145], v[182:185], v[10:13]
	v_mfma_f32_16x16x32_bf16 v[6:9], v[122:125], v[190:193], v[6:9]
	v_mfma_f32_16x16x32_bf16 v[2:5], v[142:145], v[190:193], v[2:5]
	s_setprio 0
	s_barrier
	s_add_i32 s71, s71, 2
	s_add_u32 s8, s8, 0x100
	s_addc_u32 s9, s9, 0
	s_add_u32 s63, s63, 0x100
	s_addc_u32 s70, s70, 0
	s_cmp_gt_u32 s71, 5
	s_cbranch_scc1 .Lpk_done_g1048
.LBB0_1048:
	s_add_u32 s14, s8, 0xfffe0080
	s_addc_u32 s15, s9, -1
	s_add_i32 s20, 0, 0x10000
	s_cmp_eq_u32 s71, 4
	s_cselect_b32 s37, s31, s15
	s_cselect_b32 s36, s61, s14
	s_cselect_b32 s15, s29, s70
	s_cselect_b32 s14, s62, s63
	s_add_i32 s21, 0, 0x14000
	v_add_u32_e32 v102, s20, v239
	v_add_u32_e32 v142, s21, v239
	ds_read_b128 v[82:85], v102
	ds_read_b128 v[86:89], v102 offset:1024
	ds_read_b128 v[94:97], v102 offset:2048
	ds_read_b128 v[102:105], v102 offset:3072
	ds_read_b128 v[114:117], v142
	ds_read_b128 v[122:125], v142 offset:1024
	ds_read_b128 v[134:137], v142 offset:2048
	ds_read_b128 v[142:145], v142 offset:3072
	v_lshl_add_u64 v[194:195], s[8:9], 0, v[214:215]
	s_add_i32 m0, s52, 0xc000
	ds_read_b128 v[154:157], v241
	ds_read_b128 v[166:169], v241 offset:1024
	ds_read_b128 v[170:173], v241 offset:2048
	ds_read_b128 v[174:177], v241 offset:3072
	ds_read_b128 v[178:181], v241 offset:4096
	ds_read_b128 v[182:185], v241 offset:5120
	ds_read_b128 v[186:189], v241 offset:6144
	ds_read_b128 v[190:193], v241 offset:7168
	global_load_lds_dwordx4 v[194:195], off
	v_lshl_add_u64 v[194:195], s[8:9], 0, v[216:217]
	s_add_i32 m0, s52, 0xe000
	s_nop 0
	global_load_lds_dwordx4 v[194:195], off
	s_waitcnt vmcnt(8)
	s_waitcnt lgkmcnt(0)
	s_barrier
; #define PG8_STAGE(bufoff, gbase, voff) do { _Pragma("unroll") for (int _i = 0; _i < 2; ++_i) \
;         __builtin_amdgcn_global_load_lds((const unsigned*)((const char*)(gbase) + (voff)[_i]), (PG8_LAS unsigned*)(lds + (bufoff) + ldsw + _i * 8192), 16, 0, 0); } while (0)
; #define PG8_LDA(dst, b, h) do { _Pragma("unroll") for (int m = 0; m < 4; ++m) _Pragma("unroll") for (int k = 0; k < 2; ++k) dst[m][k] = *(const PG8_LAS bf16x8*)(lds + PG8_SA(b, h) + aoff + m * 2048 + k * 1024); } while (0)
; #define PG8_LDB(dst, b, h) do { _Pragma("unroll") for (int n = 0; n < 2; ++n) _Pragma("unroll") for (int k = 0; k < 2; ++k) dst[n][k] = *(const PG8_LAS bf16x8*)(lds + PG8_SB(b, h) + boff + n * 2048 + k * 1024); } while (0)
; #define PG8_MMA(ai, bj, At, Bt) do { __builtin_amdgcn_s_setprio(1); _Pragma("unroll") for (int m = 0; m < 4; ++m) _Pragma("unroll") for (int n = 0; n < 2; ++n) _Pragma("unroll") for (int k = 0; k < 2; ++k) \
;         acc[ai][bj][m][n] = __builtin_amdgcn_mfma_f32_16x16x32_bf16(Bt[n][k], At[m][k], acc[ai][bj][m][n], 0, 0, 0); __builtin_amdgcn_s_setprio(0); } while (0)
; #define PG8_WAIT_V(n) asm volatile("s_waitcnt vmcnt(" #n ")" ::: "memory")
; #define PG8_WAIT_L(n) asm volatile("s_waitcnt lgkmcnt(" #n ")" ::: "memory")
; #define PG8_BAR __builtin_amdgcn_s_barrier()
; #define PG8_SCHED __builtin_amdgcn_sched_barrier(0)
; template <class Epi, class Sched, bool ALIGN_EPI = false, bool SP2 = false>
; __device__ __forceinline__ void gemm_phase(PG8_LAS unsigned char* lds, const Gemm g, const Sched& S, const Epi& E) {
;     ...
;             PG8_LDB(B0, 0, 0); PG8_LDB(B1, 0, 1); PG8_SCHED; PG8_LDA(At, 0, 0); PG8_STAGE(PG8_SA(1, 1), a1 + hstepA, voffA);
;             PG8_WAIT_V(8); PG8_WAIT_L(0); PG8_BAR; PG8_MMA(0, 0, At, B0); PG8_MMA(0, 1, At, B1); PG8_BAR; PG8_SCHED;
;             PG8_LDA(At, 0, 1); PG8_STAGE(PG8_SB(0, 0), b2, voffB); PG8_STAGE(PG8_SB(0, 1), b2 + hstepB, voffB); PG8_STAGE(PG8_SA(0, 0), a2, voffA);
;             PG8_WAIT_V(8); PG8_WAIT_L(0); PG8_BAR; PG8_MMA(1, 0, At, B0); PG8_MMA(1, 1, At, B1); PG8_BAR; PG8_SCHED;
	s_setprio 1
	s_waitcnt lgkmcnt(0)
	v_mfma_f32_16x16x32_bf16 v[162:165], v[82:85], v[154:157], v[162:165]
	v_mfma_f32_16x16x32_bf16 v[158:161], v[94:97], v[154:157], v[158:161]
	v_mfma_f32_16x16x32_bf16 v[150:153], v[82:85], v[170:173], v[150:153]
	v_mfma_f32_16x16x32_bf16 v[146:149], v[94:97], v[170:173], v[146:149]
	v_mfma_f32_16x16x32_bf16 v[138:141], v[82:85], v[178:181], v[138:141]
	v_mfma_f32_16x16x32_bf16 v[130:133], v[94:97], v[178:181], v[130:133]
	v_mfma_f32_16x16x32_bf16 v[126:129], v[82:85], v[186:189], v[126:129]
	v_mfma_f32_16x16x32_bf16 v[118:121], v[94:97], v[186:189], v[118:121]
	v_mfma_f32_16x16x32_bf16 v[162:165], v[86:89], v[166:169], v[162:165]
	v_mfma_f32_16x16x32_bf16 v[158:161], v[102:105], v[166:169], v[158:161]
	v_mfma_f32_16x16x32_bf16 v[150:153], v[86:89], v[174:177], v[150:153]
	v_mfma_f32_16x16x32_bf16 v[146:149], v[102:105], v[174:177], v[146:149]
	v_mfma_f32_16x16x32_bf16 v[138:141], v[86:89], v[182:185], v[138:141]
	v_mfma_f32_16x16x32_bf16 v[130:133], v[102:105], v[182:185], v[130:133]
	v_mfma_f32_16x16x32_bf16 v[126:129], v[86:89], v[190:193], v[126:129]
	v_mfma_f32_16x16x32_bf16 v[118:121], v[102:105], v[190:193], v[118:121]
	v_mfma_f32_16x16x32_bf16 v[62:65], v[114:117], v[154:157], v[62:65]
	v_mfma_f32_16x16x32_bf16 v[58:61], v[134:137], v[154:157], v[58:61]
	v_mfma_f32_16x16x32_bf16 v[54:57], v[114:117], v[170:173], v[54:57]
	v_mfma_f32_16x16x32_bf16 v[50:53], v[134:137], v[170:173], v[50:53]
	v_mfma_f32_16x16x32_bf16 v[46:49], v[114:117], v[178:181], v[46:49]
	v_mfma_f32_16x16x32_bf16 v[42:45], v[134:137], v[178:181], v[42:45]
	v_mfma_f32_16x16x32_bf16 v[38:41], v[114:117], v[186:189], v[38:41]
	v_mfma_f32_16x16x32_bf16 v[34:37], v[134:137], v[186:189], v[34:37]
	v_mfma_f32_16x16x32_bf16 v[62:65], v[122:125], v[166:169], v[62:65]
	v_mfma_f32_16x16x32_bf16 v[58:61], v[142:145], v[166:169], v[58:61]
	v_mfma_f32_16x16x32_bf16 v[54:57], v[122:125], v[174:177], v[54:57]
	v_mfma_f32_16x16x32_bf16 v[50:53], v[142:145], v[174:177], v[50:53]
	v_mfma_f32_16x16x32_bf16 v[46:49], v[122:125], v[182:185], v[46:49]
	v_mfma_f32_16x16x32_bf16 v[42:45], v[142:145], v[182:185], v[42:45]
	v_mfma_f32_16x16x32_bf16 v[38:41], v[122:125], v[190:193], v[38:41]
	v_mfma_f32_16x16x32_bf16 v[34:37], v[142:145], v[190:193], v[34:37]
	s_setprio 0
	s_barrier
	s_add_i32 s20, s20, s47
	v_lshl_add_u64 v[194:195], s[14:15], 0, v[0:1]
	s_mov_b32 m0, s20
	ds_read_b128 v[154:157], v241 offset:16384
	ds_read_b128 v[166:169], v241 offset:17408
	ds_read_b128 v[170:173], v241 offset:18432
	ds_read_b128 v[174:177], v241 offset:19456
	ds_read_b128 v[178:181], v241 offset:20480
	ds_read_b128 v[182:185], v241 offset:21504
	ds_read_b128 v[186:189], v241 offset:22528
	ds_read_b128 v[190:193], v241 offset:23552
	global_load_lds_dwordx4 v[194:195], off
	s_add_i32 m0, s20, 0x2000
	s_add_u32 s78, s14, 0x20000
	v_lshl_add_u64 v[196:197], s[14:15], 0, v[208:209]
	s_addc_u32 s79, s15, 0
	s_add_i32 s20, s21, s47
	global_load_lds_dwordx4 v[196:197], off
	v_lshl_add_u64 v[198:199], s[78:79], 0, v[0:1]
	s_mov_b32 m0, s20
	v_lshl_add_u64 v[200:201], s[36:37], 0, v[210:211]
	global_load_lds_dwordx4 v[198:199], off
	v_lshl_add_u64 v[198:199], s[78:79], 0, v[208:209]
	s_add_i32 m0, s20, 0x2000
	s_nop 0
	global_load_lds_dwordx4 v[198:199], off
	v_lshl_add_u64 v[198:199], s[36:37], 0, v[212:213]
	s_mov_b32 m0, s52
	s_nop 0
	global_load_lds_dwordx4 v[198:199], off
	s_mov_b32 m0, s53
	s_nop 0
	global_load_lds_dwordx4 v[200:201], off
	s_waitcnt vmcnt(8)
	s_waitcnt lgkmcnt(0)
	s_barrier
	s_setprio 1
	s_waitcnt lgkmcnt(0)
	v_mfma_f32_16x16x32_bf16 v[110:113], v[82:85], v[154:157], v[110:113]
	v_mfma_f32_16x16x32_bf16 v[106:109], v[94:97], v[154:157], v[106:109]
	v_mfma_f32_16x16x32_bf16 v[98:101], v[82:85], v[170:173], v[98:101]
	v_mfma_f32_16x16x32_bf16 v[90:93], v[94:97], v[170:173], v[90:93]
	v_mfma_f32_16x16x32_bf16 v[78:81], v[82:85], v[178:181], v[78:81]
	v_mfma_f32_16x16x32_bf16 v[74:77], v[94:97], v[178:181], v[74:77]
	v_mfma_f32_16x16x32_bf16 v[70:73], v[82:85], v[186:189], v[70:73]
	v_mfma_f32_16x16x32_bf16 v[66:69], v[94:97], v[186:189], v[66:69]
	v_mfma_f32_16x16x32_bf16 v[110:113], v[86:89], v[166:169], v[110:113]
	v_mfma_f32_16x16x32_bf16 v[106:109], v[102:105], v[166:169], v[106:109]
	v_mfma_f32_16x16x32_bf16 v[98:101], v[86:89], v[174:177], v[98:101]
	v_mfma_f32_16x16x32_bf16 v[90:93], v[102:105], v[174:177], v[90:93]
	v_mfma_f32_16x16x32_bf16 v[78:81], v[86:89], v[182:185], v[78:81]
	v_mfma_f32_16x16x32_bf16 v[74:77], v[102:105], v[182:185], v[74:77]
	v_mfma_f32_16x16x32_bf16 v[70:73], v[86:89], v[190:193], v[70:73]
	v_mfma_f32_16x16x32_bf16 v[66:69], v[102:105], v[190:193], v[66:69]
	v_mfma_f32_16x16x32_bf16 v[30:33], v[114:117], v[154:157], v[30:33]
	v_mfma_f32_16x16x32_bf16 v[26:29], v[134:137], v[154:157], v[26:29]
	v_mfma_f32_16x16x32_bf16 v[22:25], v[114:117], v[170:173], v[22:25]
	v_mfma_f32_16x16x32_bf16 v[18:21], v[134:137], v[170:173], v[18:21]
	v_mfma_f32_16x16x32_bf16 v[14:17], v[114:117], v[178:181], v[14:17]
	v_mfma_f32_16x16x32_bf16 v[10:13], v[134:137], v[178:181], v[10:13]
	v_mfma_f32_16x16x32_bf16 v[6:9], v[114:117], v[186:189], v[6:9]
	v_mfma_f32_16x16x32_bf16 v[2:5], v[134:137], v[186:189], v[2:5]
	v_mfma_f32_16x16x32_bf16 v[30:33], v[122:125], v[166:169], v[30:33]
	v_mfma_f32_16x16x32_bf16 v[26:29], v[142:145], v[166:169], v[26:29]
	v_mfma_f32_16x16x32_bf16 v[22:25], v[122:125], v[174:177], v[22:25]
	v_mfma_f32_16x16x32_bf16 v[18:21], v[142:145], v[174:177], v[18:21]
	v_mfma_f32_16x16x32_bf16 v[14:17], v[122:125], v[182:185], v[14:17]
	v_mfma_f32_16x16x32_bf16 v[10:13], v[142:145], v[182:185], v[10:13]
	v_mfma_f32_16x16x32_bf16 v[6:9], v[122:125], v[190:193], v[6:9]
	v_mfma_f32_16x16x32_bf16 v[2:5], v[142:145], v[190:193], v[2:5]
	s_setprio 0
	s_barrier
; #define PG8_STAGE(bufoff, gbase, voff) do { _Pragma("unroll") for (int _i = 0; _i < 2; ++_i) \
;         __builtin_amdgcn_global_load_lds((const unsigned*)((const char*)(gbase) + (voff)[_i]), (PG8_LAS unsigned*)(lds + (bufoff) + ldsw + _i * 8192), 16, 0, 0); } while (0)
; #define PG8_LDA(dst, b, h) do { _Pragma("unroll") for (int m = 0; m < 4; ++m) _Pragma("unroll") for (int k = 0; k < 2; ++k) dst[m][k] = *(const PG8_LAS bf16x8*)(lds + PG8_SA(b, h) + aoff + m * 2048 + k * 1024); } while (0)
; #define PG8_LDB(dst, b, h) do { _Pragma("unroll") for (int n = 0; n < 2; ++n) _Pragma("unroll") for (int k = 0; k < 2; ++k) dst[n][k] = *(const PG8_LAS bf16x8*)(lds + PG8_SB(b, h) + boff + n * 2048 + k * 1024); } while (0)
; #define PG8_MMA(ai, bj, At, Bt) do { __builtin_amdgcn_s_setprio(1); _Pragma("unroll") for (int m = 0; m < 4; ++m) _Pragma("unroll") for (int n = 0; n < 2; ++n) _Pragma("unroll") for (int k = 0; k < 2; ++k) \
;         acc[ai][bj][m][n] = __builtin_amdgcn_mfma_f32_16x16x32_bf16(Bt[n][k], At[m][k], acc[ai][bj][m][n], 0, 0, 0); __builtin_amdgcn_s_setprio(0); } while (0)
; #define PG8_WAIT_V(n) asm volatile("s_waitcnt vmcnt(" #n ")" ::: "memory")
; #define PG8_WAIT_L(n) asm volatile("s_waitcnt lgkmcnt(" #n ")" ::: "memory")
; #define PG8_BAR __builtin_amdgcn_s_barrier()
; #define PG8_SCHED __builtin_amdgcn_sched_barrier(0)
; template <class Epi, class Sched, bool ALIGN_EPI = false, bool SP2 = false>
; __device__ __forceinline__ void gemm_phase(PG8_LAS unsigned char* lds, const Gemm g, const Sched& S, const Epi& E) {
;     ...
;             PG8_LDB(B0, 1, 0); PG8_LDB(B1, 1, 1); PG8_SCHED; PG8_LDA(At, 1, 0); PG8_STAGE(PG8_SA(0, 1), a2 + hstepA, voffA);
;             PG8_WAIT_V(8); PG8_WAIT_L(0); PG8_BAR; PG8_MMA(0, 0, At, B0); PG8_MMA(0, 1, At, B1); PG8_BAR; PG8_SCHED;
	s_add_i32 s20, 0, 0x18000
	s_add_i32 s21, 0, 0x1c000
	v_add_u32_e32 v102, s20, v239
	v_add_u32_e32 v142, s21, v239
	ds_read_b128 v[82:85], v102
	ds_read_b128 v[86:89], v102 offset:1024
	ds_read_b128 v[94:97], v102 offset:2048
	ds_read_b128 v[102:105], v102 offset:3072
	ds_read_b128 v[114:117], v142
	ds_read_b128 v[122:125], v142 offset:1024
	ds_read_b128 v[134:137], v142 offset:2048
	ds_read_b128 v[142:145], v142 offset:3072
	s_add_u32 s36, s36, 0x20000
	s_addc_u32 s37, s37, 0
	s_mov_b32 m0, s54
	v_lshl_add_u64 v[218:219], s[36:37], 0, v[212:213]
	ds_read_b128 v[154:157], v241 offset:32768
	ds_read_b128 v[166:169], v241 offset:33792
	ds_read_b128 v[170:173], v241 offset:34816
	ds_read_b128 v[174:177], v241 offset:35840
	ds_read_b128 v[178:181], v241 offset:36864
	ds_read_b128 v[182:185], v241 offset:37888
	ds_read_b128 v[186:189], v241 offset:38912
	ds_read_b128 v[190:193], v241 offset:39936
	global_load_lds_dwordx4 v[218:219], off
	v_lshl_add_u64 v[218:219], s[36:37], 0, v[210:211]
	s_mov_b32 m0, s55
	s_nop 0
	global_load_lds_dwordx4 v[218:219], off
	s_waitcnt vmcnt(8)
	s_waitcnt lgkmcnt(0)
	s_barrier
	s_setprio 1
	s_waitcnt lgkmcnt(0)
	v_mfma_f32_16x16x32_bf16 v[162:165], v[82:85], v[154:157], v[162:165]
	v_mfma_f32_16x16x32_bf16 v[158:161], v[94:97], v[154:157], v[158:161]
	v_mfma_f32_16x16x32_bf16 v[150:153], v[82:85], v[170:173], v[150:153]
	v_mfma_f32_16x16x32_bf16 v[146:149], v[94:97], v[170:173], v[146:149]
	v_mfma_f32_16x16x32_bf16 v[138:141], v[82:85], v[178:181], v[138:141]
	v_mfma_f32_16x16x32_bf16 v[130:133], v[94:97], v[178:181], v[130:133]
	v_mfma_f32_16x16x32_bf16 v[126:129], v[82:85], v[186:189], v[126:129]
	v_mfma_f32_16x16x32_bf16 v[118:121], v[94:97], v[186:189], v[118:121]
	v_mfma_f32_16x16x32_bf16 v[162:165], v[86:89], v[166:169], v[162:165]
	v_mfma_f32_16x16x32_bf16 v[158:161], v[102:105], v[166:169], v[158:161]
	v_mfma_f32_16x16x32_bf16 v[150:153], v[86:89], v[174:177], v[150:153]
	v_mfma_f32_16x16x32_bf16 v[146:149], v[102:105], v[174:177], v[146:149]
	v_mfma_f32_16x16x32_bf16 v[138:141], v[86:89], v[182:185], v[138:141]
	v_mfma_f32_16x16x32_bf16 v[130:133], v[102:105], v[182:185], v[130:133]
	v_mfma_f32_16x16x32_bf16 v[126:129], v[86:89], v[190:193], v[126:129]
	v_mfma_f32_16x16x32_bf16 v[118:121], v[102:105], v[190:193], v[118:121]
	v_mfma_f32_16x16x32_bf16 v[62:65], v[114:117], v[154:157], v[62:65]
	v_mfma_f32_16x16x32_bf16 v[58:61], v[134:137], v[154:157], v[58:61]
	v_mfma_f32_16x16x32_bf16 v[54:57], v[114:117], v[170:173], v[54:57]
	v_mfma_f32_16x16x32_bf16 v[50:53], v[134:137], v[170:173], v[50:53]
	v_mfma_f32_16x16x32_bf16 v[46:49], v[114:117], v[178:181], v[46:49]
	v_mfma_f32_16x16x32_bf16 v[42:45], v[134:137], v[178:181], v[42:45]
	v_mfma_f32_16x16x32_bf16 v[38:41], v[114:117], v[186:189], v[38:41]
	v_mfma_f32_16x16x32_bf16 v[34:37], v[134:137], v[186:189], v[34:37]
	v_mfma_f32_16x16x32_bf16 v[62:65], v[122:125], v[166:169], v[62:65]
	v_mfma_f32_16x16x32_bf16 v[58:61], v[142:145], v[166:169], v[58:61]
	v_mfma_f32_16x16x32_bf16 v[54:57], v[122:125], v[174:177], v[54:57]
	v_mfma_f32_16x16x32_bf16 v[50:53], v[142:145], v[174:177], v[50:53]
	v_mfma_f32_16x16x32_bf16 v[46:49], v[122:125], v[182:185], v[46:49]
	v_mfma_f32_16x16x32_bf16 v[42:45], v[142:145], v[182:185], v[42:45]
	v_mfma_f32_16x16x32_bf16 v[38:41], v[122:125], v[190:193], v[38:41]
	v_mfma_f32_16x16x32_bf16 v[34:37], v[142:145], v[190:193], v[34:37]
	s_setprio 0
	s_barrier
; #define PG8_STAGE(bufoff, gbase, voff) do { _Pragma("unroll") for (int _i = 0; _i < 2; ++_i) \
;         __builtin_amdgcn_global_load_lds((const unsigned*)((const char*)(gbase) + (voff)[_i]), (PG8_LAS unsigned*)(lds + (bufoff) + ldsw + _i * 8192), 16, 0, 0); } while (0)
; #define PG8_LDA(dst, b, h) do { _Pragma("unroll") for (int m = 0; m < 4; ++m) _Pragma("unroll") for (int k = 0; k < 2; ++k) dst[m][k] = *(const PG8_LAS bf16x8*)(lds + PG8_SA(b, h) + aoff + m * 2048 + k * 1024); } while (0)
; #define PG8_MMA(ai, bj, At, Bt) do { __builtin_amdgcn_s_setprio(1); _Pragma("unroll") for (int m = 0; m < 4; ++m) _Pragma("unroll") for (int n = 0; n < 2; ++n) _Pragma("unroll") for (int k = 0; k < 2; ++k) \
;         acc[ai][bj][m][n] = __builtin_amdgcn_mfma_f32_16x16x32_bf16(Bt[n][k], At[m][k], acc[ai][bj][m][n], 0, 0, 0); __builtin_amdgcn_s_setprio(0); } while (0)
; #define PG8_WAIT_V(n) asm volatile("s_waitcnt vmcnt(" #n ")" ::: "memory")
; #define PG8_WAIT_L(n) asm volatile("s_waitcnt lgkmcnt(" #n ")" ::: "memory")
; #define PG8_BAR __builtin_amdgcn_s_barrier()
; #define PG8_SCHED __builtin_amdgcn_sched_barrier(0)
; template <class Epi, class Sched, bool ALIGN_EPI = false, bool SP2 = false>
; __device__ __forceinline__ void gemm_phase(PG8_LAS unsigned char* lds, const Gemm g, const Sched& S, const Epi& E) {
;     ...
;         for (int t = 0; t < nt; t += 2) {
;     ...
;             PG8_LDA(At, 1, 1); PG8_STAGE(PG8_SB(1, 0), b3, voffB); PG8_STAGE(PG8_SB(1, 1), b3 + hstepB, voffB); PG8_STAGE(PG8_SA(1, 0), a3, voffA);
;             PG8_WAIT_V(8); PG8_WAIT_L(0); PG8_BAR; PG8_MMA(1, 0, At, B0); PG8_MMA(1, 1, At, B1); PG8_BAR; PG8_SCHED;
	s_add_i32 s20, s20, s47
	v_lshl_add_u64 v[194:195], v[194:195], 0, s[22:23]
	s_mov_b32 m0, s20
	ds_read_b128 v[154:157], v241 offset:49152
	ds_read_b128 v[166:169], v241 offset:50176
	ds_read_b128 v[170:173], v241 offset:51200
	ds_read_b128 v[174:177], v241 offset:52224
	ds_read_b128 v[178:181], v241 offset:53248
	ds_read_b128 v[182:185], v241 offset:54272
	ds_read_b128 v[186:189], v241 offset:55296
	ds_read_b128 v[190:193], v241 offset:56320
	global_load_lds_dwordx4 v[194:195], off
	s_add_i32 m0, s20, 0x2000
	s_add_u32 s14, s14, 0x20080
	v_lshl_add_u64 v[194:195], v[196:197], 0, s[22:23]
	s_addc_u32 s15, s15, 0
	s_add_i32 s20, s21, s47
	global_load_lds_dwordx4 v[194:195], off
	v_lshl_add_u64 v[194:195], s[14:15], 0, v[0:1]
	s_mov_b32 m0, s20
	s_nop 0
	global_load_lds_dwordx4 v[194:195], off
	v_lshl_add_u64 v[194:195], s[14:15], 0, v[208:209]
	s_add_i32 m0, s20, 0x2000
	s_nop 0
	global_load_lds_dwordx4 v[194:195], off
	v_lshl_add_u64 v[194:195], v[198:199], 0, s[22:23]
	s_mov_b32 m0, s56
	s_nop 0
	global_load_lds_dwordx4 v[194:195], off
	v_lshl_add_u64 v[194:195], v[200:201], 0, s[22:23]
	s_mov_b32 m0, s57
	s_nop 0
	global_load_lds_dwordx4 v[194:195], off
	s_waitcnt vmcnt(8)
	s_waitcnt lgkmcnt(0)
	s_barrier
	s_setprio 1
	s_waitcnt lgkmcnt(0)
	v_mfma_f32_16x16x32_bf16 v[110:113], v[82:85], v[154:157], v[110:113]
	v_mfma_f32_16x16x32_bf16 v[106:109], v[94:97], v[154:157], v[106:109]
	v_mfma_f32_16x16x32_bf16 v[98:101], v[82:85], v[170:173], v[98:101]
	v_mfma_f32_16x16x32_bf16 v[90:93], v[94:97], v[170:173], v[90:93]
	v_mfma_f32_16x16x32_bf16 v[78:81], v[82:85], v[178:181], v[78:81]
	v_mfma_f32_16x16x32_bf16 v[74:77], v[94:97], v[178:181], v[74:77]
	v_mfma_f32_16x16x32_bf16 v[70:73], v[82:85], v[186:189], v[70:73]
	v_mfma_f32_16x16x32_bf16 v[66:69], v[94:97], v[186:189], v[66:69]
	v_mfma_f32_16x16x32_bf16 v[110:113], v[86:89], v[166:169], v[110:113]
	v_mfma_f32_16x16x32_bf16 v[106:109], v[102:105], v[166:169], v[106:109]
	v_mfma_f32_16x16x32_bf16 v[98:101], v[86:89], v[174:177], v[98:101]
	v_mfma_f32_16x16x32_bf16 v[90:93], v[102:105], v[174:177], v[90:93]
	v_mfma_f32_16x16x32_bf16 v[78:81], v[86:89], v[182:185], v[78:81]
	v_mfma_f32_16x16x32_bf16 v[74:77], v[102:105], v[182:185], v[74:77]
	v_mfma_f32_16x16x32_bf16 v[70:73], v[86:89], v[190:193], v[70:73]
	v_mfma_f32_16x16x32_bf16 v[66:69], v[102:105], v[190:193], v[66:69]
	v_mfma_f32_16x16x32_bf16 v[30:33], v[114:117], v[154:157], v[30:33]
	v_mfma_f32_16x16x32_bf16 v[26:29], v[134:137], v[154:157], v[26:29]
	v_mfma_f32_16x16x32_bf16 v[22:25], v[114:117], v[170:173], v[22:25]
	v_mfma_f32_16x16x32_bf16 v[18:21], v[134:137], v[170:173], v[18:21]
	v_mfma_f32_16x16x32_bf16 v[14:17], v[114:117], v[178:181], v[14:17]
	v_mfma_f32_16x16x32_bf16 v[10:13], v[134:137], v[178:181], v[10:13]
	v_mfma_f32_16x16x32_bf16 v[6:9], v[114:117], v[186:189], v[6:9]
	v_mfma_f32_16x16x32_bf16 v[2:5], v[134:137], v[186:189], v[2:5]
	v_mfma_f32_16x16x32_bf16 v[30:33], v[122:125], v[166:169], v[30:33]
	v_mfma_f32_16x16x32_bf16 v[26:29], v[142:145], v[166:169], v[26:29]
	v_mfma_f32_16x16x32_bf16 v[22:25], v[122:125], v[174:177], v[22:25]
	v_mfma_f32_16x16x32_bf16 v[18:21], v[142:145], v[174:177], v[18:21]
	v_mfma_f32_16x16x32_bf16 v[14:17], v[122:125], v[182:185], v[14:17]
	v_mfma_f32_16x16x32_bf16 v[10:13], v[142:145], v[182:185], v[10:13]
	v_mfma_f32_16x16x32_bf16 v[6:9], v[122:125], v[190:193], v[6:9]
	v_mfma_f32_16x16x32_bf16 v[2:5], v[142:145], v[190:193], v[2:5]
	s_setprio 0
	s_barrier
	s_add_i32 s71, s71, 2
	s_add_u32 s8, s8, 0x100
	s_addc_u32 s9, s9, 0
	s_add_u32 s63, s63, 0x100
	s_addc_u32 s70, s70, 0
	s_cmp_gt_u32 s71, 5
	s_cbranch_scc0 .LBB0_1048

; #define PG8_STAGE(bufoff, gbase, voff) do { _Pragma("unroll") for (int _i = 0; _i < 2; ++_i) \
;         __builtin_amdgcn_global_load_lds((const unsigned*)((const char*)(gbase) + (voff)[_i]), (PG8_LAS unsigned*)(lds + (bufoff) + ldsw + _i * 8192), 16, 0, 0); } while (0)
; #define PG8_LDA(dst, b, h) do { _Pragma("unroll") for (int m = 0; m < 4; ++m) _Pragma("unroll") for (int k = 0; k < 2; ++k) dst[m][k] = *(const PG8_LAS bf16x8*)(lds + PG8_SA(b, h) + aoff + m * 2048 + k * 1024); } while (0)
; #define PG8_LDB(dst, b, h) do { _Pragma("unroll") for (int n = 0; n < 2; ++n) _Pragma("unroll") for (int k = 0; k < 2; ++k) dst[n][k] = *(const PG8_LAS bf16x8*)(lds + PG8_SB(b, h) + boff + n * 2048 + k * 1024); } while (0)
; #define PG8_MMA(ai, bj, At, Bt) do { __builtin_amdgcn_s_setprio(1); _Pragma("unroll") for (int m = 0; m < 4; ++m) _Pragma("unroll") for (int n = 0; n < 2; ++n) _Pragma("unroll") for (int k = 0; k < 2; ++k) \
;         acc[ai][bj][m][n] = __builtin_amdgcn_mfma_f32_16x16x32_bf16(Bt[n][k], At[m][k], acc[ai][bj][m][n], 0, 0, 0); __builtin_amdgcn_s_setprio(0); } while (0)
; #define PG8_WAIT_V(n) asm volatile("s_waitcnt vmcnt(" #n ")" ::: "memory")
; #define PG8_BAR __builtin_amdgcn_s_barrier()
; template <class Epi, class Sched, bool ALIGN_EPI = false, bool SP2 = false>
; __device__ __forceinline__ void gemm_phase(PG8_LAS unsigned char* lds, const Gemm g, const Sched& S, const Epi& E) {
;     ...
;         const bool has_next = S.next(ui + 1, nxt);
;         const char* nA = has_next ? (const char*)g.A + (size_t)nxt.pm * tstepA + (size_t)nxt.pb * g.sA : cA; const char* nB = has_next ? (const char*)g.Bt + (size_t)nxt.pn * tstepB + (size_t)nxt.pb * g.sB : cB;
;         for (int t = 0; t < nt; t += 2) {
;             const bool last = (t == nt - 2);
;             const char* a1 = cA + (size_t)(t + 1) * kstep;
;             const char* a2 = last ? nA : cA + (size_t)(t + 2) * kstep; const char* b2 = last ? nB : cB + (size_t)(t + 2) * kstep;
;             const char* a3 = a2 + kstep; const char* b3 = b2 + kstep;
;             if (last && has_next) S.a_ready(nxt);
;             if constexpr (SP2) {
;             PG8_LDB(B0, 0, 0); PG8_LDB(B1, 0, 1); PG8_SCHED; PG8_LDA(At, 0, 0); PG8_STAGE(PG8_SA(1, 1), a1 + hstepA, voffA);
;             PG8_WAIT_V(8); PG8_WAIT_L(0); PG8_BAR; PG8_MMA(0, 0, At, B0); PG8_MMA(0, 1, At, B1); PG8_BAR; PG8_SCHED;
.LBB0_1136:
	s_ashr_i32 s53, s52, 31
	s_lshl_b64 s[34:35], s[52:53], 19
	s_add_u32 s62, s56, s34
	s_addc_u32 s63, s57, s35
	s_and_b64 s[34:35], s[44:45], exec
	s_cselect_b32 s9, s63, s1
	s_cselect_b32 s39, s62, s0
	s_ashr_i32 s47, s46, 31
	s_lshl_b64 s[34:35], s[46:47], 19
	s_add_u32 s34, s26, s34
	s_addc_u32 s35, s60, s35
	s_and_b64 s[36:37], s[44:45], exec
	s_cselect_b32 s47, s35, s15
	s_cselect_b32 s53, s34, s14
	s_add_u32 s0, s0, 0x40080
	s_addc_u32 s1, s1, 0
	s_add_u32 s54, s14, 0x100
	s_addc_u32 s55, s15, 0
	s_mov_b32 s85, -2
	s_waitcnt lgkmcnt(0)
	s_add_u32 s14, s0, 0xfffc0080
	s_addc_u32 s15, s1, -1
	s_add_i32 s20, 0, 0x10000
	s_cmp_eq_u32 s85, 12
	s_cselect_b32 s37, s9, s15
	s_cselect_b32 s36, s39, s14
	s_cselect_b32 s15, s47, s55
	s_cselect_b32 s14, s53, s54
	s_add_i32 s21, 0, 0x14000
	v_add_u32_e32 v102, s20, v222
	v_add_u32_e32 v158, s21, v222
	ds_read_b128 v[90:93], v102
	ds_read_b128 v[94:97], v102 offset:1024
	ds_read_b128 v[98:101], v102 offset:2048
	ds_read_b128 v[102:105], v102 offset:3072
	ds_read_b128 v[146:149], v158
	ds_read_b128 v[150:153], v158 offset:1024
	ds_read_b128 v[154:157], v158 offset:2048
	ds_read_b128 v[158:161], v158 offset:3072
	v_lshl_add_u64 v[204:205], s[0:1], 0, v[214:215]
	s_add_i32 m0, s70, 0xc000
	ds_read_b128 v[162:165], v227
	ds_read_b128 v[166:169], v227 offset:1024
	ds_read_b128 v[170:173], v227 offset:2048
	ds_read_b128 v[174:177], v227 offset:3072
	ds_read_b128 v[178:181], v227 offset:4096
	ds_read_b128 v[182:185], v227 offset:5120
	ds_read_b128 v[218:221], v227 offset:6144
	ds_read_b128 v[240:243], v227 offset:7168
	global_load_lds_dwordx4 v[204:205], off
	v_lshl_add_u64 v[204:205], s[0:1], 0, v[216:217]
	s_add_i32 m0, s70, 0xe000
	s_nop 0
	global_load_lds_dwordx4 v[204:205], off
	s_waitcnt vmcnt(8)
	s_waitcnt lgkmcnt(0)
	s_barrier
	s_setprio 1
	s_waitcnt lgkmcnt(0)
	v_mfma_f32_16x16x32_bf16 v[142:145], v[90:93], v[162:165], 0
	v_mfma_f32_16x16x32_bf16 v[138:141], v[98:101], v[162:165], 0
	v_mfma_f32_16x16x32_bf16 v[126:129], v[90:93], v[170:173], 0
	v_mfma_f32_16x16x32_bf16 v[122:125], v[98:101], v[170:173], 0
	v_mfma_f32_16x16x32_bf16 v[110:113], v[90:93], v[178:181], 0
	v_mfma_f32_16x16x32_bf16 v[106:109], v[98:101], v[178:181], 0
	v_mfma_f32_16x16x32_bf16 v[78:81], v[90:93], v[218:221], 0
	v_mfma_f32_16x16x32_bf16 v[74:77], v[98:101], v[218:221], 0
	v_mfma_f32_16x16x32_bf16 v[142:145], v[94:97], v[166:169], v[142:145]
	v_mfma_f32_16x16x32_bf16 v[138:141], v[102:105], v[166:169], v[138:141]
	v_mfma_f32_16x16x32_bf16 v[126:129], v[94:97], v[174:177], v[126:129]
	v_mfma_f32_16x16x32_bf16 v[122:125], v[102:105], v[174:177], v[122:125]
	v_mfma_f32_16x16x32_bf16 v[110:113], v[94:97], v[182:185], v[110:113]
	v_mfma_f32_16x16x32_bf16 v[106:109], v[102:105], v[182:185], v[106:109]
	v_mfma_f32_16x16x32_bf16 v[78:81], v[94:97], v[240:243], v[78:81]
	v_mfma_f32_16x16x32_bf16 v[74:77], v[102:105], v[240:243], v[74:77]
	v_mfma_f32_16x16x32_bf16 v[134:137], v[146:149], v[162:165], 0
	v_mfma_f32_16x16x32_bf16 v[130:133], v[154:157], v[162:165], 0
	v_mfma_f32_16x16x32_bf16 v[118:121], v[146:149], v[170:173], 0
	v_mfma_f32_16x16x32_bf16 v[114:117], v[154:157], v[170:173], 0
	v_mfma_f32_16x16x32_bf16 v[86:89], v[146:149], v[178:181], 0
	v_mfma_f32_16x16x32_bf16 v[82:85], v[154:157], v[178:181], 0
	v_mfma_f32_16x16x32_bf16 v[70:73], v[146:149], v[218:221], 0
	v_mfma_f32_16x16x32_bf16 v[66:69], v[154:157], v[218:221], 0
	v_mfma_f32_16x16x32_bf16 v[134:137], v[150:153], v[166:169], v[134:137]
	v_mfma_f32_16x16x32_bf16 v[130:133], v[158:161], v[166:169], v[130:133]
	v_mfma_f32_16x16x32_bf16 v[118:121], v[150:153], v[174:177], v[118:121]
	v_mfma_f32_16x16x32_bf16 v[114:117], v[158:161], v[174:177], v[114:117]
	v_mfma_f32_16x16x32_bf16 v[86:89], v[150:153], v[182:185], v[86:89]
	v_mfma_f32_16x16x32_bf16 v[82:85], v[158:161], v[182:185], v[82:85]
	v_mfma_f32_16x16x32_bf16 v[70:73], v[150:153], v[240:243], v[70:73]
	v_mfma_f32_16x16x32_bf16 v[66:69], v[158:161], v[240:243], v[66:69]
	s_setprio 0
	s_barrier
	s_add_i32 s20, s20, s61
	v_lshl_add_u64 v[204:205], s[14:15], 0, v[0:1]
	s_mov_b32 m0, s20
	ds_read_b128 v[162:165], v227 offset:16384
	ds_read_b128 v[166:169], v227 offset:17408
	ds_read_b128 v[170:173], v227 offset:18432
	ds_read_b128 v[174:177], v227 offset:19456
	ds_read_b128 v[178:181], v227 offset:20480
	ds_read_b128 v[182:185], v227 offset:21504
	ds_read_b128 v[218:221], v227 offset:22528
	ds_read_b128 v[240:243], v227 offset:23552
	global_load_lds_dwordx4 v[204:205], off
	s_add_i32 m0, s20, 0x2000
	s_add_u32 s86, s14, 0x40000
	v_lshl_add_u64 v[234:235], s[14:15], 0, v[186:187]
	s_addc_u32 s87, s15, 0
	s_add_i32 s20, s21, s61
	global_load_lds_dwordx4 v[234:235], off
	v_lshl_add_u64 v[244:245], s[86:87], 0, v[0:1]
	s_mov_b32 m0, s20
	v_lshl_add_u64 v[246:247], s[36:37], 0, v[188:189]
	global_load_lds_dwordx4 v[244:245], off
	v_lshl_add_u64 v[244:245], s[86:87], 0, v[186:187]
	s_add_i32 m0, s20, 0x2000
	s_nop 0
	global_load_lds_dwordx4 v[244:245], off
	v_lshl_add_u64 v[244:245], s[36:37], 0, v[190:191]
	s_mov_b32 m0, s70
	s_nop 0
	global_load_lds_dwordx4 v[244:245], off
	s_mov_b32 m0, s71
	s_nop 0
	global_load_lds_dwordx4 v[246:247], off
	s_waitcnt vmcnt(8)
	s_waitcnt lgkmcnt(0)
	s_barrier
; #define PG8_STAGE(bufoff, gbase, voff) do { _Pragma("unroll") for (int _i = 0; _i < 2; ++_i) \
;         __builtin_amdgcn_global_load_lds((const unsigned*)((const char*)(gbase) + (voff)[_i]), (PG8_LAS unsigned*)(lds + (bufoff) + ldsw + _i * 8192), 16, 0, 0); } while (0)
; #define PG8_LDA(dst, b, h) do { _Pragma("unroll") for (int m = 0; m < 4; ++m) _Pragma("unroll") for (int k = 0; k < 2; ++k) dst[m][k] = *(const PG8_LAS bf16x8*)(lds + PG8_SA(b, h) + aoff + m * 2048 + k * 1024); } while (0)
; #define PG8_LDB(dst, b, h) do { _Pragma("unroll") for (int n = 0; n < 2; ++n) _Pragma("unroll") for (int k = 0; k < 2; ++k) dst[n][k] = *(const PG8_LAS bf16x8*)(lds + PG8_SB(b, h) + boff + n * 2048 + k * 1024); } while (0)
; #define PG8_MMA(ai, bj, At, Bt) do { __builtin_amdgcn_s_setprio(1); _Pragma("unroll") for (int m = 0; m < 4; ++m) _Pragma("unroll") for (int n = 0; n < 2; ++n) _Pragma("unroll") for (int k = 0; k < 2; ++k) \
;         acc[ai][bj][m][n] = __builtin_amdgcn_mfma_f32_16x16x32_bf16(Bt[n][k], At[m][k], acc[ai][bj][m][n], 0, 0, 0); __builtin_amdgcn_s_setprio(0); } while (0)
; #define PG8_WAIT_V(n) asm volatile("s_waitcnt vmcnt(" #n ")" ::: "memory")
; #define PG8_WAIT_L(n) asm volatile("s_waitcnt lgkmcnt(" #n ")" ::: "memory")
; #define PG8_BAR __builtin_amdgcn_s_barrier()
; #define PG8_SCHED __builtin_amdgcn_sched_barrier(0)
; template <class Epi, class Sched, bool ALIGN_EPI = false, bool SP2 = false>
; __device__ __forceinline__ void gemm_phase(PG8_LAS unsigned char* lds, const Gemm g, const Sched& S, const Epi& E) {
;     ...
;             PG8_LDA(At, 0, 1); PG8_STAGE(PG8_SB(0, 0), b2, voffB); PG8_STAGE(PG8_SB(0, 1), b2 + hstepB, voffB); PG8_STAGE(PG8_SA(0, 0), a2, voffA);
;             PG8_WAIT_V(8); PG8_WAIT_L(0); PG8_BAR; PG8_MMA(1, 0, At, B0); PG8_MMA(1, 1, At, B1); PG8_BAR; PG8_SCHED;
;             PG8_LDB(B0, 1, 0); PG8_LDB(B1, 1, 1); PG8_SCHED; PG8_LDA(At, 1, 0); PG8_STAGE(PG8_SA(0, 1), a2 + hstepA, voffA);
;             PG8_WAIT_V(8); PG8_WAIT_L(0); PG8_BAR; PG8_MMA(0, 0, At, B0); PG8_MMA(0, 1, At, B1); PG8_BAR; PG8_SCHED;
	s_setprio 1
	s_waitcnt lgkmcnt(0)
	v_mfma_f32_16x16x32_bf16 v[62:65], v[90:93], v[162:165], 0
	v_mfma_f32_16x16x32_bf16 v[58:61], v[98:101], v[162:165], 0
	v_mfma_f32_16x16x32_bf16 v[46:49], v[90:93], v[170:173], 0
	v_mfma_f32_16x16x32_bf16 v[42:45], v[98:101], v[170:173], 0
	v_mfma_f32_16x16x32_bf16 v[30:33], v[90:93], v[178:181], 0
	v_mfma_f32_16x16x32_bf16 v[26:29], v[98:101], v[178:181], 0
	v_mfma_f32_16x16x32_bf16 v[14:17], v[90:93], v[218:221], 0
	v_mfma_f32_16x16x32_bf16 v[10:13], v[98:101], v[218:221], 0
	v_mfma_f32_16x16x32_bf16 v[62:65], v[94:97], v[166:169], v[62:65]
	v_mfma_f32_16x16x32_bf16 v[58:61], v[102:105], v[166:169], v[58:61]
	v_mfma_f32_16x16x32_bf16 v[46:49], v[94:97], v[174:177], v[46:49]
	v_mfma_f32_16x16x32_bf16 v[42:45], v[102:105], v[174:177], v[42:45]
	v_mfma_f32_16x16x32_bf16 v[30:33], v[94:97], v[182:185], v[30:33]
	v_mfma_f32_16x16x32_bf16 v[26:29], v[102:105], v[182:185], v[26:29]
	v_mfma_f32_16x16x32_bf16 v[14:17], v[94:97], v[240:243], v[14:17]
	v_mfma_f32_16x16x32_bf16 v[10:13], v[102:105], v[240:243], v[10:13]
	v_mfma_f32_16x16x32_bf16 v[54:57], v[146:149], v[162:165], 0
	v_mfma_f32_16x16x32_bf16 v[50:53], v[154:157], v[162:165], 0
	v_mfma_f32_16x16x32_bf16 v[38:41], v[146:149], v[170:173], 0
	v_mfma_f32_16x16x32_bf16 v[34:37], v[154:157], v[170:173], 0
	v_mfma_f32_16x16x32_bf16 v[22:25], v[146:149], v[178:181], 0
	v_mfma_f32_16x16x32_bf16 v[18:21], v[154:157], v[178:181], 0
	v_mfma_f32_16x16x32_bf16 v[6:9], v[146:149], v[218:221], 0
	v_mfma_f32_16x16x32_bf16 v[2:5], v[154:157], v[218:221], 0
	v_mfma_f32_16x16x32_bf16 v[54:57], v[150:153], v[166:169], v[54:57]
	v_mfma_f32_16x16x32_bf16 v[50:53], v[158:161], v[166:169], v[50:53]
	v_mfma_f32_16x16x32_bf16 v[38:41], v[150:153], v[174:177], v[38:41]
	v_mfma_f32_16x16x32_bf16 v[34:37], v[158:161], v[174:177], v[34:37]
	v_mfma_f32_16x16x32_bf16 v[22:25], v[150:153], v[182:185], v[22:25]
	v_mfma_f32_16x16x32_bf16 v[18:21], v[158:161], v[182:185], v[18:21]
	v_mfma_f32_16x16x32_bf16 v[6:9], v[150:153], v[240:243], v[6:9]
	v_mfma_f32_16x16x32_bf16 v[2:5], v[158:161], v[240:243], v[2:5]
	s_setprio 0
	s_barrier
	s_add_i32 s20, 0, 0x18000
	s_add_i32 s21, 0, 0x1c000
	v_add_u32_e32 v102, s20, v222
	v_add_u32_e32 v158, s21, v222
	ds_read_b128 v[90:93], v102
	ds_read_b128 v[94:97], v102 offset:1024
	ds_read_b128 v[98:101], v102 offset:2048
	ds_read_b128 v[102:105], v102 offset:3072
	ds_read_b128 v[146:149], v158
	ds_read_b128 v[150:153], v158 offset:1024
	ds_read_b128 v[154:157], v158 offset:2048
	ds_read_b128 v[158:161], v158 offset:3072
	s_add_u32 s36, s36, 0x40000
	s_addc_u32 s37, s37, 0
	s_mov_b32 m0, s78
	v_lshl_add_u64 v[248:249], s[36:37], 0, v[190:191]
	ds_read_b128 v[162:165], v227 offset:32768
	ds_read_b128 v[166:169], v227 offset:33792
	ds_read_b128 v[170:173], v227 offset:34816
	ds_read_b128 v[174:177], v227 offset:35840
	ds_read_b128 v[178:181], v227 offset:36864
	ds_read_b128 v[182:185], v227 offset:37888
	ds_read_b128 v[218:221], v227 offset:38912
	ds_read_b128 v[240:243], v227 offset:39936
	global_load_lds_dwordx4 v[248:249], off
	v_lshl_add_u64 v[248:249], s[36:37], 0, v[188:189]
	s_mov_b32 m0, s79
	s_nop 0
	global_load_lds_dwordx4 v[248:249], off
	s_waitcnt vmcnt(8)
	s_waitcnt lgkmcnt(0)
	s_barrier
	s_setprio 1
	s_waitcnt lgkmcnt(0)
	v_mfma_f32_16x16x32_bf16 v[142:145], v[90:93], v[162:165], v[142:145]
	v_mfma_f32_16x16x32_bf16 v[138:141], v[98:101], v[162:165], v[138:141]
	v_mfma_f32_16x16x32_bf16 v[126:129], v[90:93], v[170:173], v[126:129]
	v_mfma_f32_16x16x32_bf16 v[122:125], v[98:101], v[170:173], v[122:125]
	v_mfma_f32_16x16x32_bf16 v[110:113], v[90:93], v[178:181], v[110:113]
	v_mfma_f32_16x16x32_bf16 v[106:109], v[98:101], v[178:181], v[106:109]
	v_mfma_f32_16x16x32_bf16 v[78:81], v[90:93], v[218:221], v[78:81]
	v_mfma_f32_16x16x32_bf16 v[74:77], v[98:101], v[218:221], v[74:77]
	v_mfma_f32_16x16x32_bf16 v[142:145], v[94:97], v[166:169], v[142:145]
	v_mfma_f32_16x16x32_bf16 v[138:141], v[102:105], v[166:169], v[138:141]
	v_mfma_f32_16x16x32_bf16 v[126:129], v[94:97], v[174:177], v[126:129]
	v_mfma_f32_16x16x32_bf16 v[122:125], v[102:105], v[174:177], v[122:125]
	v_mfma_f32_16x16x32_bf16 v[110:113], v[94:97], v[182:185], v[110:113]
	v_mfma_f32_16x16x32_bf16 v[106:109], v[102:105], v[182:185], v[106:109]
	v_mfma_f32_16x16x32_bf16 v[78:81], v[94:97], v[240:243], v[78:81]
	v_mfma_f32_16x16x32_bf16 v[74:77], v[102:105], v[240:243], v[74:77]
	v_mfma_f32_16x16x32_bf16 v[134:137], v[146:149], v[162:165], v[134:137]
	v_mfma_f32_16x16x32_bf16 v[130:133], v[154:157], v[162:165], v[130:133]
	v_mfma_f32_16x16x32_bf16 v[118:121], v[146:149], v[170:173], v[118:121]
	v_mfma_f32_16x16x32_bf16 v[114:117], v[154:157], v[170:173], v[114:117]
	v_mfma_f32_16x16x32_bf16 v[86:89], v[146:149], v[178:181], v[86:89]
	v_mfma_f32_16x16x32_bf16 v[82:85], v[154:157], v[178:181], v[82:85]
	v_mfma_f32_16x16x32_bf16 v[70:73], v[146:149], v[218:221], v[70:73]
	v_mfma_f32_16x16x32_bf16 v[66:69], v[154:157], v[218:221], v[66:69]
	v_mfma_f32_16x16x32_bf16 v[134:137], v[150:153], v[166:169], v[134:137]
	v_mfma_f32_16x16x32_bf16 v[130:133], v[158:161], v[166:169], v[130:133]
	v_mfma_f32_16x16x32_bf16 v[118:121], v[150:153], v[174:177], v[118:121]
	v_mfma_f32_16x16x32_bf16 v[114:117], v[158:161], v[174:177], v[114:117]
	v_mfma_f32_16x16x32_bf16 v[86:89], v[150:153], v[182:185], v[86:89]
	v_mfma_f32_16x16x32_bf16 v[82:85], v[158:161], v[182:185], v[82:85]
	v_mfma_f32_16x16x32_bf16 v[70:73], v[150:153], v[240:243], v[70:73]
	v_mfma_f32_16x16x32_bf16 v[66:69], v[158:161], v[240:243], v[66:69]
	s_setprio 0
	s_barrier
; #define PG8_STAGE(bufoff, gbase, voff) do { _Pragma("unroll") for (int _i = 0; _i < 2; ++_i) \
;         __builtin_amdgcn_global_load_lds((const unsigned*)((const char*)(gbase) + (voff)[_i]), (PG8_LAS unsigned*)(lds + (bufoff) + ldsw + _i * 8192), 16, 0, 0); } while (0)
; #define PG8_LDA(dst, b, h) do { _Pragma("unroll") for (int m = 0; m < 4; ++m) _Pragma("unroll") for (int k = 0; k < 2; ++k) dst[m][k] = *(const PG8_LAS bf16x8*)(lds + PG8_SA(b, h) + aoff + m * 2048 + k * 1024); } while (0)
; #define PG8_LDB(dst, b, h) do { _Pragma("unroll") for (int n = 0; n < 2; ++n) _Pragma("unroll") for (int k = 0; k < 2; ++k) dst[n][k] = *(const PG8_LAS bf16x8*)(lds + PG8_SB(b, h) + boff + n * 2048 + k * 1024); } while (0)
; #define PG8_MMA(ai, bj, At, Bt) do { __builtin_amdgcn_s_setprio(1); _Pragma("unroll") for (int m = 0; m < 4; ++m) _Pragma("unroll") for (int n = 0; n < 2; ++n) _Pragma("unroll") for (int k = 0; k < 2; ++k) \
;         acc[ai][bj][m][n] = __builtin_amdgcn_mfma_f32_16x16x32_bf16(Bt[n][k], At[m][k], acc[ai][bj][m][n], 0, 0, 0); __builtin_amdgcn_s_setprio(0); } while (0)
; #define PG8_WAIT_V(n) asm volatile("s_waitcnt vmcnt(" #n ")" ::: "memory")
; #define PG8_BAR __builtin_amdgcn_s_barrier()
; template <class Epi, class Sched, bool ALIGN_EPI = false, bool SP2 = false>
; __device__ __forceinline__ void gemm_phase(PG8_LAS unsigned char* lds, const Gemm g, const Sched& S, const Epi& E) {
;     ...
;         for (int t = 0; t < nt; t += 2) {
;             const bool last = (t == nt - 2);
;             const char* a1 = cA + (size_t)(t + 1) * kstep;
;             const char* a2 = last ? nA : cA + (size_t)(t + 2) * kstep; const char* b2 = last ? nB : cB + (size_t)(t + 2) * kstep;
;             const char* a3 = a2 + kstep; const char* b3 = b2 + kstep;
;             if (last && has_next) S.a_ready(nxt);
;             if constexpr (SP2) {
;             PG8_LDB(B0, 0, 0); PG8_LDB(B1, 0, 1); PG8_SCHED; PG8_LDA(At, 0, 0); PG8_STAGE(PG8_SA(1, 1), a1 + hstepA, voffA);
;     ...
;             PG8_LDA(At, 1, 1); PG8_STAGE(PG8_SB(1, 0), b3, voffB); PG8_STAGE(PG8_SB(1, 1), b3 + hstepB, voffB); PG8_STAGE(PG8_SA(1, 0), a3, voffA);
;             PG8_WAIT_V(8); PG8_WAIT_L(0); PG8_BAR; PG8_MMA(1, 0, At, B0); PG8_MMA(1, 1, At, B1); PG8_BAR; PG8_SCHED;
;             } else {
;             PG8_LDB(B0, 0, 0); PG8_SCHED; PG8_LDA(At, 0, 0); PG8_STAGE(PG8_SA(1, 1), a1 + hstepA, voffA);
	s_add_i32 s20, s20, s61
	v_lshl_add_u64 v[204:205], v[204:205], 0, s[22:23]
	s_mov_b32 m0, s20
	ds_read_b128 v[162:165], v227 offset:49152
	ds_read_b128 v[166:169], v227 offset:50176
	ds_read_b128 v[170:173], v227 offset:51200
	ds_read_b128 v[174:177], v227 offset:52224
	ds_read_b128 v[178:181], v227 offset:53248
	ds_read_b128 v[182:185], v227 offset:54272
	ds_read_b128 v[218:221], v227 offset:55296
	ds_read_b128 v[240:243], v227 offset:56320
	global_load_lds_dwordx4 v[204:205], off
	s_add_i32 m0, s20, 0x2000
	s_add_u32 s14, s14, 0x40080
	v_lshl_add_u64 v[204:205], v[234:235], 0, s[22:23]
	s_addc_u32 s15, s15, 0
	s_add_i32 s20, s21, s61
	global_load_lds_dwordx4 v[204:205], off
	v_lshl_add_u64 v[204:205], s[14:15], 0, v[0:1]
	s_mov_b32 m0, s20
	s_nop 0
	global_load_lds_dwordx4 v[204:205], off
	v_lshl_add_u64 v[204:205], s[14:15], 0, v[186:187]
	s_add_i32 m0, s20, 0x2000
	s_nop 0
	global_load_lds_dwordx4 v[204:205], off
	v_lshl_add_u64 v[204:205], v[244:245], 0, s[22:23]
	s_mov_b32 m0, s82
	s_nop 0
	global_load_lds_dwordx4 v[204:205], off
	v_lshl_add_u64 v[204:205], v[246:247], 0, s[22:23]
	s_mov_b32 m0, s83
	s_nop 0
	global_load_lds_dwordx4 v[204:205], off
	s_waitcnt vmcnt(8)
	s_waitcnt lgkmcnt(0)
	s_barrier
	s_setprio 1
	s_waitcnt lgkmcnt(0)
	v_mfma_f32_16x16x32_bf16 v[62:65], v[90:93], v[162:165], v[62:65]
	v_mfma_f32_16x16x32_bf16 v[58:61], v[98:101], v[162:165], v[58:61]
	v_mfma_f32_16x16x32_bf16 v[46:49], v[90:93], v[170:173], v[46:49]
	v_mfma_f32_16x16x32_bf16 v[42:45], v[98:101], v[170:173], v[42:45]
	v_mfma_f32_16x16x32_bf16 v[30:33], v[90:93], v[178:181], v[30:33]
	v_mfma_f32_16x16x32_bf16 v[26:29], v[98:101], v[178:181], v[26:29]
	v_mfma_f32_16x16x32_bf16 v[14:17], v[90:93], v[218:221], v[14:17]
	v_mfma_f32_16x16x32_bf16 v[10:13], v[98:101], v[218:221], v[10:13]
	v_mfma_f32_16x16x32_bf16 v[62:65], v[94:97], v[166:169], v[62:65]
	v_mfma_f32_16x16x32_bf16 v[58:61], v[102:105], v[166:169], v[58:61]
	v_mfma_f32_16x16x32_bf16 v[46:49], v[94:97], v[174:177], v[46:49]
	v_mfma_f32_16x16x32_bf16 v[42:45], v[102:105], v[174:177], v[42:45]
	v_mfma_f32_16x16x32_bf16 v[30:33], v[94:97], v[182:185], v[30:33]
	v_mfma_f32_16x16x32_bf16 v[26:29], v[102:105], v[182:185], v[26:29]
	v_mfma_f32_16x16x32_bf16 v[14:17], v[94:97], v[240:243], v[14:17]
	v_mfma_f32_16x16x32_bf16 v[10:13], v[102:105], v[240:243], v[10:13]
	v_mfma_f32_16x16x32_bf16 v[54:57], v[146:149], v[162:165], v[54:57]
	v_mfma_f32_16x16x32_bf16 v[50:53], v[154:157], v[162:165], v[50:53]
	v_mfma_f32_16x16x32_bf16 v[38:41], v[146:149], v[170:173], v[38:41]
	v_mfma_f32_16x16x32_bf16 v[34:37], v[154:157], v[170:173], v[34:37]
	v_mfma_f32_16x16x32_bf16 v[22:25], v[146:149], v[178:181], v[22:25]
	v_mfma_f32_16x16x32_bf16 v[18:21], v[154:157], v[178:181], v[18:21]
	v_mfma_f32_16x16x32_bf16 v[6:9], v[146:149], v[218:221], v[6:9]
	v_mfma_f32_16x16x32_bf16 v[2:5], v[154:157], v[218:221], v[2:5]
	v_mfma_f32_16x16x32_bf16 v[54:57], v[150:153], v[166:169], v[54:57]
	v_mfma_f32_16x16x32_bf16 v[50:53], v[158:161], v[166:169], v[50:53]
	v_mfma_f32_16x16x32_bf16 v[38:41], v[150:153], v[174:177], v[38:41]
	v_mfma_f32_16x16x32_bf16 v[34:37], v[158:161], v[174:177], v[34:37]
	v_mfma_f32_16x16x32_bf16 v[22:25], v[150:153], v[182:185], v[22:25]
	v_mfma_f32_16x16x32_bf16 v[18:21], v[158:161], v[182:185], v[18:21]
	v_mfma_f32_16x16x32_bf16 v[6:9], v[150:153], v[240:243], v[6:9]
	v_mfma_f32_16x16x32_bf16 v[2:5], v[158:161], v[240:243], v[2:5]
	s_setprio 0
	s_barrier
	s_add_i32 s85, s85, 2
	s_add_u32 s0, s0, 0x100
	s_addc_u32 s1, s1, 0
	s_add_u32 s54, s54, 0x100
	s_addc_u32 s55, s55, 0
	s_cmp_gt_u32 s85, 13
	s_cbranch_scc1 .Lpk_done_g1137
.LBB0_1137:
	s_add_u32 s14, s0, 0xfffc0080
	s_addc_u32 s15, s1, -1
	s_add_i32 s20, 0, 0x10000
	s_cmp_eq_u32 s85, 12
	s_cselect_b32 s37, s9, s15
	s_cselect_b32 s36, s39, s14
	s_cselect_b32 s15, s47, s55
	s_cselect_b32 s14, s53, s54
	s_add_i32 s21, 0, 0x14000
	v_add_u32_e32 v102, s20, v222
	v_add_u32_e32 v158, s21, v222
	ds_read_b128 v[90:93], v102
	ds_read_b128 v[94:97], v102 offset:1024
	ds_read_b128 v[98:101], v102 offset:2048
	ds_read_b128 v[102:105], v102 offset:3072
	ds_read_b128 v[146:149], v158
	ds_read_b128 v[150:153], v158 offset:1024
	ds_read_b128 v[154:157], v158 offset:2048
	ds_read_b128 v[158:161], v158 offset:3072
	v_lshl_add_u64 v[204:205], s[0:1], 0, v[214:215]
	s_add_i32 m0, s70, 0xc000
	ds_read_b128 v[162:165], v227
	ds_read_b128 v[166:169], v227 offset:1024
	ds_read_b128 v[170:173], v227 offset:2048
	ds_read_b128 v[174:177], v227 offset:3072
	ds_read_b128 v[178:181], v227 offset:4096
	ds_read_b128 v[182:185], v227 offset:5120
	ds_read_b128 v[218:221], v227 offset:6144
	ds_read_b128 v[240:243], v227 offset:7168
	global_load_lds_dwordx4 v[204:205], off
	v_lshl_add_u64 v[204:205], s[0:1], 0, v[216:217]
	s_add_i32 m0, s70, 0xe000
	s_nop 0
	global_load_lds_dwordx4 v[204:205], off
	s_waitcnt vmcnt(8)
	s_waitcnt lgkmcnt(0)
	s_barrier
; #define PG8_STAGE(bufoff, gbase, voff) do { _Pragma("unroll") for (int _i = 0; _i < 2; ++_i) \
;         __builtin_amdgcn_global_load_lds((const unsigned*)((const char*)(gbase) + (voff)[_i]), (PG8_LAS unsigned*)(lds + (bufoff) + ldsw + _i * 8192), 16, 0, 0); } while (0)
; #define PG8_LDA(dst, b, h) do { _Pragma("unroll") for (int m = 0; m < 4; ++m) _Pragma("unroll") for (int k = 0; k < 2; ++k) dst[m][k] = *(const PG8_LAS bf16x8*)(lds + PG8_SA(b, h) + aoff + m * 2048 + k * 1024); } while (0)
; #define PG8_LDB(dst, b, h) do { _Pragma("unroll") for (int n = 0; n < 2; ++n) _Pragma("unroll") for (int k = 0; k < 2; ++k) dst[n][k] = *(const PG8_LAS bf16x8*)(lds + PG8_SB(b, h) + boff + n * 2048 + k * 1024); } while (0)
; #define PG8_MMA(ai, bj, At, Bt) do { __builtin_amdgcn_s_setprio(1); _Pragma("unroll") for (int m = 0; m < 4; ++m) _Pragma("unroll") for (int n = 0; n < 2; ++n) _Pragma("unroll") for (int k = 0; k < 2; ++k) \
;         acc[ai][bj][m][n] = __builtin_amdgcn_mfma_f32_16x16x32_bf16(Bt[n][k], At[m][k], acc[ai][bj][m][n], 0, 0, 0); __builtin_amdgcn_s_setprio(0); } while (0)
; #define PG8_WAIT_V(n) asm volatile("s_waitcnt vmcnt(" #n ")" ::: "memory")
; #define PG8_WAIT_L(n) asm volatile("s_waitcnt lgkmcnt(" #n ")" ::: "memory")
; #define PG8_BAR __builtin_amdgcn_s_barrier()
; #define PG8_SCHED __builtin_amdgcn_sched_barrier(0)
; template <class Epi, class Sched, bool ALIGN_EPI = false, bool SP2 = false>
; __device__ __forceinline__ void gemm_phase(PG8_LAS unsigned char* lds, const Gemm g, const Sched& S, const Epi& E) {
;     ...
;             PG8_LDB(B0, 0, 0); PG8_LDB(B1, 0, 1); PG8_SCHED; PG8_LDA(At, 0, 0); PG8_STAGE(PG8_SA(1, 1), a1 + hstepA, voffA);
;             PG8_WAIT_V(8); PG8_WAIT_L(0); PG8_BAR; PG8_MMA(0, 0, At, B0); PG8_MMA(0, 1, At, B1); PG8_BAR; PG8_SCHED;
;             PG8_LDA(At, 0, 1); PG8_STAGE(PG8_SB(0, 0), b2, voffB); PG8_STAGE(PG8_SB(0, 1), b2 + hstepB, voffB); PG8_STAGE(PG8_SA(0, 0), a2, voffA);
;             PG8_WAIT_V(8); PG8_WAIT_L(0); PG8_BAR; PG8_MMA(1, 0, At, B0); PG8_MMA(1, 1, At, B1); PG8_BAR; PG8_SCHED;
	s_setprio 1
	s_waitcnt lgkmcnt(0)
	v_mfma_f32_16x16x32_bf16 v[142:145], v[90:93], v[162:165], v[142:145]
	v_mfma_f32_16x16x32_bf16 v[138:141], v[98:101], v[162:165], v[138:141]
	v_mfma_f32_16x16x32_bf16 v[126:129], v[90:93], v[170:173], v[126:129]
	v_mfma_f32_16x16x32_bf16 v[122:125], v[98:101], v[170:173], v[122:125]
	v_mfma_f32_16x16x32_bf16 v[110:113], v[90:93], v[178:181], v[110:113]
	v_mfma_f32_16x16x32_bf16 v[106:109], v[98:101], v[178:181], v[106:109]
	v_mfma_f32_16x16x32_bf16 v[78:81], v[90:93], v[218:221], v[78:81]
	v_mfma_f32_16x16x32_bf16 v[74:77], v[98:101], v[218:221], v[74:77]
	v_mfma_f32_16x16x32_bf16 v[142:145], v[94:97], v[166:169], v[142:145]
	v_mfma_f32_16x16x32_bf16 v[138:141], v[102:105], v[166:169], v[138:141]
	v_mfma_f32_16x16x32_bf16 v[126:129], v[94:97], v[174:177], v[126:129]
	v_mfma_f32_16x16x32_bf16 v[122:125], v[102:105], v[174:177], v[122:125]
	v_mfma_f32_16x16x32_bf16 v[110:113], v[94:97], v[182:185], v[110:113]
	v_mfma_f32_16x16x32_bf16 v[106:109], v[102:105], v[182:185], v[106:109]
	v_mfma_f32_16x16x32_bf16 v[78:81], v[94:97], v[240:243], v[78:81]
	v_mfma_f32_16x16x32_bf16 v[74:77], v[102:105], v[240:243], v[74:77]
	v_mfma_f32_16x16x32_bf16 v[134:137], v[146:149], v[162:165], v[134:137]
	v_mfma_f32_16x16x32_bf16 v[130:133], v[154:157], v[162:165], v[130:133]
	v_mfma_f32_16x16x32_bf16 v[118:121], v[146:149], v[170:173], v[118:121]
	v_mfma_f32_16x16x32_bf16 v[114:117], v[154:157], v[170:173], v[114:117]
	v_mfma_f32_16x16x32_bf16 v[86:89], v[146:149], v[178:181], v[86:89]
	v_mfma_f32_16x16x32_bf16 v[82:85], v[154:157], v[178:181], v[82:85]
	v_mfma_f32_16x16x32_bf16 v[70:73], v[146:149], v[218:221], v[70:73]
	v_mfma_f32_16x16x32_bf16 v[66:69], v[154:157], v[218:221], v[66:69]
	v_mfma_f32_16x16x32_bf16 v[134:137], v[150:153], v[166:169], v[134:137]
	v_mfma_f32_16x16x32_bf16 v[130:133], v[158:161], v[166:169], v[130:133]
	v_mfma_f32_16x16x32_bf16 v[118:121], v[150:153], v[174:177], v[118:121]
	v_mfma_f32_16x16x32_bf16 v[114:117], v[158:161], v[174:177], v[114:117]
	v_mfma_f32_16x16x32_bf16 v[86:89], v[150:153], v[182:185], v[86:89]
	v_mfma_f32_16x16x32_bf16 v[82:85], v[158:161], v[182:185], v[82:85]
	v_mfma_f32_16x16x32_bf16 v[70:73], v[150:153], v[240:243], v[70:73]
	v_mfma_f32_16x16x32_bf16 v[66:69], v[158:161], v[240:243], v[66:69]
	s_setprio 0
	s_barrier
	s_add_i32 s20, s20, s61
	v_lshl_add_u64 v[204:205], s[14:15], 0, v[0:1]
	s_mov_b32 m0, s20
	ds_read_b128 v[162:165], v227 offset:16384
	ds_read_b128 v[166:169], v227 offset:17408
	ds_read_b128 v[170:173], v227 offset:18432
	ds_read_b128 v[174:177], v227 offset:19456
	ds_read_b128 v[178:181], v227 offset:20480
	ds_read_b128 v[182:185], v227 offset:21504
	ds_read_b128 v[218:221], v227 offset:22528
	ds_read_b128 v[240:243], v227 offset:23552
	global_load_lds_dwordx4 v[204:205], off
	s_add_i32 m0, s20, 0x2000
	s_add_u32 s86, s14, 0x40000
	v_lshl_add_u64 v[234:235], s[14:15], 0, v[186:187]
	s_addc_u32 s87, s15, 0
	s_add_i32 s20, s21, s61
	global_load_lds_dwordx4 v[234:235], off
	v_lshl_add_u64 v[244:245], s[86:87], 0, v[0:1]
	s_mov_b32 m0, s20
	v_lshl_add_u64 v[246:247], s[36:37], 0, v[188:189]
	global_load_lds_dwordx4 v[244:245], off
	v_lshl_add_u64 v[244:245], s[86:87], 0, v[186:187]
	s_add_i32 m0, s20, 0x2000
	s_nop 0
	global_load_lds_dwordx4 v[244:245], off
	v_lshl_add_u64 v[244:245], s[36:37], 0, v[190:191]
	s_mov_b32 m0, s70
	s_nop 0
	global_load_lds_dwordx4 v[244:245], off
	s_mov_b32 m0, s71
	s_nop 0
	global_load_lds_dwordx4 v[246:247], off
	s_waitcnt vmcnt(8)
	s_waitcnt lgkmcnt(0)
	s_barrier
	s_setprio 1
	s_waitcnt lgkmcnt(0)
	v_mfma_f32_16x16x32_bf16 v[62:65], v[90:93], v[162:165], v[62:65]
	v_mfma_f32_16x16x32_bf16 v[58:61], v[98:101], v[162:165], v[58:61]
	v_mfma_f32_16x16x32_bf16 v[46:49], v[90:93], v[170:173], v[46:49]
	v_mfma_f32_16x16x32_bf16 v[42:45], v[98:101], v[170:173], v[42:45]
	v_mfma_f32_16x16x32_bf16 v[30:33], v[90:93], v[178:181], v[30:33]
	v_mfma_f32_16x16x32_bf16 v[26:29], v[98:101], v[178:181], v[26:29]
	v_mfma_f32_16x16x32_bf16 v[14:17], v[90:93], v[218:221], v[14:17]
	v_mfma_f32_16x16x32_bf16 v[10:13], v[98:101], v[218:221], v[10:13]
	v_mfma_f32_16x16x32_bf16 v[62:65], v[94:97], v[166:169], v[62:65]
	v_mfma_f32_16x16x32_bf16 v[58:61], v[102:105], v[166:169], v[58:61]
	v_mfma_f32_16x16x32_bf16 v[46:49], v[94:97], v[174:177], v[46:49]
	v_mfma_f32_16x16x32_bf16 v[42:45], v[102:105], v[174:177], v[42:45]
	v_mfma_f32_16x16x32_bf16 v[30:33], v[94:97], v[182:185], v[30:33]
	v_mfma_f32_16x16x32_bf16 v[26:29], v[102:105], v[182:185], v[26:29]
	v_mfma_f32_16x16x32_bf16 v[14:17], v[94:97], v[240:243], v[14:17]
	v_mfma_f32_16x16x32_bf16 v[10:13], v[102:105], v[240:243], v[10:13]
	v_mfma_f32_16x16x32_bf16 v[54:57], v[146:149], v[162:165], v[54:57]
	v_mfma_f32_16x16x32_bf16 v[50:53], v[154:157], v[162:165], v[50:53]
	v_mfma_f32_16x16x32_bf16 v[38:41], v[146:149], v[170:173], v[38:41]
	v_mfma_f32_16x16x32_bf16 v[34:37], v[154:157], v[170:173], v[34:37]
	v_mfma_f32_16x16x32_bf16 v[22:25], v[146:149], v[178:181], v[22:25]
	v_mfma_f32_16x16x32_bf16 v[18:21], v[154:157], v[178:181], v[18:21]
	v_mfma_f32_16x16x32_bf16 v[6:9], v[146:149], v[218:221], v[6:9]
	v_mfma_f32_16x16x32_bf16 v[2:5], v[154:157], v[218:221], v[2:5]
	v_mfma_f32_16x16x32_bf16 v[54:57], v[150:153], v[166:169], v[54:57]
	v_mfma_f32_16x16x32_bf16 v[50:53], v[158:161], v[166:169], v[50:53]
	v_mfma_f32_16x16x32_bf16 v[38:41], v[150:153], v[174:177], v[38:41]
	v_mfma_f32_16x16x32_bf16 v[34:37], v[158:161], v[174:177], v[34:37]
	v_mfma_f32_16x16x32_bf16 v[22:25], v[150:153], v[182:185], v[22:25]
	v_mfma_f32_16x16x32_bf16 v[18:21], v[158:161], v[182:185], v[18:21]
	v_mfma_f32_16x16x32_bf16 v[6:9], v[150:153], v[240:243], v[6:9]
	v_mfma_f32_16x16x32_bf16 v[2:5], v[158:161], v[240:243], v[2:5]
	s_setprio 0
	s_barrier
; #define PG8_STAGE(bufoff, gbase, voff) do { _Pragma("unroll") for (int _i = 0; _i < 2; ++_i) \
;         __builtin_amdgcn_global_load_lds((const unsigned*)((const char*)(gbase) + (voff)[_i]), (PG8_LAS unsigned*)(lds + (bufoff) + ldsw + _i * 8192), 16, 0, 0); } while (0)
; #define PG8_LDA(dst, b, h) do { _Pragma("unroll") for (int m = 0; m < 4; ++m) _Pragma("unroll") for (int k = 0; k < 2; ++k) dst[m][k] = *(const PG8_LAS bf16x8*)(lds + PG8_SA(b, h) + aoff + m * 2048 + k * 1024); } while (0)
; #define PG8_LDB(dst, b, h) do { _Pragma("unroll") for (int n = 0; n < 2; ++n) _Pragma("unroll") for (int k = 0; k < 2; ++k) dst[n][k] = *(const PG8_LAS bf16x8*)(lds + PG8_SB(b, h) + boff + n * 2048 + k * 1024); } while (0)
; #define PG8_MMA(ai, bj, At, Bt) do { __builtin_amdgcn_s_setprio(1); _Pragma("unroll") for (int m = 0; m < 4; ++m) _Pragma("unroll") for (int n = 0; n < 2; ++n) _Pragma("unroll") for (int k = 0; k < 2; ++k) \
;         acc[ai][bj][m][n] = __builtin_amdgcn_mfma_f32_16x16x32_bf16(Bt[n][k], At[m][k], acc[ai][bj][m][n], 0, 0, 0); __builtin_amdgcn_s_setprio(0); } while (0)
; #define PG8_WAIT_V(n) asm volatile("s_waitcnt vmcnt(" #n ")" ::: "memory")
; #define PG8_WAIT_L(n) asm volatile("s_waitcnt lgkmcnt(" #n ")" ::: "memory")
; #define PG8_BAR __builtin_amdgcn_s_barrier()
; #define PG8_SCHED __builtin_amdgcn_sched_barrier(0)
; template <class Epi, class Sched, bool ALIGN_EPI = false, bool SP2 = false>
; __device__ __forceinline__ void gemm_phase(PG8_LAS unsigned char* lds, const Gemm g, const Sched& S, const Epi& E) {
;     ...
;             PG8_LDB(B0, 1, 0); PG8_LDB(B1, 1, 1); PG8_SCHED; PG8_LDA(At, 1, 0); PG8_STAGE(PG8_SA(0, 1), a2 + hstepA, voffA);
;             PG8_WAIT_V(8); PG8_WAIT_L(0); PG8_BAR; PG8_MMA(0, 0, At, B0); PG8_MMA(0, 1, At, B1); PG8_BAR; PG8_SCHED;
	s_add_i32 s20, 0, 0x18000
	s_add_i32 s21, 0, 0x1c000
	v_add_u32_e32 v102, s20, v222
	v_add_u32_e32 v158, s21, v222
	ds_read_b128 v[90:93], v102
	ds_read_b128 v[94:97], v102 offset:1024
	ds_read_b128 v[98:101], v102 offset:2048
	ds_read_b128 v[102:105], v102 offset:3072
	ds_read_b128 v[146:149], v158
	ds_read_b128 v[150:153], v158 offset:1024
	ds_read_b128 v[154:157], v158 offset:2048
	ds_read_b128 v[158:161], v158 offset:3072
	s_add_u32 s36, s36, 0x40000
	s_addc_u32 s37, s37, 0
	s_mov_b32 m0, s78
	v_lshl_add_u64 v[248:249], s[36:37], 0, v[190:191]
	ds_read_b128 v[162:165], v227 offset:32768
	ds_read_b128 v[166:169], v227 offset:33792
	ds_read_b128 v[170:173], v227 offset:34816
	ds_read_b128 v[174:177], v227 offset:35840
	ds_read_b128 v[178:181], v227 offset:36864
	ds_read_b128 v[182:185], v227 offset:37888
	ds_read_b128 v[218:221], v227 offset:38912
	ds_read_b128 v[240:243], v227 offset:39936
	global_load_lds_dwordx4 v[248:249], off
	v_lshl_add_u64 v[248:249], s[36:37], 0, v[188:189]
	s_mov_b32 m0, s79
	s_nop 0
	global_load_lds_dwordx4 v[248:249], off
	s_waitcnt vmcnt(8)
	s_waitcnt lgkmcnt(0)
	s_barrier
	s_setprio 1
	s_waitcnt lgkmcnt(0)
	v_mfma_f32_16x16x32_bf16 v[142:145], v[90:93], v[162:165], v[142:145]
	v_mfma_f32_16x16x32_bf16 v[138:141], v[98:101], v[162:165], v[138:141]
	v_mfma_f32_16x16x32_bf16 v[126:129], v[90:93], v[170:173], v[126:129]
	v_mfma_f32_16x16x32_bf16 v[122:125], v[98:101], v[170:173], v[122:125]
	v_mfma_f32_16x16x32_bf16 v[110:113], v[90:93], v[178:181], v[110:113]
	v_mfma_f32_16x16x32_bf16 v[106:109], v[98:101], v[178:181], v[106:109]
	v_mfma_f32_16x16x32_bf16 v[78:81], v[90:93], v[218:221], v[78:81]
	v_mfma_f32_16x16x32_bf16 v[74:77], v[98:101], v[218:221], v[74:77]
	v_mfma_f32_16x16x32_bf16 v[142:145], v[94:97], v[166:169], v[142:145]
	v_mfma_f32_16x16x32_bf16 v[138:141], v[102:105], v[166:169], v[138:141]
	v_mfma_f32_16x16x32_bf16 v[126:129], v[94:97], v[174:177], v[126:129]
	v_mfma_f32_16x16x32_bf16 v[122:125], v[102:105], v[174:177], v[122:125]
	v_mfma_f32_16x16x32_bf16 v[110:113], v[94:97], v[182:185], v[110:113]
	v_mfma_f32_16x16x32_bf16 v[106:109], v[102:105], v[182:185], v[106:109]
	v_mfma_f32_16x16x32_bf16 v[78:81], v[94:97], v[240:243], v[78:81]
	v_mfma_f32_16x16x32_bf16 v[74:77], v[102:105], v[240:243], v[74:77]
	v_mfma_f32_16x16x32_bf16 v[134:137], v[146:149], v[162:165], v[134:137]
	v_mfma_f32_16x16x32_bf16 v[130:133], v[154:157], v[162:165], v[130:133]
	v_mfma_f32_16x16x32_bf16 v[118:121], v[146:149], v[170:173], v[118:121]
	v_mfma_f32_16x16x32_bf16 v[114:117], v[154:157], v[170:173], v[114:117]
	v_mfma_f32_16x16x32_bf16 v[86:89], v[146:149], v[178:181], v[86:89]
	v_mfma_f32_16x16x32_bf16 v[82:85], v[154:157], v[178:181], v[82:85]
	v_mfma_f32_16x16x32_bf16 v[70:73], v[146:149], v[218:221], v[70:73]
	v_mfma_f32_16x16x32_bf16 v[66:69], v[154:157], v[218:221], v[66:69]
	v_mfma_f32_16x16x32_bf16 v[134:137], v[150:153], v[166:169], v[134:137]
	v_mfma_f32_16x16x32_bf16 v[130:133], v[158:161], v[166:169], v[130:133]
	v_mfma_f32_16x16x32_bf16 v[118:121], v[150:153], v[174:177], v[118:121]
	v_mfma_f32_16x16x32_bf16 v[114:117], v[158:161], v[174:177], v[114:117]
	v_mfma_f32_16x16x32_bf16 v[86:89], v[150:153], v[182:185], v[86:89]
	v_mfma_f32_16x16x32_bf16 v[82:85], v[158:161], v[182:185], v[82:85]
	v_mfma_f32_16x16x32_bf16 v[70:73], v[150:153], v[240:243], v[70:73]
	v_mfma_f32_16x16x32_bf16 v[66:69], v[158:161], v[240:243], v[66:69]
	s_setprio 0
	s_barrier
; #define PG8_STAGE(bufoff, gbase, voff) do { _Pragma("unroll") for (int _i = 0; _i < 2; ++_i) \
;         __builtin_amdgcn_global_load_lds((const unsigned*)((const char*)(gbase) + (voff)[_i]), (PG8_LAS unsigned*)(lds + (bufoff) + ldsw + _i * 8192), 16, 0, 0); } while (0)
; #define PG8_LDA(dst, b, h) do { _Pragma("unroll") for (int m = 0; m < 4; ++m) _Pragma("unroll") for (int k = 0; k < 2; ++k) dst[m][k] = *(const PG8_LAS bf16x8*)(lds + PG8_SA(b, h) + aoff + m * 2048 + k * 1024); } while (0)
; #define PG8_MMA(ai, bj, At, Bt) do { __builtin_amdgcn_s_setprio(1); _Pragma("unroll") for (int m = 0; m < 4; ++m) _Pragma("unroll") for (int n = 0; n < 2; ++n) _Pragma("unroll") for (int k = 0; k < 2; ++k) \
;         acc[ai][bj][m][n] = __builtin_amdgcn_mfma_f32_16x16x32_bf16(Bt[n][k], At[m][k], acc[ai][bj][m][n], 0, 0, 0); __builtin_amdgcn_s_setprio(0); } while (0)
; #define PG8_WAIT_V(n) asm volatile("s_waitcnt vmcnt(" #n ")" ::: "memory")
; #define PG8_WAIT_L(n) asm volatile("s_waitcnt lgkmcnt(" #n ")" ::: "memory")
; #define PG8_BAR __builtin_amdgcn_s_barrier()
; #define PG8_SCHED __builtin_amdgcn_sched_barrier(0)
; template <class Epi, class Sched, bool ALIGN_EPI = false, bool SP2 = false>
; __device__ __forceinline__ void gemm_phase(PG8_LAS unsigned char* lds, const Gemm g, const Sched& S, const Epi& E) {
;     ...
;         for (int t = 0; t < nt; t += 2) {
;     ...
;             PG8_LDA(At, 1, 1); PG8_STAGE(PG8_SB(1, 0), b3, voffB); PG8_STAGE(PG8_SB(1, 1), b3 + hstepB, voffB); PG8_STAGE(PG8_SA(1, 0), a3, voffA);
;             PG8_WAIT_V(8); PG8_WAIT_L(0); PG8_BAR; PG8_MMA(1, 0, At, B0); PG8_MMA(1, 1, At, B1); PG8_BAR; PG8_SCHED;
	s_add_i32 s20, s20, s61
	v_lshl_add_u64 v[204:205], v[204:205], 0, s[22:23]
	s_mov_b32 m0, s20
	ds_read_b128 v[162:165], v227 offset:49152
	ds_read_b128 v[166:169], v227 offset:50176
	ds_read_b128 v[170:173], v227 offset:51200
	ds_read_b128 v[174:177], v227 offset:52224
	ds_read_b128 v[178:181], v227 offset:53248
	ds_read_b128 v[182:185], v227 offset:54272
	ds_read_b128 v[218:221], v227 offset:55296
	ds_read_b128 v[240:243], v227 offset:56320
	global_load_lds_dwordx4 v[204:205], off
	s_add_i32 m0, s20, 0x2000
	s_add_u32 s14, s14, 0x40080
	v_lshl_add_u64 v[204:205], v[234:235], 0, s[22:23]
	s_addc_u32 s15, s15, 0
	s_add_i32 s20, s21, s61
	global_load_lds_dwordx4 v[204:205], off
	v_lshl_add_u64 v[204:205], s[14:15], 0, v[0:1]
	s_mov_b32 m0, s20
	s_nop 0
	global_load_lds_dwordx4 v[204:205], off
	v_lshl_add_u64 v[204:205], s[14:15], 0, v[186:187]
	s_add_i32 m0, s20, 0x2000
	s_nop 0
	global_load_lds_dwordx4 v[204:205], off
	v_lshl_add_u64 v[204:205], v[244:245], 0, s[22:23]
	s_mov_b32 m0, s82
	s_nop 0
	global_load_lds_dwordx4 v[204:205], off
	v_lshl_add_u64 v[204:205], v[246:247], 0, s[22:23]
	s_mov_b32 m0, s83
	s_nop 0
	global_load_lds_dwordx4 v[204:205], off
	s_waitcnt vmcnt(8)
	s_waitcnt lgkmcnt(0)
	s_barrier
	s_setprio 1
	s_waitcnt lgkmcnt(0)
	v_mfma_f32_16x16x32_bf16 v[62:65], v[90:93], v[162:165], v[62:65]
	v_mfma_f32_16x16x32_bf16 v[58:61], v[98:101], v[162:165], v[58:61]
	v_mfma_f32_16x16x32_bf16 v[46:49], v[90:93], v[170:173], v[46:49]
	v_mfma_f32_16x16x32_bf16 v[42:45], v[98:101], v[170:173], v[42:45]
	v_mfma_f32_16x16x32_bf16 v[30:33], v[90:93], v[178:181], v[30:33]
	v_mfma_f32_16x16x32_bf16 v[26:29], v[98:101], v[178:181], v[26:29]
	v_mfma_f32_16x16x32_bf16 v[14:17], v[90:93], v[218:221], v[14:17]
	v_mfma_f32_16x16x32_bf16 v[10:13], v[98:101], v[218:221], v[10:13]
	v_mfma_f32_16x16x32_bf16 v[62:65], v[94:97], v[166:169], v[62:65]
	v_mfma_f32_16x16x32_bf16 v[58:61], v[102:105], v[166:169], v[58:61]
	v_mfma_f32_16x16x32_bf16 v[46:49], v[94:97], v[174:177], v[46:49]
	v_mfma_f32_16x16x32_bf16 v[42:45], v[102:105], v[174:177], v[42:45]
	v_mfma_f32_16x16x32_bf16 v[30:33], v[94:97], v[182:185], v[30:33]
	v_mfma_f32_16x16x32_bf16 v[26:29], v[102:105], v[182:185], v[26:29]
	v_mfma_f32_16x16x32_bf16 v[14:17], v[94:97], v[240:243], v[14:17]
	v_mfma_f32_16x16x32_bf16 v[10:13], v[102:105], v[240:243], v[10:13]
	v_mfma_f32_16x16x32_bf16 v[54:57], v[146:149], v[162:165], v[54:57]
	v_mfma_f32_16x16x32_bf16 v[50:53], v[154:157], v[162:165], v[50:53]
	v_mfma_f32_16x16x32_bf16 v[38:41], v[146:149], v[170:173], v[38:41]
	v_mfma_f32_16x16x32_bf16 v[34:37], v[154:157], v[170:173], v[34:37]
	v_mfma_f32_16x16x32_bf16 v[22:25], v[146:149], v[178:181], v[22:25]
	v_mfma_f32_16x16x32_bf16 v[18:21], v[154:157], v[178:181], v[18:21]
	v_mfma_f32_16x16x32_bf16 v[6:9], v[146:149], v[218:221], v[6:9]
	v_mfma_f32_16x16x32_bf16 v[2:5], v[154:157], v[218:221], v[2:5]
	v_mfma_f32_16x16x32_bf16 v[54:57], v[150:153], v[166:169], v[54:57]
	v_mfma_f32_16x16x32_bf16 v[50:53], v[158:161], v[166:169], v[50:53]
	v_mfma_f32_16x16x32_bf16 v[38:41], v[150:153], v[174:177], v[38:41]
	v_mfma_f32_16x16x32_bf16 v[34:37], v[158:161], v[174:177], v[34:37]
	v_mfma_f32_16x16x32_bf16 v[22:25], v[150:153], v[182:185], v[22:25]
	v_mfma_f32_16x16x32_bf16 v[18:21], v[158:161], v[182:185], v[18:21]
	v_mfma_f32_16x16x32_bf16 v[6:9], v[150:153], v[240:243], v[6:9]
	v_mfma_f32_16x16x32_bf16 v[2:5], v[158:161], v[240:243], v[2:5]
	s_setprio 0
	s_barrier
	s_add_i32 s85, s85, 2
	s_add_u32 s0, s0, 0x100
	s_addc_u32 s1, s1, 0
	s_add_u32 s54, s54, 0x100
	s_addc_u32 s55, s55, 0
	s_cmp_gt_u32 s85, 13
	s_cbranch_scc0 .LBB0_1137

; #define PG8_STAGE(bufoff, gbase, voff) do { _Pragma("unroll") for (int _i = 0; _i < 2; ++_i) \
;         __builtin_amdgcn_global_load_lds((const unsigned*)((const char*)(gbase) + (voff)[_i]), (PG8_LAS unsigned*)(lds + (bufoff) + ldsw + _i * 8192), 16, 0, 0); } while (0)
; #define PG8_LDA(dst, b, h) do { _Pragma("unroll") for (int m = 0; m < 4; ++m) _Pragma("unroll") for (int k = 0; k < 2; ++k) dst[m][k] = *(const PG8_LAS bf16x8*)(lds + PG8_SA(b, h) + aoff + m * 2048 + k * 1024); } while (0)
; #define PG8_LDB(dst, b, h) do { _Pragma("unroll") for (int n = 0; n < 2; ++n) _Pragma("unroll") for (int k = 0; k < 2; ++k) dst[n][k] = *(const PG8_LAS bf16x8*)(lds + PG8_SB(b, h) + boff + n * 2048 + k * 1024); } while (0)
; #define PG8_MMA(ai, bj, At, Bt) do { __builtin_amdgcn_s_setprio(1); _Pragma("unroll") for (int m = 0; m < 4; ++m) _Pragma("unroll") for (int n = 0; n < 2; ++n) _Pragma("unroll") for (int k = 0; k < 2; ++k) \
;         acc[ai][bj][m][n] = __builtin_amdgcn_mfma_f32_16x16x32_bf16(Bt[n][k], At[m][k], acc[ai][bj][m][n], 0, 0, 0); __builtin_amdgcn_s_setprio(0); } while (0)
; #define PG8_WAIT_V(n) asm volatile("s_waitcnt vmcnt(" #n ")" ::: "memory")
; #define PG8_BAR __builtin_amdgcn_s_barrier()
; template <class Epi, class Sched, bool ALIGN_EPI = false, bool SP2 = false>
; __device__ __forceinline__ void gemm_phase(PG8_LAS unsigned char* lds, const Gemm g, const Sched& S, const Epi& E) {
;     ...
;         const bool has_next = S.next(ui + 1, nxt);
;         const char* nA = has_next ? (const char*)g.A + (size_t)nxt.pm * tstepA + (size_t)nxt.pb * g.sA : cA; const char* nB = has_next ? (const char*)g.Bt + (size_t)nxt.pn * tstepB + (size_t)nxt.pb * g.sB : cB;
;         for (int t = 0; t < nt; t += 2) {
;             const bool last = (t == nt - 2);
;             const char* a1 = cA + (size_t)(t + 1) * kstep;
;             const char* a2 = last ? nA : cA + (size_t)(t + 2) * kstep; const char* b2 = last ? nB : cB + (size_t)(t + 2) * kstep;
;             const char* a3 = a2 + kstep; const char* b3 = b2 + kstep;
;             if (last && has_next) S.a_ready(nxt);
;             if constexpr (SP2) {
;             PG8_LDB(B0, 0, 0); PG8_LDB(B1, 0, 1); PG8_SCHED; PG8_LDA(At, 0, 0); PG8_STAGE(PG8_SA(1, 1), a1 + hstepA, voffA);
;             PG8_WAIT_V(8); PG8_WAIT_L(0); PG8_BAR; PG8_MMA(0, 0, At, B0); PG8_MMA(0, 1, At, B1); PG8_BAR; PG8_SCHED;
.LBB0_1211:
	s_ashr_i32 s29, s28, 31
	s_lshl_b64 s[20:21], s[28:29], 19
	s_add_u32 s30, s10, s20
	s_addc_u32 s31, s11, s21
	s_and_b64 s[20:21], s[42:43], exec
	s_cselect_b32 s29, s31, s9
	s_cselect_b32 s62, s30, s8
	s_ashr_i32 s19, s18, 31
	s_lshl_b64 s[20:21], s[18:19], 19
	s_add_u32 s34, s45, s20
	s_addc_u32 s35, s46, s21
	s_and_b64 s[20:21], s[42:43], exec
	s_cselect_b32 s19, s35, s37
	s_cselect_b32 s63, s34, s36
	s_add_u32 s8, s8, 0x40080
	s_addc_u32 s9, s9, 0
	s_add_u32 s70, s36, 0x100
	s_addc_u32 s71, s37, 0
	s_mov_b32 s76, -2
	s_add_u32 s20, s8, 0xfffc0080
	s_addc_u32 s21, s9, -1
	s_add_i32 s77, 0, 0x10000
	s_cmp_eq_u32 s76, 12
	s_cselect_b32 s39, s29, s21
	s_cselect_b32 s38, s62, s20
	v_add_u32_e32 v149, s77, v146
	s_cselect_b32 s37, s19, s71
	s_cselect_b32 s36, s63, s70
	s_add_i32 s78, 0, 0x14000
	ds_read_b128 v[140:143], v149
	ds_read_b128 v[150:153], v149 offset:1024
	ds_read_b128 v[154:157], v149 offset:2048
	ds_read_b128 v[158:161], v149 offset:3072
	v_add_u32_e32 v149, s78, v146
	ds_read_b128 v[162:165], v149
	ds_read_b128 v[166:169], v149 offset:1024
	ds_read_b128 v[170:173], v149 offset:2048
	ds_read_b128 v[174:177], v149 offset:3072
	v_lshl_add_u64 v[204:205], s[8:9], 0, v[136:137]
	s_add_i32 m0, s52, 0xc000
	ds_read_b128 v[178:181], v148
	ds_read_b128 v[182:185], v148 offset:1024
	ds_read_b128 v[186:189], v148 offset:2048
	ds_read_b128 v[190:193], v148 offset:3072
	ds_read_b128 v[194:197], v148 offset:4096
	ds_read_b128 v[198:201], v148 offset:5120
	ds_read_b128 v[208:211], v148 offset:6144
	ds_read_b128 v[212:215], v148 offset:7168
	global_load_lds_dwordx4 v[204:205], off
	v_lshl_add_u64 v[204:205], s[8:9], 0, v[138:139]
	s_add_i32 m0, s52, 0xe000
	s_nop 0
	global_load_lds_dwordx4 v[204:205], off
	s_waitcnt vmcnt(8)
	s_waitcnt lgkmcnt(0)
	s_barrier
	s_setprio 1
	s_waitcnt lgkmcnt(0)
	v_mfma_f32_16x16x32_bf16 v[126:129], v[140:143], v[178:181], 0
	v_mfma_f32_16x16x32_bf16 v[118:121], v[154:157], v[178:181], 0
	v_mfma_f32_16x16x32_bf16 v[110:113], v[140:143], v[186:189], 0
	v_mfma_f32_16x16x32_bf16 v[102:105], v[154:157], v[186:189], 0
	v_mfma_f32_16x16x32_bf16 v[94:97], v[140:143], v[194:197], 0
	v_mfma_f32_16x16x32_bf16 v[86:89], v[154:157], v[194:197], 0
	v_mfma_f32_16x16x32_bf16 v[78:81], v[140:143], v[208:211], 0
	v_mfma_f32_16x16x32_bf16 v[70:73], v[154:157], v[208:211], 0
	v_mfma_f32_16x16x32_bf16 v[126:129], v[150:153], v[182:185], v[126:129]
	v_mfma_f32_16x16x32_bf16 v[118:121], v[158:161], v[182:185], v[118:121]
	v_mfma_f32_16x16x32_bf16 v[110:113], v[150:153], v[190:193], v[110:113]
	v_mfma_f32_16x16x32_bf16 v[102:105], v[158:161], v[190:193], v[102:105]
	v_mfma_f32_16x16x32_bf16 v[94:97], v[150:153], v[198:201], v[94:97]
	v_mfma_f32_16x16x32_bf16 v[86:89], v[158:161], v[198:201], v[86:89]
	v_mfma_f32_16x16x32_bf16 v[78:81], v[150:153], v[212:215], v[78:81]
	v_mfma_f32_16x16x32_bf16 v[70:73], v[158:161], v[212:215], v[70:73]
	v_mfma_f32_16x16x32_bf16 v[122:125], v[162:165], v[178:181], 0
	v_mfma_f32_16x16x32_bf16 v[114:117], v[170:173], v[178:181], 0
	v_mfma_f32_16x16x32_bf16 v[106:109], v[162:165], v[186:189], 0
	v_mfma_f32_16x16x32_bf16 v[98:101], v[170:173], v[186:189], 0
	v_mfma_f32_16x16x32_bf16 v[90:93], v[162:165], v[194:197], 0
	v_mfma_f32_16x16x32_bf16 v[82:85], v[170:173], v[194:197], 0
	v_mfma_f32_16x16x32_bf16 v[74:77], v[162:165], v[208:211], 0
	v_mfma_f32_16x16x32_bf16 v[66:69], v[170:173], v[208:211], 0
	v_mfma_f32_16x16x32_bf16 v[122:125], v[166:169], v[182:185], v[122:125]
	v_mfma_f32_16x16x32_bf16 v[114:117], v[174:177], v[182:185], v[114:117]
	v_mfma_f32_16x16x32_bf16 v[106:109], v[166:169], v[190:193], v[106:109]
	v_mfma_f32_16x16x32_bf16 v[98:101], v[174:177], v[190:193], v[98:101]
	v_mfma_f32_16x16x32_bf16 v[90:93], v[166:169], v[198:201], v[90:93]
	v_mfma_f32_16x16x32_bf16 v[82:85], v[174:177], v[198:201], v[82:85]
	v_mfma_f32_16x16x32_bf16 v[74:77], v[166:169], v[212:215], v[74:77]
	v_mfma_f32_16x16x32_bf16 v[66:69], v[174:177], v[212:215], v[66:69]
	s_setprio 0
	s_barrier
	s_add_i32 s20, s77, s47
	v_lshl_add_u64 v[204:205], s[36:37], 0, v[0:1]
	s_mov_b32 m0, s20
	ds_read_b128 v[178:181], v148 offset:16384
	ds_read_b128 v[182:185], v148 offset:17408
	ds_read_b128 v[186:189], v148 offset:18432
	ds_read_b128 v[190:193], v148 offset:19456
	ds_read_b128 v[194:197], v148 offset:20480
	ds_read_b128 v[198:201], v148 offset:21504
	ds_read_b128 v[208:211], v148 offset:22528
	ds_read_b128 v[212:215], v148 offset:23552
	global_load_lds_dwordx4 v[204:205], off
	s_add_i32 m0, s20, 0x2000
	s_add_u32 s20, s36, 0x40000
	v_lshl_add_u64 v[216:217], s[36:37], 0, v[130:131]
	s_addc_u32 s21, s37, 0
	s_add_i32 s77, s78, s47
	global_load_lds_dwordx4 v[216:217], off
	v_lshl_add_u64 v[218:219], s[20:21], 0, v[0:1]
	s_mov_b32 m0, s77
	v_lshl_add_u64 v[220:221], s[38:39], 0, v[132:133]
	global_load_lds_dwordx4 v[218:219], off
	v_lshl_add_u64 v[218:219], s[20:21], 0, v[130:131]
	s_add_i32 m0, s77, 0x2000
	s_nop 0
	global_load_lds_dwordx4 v[218:219], off
	v_lshl_add_u64 v[218:219], s[38:39], 0, v[134:135]
	s_mov_b32 m0, s52
	s_nop 0
	global_load_lds_dwordx4 v[218:219], off
	s_mov_b32 m0, s53
	s_nop 0
	global_load_lds_dwordx4 v[220:221], off
	s_waitcnt vmcnt(8)
	s_waitcnt lgkmcnt(0)
	s_barrier
; #define PG8_STAGE(bufoff, gbase, voff) do { _Pragma("unroll") for (int _i = 0; _i < 2; ++_i) \
;         __builtin_amdgcn_global_load_lds((const unsigned*)((const char*)(gbase) + (voff)[_i]), (PG8_LAS unsigned*)(lds + (bufoff) + ldsw + _i * 8192), 16, 0, 0); } while (0)
; #define PG8_LDA(dst, b, h) do { _Pragma("unroll") for (int m = 0; m < 4; ++m) _Pragma("unroll") for (int k = 0; k < 2; ++k) dst[m][k] = *(const PG8_LAS bf16x8*)(lds + PG8_SA(b, h) + aoff + m * 2048 + k * 1024); } while (0)
; #define PG8_LDB(dst, b, h) do { _Pragma("unroll") for (int n = 0; n < 2; ++n) _Pragma("unroll") for (int k = 0; k < 2; ++k) dst[n][k] = *(const PG8_LAS bf16x8*)(lds + PG8_SB(b, h) + boff + n * 2048 + k * 1024); } while (0)
; #define PG8_MMA(ai, bj, At, Bt) do { __builtin_amdgcn_s_setprio(1); _Pragma("unroll") for (int m = 0; m < 4; ++m) _Pragma("unroll") for (int n = 0; n < 2; ++n) _Pragma("unroll") for (int k = 0; k < 2; ++k) \
;         acc[ai][bj][m][n] = __builtin_amdgcn_mfma_f32_16x16x32_bf16(Bt[n][k], At[m][k], acc[ai][bj][m][n], 0, 0, 0); __builtin_amdgcn_s_setprio(0); } while (0)
; #define PG8_WAIT_V(n) asm volatile("s_waitcnt vmcnt(" #n ")" ::: "memory")
; #define PG8_WAIT_L(n) asm volatile("s_waitcnt lgkmcnt(" #n ")" ::: "memory")
; #define PG8_BAR __builtin_amdgcn_s_barrier()
; #define PG8_SCHED __builtin_amdgcn_sched_barrier(0)
; template <class Epi, class Sched, bool ALIGN_EPI = false, bool SP2 = false>
; __device__ __forceinline__ void gemm_phase(PG8_LAS unsigned char* lds, const Gemm g, const Sched& S, const Epi& E) {
;     ...
;             PG8_LDA(At, 0, 1); PG8_STAGE(PG8_SB(0, 0), b2, voffB); PG8_STAGE(PG8_SB(0, 1), b2 + hstepB, voffB); PG8_STAGE(PG8_SA(0, 0), a2, voffA);
;             PG8_WAIT_V(8); PG8_WAIT_L(0); PG8_BAR; PG8_MMA(1, 0, At, B0); PG8_MMA(1, 1, At, B1); PG8_BAR; PG8_SCHED;
;             PG8_LDB(B0, 1, 0); PG8_LDB(B1, 1, 1); PG8_SCHED; PG8_LDA(At, 1, 0); PG8_STAGE(PG8_SA(0, 1), a2 + hstepA, voffA);
;             PG8_WAIT_V(8); PG8_WAIT_L(0); PG8_BAR; PG8_MMA(0, 0, At, B0); PG8_MMA(0, 1, At, B1); PG8_BAR; PG8_SCHED;
	s_setprio 1
	s_waitcnt lgkmcnt(0)
	v_mfma_f32_16x16x32_bf16 v[62:65], v[140:143], v[178:181], 0
	v_mfma_f32_16x16x32_bf16 v[54:57], v[154:157], v[178:181], 0
	v_mfma_f32_16x16x32_bf16 v[46:49], v[140:143], v[186:189], 0
	v_mfma_f32_16x16x32_bf16 v[38:41], v[154:157], v[186:189], 0
	v_mfma_f32_16x16x32_bf16 v[30:33], v[140:143], v[194:197], 0
	v_mfma_f32_16x16x32_bf16 v[22:25], v[154:157], v[194:197], 0
	v_mfma_f32_16x16x32_bf16 v[14:17], v[140:143], v[208:211], 0
	v_mfma_f32_16x16x32_bf16 v[6:9], v[154:157], v[208:211], 0
	v_mfma_f32_16x16x32_bf16 v[62:65], v[150:153], v[182:185], v[62:65]
	v_mfma_f32_16x16x32_bf16 v[54:57], v[158:161], v[182:185], v[54:57]
	v_mfma_f32_16x16x32_bf16 v[46:49], v[150:153], v[190:193], v[46:49]
	v_mfma_f32_16x16x32_bf16 v[38:41], v[158:161], v[190:193], v[38:41]
	v_mfma_f32_16x16x32_bf16 v[30:33], v[150:153], v[198:201], v[30:33]
	v_mfma_f32_16x16x32_bf16 v[22:25], v[158:161], v[198:201], v[22:25]
	v_mfma_f32_16x16x32_bf16 v[14:17], v[150:153], v[212:215], v[14:17]
	v_mfma_f32_16x16x32_bf16 v[6:9], v[158:161], v[212:215], v[6:9]
	v_mfma_f32_16x16x32_bf16 v[58:61], v[162:165], v[178:181], 0
	v_mfma_f32_16x16x32_bf16 v[50:53], v[170:173], v[178:181], 0
	v_mfma_f32_16x16x32_bf16 v[42:45], v[162:165], v[186:189], 0
	v_mfma_f32_16x16x32_bf16 v[34:37], v[170:173], v[186:189], 0
	v_mfma_f32_16x16x32_bf16 v[26:29], v[162:165], v[194:197], 0
	v_mfma_f32_16x16x32_bf16 v[18:21], v[170:173], v[194:197], 0
	v_mfma_f32_16x16x32_bf16 v[10:13], v[162:165], v[208:211], 0
	v_mfma_f32_16x16x32_bf16 v[2:5], v[170:173], v[208:211], 0
	v_mfma_f32_16x16x32_bf16 v[58:61], v[166:169], v[182:185], v[58:61]
	v_mfma_f32_16x16x32_bf16 v[50:53], v[174:177], v[182:185], v[50:53]
	v_mfma_f32_16x16x32_bf16 v[42:45], v[166:169], v[190:193], v[42:45]
	v_mfma_f32_16x16x32_bf16 v[34:37], v[174:177], v[190:193], v[34:37]
	v_mfma_f32_16x16x32_bf16 v[26:29], v[166:169], v[198:201], v[26:29]
	v_mfma_f32_16x16x32_bf16 v[18:21], v[174:177], v[198:201], v[18:21]
	v_mfma_f32_16x16x32_bf16 v[10:13], v[166:169], v[212:215], v[10:13]
	v_mfma_f32_16x16x32_bf16 v[2:5], v[174:177], v[212:215], v[2:5]
	s_setprio 0
	s_barrier
	s_add_i32 s77, 0, 0x18000
	v_add_u32_e32 v149, s77, v146
	s_add_i32 s78, 0, 0x1c000
	ds_read_b128 v[140:143], v149
	ds_read_b128 v[150:153], v149 offset:1024
	ds_read_b128 v[154:157], v149 offset:2048
	ds_read_b128 v[158:161], v149 offset:3072
	v_add_u32_e32 v149, s78, v146
	ds_read_b128 v[162:165], v149
	ds_read_b128 v[166:169], v149 offset:1024
	ds_read_b128 v[170:173], v149 offset:2048
	ds_read_b128 v[174:177], v149 offset:3072
	s_add_u32 s20, s38, 0x40000
	s_addc_u32 s21, s39, 0
	s_mov_b32 m0, s54
	v_lshl_add_u64 v[222:223], s[20:21], 0, v[134:135]
	ds_read_b128 v[178:181], v148 offset:32768
	ds_read_b128 v[182:185], v148 offset:33792
	ds_read_b128 v[186:189], v148 offset:34816
	ds_read_b128 v[190:193], v148 offset:35840
	ds_read_b128 v[194:197], v148 offset:36864
	ds_read_b128 v[198:201], v148 offset:37888
	ds_read_b128 v[208:211], v148 offset:38912
	ds_read_b128 v[212:215], v148 offset:39936
	global_load_lds_dwordx4 v[222:223], off
	v_lshl_add_u64 v[222:223], s[20:21], 0, v[132:133]
	s_mov_b32 m0, s55
	s_nop 0
	global_load_lds_dwordx4 v[222:223], off
	s_waitcnt vmcnt(8)
	s_waitcnt lgkmcnt(0)
	s_barrier
	s_setprio 1
	s_waitcnt lgkmcnt(0)
	v_mfma_f32_16x16x32_bf16 v[126:129], v[140:143], v[178:181], v[126:129]
	v_mfma_f32_16x16x32_bf16 v[118:121], v[154:157], v[178:181], v[118:121]
	v_mfma_f32_16x16x32_bf16 v[110:113], v[140:143], v[186:189], v[110:113]
	v_mfma_f32_16x16x32_bf16 v[102:105], v[154:157], v[186:189], v[102:105]
	v_mfma_f32_16x16x32_bf16 v[94:97], v[140:143], v[194:197], v[94:97]
	v_mfma_f32_16x16x32_bf16 v[86:89], v[154:157], v[194:197], v[86:89]
	v_mfma_f32_16x16x32_bf16 v[78:81], v[140:143], v[208:211], v[78:81]
	v_mfma_f32_16x16x32_bf16 v[70:73], v[154:157], v[208:211], v[70:73]
	v_mfma_f32_16x16x32_bf16 v[126:129], v[150:153], v[182:185], v[126:129]
	v_mfma_f32_16x16x32_bf16 v[118:121], v[158:161], v[182:185], v[118:121]
	v_mfma_f32_16x16x32_bf16 v[110:113], v[150:153], v[190:193], v[110:113]
	v_mfma_f32_16x16x32_bf16 v[102:105], v[158:161], v[190:193], v[102:105]
	v_mfma_f32_16x16x32_bf16 v[94:97], v[150:153], v[198:201], v[94:97]
	v_mfma_f32_16x16x32_bf16 v[86:89], v[158:161], v[198:201], v[86:89]
	v_mfma_f32_16x16x32_bf16 v[78:81], v[150:153], v[212:215], v[78:81]
	v_mfma_f32_16x16x32_bf16 v[70:73], v[158:161], v[212:215], v[70:73]
	v_mfma_f32_16x16x32_bf16 v[122:125], v[162:165], v[178:181], v[122:125]
	v_mfma_f32_16x16x32_bf16 v[114:117], v[170:173], v[178:181], v[114:117]
	v_mfma_f32_16x16x32_bf16 v[106:109], v[162:165], v[186:189], v[106:109]
	v_mfma_f32_16x16x32_bf16 v[98:101], v[170:173], v[186:189], v[98:101]
	v_mfma_f32_16x16x32_bf16 v[90:93], v[162:165], v[194:197], v[90:93]
	v_mfma_f32_16x16x32_bf16 v[82:85], v[170:173], v[194:197], v[82:85]
	v_mfma_f32_16x16x32_bf16 v[74:77], v[162:165], v[208:211], v[74:77]
	v_mfma_f32_16x16x32_bf16 v[66:69], v[170:173], v[208:211], v[66:69]
	v_mfma_f32_16x16x32_bf16 v[122:125], v[166:169], v[182:185], v[122:125]
	v_mfma_f32_16x16x32_bf16 v[114:117], v[174:177], v[182:185], v[114:117]
	v_mfma_f32_16x16x32_bf16 v[106:109], v[166:169], v[190:193], v[106:109]
	v_mfma_f32_16x16x32_bf16 v[98:101], v[174:177], v[190:193], v[98:101]
	v_mfma_f32_16x16x32_bf16 v[90:93], v[166:169], v[198:201], v[90:93]
	v_mfma_f32_16x16x32_bf16 v[82:85], v[174:177], v[198:201], v[82:85]
	v_mfma_f32_16x16x32_bf16 v[74:77], v[166:169], v[212:215], v[74:77]
	v_mfma_f32_16x16x32_bf16 v[66:69], v[174:177], v[212:215], v[66:69]
	s_setprio 0
	s_barrier
; #define PG8_STAGE(bufoff, gbase, voff) do { _Pragma("unroll") for (int _i = 0; _i < 2; ++_i) \
;         __builtin_amdgcn_global_load_lds((const unsigned*)((const char*)(gbase) + (voff)[_i]), (PG8_LAS unsigned*)(lds + (bufoff) + ldsw + _i * 8192), 16, 0, 0); } while (0)
; #define PG8_LDA(dst, b, h) do { _Pragma("unroll") for (int m = 0; m < 4; ++m) _Pragma("unroll") for (int k = 0; k < 2; ++k) dst[m][k] = *(const PG8_LAS bf16x8*)(lds + PG8_SA(b, h) + aoff + m * 2048 + k * 1024); } while (0)
; #define PG8_LDB(dst, b, h) do { _Pragma("unroll") for (int n = 0; n < 2; ++n) _Pragma("unroll") for (int k = 0; k < 2; ++k) dst[n][k] = *(const PG8_LAS bf16x8*)(lds + PG8_SB(b, h) + boff + n * 2048 + k * 1024); } while (0)
; #define PG8_MMA(ai, bj, At, Bt) do { __builtin_amdgcn_s_setprio(1); _Pragma("unroll") for (int m = 0; m < 4; ++m) _Pragma("unroll") for (int n = 0; n < 2; ++n) _Pragma("unroll") for (int k = 0; k < 2; ++k) \
;         acc[ai][bj][m][n] = __builtin_amdgcn_mfma_f32_16x16x32_bf16(Bt[n][k], At[m][k], acc[ai][bj][m][n], 0, 0, 0); __builtin_amdgcn_s_setprio(0); } while (0)
; #define PG8_WAIT_V(n) asm volatile("s_waitcnt vmcnt(" #n ")" ::: "memory")
; #define PG8_BAR __builtin_amdgcn_s_barrier()
; template <class Epi, class Sched, bool ALIGN_EPI = false, bool SP2 = false>
; __device__ __forceinline__ void gemm_phase(PG8_LAS unsigned char* lds, const Gemm g, const Sched& S, const Epi& E) {
;     ...
;         for (int t = 0; t < nt; t += 2) {
;             const bool last = (t == nt - 2);
;             const char* a1 = cA + (size_t)(t + 1) * kstep;
;             const char* a2 = last ? nA : cA + (size_t)(t + 2) * kstep; const char* b2 = last ? nB : cB + (size_t)(t + 2) * kstep;
;             const char* a3 = a2 + kstep; const char* b3 = b2 + kstep;
;             if (last && has_next) S.a_ready(nxt);
;             if constexpr (SP2) {
;             PG8_LDB(B0, 0, 0); PG8_LDB(B1, 0, 1); PG8_SCHED; PG8_LDA(At, 0, 0); PG8_STAGE(PG8_SA(1, 1), a1 + hstepA, voffA);
;     ...
;             PG8_LDA(At, 1, 1); PG8_STAGE(PG8_SB(1, 0), b3, voffB); PG8_STAGE(PG8_SB(1, 1), b3 + hstepB, voffB); PG8_STAGE(PG8_SA(1, 0), a3, voffA);
;             PG8_WAIT_V(8); PG8_WAIT_L(0); PG8_BAR; PG8_MMA(1, 0, At, B0); PG8_MMA(1, 1, At, B1); PG8_BAR; PG8_SCHED;
;             } else {
;             PG8_LDB(B0, 0, 0); PG8_SCHED; PG8_LDA(At, 0, 0); PG8_STAGE(PG8_SA(1, 1), a1 + hstepA, voffA);
	s_add_i32 s20, s77, s47
	v_lshl_add_u64 v[204:205], v[204:205], 0, s[22:23]
	s_mov_b32 m0, s20
	ds_read_b128 v[178:181], v148 offset:49152
	ds_read_b128 v[182:185], v148 offset:50176
	ds_read_b128 v[186:189], v148 offset:51200
	ds_read_b128 v[190:193], v148 offset:52224
	ds_read_b128 v[194:197], v148 offset:53248
	ds_read_b128 v[198:201], v148 offset:54272
	ds_read_b128 v[208:211], v148 offset:55296
	ds_read_b128 v[212:215], v148 offset:56320
	global_load_lds_dwordx4 v[204:205], off
	s_add_i32 m0, s20, 0x2000
	s_add_u32 s20, s36, 0x40080
	v_lshl_add_u64 v[204:205], v[216:217], 0, s[22:23]
	s_addc_u32 s21, s37, 0
	s_add_i32 s36, s78, s47
	global_load_lds_dwordx4 v[204:205], off
	v_lshl_add_u64 v[204:205], s[20:21], 0, v[0:1]
	s_mov_b32 m0, s36
	s_nop 0
	global_load_lds_dwordx4 v[204:205], off
	v_lshl_add_u64 v[204:205], s[20:21], 0, v[130:131]
	s_add_i32 m0, s36, 0x2000
	s_nop 0
	global_load_lds_dwordx4 v[204:205], off
	v_lshl_add_u64 v[204:205], v[218:219], 0, s[22:23]
	s_mov_b32 m0, s56
	s_nop 0
	global_load_lds_dwordx4 v[204:205], off
	v_lshl_add_u64 v[204:205], v[220:221], 0, s[22:23]
	s_mov_b32 m0, s57
	s_nop 0
	global_load_lds_dwordx4 v[204:205], off
	s_waitcnt vmcnt(8)
	s_waitcnt lgkmcnt(0)
	s_barrier
	s_setprio 1
	s_waitcnt lgkmcnt(0)
	v_mfma_f32_16x16x32_bf16 v[62:65], v[140:143], v[178:181], v[62:65]
	v_mfma_f32_16x16x32_bf16 v[54:57], v[154:157], v[178:181], v[54:57]
	v_mfma_f32_16x16x32_bf16 v[46:49], v[140:143], v[186:189], v[46:49]
	v_mfma_f32_16x16x32_bf16 v[38:41], v[154:157], v[186:189], v[38:41]
	v_mfma_f32_16x16x32_bf16 v[30:33], v[140:143], v[194:197], v[30:33]
	v_mfma_f32_16x16x32_bf16 v[22:25], v[154:157], v[194:197], v[22:25]
	v_mfma_f32_16x16x32_bf16 v[14:17], v[140:143], v[208:211], v[14:17]
	v_mfma_f32_16x16x32_bf16 v[6:9], v[154:157], v[208:211], v[6:9]
	v_mfma_f32_16x16x32_bf16 v[62:65], v[150:153], v[182:185], v[62:65]
	v_mfma_f32_16x16x32_bf16 v[54:57], v[158:161], v[182:185], v[54:57]
	v_mfma_f32_16x16x32_bf16 v[46:49], v[150:153], v[190:193], v[46:49]
	v_mfma_f32_16x16x32_bf16 v[38:41], v[158:161], v[190:193], v[38:41]
	v_mfma_f32_16x16x32_bf16 v[30:33], v[150:153], v[198:201], v[30:33]
	v_mfma_f32_16x16x32_bf16 v[22:25], v[158:161], v[198:201], v[22:25]
	v_mfma_f32_16x16x32_bf16 v[14:17], v[150:153], v[212:215], v[14:17]
	v_mfma_f32_16x16x32_bf16 v[6:9], v[158:161], v[212:215], v[6:9]
	v_mfma_f32_16x16x32_bf16 v[58:61], v[162:165], v[178:181], v[58:61]
	v_mfma_f32_16x16x32_bf16 v[50:53], v[170:173], v[178:181], v[50:53]
	v_mfma_f32_16x16x32_bf16 v[42:45], v[162:165], v[186:189], v[42:45]
	v_mfma_f32_16x16x32_bf16 v[34:37], v[170:173], v[186:189], v[34:37]
	v_mfma_f32_16x16x32_bf16 v[26:29], v[162:165], v[194:197], v[26:29]
	v_mfma_f32_16x16x32_bf16 v[18:21], v[170:173], v[194:197], v[18:21]
	v_mfma_f32_16x16x32_bf16 v[10:13], v[162:165], v[208:211], v[10:13]
	v_mfma_f32_16x16x32_bf16 v[2:5], v[170:173], v[208:211], v[2:5]
	v_mfma_f32_16x16x32_bf16 v[58:61], v[166:169], v[182:185], v[58:61]
	v_mfma_f32_16x16x32_bf16 v[50:53], v[174:177], v[182:185], v[50:53]
	v_mfma_f32_16x16x32_bf16 v[42:45], v[166:169], v[190:193], v[42:45]
	v_mfma_f32_16x16x32_bf16 v[34:37], v[174:177], v[190:193], v[34:37]
	v_mfma_f32_16x16x32_bf16 v[26:29], v[166:169], v[198:201], v[26:29]
	v_mfma_f32_16x16x32_bf16 v[18:21], v[174:177], v[198:201], v[18:21]
	v_mfma_f32_16x16x32_bf16 v[10:13], v[166:169], v[212:215], v[10:13]
	v_mfma_f32_16x16x32_bf16 v[2:5], v[174:177], v[212:215], v[2:5]
	s_setprio 0
	s_barrier
	s_add_i32 s76, s76, 2
	s_add_u32 s8, s8, 0x100
	s_addc_u32 s9, s9, 0
	s_add_u32 s70, s70, 0x100
	s_addc_u32 s71, s71, 0
	s_cmp_gt_u32 s76, 13
	s_cbranch_scc1 .Lpk_done_up
.LBB0_1212:
	s_add_u32 s20, s8, 0xfffc0080
	s_addc_u32 s21, s9, -1
	s_add_i32 s77, 0, 0x10000
	s_cmp_eq_u32 s76, 12
	s_cselect_b32 s39, s29, s21
	s_cselect_b32 s38, s62, s20
	v_add_u32_e32 v149, s77, v146
	s_cselect_b32 s37, s19, s71
	s_cselect_b32 s36, s63, s70
	s_add_i32 s78, 0, 0x14000
	ds_read_b128 v[140:143], v149
	ds_read_b128 v[150:153], v149 offset:1024
	ds_read_b128 v[154:157], v149 offset:2048
	ds_read_b128 v[158:161], v149 offset:3072
	v_add_u32_e32 v149, s78, v146
	ds_read_b128 v[162:165], v149
	ds_read_b128 v[166:169], v149 offset:1024
	ds_read_b128 v[170:173], v149 offset:2048
	ds_read_b128 v[174:177], v149 offset:3072
	v_lshl_add_u64 v[204:205], s[8:9], 0, v[136:137]
	s_add_i32 m0, s52, 0xc000
	ds_read_b128 v[178:181], v148
	ds_read_b128 v[182:185], v148 offset:1024
	ds_read_b128 v[186:189], v148 offset:2048
	ds_read_b128 v[190:193], v148 offset:3072
	ds_read_b128 v[194:197], v148 offset:4096
	ds_read_b128 v[198:201], v148 offset:5120
	ds_read_b128 v[208:211], v148 offset:6144
	ds_read_b128 v[212:215], v148 offset:7168
	global_load_lds_dwordx4 v[204:205], off
	v_lshl_add_u64 v[204:205], s[8:9], 0, v[138:139]
	s_add_i32 m0, s52, 0xe000
	s_nop 0
	global_load_lds_dwordx4 v[204:205], off
	s_waitcnt vmcnt(8)
	s_waitcnt lgkmcnt(0)
	s_barrier
; #define PG8_STAGE(bufoff, gbase, voff) do { _Pragma("unroll") for (int _i = 0; _i < 2; ++_i) \
;         __builtin_amdgcn_global_load_lds((const unsigned*)((const char*)(gbase) + (voff)[_i]), (PG8_LAS unsigned*)(lds + (bufoff) + ldsw + _i * 8192), 16, 0, 0); } while (0)
; #define PG8_LDA(dst, b, h) do { _Pragma("unroll") for (int m = 0; m < 4; ++m) _Pragma("unroll") for (int k = 0; k < 2; ++k) dst[m][k] = *(const PG8_LAS bf16x8*)(lds + PG8_SA(b, h) + aoff + m * 2048 + k * 1024); } while (0)
; #define PG8_LDB(dst, b, h) do { _Pragma("unroll") for (int n = 0; n < 2; ++n) _Pragma("unroll") for (int k = 0; k < 2; ++k) dst[n][k] = *(const PG8_LAS bf16x8*)(lds + PG8_SB(b, h) + boff + n * 2048 + k * 1024); } while (0)
; #define PG8_MMA(ai, bj, At, Bt) do { __builtin_amdgcn_s_setprio(1); _Pragma("unroll") for (int m = 0; m < 4; ++m) _Pragma("unroll") for (int n = 0; n < 2; ++n) _Pragma("unroll") for (int k = 0; k < 2; ++k) \
;         acc[ai][bj][m][n] = __builtin_amdgcn_mfma_f32_16x16x32_bf16(Bt[n][k], At[m][k], acc[ai][bj][m][n], 0, 0, 0); __builtin_amdgcn_s_setprio(0); } while (0)
; #define PG8_WAIT_V(n) asm volatile("s_waitcnt vmcnt(" #n ")" ::: "memory")
; #define PG8_WAIT_L(n) asm volatile("s_waitcnt lgkmcnt(" #n ")" ::: "memory")
; #define PG8_BAR __builtin_amdgcn_s_barrier()
; #define PG8_SCHED __builtin_amdgcn_sched_barrier(0)
; template <class Epi, class Sched, bool ALIGN_EPI = false, bool SP2 = false>
; __device__ __forceinline__ void gemm_phase(PG8_LAS unsigned char* lds, const Gemm g, const Sched& S, const Epi& E) {
;     ...
;             PG8_LDB(B0, 0, 0); PG8_LDB(B1, 0, 1); PG8_SCHED; PG8_LDA(At, 0, 0); PG8_STAGE(PG8_SA(1, 1), a1 + hstepA, voffA);
;             PG8_WAIT_V(8); PG8_WAIT_L(0); PG8_BAR; PG8_MMA(0, 0, At, B0); PG8_MMA(0, 1, At, B1); PG8_BAR; PG8_SCHED;
;             PG8_LDA(At, 0, 1); PG8_STAGE(PG8_SB(0, 0), b2, voffB); PG8_STAGE(PG8_SB(0, 1), b2 + hstepB, voffB); PG8_STAGE(PG8_SA(0, 0), a2, voffA);
;             PG8_WAIT_V(8); PG8_WAIT_L(0); PG8_BAR; PG8_MMA(1, 0, At, B0); PG8_MMA(1, 1, At, B1); PG8_BAR; PG8_SCHED;
	s_setprio 1
	s_waitcnt lgkmcnt(0)
	v_mfma_f32_16x16x32_bf16 v[126:129], v[140:143], v[178:181], v[126:129]
	v_mfma_f32_16x16x32_bf16 v[118:121], v[154:157], v[178:181], v[118:121]
	v_mfma_f32_16x16x32_bf16 v[110:113], v[140:143], v[186:189], v[110:113]
	v_mfma_f32_16x16x32_bf16 v[102:105], v[154:157], v[186:189], v[102:105]
	v_mfma_f32_16x16x32_bf16 v[94:97], v[140:143], v[194:197], v[94:97]
	v_mfma_f32_16x16x32_bf16 v[86:89], v[154:157], v[194:197], v[86:89]
	v_mfma_f32_16x16x32_bf16 v[78:81], v[140:143], v[208:211], v[78:81]
	v_mfma_f32_16x16x32_bf16 v[70:73], v[154:157], v[208:211], v[70:73]
	v_mfma_f32_16x16x32_bf16 v[126:129], v[150:153], v[182:185], v[126:129]
	v_mfma_f32_16x16x32_bf16 v[118:121], v[158:161], v[182:185], v[118:121]
	v_mfma_f32_16x16x32_bf16 v[110:113], v[150:153], v[190:193], v[110:113]
	v_mfma_f32_16x16x32_bf16 v[102:105], v[158:161], v[190:193], v[102:105]
	v_mfma_f32_16x16x32_bf16 v[94:97], v[150:153], v[198:201], v[94:97]
	v_mfma_f32_16x16x32_bf16 v[86:89], v[158:161], v[198:201], v[86:89]
	v_mfma_f32_16x16x32_bf16 v[78:81], v[150:153], v[212:215], v[78:81]
	v_mfma_f32_16x16x32_bf16 v[70:73], v[158:161], v[212:215], v[70:73]
	v_mfma_f32_16x16x32_bf16 v[122:125], v[162:165], v[178:181], v[122:125]
	v_mfma_f32_16x16x32_bf16 v[114:117], v[170:173], v[178:181], v[114:117]
	v_mfma_f32_16x16x32_bf16 v[106:109], v[162:165], v[186:189], v[106:109]
	v_mfma_f32_16x16x32_bf16 v[98:101], v[170:173], v[186:189], v[98:101]
	v_mfma_f32_16x16x32_bf16 v[90:93], v[162:165], v[194:197], v[90:93]
	v_mfma_f32_16x16x32_bf16 v[82:85], v[170:173], v[194:197], v[82:85]
	v_mfma_f32_16x16x32_bf16 v[74:77], v[162:165], v[208:211], v[74:77]
	v_mfma_f32_16x16x32_bf16 v[66:69], v[170:173], v[208:211], v[66:69]
	v_mfma_f32_16x16x32_bf16 v[122:125], v[166:169], v[182:185], v[122:125]
	v_mfma_f32_16x16x32_bf16 v[114:117], v[174:177], v[182:185], v[114:117]
	v_mfma_f32_16x16x32_bf16 v[106:109], v[166:169], v[190:193], v[106:109]
	v_mfma_f32_16x16x32_bf16 v[98:101], v[174:177], v[190:193], v[98:101]
	v_mfma_f32_16x16x32_bf16 v[90:93], v[166:169], v[198:201], v[90:93]
	v_mfma_f32_16x16x32_bf16 v[82:85], v[174:177], v[198:201], v[82:85]
	v_mfma_f32_16x16x32_bf16 v[74:77], v[166:169], v[212:215], v[74:77]
	v_mfma_f32_16x16x32_bf16 v[66:69], v[174:177], v[212:215], v[66:69]
	s_setprio 0
	s_barrier
	s_add_i32 s20, s77, s47
	v_lshl_add_u64 v[204:205], s[36:37], 0, v[0:1]
	s_mov_b32 m0, s20
	ds_read_b128 v[178:181], v148 offset:16384
	ds_read_b128 v[182:185], v148 offset:17408
	ds_read_b128 v[186:189], v148 offset:18432
	ds_read_b128 v[190:193], v148 offset:19456
	ds_read_b128 v[194:197], v148 offset:20480
	ds_read_b128 v[198:201], v148 offset:21504
	ds_read_b128 v[208:211], v148 offset:22528
	ds_read_b128 v[212:215], v148 offset:23552
	global_load_lds_dwordx4 v[204:205], off
	s_add_i32 m0, s20, 0x2000
	s_add_u32 s20, s36, 0x40000
	v_lshl_add_u64 v[216:217], s[36:37], 0, v[130:131]
	s_addc_u32 s21, s37, 0
	s_add_i32 s77, s78, s47
	global_load_lds_dwordx4 v[216:217], off
	v_lshl_add_u64 v[218:219], s[20:21], 0, v[0:1]
	s_mov_b32 m0, s77
	v_lshl_add_u64 v[220:221], s[38:39], 0, v[132:133]
	global_load_lds_dwordx4 v[218:219], off
	v_lshl_add_u64 v[218:219], s[20:21], 0, v[130:131]
	s_add_i32 m0, s77, 0x2000
	s_nop 0
	global_load_lds_dwordx4 v[218:219], off
	v_lshl_add_u64 v[218:219], s[38:39], 0, v[134:135]
	s_mov_b32 m0, s52
	s_nop 0
	global_load_lds_dwordx4 v[218:219], off
	s_mov_b32 m0, s53
	s_nop 0
	global_load_lds_dwordx4 v[220:221], off
	s_waitcnt vmcnt(8)
	s_waitcnt lgkmcnt(0)
	s_barrier
	s_setprio 1
	s_waitcnt lgkmcnt(0)
	v_mfma_f32_16x16x32_bf16 v[62:65], v[140:143], v[178:181], v[62:65]
	v_mfma_f32_16x16x32_bf16 v[54:57], v[154:157], v[178:181], v[54:57]
	v_mfma_f32_16x16x32_bf16 v[46:49], v[140:143], v[186:189], v[46:49]
	v_mfma_f32_16x16x32_bf16 v[38:41], v[154:157], v[186:189], v[38:41]
	v_mfma_f32_16x16x32_bf16 v[30:33], v[140:143], v[194:197], v[30:33]
	v_mfma_f32_16x16x32_bf16 v[22:25], v[154:157], v[194:197], v[22:25]
	v_mfma_f32_16x16x32_bf16 v[14:17], v[140:143], v[208:211], v[14:17]
	v_mfma_f32_16x16x32_bf16 v[6:9], v[154:157], v[208:211], v[6:9]
	v_mfma_f32_16x16x32_bf16 v[62:65], v[150:153], v[182:185], v[62:65]
	v_mfma_f32_16x16x32_bf16 v[54:57], v[158:161], v[182:185], v[54:57]
	v_mfma_f32_16x16x32_bf16 v[46:49], v[150:153], v[190:193], v[46:49]
	v_mfma_f32_16x16x32_bf16 v[38:41], v[158:161], v[190:193], v[38:41]
	v_mfma_f32_16x16x32_bf16 v[30:33], v[150:153], v[198:201], v[30:33]
	v_mfma_f32_16x16x32_bf16 v[22:25], v[158:161], v[198:201], v[22:25]
	v_mfma_f32_16x16x32_bf16 v[14:17], v[150:153], v[212:215], v[14:17]
	v_mfma_f32_16x16x32_bf16 v[6:9], v[158:161], v[212:215], v[6:9]
	v_mfma_f32_16x16x32_bf16 v[58:61], v[162:165], v[178:181], v[58:61]
	v_mfma_f32_16x16x32_bf16 v[50:53], v[170:173], v[178:181], v[50:53]
	v_mfma_f32_16x16x32_bf16 v[42:45], v[162:165], v[186:189], v[42:45]
	v_mfma_f32_16x16x32_bf16 v[34:37], v[170:173], v[186:189], v[34:37]
	v_mfma_f32_16x16x32_bf16 v[26:29], v[162:165], v[194:197], v[26:29]
	v_mfma_f32_16x16x32_bf16 v[18:21], v[170:173], v[194:197], v[18:21]
	v_mfma_f32_16x16x32_bf16 v[10:13], v[162:165], v[208:211], v[10:13]
	v_mfma_f32_16x16x32_bf16 v[2:5], v[170:173], v[208:211], v[2:5]
	v_mfma_f32_16x16x32_bf16 v[58:61], v[166:169], v[182:185], v[58:61]
	v_mfma_f32_16x16x32_bf16 v[50:53], v[174:177], v[182:185], v[50:53]
	v_mfma_f32_16x16x32_bf16 v[42:45], v[166:169], v[190:193], v[42:45]
	v_mfma_f32_16x16x32_bf16 v[34:37], v[174:177], v[190:193], v[34:37]
	v_mfma_f32_16x16x32_bf16 v[26:29], v[166:169], v[198:201], v[26:29]
	v_mfma_f32_16x16x32_bf16 v[18:21], v[174:177], v[198:201], v[18:21]
	v_mfma_f32_16x16x32_bf16 v[10:13], v[166:169], v[212:215], v[10:13]
	v_mfma_f32_16x16x32_bf16 v[2:5], v[174:177], v[212:215], v[2:5]
	s_setprio 0
	s_barrier
; #define PG8_STAGE(bufoff, gbase, voff) do { _Pragma("unroll") for (int _i = 0; _i < 2; ++_i) \
;         __builtin_amdgcn_global_load_lds((const unsigned*)((const char*)(gbase) + (voff)[_i]), (PG8_LAS unsigned*)(lds + (bufoff) + ldsw + _i * 8192), 16, 0, 0); } while (0)
; #define PG8_LDA(dst, b, h) do { _Pragma("unroll") for (int m = 0; m < 4; ++m) _Pragma("unroll") for (int k = 0; k < 2; ++k) dst[m][k] = *(const PG8_LAS bf16x8*)(lds + PG8_SA(b, h) + aoff + m * 2048 + k * 1024); } while (0)
; #define PG8_LDB(dst, b, h) do { _Pragma("unroll") for (int n = 0; n < 2; ++n) _Pragma("unroll") for (int k = 0; k < 2; ++k) dst[n][k] = *(const PG8_LAS bf16x8*)(lds + PG8_SB(b, h) + boff + n * 2048 + k * 1024); } while (0)
; #define PG8_MMA(ai, bj, At, Bt) do { __builtin_amdgcn_s_setprio(1); _Pragma("unroll") for (int m = 0; m < 4; ++m) _Pragma("unroll") for (int n = 0; n < 2; ++n) _Pragma("unroll") for (int k = 0; k < 2; ++k) \
;         acc[ai][bj][m][n] = __builtin_amdgcn_mfma_f32_16x16x32_bf16(Bt[n][k], At[m][k], acc[ai][bj][m][n], 0, 0, 0); __builtin_amdgcn_s_setprio(0); } while (0)
; #define PG8_WAIT_V(n) asm volatile("s_waitcnt vmcnt(" #n ")" ::: "memory")
; #define PG8_WAIT_L(n) asm volatile("s_waitcnt lgkmcnt(" #n ")" ::: "memory")
; #define PG8_BAR __builtin_amdgcn_s_barrier()
; #define PG8_SCHED __builtin_amdgcn_sched_barrier(0)
; template <class Epi, class Sched, bool ALIGN_EPI = false, bool SP2 = false>
; __device__ __forceinline__ void gemm_phase(PG8_LAS unsigned char* lds, const Gemm g, const Sched& S, const Epi& E) {
;     ...
;             PG8_LDB(B0, 1, 0); PG8_LDB(B1, 1, 1); PG8_SCHED; PG8_LDA(At, 1, 0); PG8_STAGE(PG8_SA(0, 1), a2 + hstepA, voffA);
;             PG8_WAIT_V(8); PG8_WAIT_L(0); PG8_BAR; PG8_MMA(0, 0, At, B0); PG8_MMA(0, 1, At, B1); PG8_BAR; PG8_SCHED;
	s_add_i32 s77, 0, 0x18000
	v_add_u32_e32 v149, s77, v146
	s_add_i32 s78, 0, 0x1c000
	ds_read_b128 v[140:143], v149
	ds_read_b128 v[150:153], v149 offset:1024
	ds_read_b128 v[154:157], v149 offset:2048
	ds_read_b128 v[158:161], v149 offset:3072
	v_add_u32_e32 v149, s78, v146
	ds_read_b128 v[162:165], v149
	ds_read_b128 v[166:169], v149 offset:1024
	ds_read_b128 v[170:173], v149 offset:2048
	ds_read_b128 v[174:177], v149 offset:3072
	s_add_u32 s20, s38, 0x40000
	s_addc_u32 s21, s39, 0
	s_mov_b32 m0, s54
	v_lshl_add_u64 v[222:223], s[20:21], 0, v[134:135]
	ds_read_b128 v[178:181], v148 offset:32768
	ds_read_b128 v[182:185], v148 offset:33792
	ds_read_b128 v[186:189], v148 offset:34816
	ds_read_b128 v[190:193], v148 offset:35840
	ds_read_b128 v[194:197], v148 offset:36864
	ds_read_b128 v[198:201], v148 offset:37888
	ds_read_b128 v[208:211], v148 offset:38912
	ds_read_b128 v[212:215], v148 offset:39936
	global_load_lds_dwordx4 v[222:223], off
	v_lshl_add_u64 v[222:223], s[20:21], 0, v[132:133]
	s_mov_b32 m0, s55
	s_nop 0
	global_load_lds_dwordx4 v[222:223], off
	s_waitcnt vmcnt(8)
	s_waitcnt lgkmcnt(0)
	s_barrier
	s_setprio 1
	s_waitcnt lgkmcnt(0)
	v_mfma_f32_16x16x32_bf16 v[126:129], v[140:143], v[178:181], v[126:129]
	v_mfma_f32_16x16x32_bf16 v[118:121], v[154:157], v[178:181], v[118:121]
	v_mfma_f32_16x16x32_bf16 v[110:113], v[140:143], v[186:189], v[110:113]
	v_mfma_f32_16x16x32_bf16 v[102:105], v[154:157], v[186:189], v[102:105]
	v_mfma_f32_16x16x32_bf16 v[94:97], v[140:143], v[194:197], v[94:97]
	v_mfma_f32_16x16x32_bf16 v[86:89], v[154:157], v[194:197], v[86:89]
	v_mfma_f32_16x16x32_bf16 v[78:81], v[140:143], v[208:211], v[78:81]
	v_mfma_f32_16x16x32_bf16 v[70:73], v[154:157], v[208:211], v[70:73]
	v_mfma_f32_16x16x32_bf16 v[126:129], v[150:153], v[182:185], v[126:129]
	v_mfma_f32_16x16x32_bf16 v[118:121], v[158:161], v[182:185], v[118:121]
	v_mfma_f32_16x16x32_bf16 v[110:113], v[150:153], v[190:193], v[110:113]
	v_mfma_f32_16x16x32_bf16 v[102:105], v[158:161], v[190:193], v[102:105]
	v_mfma_f32_16x16x32_bf16 v[94:97], v[150:153], v[198:201], v[94:97]
	v_mfma_f32_16x16x32_bf16 v[86:89], v[158:161], v[198:201], v[86:89]
	v_mfma_f32_16x16x32_bf16 v[78:81], v[150:153], v[212:215], v[78:81]
	v_mfma_f32_16x16x32_bf16 v[70:73], v[158:161], v[212:215], v[70:73]
	v_mfma_f32_16x16x32_bf16 v[122:125], v[162:165], v[178:181], v[122:125]
	v_mfma_f32_16x16x32_bf16 v[114:117], v[170:173], v[178:181], v[114:117]
	v_mfma_f32_16x16x32_bf16 v[106:109], v[162:165], v[186:189], v[106:109]
	v_mfma_f32_16x16x32_bf16 v[98:101], v[170:173], v[186:189], v[98:101]
	v_mfma_f32_16x16x32_bf16 v[90:93], v[162:165], v[194:197], v[90:93]
	v_mfma_f32_16x16x32_bf16 v[82:85], v[170:173], v[194:197], v[82:85]
	v_mfma_f32_16x16x32_bf16 v[74:77], v[162:165], v[208:211], v[74:77]
	v_mfma_f32_16x16x32_bf16 v[66:69], v[170:173], v[208:211], v[66:69]
	v_mfma_f32_16x16x32_bf16 v[122:125], v[166:169], v[182:185], v[122:125]
	v_mfma_f32_16x16x32_bf16 v[114:117], v[174:177], v[182:185], v[114:117]
	v_mfma_f32_16x16x32_bf16 v[106:109], v[166:169], v[190:193], v[106:109]
	v_mfma_f32_16x16x32_bf16 v[98:101], v[174:177], v[190:193], v[98:101]
	v_mfma_f32_16x16x32_bf16 v[90:93], v[166:169], v[198:201], v[90:93]
	v_mfma_f32_16x16x32_bf16 v[82:85], v[174:177], v[198:201], v[82:85]
	v_mfma_f32_16x16x32_bf16 v[74:77], v[166:169], v[212:215], v[74:77]
	v_mfma_f32_16x16x32_bf16 v[66:69], v[174:177], v[212:215], v[66:69]
	s_setprio 0
	s_barrier
; #define PG8_STAGE(bufoff, gbase, voff) do { _Pragma("unroll") for (int _i = 0; _i < 2; ++_i) \
;         __builtin_amdgcn_global_load_lds((const unsigned*)((const char*)(gbase) + (voff)[_i]), (PG8_LAS unsigned*)(lds + (bufoff) + ldsw + _i * 8192), 16, 0, 0); } while (0)
; #define PG8_LDA(dst, b, h) do { _Pragma("unroll") for (int m = 0; m < 4; ++m) _Pragma("unroll") for (int k = 0; k < 2; ++k) dst[m][k] = *(const PG8_LAS bf16x8*)(lds + PG8_SA(b, h) + aoff + m * 2048 + k * 1024); } while (0)
; #define PG8_MMA(ai, bj, At, Bt) do { __builtin_amdgcn_s_setprio(1); _Pragma("unroll") for (int m = 0; m < 4; ++m) _Pragma("unroll") for (int n = 0; n < 2; ++n) _Pragma("unroll") for (int k = 0; k < 2; ++k) \
;         acc[ai][bj][m][n] = __builtin_amdgcn_mfma_f32_16x16x32_bf16(Bt[n][k], At[m][k], acc[ai][bj][m][n], 0, 0, 0); __builtin_amdgcn_s_setprio(0); } while (0)
; #define PG8_WAIT_V(n) asm volatile("s_waitcnt vmcnt(" #n ")" ::: "memory")
; #define PG8_WAIT_L(n) asm volatile("s_waitcnt lgkmcnt(" #n ")" ::: "memory")
; #define PG8_BAR __builtin_amdgcn_s_barrier()
; #define PG8_SCHED __builtin_amdgcn_sched_barrier(0)
; template <class Epi, class Sched, bool ALIGN_EPI = false, bool SP2 = false>
; __device__ __forceinline__ void gemm_phase(PG8_LAS unsigned char* lds, const Gemm g, const Sched& S, const Epi& E) {
;     ...
;         for (int t = 0; t < nt; t += 2) {
;     ...
;             PG8_LDA(At, 1, 1); PG8_STAGE(PG8_SB(1, 0), b3, voffB); PG8_STAGE(PG8_SB(1, 1), b3 + hstepB, voffB); PG8_STAGE(PG8_SA(1, 0), a3, voffA);
;             PG8_WAIT_V(8); PG8_WAIT_L(0); PG8_BAR; PG8_MMA(1, 0, At, B0); PG8_MMA(1, 1, At, B1); PG8_BAR; PG8_SCHED;
	s_add_i32 s20, s77, s47
	v_lshl_add_u64 v[204:205], v[204:205], 0, s[22:23]
	s_mov_b32 m0, s20
	ds_read_b128 v[178:181], v148 offset:49152
	ds_read_b128 v[182:185], v148 offset:50176
	ds_read_b128 v[186:189], v148 offset:51200
	ds_read_b128 v[190:193], v148 offset:52224
	ds_read_b128 v[194:197], v148 offset:53248
	ds_read_b128 v[198:201], v148 offset:54272
	ds_read_b128 v[208:211], v148 offset:55296
	ds_read_b128 v[212:215], v148 offset:56320
	global_load_lds_dwordx4 v[204:205], off
	s_add_i32 m0, s20, 0x2000
	s_add_u32 s20, s36, 0x40080
	v_lshl_add_u64 v[204:205], v[216:217], 0, s[22:23]
	s_addc_u32 s21, s37, 0
	s_add_i32 s36, s78, s47
	global_load_lds_dwordx4 v[204:205], off
	v_lshl_add_u64 v[204:205], s[20:21], 0, v[0:1]
	s_mov_b32 m0, s36
	s_nop 0
	global_load_lds_dwordx4 v[204:205], off
	v_lshl_add_u64 v[204:205], s[20:21], 0, v[130:131]
	s_add_i32 m0, s36, 0x2000
	s_nop 0
	global_load_lds_dwordx4 v[204:205], off
	v_lshl_add_u64 v[204:205], v[218:219], 0, s[22:23]
	s_mov_b32 m0, s56
	s_nop 0
	global_load_lds_dwordx4 v[204:205], off
	v_lshl_add_u64 v[204:205], v[220:221], 0, s[22:23]
	s_mov_b32 m0, s57
	s_nop 0
	global_load_lds_dwordx4 v[204:205], off
	s_waitcnt vmcnt(8)
	s_waitcnt lgkmcnt(0)
	s_barrier
	s_setprio 1
	s_waitcnt lgkmcnt(0)
	v_mfma_f32_16x16x32_bf16 v[62:65], v[140:143], v[178:181], v[62:65]
	v_mfma_f32_16x16x32_bf16 v[54:57], v[154:157], v[178:181], v[54:57]
	v_mfma_f32_16x16x32_bf16 v[46:49], v[140:143], v[186:189], v[46:49]
	v_mfma_f32_16x16x32_bf16 v[38:41], v[154:157], v[186:189], v[38:41]
	v_mfma_f32_16x16x32_bf16 v[30:33], v[140:143], v[194:197], v[30:33]
	v_mfma_f32_16x16x32_bf16 v[22:25], v[154:157], v[194:197], v[22:25]
	v_mfma_f32_16x16x32_bf16 v[14:17], v[140:143], v[208:211], v[14:17]
	v_mfma_f32_16x16x32_bf16 v[6:9], v[154:157], v[208:211], v[6:9]
	v_mfma_f32_16x16x32_bf16 v[62:65], v[150:153], v[182:185], v[62:65]
	v_mfma_f32_16x16x32_bf16 v[54:57], v[158:161], v[182:185], v[54:57]
	v_mfma_f32_16x16x32_bf16 v[46:49], v[150:153], v[190:193], v[46:49]
	v_mfma_f32_16x16x32_bf16 v[38:41], v[158:161], v[190:193], v[38:41]
	v_mfma_f32_16x16x32_bf16 v[30:33], v[150:153], v[198:201], v[30:33]
	v_mfma_f32_16x16x32_bf16 v[22:25], v[158:161], v[198:201], v[22:25]
	v_mfma_f32_16x16x32_bf16 v[14:17], v[150:153], v[212:215], v[14:17]
	v_mfma_f32_16x16x32_bf16 v[6:9], v[158:161], v[212:215], v[6:9]
	v_mfma_f32_16x16x32_bf16 v[58:61], v[162:165], v[178:181], v[58:61]
	v_mfma_f32_16x16x32_bf16 v[50:53], v[170:173], v[178:181], v[50:53]
	v_mfma_f32_16x16x32_bf16 v[42:45], v[162:165], v[186:189], v[42:45]
	v_mfma_f32_16x16x32_bf16 v[34:37], v[170:173], v[186:189], v[34:37]
	v_mfma_f32_16x16x32_bf16 v[26:29], v[162:165], v[194:197], v[26:29]
	v_mfma_f32_16x16x32_bf16 v[18:21], v[170:173], v[194:197], v[18:21]
	v_mfma_f32_16x16x32_bf16 v[10:13], v[162:165], v[208:211], v[10:13]
	v_mfma_f32_16x16x32_bf16 v[2:5], v[170:173], v[208:211], v[2:5]
	v_mfma_f32_16x16x32_bf16 v[58:61], v[166:169], v[182:185], v[58:61]
	v_mfma_f32_16x16x32_bf16 v[50:53], v[174:177], v[182:185], v[50:53]
	v_mfma_f32_16x16x32_bf16 v[42:45], v[166:169], v[190:193], v[42:45]
	v_mfma_f32_16x16x32_bf16 v[34:37], v[174:177], v[190:193], v[34:37]
	v_mfma_f32_16x16x32_bf16 v[26:29], v[166:169], v[198:201], v[26:29]
	v_mfma_f32_16x16x32_bf16 v[18:21], v[174:177], v[198:201], v[18:21]
	v_mfma_f32_16x16x32_bf16 v[10:13], v[166:169], v[212:215], v[10:13]
	v_mfma_f32_16x16x32_bf16 v[2:5], v[174:177], v[212:215], v[2:5]
	s_setprio 0
	s_barrier
	s_add_i32 s76, s76, 2
	s_add_u32 s8, s8, 0x100
	s_addc_u32 s9, s9, 0
	s_add_u32 s70, s70, 0x100
	s_addc_u32 s71, s71, 0
	s_cmp_gt_u32 s76, 13
	s_cbranch_scc0 .LBB0_1212

; #define PG8_STAGE(bufoff, gbase, voff) do { _Pragma("unroll") for (int _i = 0; _i < 2; ++_i) \
;         __builtin_amdgcn_global_load_lds((const unsigned*)((const char*)(gbase) + (voff)[_i]), (PG8_LAS unsigned*)(lds + (bufoff) + ldsw + _i * 8192), 16, 0, 0); } while (0)
; #define PG8_LDA(dst, b, h) do { _Pragma("unroll") for (int m = 0; m < 4; ++m) _Pragma("unroll") for (int k = 0; k < 2; ++k) dst[m][k] = *(const PG8_LAS bf16x8*)(lds + PG8_SA(b, h) + aoff + m * 2048 + k * 1024); } while (0)
; #define PG8_LDB(dst, b, h) do { _Pragma("unroll") for (int n = 0; n < 2; ++n) _Pragma("unroll") for (int k = 0; k < 2; ++k) dst[n][k] = *(const PG8_LAS bf16x8*)(lds + PG8_SB(b, h) + boff + n * 2048 + k * 1024); } while (0)
; #define PG8_MMA(ai, bj, At, Bt) do { __builtin_amdgcn_s_setprio(1); _Pragma("unroll") for (int m = 0; m < 4; ++m) _Pragma("unroll") for (int n = 0; n < 2; ++n) _Pragma("unroll") for (int k = 0; k < 2; ++k) \
;         acc[ai][bj][m][n] = __builtin_amdgcn_mfma_f32_16x16x32_bf16(Bt[n][k], At[m][k], acc[ai][bj][m][n], 0, 0, 0); __builtin_amdgcn_s_setprio(0); } while (0)
; #define PG8_WAIT_V(n) asm volatile("s_waitcnt vmcnt(" #n ")" ::: "memory")
; #define PG8_BAR __builtin_amdgcn_s_barrier()
; template <class Epi, class Sched, bool ALIGN_EPI = false, bool SP2 = false>
; __device__ __forceinline__ void gemm_phase(PG8_LAS unsigned char* lds, const Gemm g, const Sched& S, const Epi& E) {
;     ...
;         const bool has_next = S.next(ui + 1, nxt);
;         const char* nA = has_next ? (const char*)g.A + (size_t)nxt.pm * tstepA + (size_t)nxt.pb * g.sA : cA; const char* nB = has_next ? (const char*)g.Bt + (size_t)nxt.pn * tstepB + (size_t)nxt.pb * g.sB : cB;
;         for (int t = 0; t < nt; t += 2) {
;             const bool last = (t == nt - 2);
;             const char* a1 = cA + (size_t)(t + 1) * kstep;
;             const char* a2 = last ? nA : cA + (size_t)(t + 2) * kstep; const char* b2 = last ? nB : cB + (size_t)(t + 2) * kstep;
;             const char* a3 = a2 + kstep; const char* b3 = b2 + kstep;
;             if (last && has_next) S.a_ready(nxt);
;             if constexpr (SP2) {
;             PG8_LDB(B0, 0, 0); PG8_LDB(B1, 0, 1); PG8_SCHED; PG8_LDA(At, 0, 0); PG8_STAGE(PG8_SA(1, 1), a1 + hstepA, voffA);
;             PG8_WAIT_V(8); PG8_WAIT_L(0); PG8_BAR; PG8_MMA(0, 0, At, B0); PG8_MMA(0, 1, At, B1); PG8_BAR; PG8_SCHED;
.LBB0_1314:
	s_add_u32 s9, s34, 0x100
	s_addc_u32 s17, s35, 0
	s_mov_b32 s87, -2
	s_waitcnt lgkmcnt(0)
	s_add_u32 s34, s0, 0x100
	s_addc_u32 s35, s1, 0
	s_add_i32 vcc_lo, 0, 0x10000
	s_cmp_eq_u32 s87, 40
	s_cselect_b32 s47, s39, s35
	s_cselect_b32 s46, s38, s34
	s_cselect_b32 s37, s53, s17
	s_cselect_b32 s36, s52, s9
	s_add_i32 vcc_hi, 0, 0x14000
	v_add_u32_e32 v78, vcc_lo, v228
	v_add_u32_e32 v158, vcc_hi, v228
	ds_read_b128 v[58:61], v78
	ds_read_b128 v[62:65], v78 offset:1024
	ds_read_b128 v[74:77], v78 offset:2048
	ds_read_b128 v[78:81], v78 offset:3072
	ds_read_b128 v[130:133], v158
	ds_read_b128 v[142:145], v158 offset:1024
	ds_read_b128 v[154:157], v158 offset:2048
	ds_read_b128 v[158:161], v158 offset:3072
	v_lshl_add_u64 v[204:205], s[0:1], 0, v[214:215]
	s_add_i32 m0, s71, 0xc000
	ds_read_b128 v[162:165], v233
	ds_read_b128 v[166:169], v233 offset:1024
	ds_read_b128 v[170:173], v233 offset:2048
	ds_read_b128 v[174:177], v233 offset:3072
	ds_read_b128 v[178:181], v233 offset:4096
	ds_read_b128 v[182:185], v233 offset:5120
	ds_read_b128 v[218:221], v233 offset:6144
	ds_read_b128 v[222:225], v233 offset:7168
	global_load_lds_dwordx4 v[204:205], off
	v_lshl_add_u64 v[204:205], s[0:1], 0, v[216:217]
	s_add_i32 m0, s71, 0xe000
	s_nop 0
	global_load_lds_dwordx4 v[204:205], off
	s_waitcnt vmcnt(8)
	s_waitcnt lgkmcnt(0)
	s_barrier
	s_setprio 1
	s_waitcnt lgkmcnt(0)
	v_mfma_f32_16x16x32_bf16 v[150:153], v[58:61], v[162:165], 0
	v_mfma_f32_16x16x32_bf16 v[146:149], v[74:77], v[162:165], 0
	v_mfma_f32_16x16x32_bf16 v[126:129], v[58:61], v[170:173], 0
	v_mfma_f32_16x16x32_bf16 v[122:125], v[74:77], v[170:173], 0
	v_mfma_f32_16x16x32_bf16 v[110:113], v[58:61], v[178:181], 0
	v_mfma_f32_16x16x32_bf16 v[106:109], v[74:77], v[178:181], 0
	v_mfma_f32_16x16x32_bf16 v[94:97], v[58:61], v[218:221], 0
	v_mfma_f32_16x16x32_bf16 v[90:93], v[74:77], v[218:221], 0
	v_mfma_f32_16x16x32_bf16 v[150:153], v[62:65], v[166:169], v[150:153]
	v_mfma_f32_16x16x32_bf16 v[146:149], v[78:81], v[166:169], v[146:149]
	v_mfma_f32_16x16x32_bf16 v[126:129], v[62:65], v[174:177], v[126:129]
	v_mfma_f32_16x16x32_bf16 v[122:125], v[78:81], v[174:177], v[122:125]
	v_mfma_f32_16x16x32_bf16 v[110:113], v[62:65], v[182:185], v[110:113]
	v_mfma_f32_16x16x32_bf16 v[106:109], v[78:81], v[182:185], v[106:109]
	v_mfma_f32_16x16x32_bf16 v[94:97], v[62:65], v[222:225], v[94:97]
	v_mfma_f32_16x16x32_bf16 v[90:93], v[78:81], v[222:225], v[90:93]
	v_mfma_f32_16x16x32_bf16 v[138:141], v[130:133], v[162:165], 0
	v_mfma_f32_16x16x32_bf16 v[134:137], v[154:157], v[162:165], 0
	v_mfma_f32_16x16x32_bf16 v[118:121], v[130:133], v[170:173], 0
	v_mfma_f32_16x16x32_bf16 v[114:117], v[154:157], v[170:173], 0
	v_mfma_f32_16x16x32_bf16 v[102:105], v[130:133], v[178:181], 0
	v_mfma_f32_16x16x32_bf16 v[98:101], v[154:157], v[178:181], 0
	v_mfma_f32_16x16x32_bf16 v[86:89], v[130:133], v[218:221], 0
	v_mfma_f32_16x16x32_bf16 v[82:85], v[154:157], v[218:221], 0
	v_mfma_f32_16x16x32_bf16 v[138:141], v[142:145], v[166:169], v[138:141]
	v_mfma_f32_16x16x32_bf16 v[134:137], v[158:161], v[166:169], v[134:137]
	v_mfma_f32_16x16x32_bf16 v[118:121], v[142:145], v[174:177], v[118:121]
	v_mfma_f32_16x16x32_bf16 v[114:117], v[158:161], v[174:177], v[114:117]
	v_mfma_f32_16x16x32_bf16 v[102:105], v[142:145], v[182:185], v[102:105]
	v_mfma_f32_16x16x32_bf16 v[98:101], v[158:161], v[182:185], v[98:101]
	v_mfma_f32_16x16x32_bf16 v[86:89], v[142:145], v[222:225], v[86:89]
	v_mfma_f32_16x16x32_bf16 v[82:85], v[158:161], v[222:225], v[82:85]
	s_setprio 0
	s_barrier
	s_add_i32 s0, vcc_lo, s54
	v_lshl_add_u64 v[204:205], s[36:37], 0, v[0:1]
	s_mov_b32 m0, s0
	ds_read_b128 v[162:165], v233 offset:16384
	ds_read_b128 v[166:169], v233 offset:17408
	ds_read_b128 v[170:173], v233 offset:18432
	ds_read_b128 v[174:177], v233 offset:19456
	ds_read_b128 v[178:181], v233 offset:20480
	ds_read_b128 v[182:185], v233 offset:21504
	ds_read_b128 v[218:221], v233 offset:22528
	ds_read_b128 v[222:225], v233 offset:23552
	global_load_lds_dwordx4 v[204:205], off
	s_add_i32 m0, s0, 0x2000
	s_add_u32 s0, s36, 0xb0000
	v_lshl_add_u64 v[226:227], s[36:37], 0, v[186:187]
	s_addc_u32 s1, s37, 0
	s_add_i32 vcc_lo, vcc_hi, s54
	global_load_lds_dwordx4 v[226:227], off
	v_lshl_add_u64 v[234:235], s[0:1], 0, v[0:1]
	s_mov_b32 m0, vcc_lo
	v_lshl_add_u64 v[246:247], s[46:47], 0, v[188:189]
	global_load_lds_dwordx4 v[234:235], off
	v_lshl_add_u64 v[234:235], s[0:1], 0, v[186:187]
	s_add_i32 m0, vcc_lo, 0x2000
	s_nop 0
	global_load_lds_dwordx4 v[234:235], off
	v_lshl_add_u64 v[234:235], s[46:47], 0, v[190:191]
	s_mov_b32 m0, s71
	s_nop 0
	global_load_lds_dwordx4 v[234:235], off
	s_mov_b32 m0, s76
	s_nop 0
	global_load_lds_dwordx4 v[246:247], off
	s_waitcnt vmcnt(8)
	s_waitcnt lgkmcnt(0)
	s_barrier
; #define PG8_STAGE(bufoff, gbase, voff) do { _Pragma("unroll") for (int _i = 0; _i < 2; ++_i) \
;         __builtin_amdgcn_global_load_lds((const unsigned*)((const char*)(gbase) + (voff)[_i]), (PG8_LAS unsigned*)(lds + (bufoff) + ldsw + _i * 8192), 16, 0, 0); } while (0)
; #define PG8_LDA(dst, b, h) do { _Pragma("unroll") for (int m = 0; m < 4; ++m) _Pragma("unroll") for (int k = 0; k < 2; ++k) dst[m][k] = *(const PG8_LAS bf16x8*)(lds + PG8_SA(b, h) + aoff + m * 2048 + k * 1024); } while (0)
; #define PG8_LDB(dst, b, h) do { _Pragma("unroll") for (int n = 0; n < 2; ++n) _Pragma("unroll") for (int k = 0; k < 2; ++k) dst[n][k] = *(const PG8_LAS bf16x8*)(lds + PG8_SB(b, h) + boff + n * 2048 + k * 1024); } while (0)
; #define PG8_MMA(ai, bj, At, Bt) do { __builtin_amdgcn_s_setprio(1); _Pragma("unroll") for (int m = 0; m < 4; ++m) _Pragma("unroll") for (int n = 0; n < 2; ++n) _Pragma("unroll") for (int k = 0; k < 2; ++k) \
;         acc[ai][bj][m][n] = __builtin_amdgcn_mfma_f32_16x16x32_bf16(Bt[n][k], At[m][k], acc[ai][bj][m][n], 0, 0, 0); __builtin_amdgcn_s_setprio(0); } while (0)
; #define PG8_WAIT_V(n) asm volatile("s_waitcnt vmcnt(" #n ")" ::: "memory")
; #define PG8_WAIT_L(n) asm volatile("s_waitcnt lgkmcnt(" #n ")" ::: "memory")
; #define PG8_BAR __builtin_amdgcn_s_barrier()
; #define PG8_SCHED __builtin_amdgcn_sched_barrier(0)
; template <class Epi, class Sched, bool ALIGN_EPI = false, bool SP2 = false>
; __device__ __forceinline__ void gemm_phase(PG8_LAS unsigned char* lds, const Gemm g, const Sched& S, const Epi& E) {
;     ...
;             PG8_LDA(At, 0, 1); PG8_STAGE(PG8_SB(0, 0), b2, voffB); PG8_STAGE(PG8_SB(0, 1), b2 + hstepB, voffB); PG8_STAGE(PG8_SA(0, 0), a2, voffA);
;             PG8_WAIT_V(8); PG8_WAIT_L(0); PG8_BAR; PG8_MMA(1, 0, At, B0); PG8_MMA(1, 1, At, B1); PG8_BAR; PG8_SCHED;
;             PG8_LDB(B0, 1, 0); PG8_LDB(B1, 1, 1); PG8_SCHED; PG8_LDA(At, 1, 0); PG8_STAGE(PG8_SA(0, 1), a2 + hstepA, voffA);
;             PG8_WAIT_V(8); PG8_WAIT_L(0); PG8_BAR; PG8_MMA(0, 0, At, B0); PG8_MMA(0, 1, At, B1); PG8_BAR; PG8_SCHED;
	s_setprio 1
	s_waitcnt lgkmcnt(0)
	v_mfma_f32_16x16x32_bf16 v[70:73], v[58:61], v[162:165], 0
	v_mfma_f32_16x16x32_bf16 v[66:69], v[74:77], v[162:165], 0
	v_mfma_f32_16x16x32_bf16 v[46:49], v[58:61], v[170:173], 0
	v_mfma_f32_16x16x32_bf16 v[42:45], v[74:77], v[170:173], 0
	v_mfma_f32_16x16x32_bf16 v[30:33], v[58:61], v[178:181], 0
	v_mfma_f32_16x16x32_bf16 v[26:29], v[74:77], v[178:181], 0
	v_mfma_f32_16x16x32_bf16 v[14:17], v[58:61], v[218:221], 0
	v_mfma_f32_16x16x32_bf16 v[10:13], v[74:77], v[218:221], 0
	v_mfma_f32_16x16x32_bf16 v[70:73], v[62:65], v[166:169], v[70:73]
	v_mfma_f32_16x16x32_bf16 v[66:69], v[78:81], v[166:169], v[66:69]
	v_mfma_f32_16x16x32_bf16 v[46:49], v[62:65], v[174:177], v[46:49]
	v_mfma_f32_16x16x32_bf16 v[42:45], v[78:81], v[174:177], v[42:45]
	v_mfma_f32_16x16x32_bf16 v[30:33], v[62:65], v[182:185], v[30:33]
	v_mfma_f32_16x16x32_bf16 v[26:29], v[78:81], v[182:185], v[26:29]
	v_mfma_f32_16x16x32_bf16 v[14:17], v[62:65], v[222:225], v[14:17]
	v_mfma_f32_16x16x32_bf16 v[10:13], v[78:81], v[222:225], v[10:13]
	v_mfma_f32_16x16x32_bf16 v[54:57], v[130:133], v[162:165], 0
	v_mfma_f32_16x16x32_bf16 v[50:53], v[154:157], v[162:165], 0
	v_mfma_f32_16x16x32_bf16 v[38:41], v[130:133], v[170:173], 0
	v_mfma_f32_16x16x32_bf16 v[34:37], v[154:157], v[170:173], 0
	v_mfma_f32_16x16x32_bf16 v[22:25], v[130:133], v[178:181], 0
	v_mfma_f32_16x16x32_bf16 v[18:21], v[154:157], v[178:181], 0
	v_mfma_f32_16x16x32_bf16 v[6:9], v[130:133], v[218:221], 0
	v_mfma_f32_16x16x32_bf16 v[2:5], v[154:157], v[218:221], 0
	v_mfma_f32_16x16x32_bf16 v[54:57], v[142:145], v[166:169], v[54:57]
	v_mfma_f32_16x16x32_bf16 v[50:53], v[158:161], v[166:169], v[50:53]
	v_mfma_f32_16x16x32_bf16 v[38:41], v[142:145], v[174:177], v[38:41]
	v_mfma_f32_16x16x32_bf16 v[34:37], v[158:161], v[174:177], v[34:37]
	v_mfma_f32_16x16x32_bf16 v[22:25], v[142:145], v[182:185], v[22:25]
	v_mfma_f32_16x16x32_bf16 v[18:21], v[158:161], v[182:185], v[18:21]
	v_mfma_f32_16x16x32_bf16 v[6:9], v[142:145], v[222:225], v[6:9]
	v_mfma_f32_16x16x32_bf16 v[2:5], v[158:161], v[222:225], v[2:5]
	s_setprio 0
	s_barrier
	s_add_i32 vcc_lo, 0, 0x18000
	s_add_i32 vcc_hi, 0, 0x1c000
	v_add_u32_e32 v78, vcc_lo, v228
	v_add_u32_e32 v158, vcc_hi, v228
	ds_read_b128 v[58:61], v78
	ds_read_b128 v[62:65], v78 offset:1024
	ds_read_b128 v[74:77], v78 offset:2048
	ds_read_b128 v[78:81], v78 offset:3072
	ds_read_b128 v[130:133], v158
	ds_read_b128 v[142:145], v158 offset:1024
	ds_read_b128 v[154:157], v158 offset:2048
	ds_read_b128 v[158:161], v158 offset:3072
	s_add_u32 s0, s46, 0xb0000
	s_addc_u32 s1, s47, 0
	s_mov_b32 m0, s77
	v_lshl_add_u64 v[248:249], s[0:1], 0, v[190:191]
	ds_read_b128 v[162:165], v233 offset:32768
	ds_read_b128 v[166:169], v233 offset:33792
	ds_read_b128 v[170:173], v233 offset:34816
	ds_read_b128 v[174:177], v233 offset:35840
	ds_read_b128 v[178:181], v233 offset:36864
	ds_read_b128 v[182:185], v233 offset:37888
	ds_read_b128 v[218:221], v233 offset:38912
	ds_read_b128 v[222:225], v233 offset:39936
	global_load_lds_dwordx4 v[248:249], off
	v_lshl_add_u64 v[248:249], s[0:1], 0, v[188:189]
	s_mov_b32 m0, s78
	s_nop 0
	global_load_lds_dwordx4 v[248:249], off
	s_waitcnt vmcnt(8)
	s_waitcnt lgkmcnt(0)
	s_barrier
	s_setprio 1
	s_waitcnt lgkmcnt(0)
	v_mfma_f32_16x16x32_bf16 v[150:153], v[58:61], v[162:165], v[150:153]
	v_mfma_f32_16x16x32_bf16 v[146:149], v[74:77], v[162:165], v[146:149]
	v_mfma_f32_16x16x32_bf16 v[126:129], v[58:61], v[170:173], v[126:129]
	v_mfma_f32_16x16x32_bf16 v[122:125], v[74:77], v[170:173], v[122:125]
	v_mfma_f32_16x16x32_bf16 v[110:113], v[58:61], v[178:181], v[110:113]
	v_mfma_f32_16x16x32_bf16 v[106:109], v[74:77], v[178:181], v[106:109]
	v_mfma_f32_16x16x32_bf16 v[94:97], v[58:61], v[218:221], v[94:97]
	v_mfma_f32_16x16x32_bf16 v[90:93], v[74:77], v[218:221], v[90:93]
	v_mfma_f32_16x16x32_bf16 v[150:153], v[62:65], v[166:169], v[150:153]
	v_mfma_f32_16x16x32_bf16 v[146:149], v[78:81], v[166:169], v[146:149]
	v_mfma_f32_16x16x32_bf16 v[126:129], v[62:65], v[174:177], v[126:129]
	v_mfma_f32_16x16x32_bf16 v[122:125], v[78:81], v[174:177], v[122:125]
	v_mfma_f32_16x16x32_bf16 v[110:113], v[62:65], v[182:185], v[110:113]
	v_mfma_f32_16x16x32_bf16 v[106:109], v[78:81], v[182:185], v[106:109]
	v_mfma_f32_16x16x32_bf16 v[94:97], v[62:65], v[222:225], v[94:97]
	v_mfma_f32_16x16x32_bf16 v[90:93], v[78:81], v[222:225], v[90:93]
	v_mfma_f32_16x16x32_bf16 v[138:141], v[130:133], v[162:165], v[138:141]
	v_mfma_f32_16x16x32_bf16 v[134:137], v[154:157], v[162:165], v[134:137]
	v_mfma_f32_16x16x32_bf16 v[118:121], v[130:133], v[170:173], v[118:121]
	v_mfma_f32_16x16x32_bf16 v[114:117], v[154:157], v[170:173], v[114:117]
	v_mfma_f32_16x16x32_bf16 v[102:105], v[130:133], v[178:181], v[102:105]
	v_mfma_f32_16x16x32_bf16 v[98:101], v[154:157], v[178:181], v[98:101]
	v_mfma_f32_16x16x32_bf16 v[86:89], v[130:133], v[218:221], v[86:89]
	v_mfma_f32_16x16x32_bf16 v[82:85], v[154:157], v[218:221], v[82:85]
	v_mfma_f32_16x16x32_bf16 v[138:141], v[142:145], v[166:169], v[138:141]
	v_mfma_f32_16x16x32_bf16 v[134:137], v[158:161], v[166:169], v[134:137]
	v_mfma_f32_16x16x32_bf16 v[118:121], v[142:145], v[174:177], v[118:121]
	v_mfma_f32_16x16x32_bf16 v[114:117], v[158:161], v[174:177], v[114:117]
	v_mfma_f32_16x16x32_bf16 v[102:105], v[142:145], v[182:185], v[102:105]
	v_mfma_f32_16x16x32_bf16 v[98:101], v[158:161], v[182:185], v[98:101]
	v_mfma_f32_16x16x32_bf16 v[86:89], v[142:145], v[222:225], v[86:89]
	v_mfma_f32_16x16x32_bf16 v[82:85], v[158:161], v[222:225], v[82:85]
	s_setprio 0
	s_barrier
; #define PG8_STAGE(bufoff, gbase, voff) do { _Pragma("unroll") for (int _i = 0; _i < 2; ++_i) \
;         __builtin_amdgcn_global_load_lds((const unsigned*)((const char*)(gbase) + (voff)[_i]), (PG8_LAS unsigned*)(lds + (bufoff) + ldsw + _i * 8192), 16, 0, 0); } while (0)
; #define PG8_LDA(dst, b, h) do { _Pragma("unroll") for (int m = 0; m < 4; ++m) _Pragma("unroll") for (int k = 0; k < 2; ++k) dst[m][k] = *(const PG8_LAS bf16x8*)(lds + PG8_SA(b, h) + aoff + m * 2048 + k * 1024); } while (0)
; #define PG8_LDB(dst, b, h) do { _Pragma("unroll") for (int n = 0; n < 2; ++n) _Pragma("unroll") for (int k = 0; k < 2; ++k) dst[n][k] = *(const PG8_LAS bf16x8*)(lds + PG8_SB(b, h) + boff + n * 2048 + k * 1024); } while (0)
; #define PG8_MMA(ai, bj, At, Bt) do { __builtin_amdgcn_s_setprio(1); _Pragma("unroll") for (int m = 0; m < 4; ++m) _Pragma("unroll") for (int n = 0; n < 2; ++n) _Pragma("unroll") for (int k = 0; k < 2; ++k) \
;         acc[ai][bj][m][n] = __builtin_amdgcn_mfma_f32_16x16x32_bf16(Bt[n][k], At[m][k], acc[ai][bj][m][n], 0, 0, 0); __builtin_amdgcn_s_setprio(0); } while (0)
; #define PG8_WAIT_V(n) asm volatile("s_waitcnt vmcnt(" #n ")" ::: "memory")
; #define PG8_BAR __builtin_amdgcn_s_barrier()
; template <class Epi, class Sched, bool ALIGN_EPI = false, bool SP2 = false>
; __device__ __forceinline__ void gemm_phase(PG8_LAS unsigned char* lds, const Gemm g, const Sched& S, const Epi& E) {
;     ...
;         for (int t = 0; t < nt; t += 2) {
;             const bool last = (t == nt - 2);
;             const char* a1 = cA + (size_t)(t + 1) * kstep;
;             const char* a2 = last ? nA : cA + (size_t)(t + 2) * kstep; const char* b2 = last ? nB : cB + (size_t)(t + 2) * kstep;
;             const char* a3 = a2 + kstep; const char* b3 = b2 + kstep;
;             if (last && has_next) S.a_ready(nxt);
;             if constexpr (SP2) {
;             PG8_LDB(B0, 0, 0); PG8_LDB(B1, 0, 1); PG8_SCHED; PG8_LDA(At, 0, 0); PG8_STAGE(PG8_SA(1, 1), a1 + hstepA, voffA);
;     ...
;             PG8_LDA(At, 1, 1); PG8_STAGE(PG8_SB(1, 0), b3, voffB); PG8_STAGE(PG8_SB(1, 1), b3 + hstepB, voffB); PG8_STAGE(PG8_SA(1, 0), a3, voffA);
;             PG8_WAIT_V(8); PG8_WAIT_L(0); PG8_BAR; PG8_MMA(1, 0, At, B0); PG8_MMA(1, 1, At, B1); PG8_BAR; PG8_SCHED;
;             } else {
;             PG8_LDB(B0, 0, 0); PG8_SCHED; PG8_LDA(At, 0, 0); PG8_STAGE(PG8_SA(1, 1), a1 + hstepA, voffA);
	s_add_i32 s0, vcc_lo, s54
	v_lshl_add_u64 v[204:205], v[204:205], 0, s[22:23]
	s_mov_b32 m0, s0
	ds_read_b128 v[162:165], v233 offset:49152
	ds_read_b128 v[166:169], v233 offset:50176
	ds_read_b128 v[170:173], v233 offset:51200
	ds_read_b128 v[174:177], v233 offset:52224
	ds_read_b128 v[178:181], v233 offset:53248
	ds_read_b128 v[182:185], v233 offset:54272
	ds_read_b128 v[218:221], v233 offset:55296
	ds_read_b128 v[222:225], v233 offset:56320
	global_load_lds_dwordx4 v[204:205], off
	s_add_i32 m0, s0, 0x2000
	s_add_u32 s0, s36, 0xb0080
	v_lshl_add_u64 v[204:205], v[226:227], 0, s[22:23]
	s_addc_u32 s1, s37, 0
	s_add_i32 s36, vcc_hi, s54
	global_load_lds_dwordx4 v[204:205], off
	v_lshl_add_u64 v[204:205], s[0:1], 0, v[0:1]
	s_mov_b32 m0, s36
	s_nop 0
	global_load_lds_dwordx4 v[204:205], off
	v_lshl_add_u64 v[204:205], s[0:1], 0, v[186:187]
	s_add_i32 m0, s36, 0x2000
	s_nop 0
	global_load_lds_dwordx4 v[204:205], off
	v_lshl_add_u64 v[204:205], v[234:235], 0, s[22:23]
	s_mov_b32 m0, s82
	s_nop 0
	global_load_lds_dwordx4 v[204:205], off
	v_lshl_add_u64 v[204:205], v[246:247], 0, s[22:23]
	s_mov_b32 m0, s83
	s_nop 0
	global_load_lds_dwordx4 v[204:205], off
	s_waitcnt vmcnt(8)
	s_waitcnt lgkmcnt(0)
	s_barrier
	s_setprio 1
	s_waitcnt lgkmcnt(0)
	v_mfma_f32_16x16x32_bf16 v[70:73], v[58:61], v[162:165], v[70:73]
	v_mfma_f32_16x16x32_bf16 v[66:69], v[74:77], v[162:165], v[66:69]
	v_mfma_f32_16x16x32_bf16 v[46:49], v[58:61], v[170:173], v[46:49]
	v_mfma_f32_16x16x32_bf16 v[42:45], v[74:77], v[170:173], v[42:45]
	v_mfma_f32_16x16x32_bf16 v[30:33], v[58:61], v[178:181], v[30:33]
	v_mfma_f32_16x16x32_bf16 v[26:29], v[74:77], v[178:181], v[26:29]
	v_mfma_f32_16x16x32_bf16 v[14:17], v[58:61], v[218:221], v[14:17]
	v_mfma_f32_16x16x32_bf16 v[10:13], v[74:77], v[218:221], v[10:13]
	v_mfma_f32_16x16x32_bf16 v[70:73], v[62:65], v[166:169], v[70:73]
	v_mfma_f32_16x16x32_bf16 v[66:69], v[78:81], v[166:169], v[66:69]
	v_mfma_f32_16x16x32_bf16 v[46:49], v[62:65], v[174:177], v[46:49]
	v_mfma_f32_16x16x32_bf16 v[42:45], v[78:81], v[174:177], v[42:45]
	v_mfma_f32_16x16x32_bf16 v[30:33], v[62:65], v[182:185], v[30:33]
	v_mfma_f32_16x16x32_bf16 v[26:29], v[78:81], v[182:185], v[26:29]
	v_mfma_f32_16x16x32_bf16 v[14:17], v[62:65], v[222:225], v[14:17]
	v_mfma_f32_16x16x32_bf16 v[10:13], v[78:81], v[222:225], v[10:13]
	v_mfma_f32_16x16x32_bf16 v[54:57], v[130:133], v[162:165], v[54:57]
	v_mfma_f32_16x16x32_bf16 v[50:53], v[154:157], v[162:165], v[50:53]
	v_mfma_f32_16x16x32_bf16 v[38:41], v[130:133], v[170:173], v[38:41]
	v_mfma_f32_16x16x32_bf16 v[34:37], v[154:157], v[170:173], v[34:37]
	v_mfma_f32_16x16x32_bf16 v[22:25], v[130:133], v[178:181], v[22:25]
	v_mfma_f32_16x16x32_bf16 v[18:21], v[154:157], v[178:181], v[18:21]
	v_mfma_f32_16x16x32_bf16 v[6:9], v[130:133], v[218:221], v[6:9]
	v_mfma_f32_16x16x32_bf16 v[2:5], v[154:157], v[218:221], v[2:5]
	v_mfma_f32_16x16x32_bf16 v[54:57], v[142:145], v[166:169], v[54:57]
	v_mfma_f32_16x16x32_bf16 v[50:53], v[158:161], v[166:169], v[50:53]
	v_mfma_f32_16x16x32_bf16 v[38:41], v[142:145], v[174:177], v[38:41]
	v_mfma_f32_16x16x32_bf16 v[34:37], v[158:161], v[174:177], v[34:37]
	v_mfma_f32_16x16x32_bf16 v[22:25], v[142:145], v[182:185], v[22:25]
	v_mfma_f32_16x16x32_bf16 v[18:21], v[158:161], v[182:185], v[18:21]
	v_mfma_f32_16x16x32_bf16 v[6:9], v[142:145], v[222:225], v[6:9]
	v_mfma_f32_16x16x32_bf16 v[2:5], v[158:161], v[222:225], v[2:5]
	s_setprio 0
	s_barrier
	s_add_i32 s87, s87, 2
	s_add_u32 s9, s9, 0x100
	s_addc_u32 s17, s17, 0
	s_cmp_gt_u32 s87, 41
	s_mov_b64 s[0:1], s[34:35]
	s_cbranch_scc1 .Lpk_done_g1315
.LBB0_1315:
	s_add_u32 s34, s0, 0x100
	s_addc_u32 s35, s1, 0
	s_add_i32 vcc_lo, 0, 0x10000
	s_cmp_eq_u32 s87, 40
	s_cselect_b32 s47, s39, s35
	s_cselect_b32 s46, s38, s34
	s_cselect_b32 s37, s53, s17
	s_cselect_b32 s36, s52, s9
	s_add_i32 vcc_hi, 0, 0x14000
	v_add_u32_e32 v78, vcc_lo, v228
	v_add_u32_e32 v158, vcc_hi, v228
	ds_read_b128 v[58:61], v78
	ds_read_b128 v[62:65], v78 offset:1024
	ds_read_b128 v[74:77], v78 offset:2048
	ds_read_b128 v[78:81], v78 offset:3072
	ds_read_b128 v[130:133], v158
	ds_read_b128 v[142:145], v158 offset:1024
	ds_read_b128 v[154:157], v158 offset:2048
	ds_read_b128 v[158:161], v158 offset:3072
	v_lshl_add_u64 v[204:205], s[0:1], 0, v[214:215]
	s_add_i32 m0, s71, 0xc000
	ds_read_b128 v[162:165], v233
	ds_read_b128 v[166:169], v233 offset:1024
	ds_read_b128 v[170:173], v233 offset:2048
	ds_read_b128 v[174:177], v233 offset:3072
	ds_read_b128 v[178:181], v233 offset:4096
	ds_read_b128 v[182:185], v233 offset:5120
	ds_read_b128 v[218:221], v233 offset:6144
	ds_read_b128 v[222:225], v233 offset:7168
	global_load_lds_dwordx4 v[204:205], off
	v_lshl_add_u64 v[204:205], s[0:1], 0, v[216:217]
	s_add_i32 m0, s71, 0xe000
	s_nop 0
	global_load_lds_dwordx4 v[204:205], off
	s_waitcnt vmcnt(8)
	s_waitcnt lgkmcnt(0)
	s_barrier
; #define PG8_STAGE(bufoff, gbase, voff) do { _Pragma("unroll") for (int _i = 0; _i < 2; ++_i) \
;         __builtin_amdgcn_global_load_lds((const unsigned*)((const char*)(gbase) + (voff)[_i]), (PG8_LAS unsigned*)(lds + (bufoff) + ldsw + _i * 8192), 16, 0, 0); } while (0)
; #define PG8_LDA(dst, b, h) do { _Pragma("unroll") for (int m = 0; m < 4; ++m) _Pragma("unroll") for (int k = 0; k < 2; ++k) dst[m][k] = *(const PG8_LAS bf16x8*)(lds + PG8_SA(b, h) + aoff + m * 2048 + k * 1024); } while (0)
; #define PG8_LDB(dst, b, h) do { _Pragma("unroll") for (int n = 0; n < 2; ++n) _Pragma("unroll") for (int k = 0; k < 2; ++k) dst[n][k] = *(const PG8_LAS bf16x8*)(lds + PG8_SB(b, h) + boff + n * 2048 + k * 1024); } while (0)
; #define PG8_MMA(ai, bj, At, Bt) do { __builtin_amdgcn_s_setprio(1); _Pragma("unroll") for (int m = 0; m < 4; ++m) _Pragma("unroll") for (int n = 0; n < 2; ++n) _Pragma("unroll") for (int k = 0; k < 2; ++k) \
;         acc[ai][bj][m][n] = __builtin_amdgcn_mfma_f32_16x16x32_bf16(Bt[n][k], At[m][k], acc[ai][bj][m][n], 0, 0, 0); __builtin_amdgcn_s_setprio(0); } while (0)
; #define PG8_WAIT_V(n) asm volatile("s_waitcnt vmcnt(" #n ")" ::: "memory")
; #define PG8_WAIT_L(n) asm volatile("s_waitcnt lgkmcnt(" #n ")" ::: "memory")
; #define PG8_BAR __builtin_amdgcn_s_barrier()
; #define PG8_SCHED __builtin_amdgcn_sched_barrier(0)
; template <class Epi, class Sched, bool ALIGN_EPI = false, bool SP2 = false>
; __device__ __forceinline__ void gemm_phase(PG8_LAS unsigned char* lds, const Gemm g, const Sched& S, const Epi& E) {
;     ...
;             PG8_LDB(B0, 0, 0); PG8_LDB(B1, 0, 1); PG8_SCHED; PG8_LDA(At, 0, 0); PG8_STAGE(PG8_SA(1, 1), a1 + hstepA, voffA);
;             PG8_WAIT_V(8); PG8_WAIT_L(0); PG8_BAR; PG8_MMA(0, 0, At, B0); PG8_MMA(0, 1, At, B1); PG8_BAR; PG8_SCHED;
;             PG8_LDA(At, 0, 1); PG8_STAGE(PG8_SB(0, 0), b2, voffB); PG8_STAGE(PG8_SB(0, 1), b2 + hstepB, voffB); PG8_STAGE(PG8_SA(0, 0), a2, voffA);
;             PG8_WAIT_V(8); PG8_WAIT_L(0); PG8_BAR; PG8_MMA(1, 0, At, B0); PG8_MMA(1, 1, At, B1); PG8_BAR; PG8_SCHED;
	s_setprio 1
	s_waitcnt lgkmcnt(0)
	v_mfma_f32_16x16x32_bf16 v[150:153], v[58:61], v[162:165], v[150:153]
	v_mfma_f32_16x16x32_bf16 v[146:149], v[74:77], v[162:165], v[146:149]
	v_mfma_f32_16x16x32_bf16 v[126:129], v[58:61], v[170:173], v[126:129]
	v_mfma_f32_16x16x32_bf16 v[122:125], v[74:77], v[170:173], v[122:125]
	v_mfma_f32_16x16x32_bf16 v[110:113], v[58:61], v[178:181], v[110:113]
	v_mfma_f32_16x16x32_bf16 v[106:109], v[74:77], v[178:181], v[106:109]
	v_mfma_f32_16x16x32_bf16 v[94:97], v[58:61], v[218:221], v[94:97]
	v_mfma_f32_16x16x32_bf16 v[90:93], v[74:77], v[218:221], v[90:93]
	v_mfma_f32_16x16x32_bf16 v[150:153], v[62:65], v[166:169], v[150:153]
	v_mfma_f32_16x16x32_bf16 v[146:149], v[78:81], v[166:169], v[146:149]
	v_mfma_f32_16x16x32_bf16 v[126:129], v[62:65], v[174:177], v[126:129]
	v_mfma_f32_16x16x32_bf16 v[122:125], v[78:81], v[174:177], v[122:125]
	v_mfma_f32_16x16x32_bf16 v[110:113], v[62:65], v[182:185], v[110:113]
	v_mfma_f32_16x16x32_bf16 v[106:109], v[78:81], v[182:185], v[106:109]
	v_mfma_f32_16x16x32_bf16 v[94:97], v[62:65], v[222:225], v[94:97]
	v_mfma_f32_16x16x32_bf16 v[90:93], v[78:81], v[222:225], v[90:93]
	v_mfma_f32_16x16x32_bf16 v[138:141], v[130:133], v[162:165], v[138:141]
	v_mfma_f32_16x16x32_bf16 v[134:137], v[154:157], v[162:165], v[134:137]
	v_mfma_f32_16x16x32_bf16 v[118:121], v[130:133], v[170:173], v[118:121]
	v_mfma_f32_16x16x32_bf16 v[114:117], v[154:157], v[170:173], v[114:117]
	v_mfma_f32_16x16x32_bf16 v[102:105], v[130:133], v[178:181], v[102:105]
	v_mfma_f32_16x16x32_bf16 v[98:101], v[154:157], v[178:181], v[98:101]
	v_mfma_f32_16x16x32_bf16 v[86:89], v[130:133], v[218:221], v[86:89]
	v_mfma_f32_16x16x32_bf16 v[82:85], v[154:157], v[218:221], v[82:85]
	v_mfma_f32_16x16x32_bf16 v[138:141], v[142:145], v[166:169], v[138:141]
	v_mfma_f32_16x16x32_bf16 v[134:137], v[158:161], v[166:169], v[134:137]
	v_mfma_f32_16x16x32_bf16 v[118:121], v[142:145], v[174:177], v[118:121]
	v_mfma_f32_16x16x32_bf16 v[114:117], v[158:161], v[174:177], v[114:117]
	v_mfma_f32_16x16x32_bf16 v[102:105], v[142:145], v[182:185], v[102:105]
	v_mfma_f32_16x16x32_bf16 v[98:101], v[158:161], v[182:185], v[98:101]
	v_mfma_f32_16x16x32_bf16 v[86:89], v[142:145], v[222:225], v[86:89]
	v_mfma_f32_16x16x32_bf16 v[82:85], v[158:161], v[222:225], v[82:85]
	s_setprio 0
	s_barrier
	s_add_i32 s0, vcc_lo, s54
	v_lshl_add_u64 v[204:205], s[36:37], 0, v[0:1]
	s_mov_b32 m0, s0
	ds_read_b128 v[162:165], v233 offset:16384
	ds_read_b128 v[166:169], v233 offset:17408
	ds_read_b128 v[170:173], v233 offset:18432
	ds_read_b128 v[174:177], v233 offset:19456
	ds_read_b128 v[178:181], v233 offset:20480
	ds_read_b128 v[182:185], v233 offset:21504
	ds_read_b128 v[218:221], v233 offset:22528
	ds_read_b128 v[222:225], v233 offset:23552
	global_load_lds_dwordx4 v[204:205], off
	s_add_i32 m0, s0, 0x2000
	s_add_u32 s0, s36, 0xb0000
	v_lshl_add_u64 v[226:227], s[36:37], 0, v[186:187]
	s_addc_u32 s1, s37, 0
	s_add_i32 vcc_lo, vcc_hi, s54
	global_load_lds_dwordx4 v[226:227], off
	v_lshl_add_u64 v[234:235], s[0:1], 0, v[0:1]
	s_mov_b32 m0, vcc_lo
	v_lshl_add_u64 v[246:247], s[46:47], 0, v[188:189]
	global_load_lds_dwordx4 v[234:235], off
	v_lshl_add_u64 v[234:235], s[0:1], 0, v[186:187]
	s_add_i32 m0, vcc_lo, 0x2000
	s_nop 0
	global_load_lds_dwordx4 v[234:235], off
	v_lshl_add_u64 v[234:235], s[46:47], 0, v[190:191]
	s_mov_b32 m0, s71
	s_nop 0
	global_load_lds_dwordx4 v[234:235], off
	s_mov_b32 m0, s76
	s_nop 0
	global_load_lds_dwordx4 v[246:247], off
	s_waitcnt vmcnt(8)
	s_waitcnt lgkmcnt(0)
	s_barrier
	s_setprio 1
	s_waitcnt lgkmcnt(0)
	v_mfma_f32_16x16x32_bf16 v[70:73], v[58:61], v[162:165], v[70:73]
	v_mfma_f32_16x16x32_bf16 v[66:69], v[74:77], v[162:165], v[66:69]
	v_mfma_f32_16x16x32_bf16 v[46:49], v[58:61], v[170:173], v[46:49]
	v_mfma_f32_16x16x32_bf16 v[42:45], v[74:77], v[170:173], v[42:45]
	v_mfma_f32_16x16x32_bf16 v[30:33], v[58:61], v[178:181], v[30:33]
	v_mfma_f32_16x16x32_bf16 v[26:29], v[74:77], v[178:181], v[26:29]
	v_mfma_f32_16x16x32_bf16 v[14:17], v[58:61], v[218:221], v[14:17]
	v_mfma_f32_16x16x32_bf16 v[10:13], v[74:77], v[218:221], v[10:13]
	v_mfma_f32_16x16x32_bf16 v[70:73], v[62:65], v[166:169], v[70:73]
	v_mfma_f32_16x16x32_bf16 v[66:69], v[78:81], v[166:169], v[66:69]
	v_mfma_f32_16x16x32_bf16 v[46:49], v[62:65], v[174:177], v[46:49]
	v_mfma_f32_16x16x32_bf16 v[42:45], v[78:81], v[174:177], v[42:45]
	v_mfma_f32_16x16x32_bf16 v[30:33], v[62:65], v[182:185], v[30:33]
	v_mfma_f32_16x16x32_bf16 v[26:29], v[78:81], v[182:185], v[26:29]
	v_mfma_f32_16x16x32_bf16 v[14:17], v[62:65], v[222:225], v[14:17]
	v_mfma_f32_16x16x32_bf16 v[10:13], v[78:81], v[222:225], v[10:13]
	v_mfma_f32_16x16x32_bf16 v[54:57], v[130:133], v[162:165], v[54:57]
	v_mfma_f32_16x16x32_bf16 v[50:53], v[154:157], v[162:165], v[50:53]
	v_mfma_f32_16x16x32_bf16 v[38:41], v[130:133], v[170:173], v[38:41]
	v_mfma_f32_16x16x32_bf16 v[34:37], v[154:157], v[170:173], v[34:37]
	v_mfma_f32_16x16x32_bf16 v[22:25], v[130:133], v[178:181], v[22:25]
	v_mfma_f32_16x16x32_bf16 v[18:21], v[154:157], v[178:181], v[18:21]
	v_mfma_f32_16x16x32_bf16 v[6:9], v[130:133], v[218:221], v[6:9]
	v_mfma_f32_16x16x32_bf16 v[2:5], v[154:157], v[218:221], v[2:5]
	v_mfma_f32_16x16x32_bf16 v[54:57], v[142:145], v[166:169], v[54:57]
	v_mfma_f32_16x16x32_bf16 v[50:53], v[158:161], v[166:169], v[50:53]
	v_mfma_f32_16x16x32_bf16 v[38:41], v[142:145], v[174:177], v[38:41]
	v_mfma_f32_16x16x32_bf16 v[34:37], v[158:161], v[174:177], v[34:37]
	v_mfma_f32_16x16x32_bf16 v[22:25], v[142:145], v[182:185], v[22:25]
	v_mfma_f32_16x16x32_bf16 v[18:21], v[158:161], v[182:185], v[18:21]
	v_mfma_f32_16x16x32_bf16 v[6:9], v[142:145], v[222:225], v[6:9]
	v_mfma_f32_16x16x32_bf16 v[2:5], v[158:161], v[222:225], v[2:5]
	s_setprio 0
	s_barrier
; #define PG8_STAGE(bufoff, gbase, voff) do { _Pragma("unroll") for (int _i = 0; _i < 2; ++_i) \
;         __builtin_amdgcn_global_load_lds((const unsigned*)((const char*)(gbase) + (voff)[_i]), (PG8_LAS unsigned*)(lds + (bufoff) + ldsw + _i * 8192), 16, 0, 0); } while (0)
; #define PG8_LDA(dst, b, h) do { _Pragma("unroll") for (int m = 0; m < 4; ++m) _Pragma("unroll") for (int k = 0; k < 2; ++k) dst[m][k] = *(const PG8_LAS bf16x8*)(lds + PG8_SA(b, h) + aoff + m * 2048 + k * 1024); } while (0)
; #define PG8_LDB(dst, b, h) do { _Pragma("unroll") for (int n = 0; n < 2; ++n) _Pragma("unroll") for (int k = 0; k < 2; ++k) dst[n][k] = *(const PG8_LAS bf16x8*)(lds + PG8_SB(b, h) + boff + n * 2048 + k * 1024); } while (0)
; #define PG8_MMA(ai, bj, At, Bt) do { __builtin_amdgcn_s_setprio(1); _Pragma("unroll") for (int m = 0; m < 4; ++m) _Pragma("unroll") for (int n = 0; n < 2; ++n) _Pragma("unroll") for (int k = 0; k < 2; ++k) \
;         acc[ai][bj][m][n] = __builtin_amdgcn_mfma_f32_16x16x32_bf16(Bt[n][k], At[m][k], acc[ai][bj][m][n], 0, 0, 0); __builtin_amdgcn_s_setprio(0); } while (0)
; #define PG8_WAIT_V(n) asm volatile("s_waitcnt vmcnt(" #n ")" ::: "memory")
; #define PG8_WAIT_L(n) asm volatile("s_waitcnt lgkmcnt(" #n ")" ::: "memory")
; #define PG8_BAR __builtin_amdgcn_s_barrier()
; #define PG8_SCHED __builtin_amdgcn_sched_barrier(0)
; template <class Epi, class Sched, bool ALIGN_EPI = false, bool SP2 = false>
; __device__ __forceinline__ void gemm_phase(PG8_LAS unsigned char* lds, const Gemm g, const Sched& S, const Epi& E) {
;     ...
;         for (int t = 0; t < nt; t += 2) {
;     ...
;             PG8_LDB(B0, 1, 0); PG8_LDB(B1, 1, 1); PG8_SCHED; PG8_LDA(At, 1, 0); PG8_STAGE(PG8_SA(0, 1), a2 + hstepA, voffA);
;             PG8_WAIT_V(8); PG8_WAIT_L(0); PG8_BAR; PG8_MMA(0, 0, At, B0); PG8_MMA(0, 1, At, B1); PG8_BAR; PG8_SCHED;
;             PG8_LDA(At, 1, 1); PG8_STAGE(PG8_SB(1, 0), b3, voffB); PG8_STAGE(PG8_SB(1, 1), b3 + hstepB, voffB); PG8_STAGE(PG8_SA(1, 0), a3, voffA);
;             PG8_WAIT_V(8); PG8_WAIT_L(0); PG8_BAR; PG8_MMA(1, 0, At, B0); PG8_MMA(1, 1, At, B1); PG8_BAR; PG8_SCHED;
	s_add_i32 vcc_lo, 0, 0x18000
	s_add_i32 vcc_hi, 0, 0x1c000
	v_add_u32_e32 v78, vcc_lo, v228
	v_add_u32_e32 v158, vcc_hi, v228
	ds_read_b128 v[58:61], v78
	ds_read_b128 v[62:65], v78 offset:1024
	ds_read_b128 v[74:77], v78 offset:2048
	ds_read_b128 v[78:81], v78 offset:3072
	ds_read_b128 v[130:133], v158
	ds_read_b128 v[142:145], v158 offset:1024
	ds_read_b128 v[154:157], v158 offset:2048
	ds_read_b128 v[158:161], v158 offset:3072
	s_add_u32 s0, s46, 0xb0000
	s_addc_u32 s1, s47, 0
	s_mov_b32 m0, s77
	v_lshl_add_u64 v[248:249], s[0:1], 0, v[190:191]
	ds_read_b128 v[162:165], v233 offset:32768
	ds_read_b128 v[166:169], v233 offset:33792
	ds_read_b128 v[170:173], v233 offset:34816
	ds_read_b128 v[174:177], v233 offset:35840
	ds_read_b128 v[178:181], v233 offset:36864
	ds_read_b128 v[182:185], v233 offset:37888
	ds_read_b128 v[218:221], v233 offset:38912
	ds_read_b128 v[222:225], v233 offset:39936
	global_load_lds_dwordx4 v[248:249], off
	v_lshl_add_u64 v[248:249], s[0:1], 0, v[188:189]
	s_mov_b32 m0, s78
	s_nop 0
	global_load_lds_dwordx4 v[248:249], off
	s_waitcnt vmcnt(8)
	s_waitcnt lgkmcnt(0)
	s_barrier
	s_setprio 1
	s_waitcnt lgkmcnt(0)
	v_mfma_f32_16x16x32_bf16 v[150:153], v[58:61], v[162:165], v[150:153]
	v_mfma_f32_16x16x32_bf16 v[146:149], v[74:77], v[162:165], v[146:149]
	v_mfma_f32_16x16x32_bf16 v[126:129], v[58:61], v[170:173], v[126:129]
	v_mfma_f32_16x16x32_bf16 v[122:125], v[74:77], v[170:173], v[122:125]
	v_mfma_f32_16x16x32_bf16 v[110:113], v[58:61], v[178:181], v[110:113]
	v_mfma_f32_16x16x32_bf16 v[106:109], v[74:77], v[178:181], v[106:109]
	v_mfma_f32_16x16x32_bf16 v[94:97], v[58:61], v[218:221], v[94:97]
	v_mfma_f32_16x16x32_bf16 v[90:93], v[74:77], v[218:221], v[90:93]
	v_mfma_f32_16x16x32_bf16 v[150:153], v[62:65], v[166:169], v[150:153]
	v_mfma_f32_16x16x32_bf16 v[146:149], v[78:81], v[166:169], v[146:149]
	v_mfma_f32_16x16x32_bf16 v[126:129], v[62:65], v[174:177], v[126:129]
	v_mfma_f32_16x16x32_bf16 v[122:125], v[78:81], v[174:177], v[122:125]
	v_mfma_f32_16x16x32_bf16 v[110:113], v[62:65], v[182:185], v[110:113]
	v_mfma_f32_16x16x32_bf16 v[106:109], v[78:81], v[182:185], v[106:109]
	v_mfma_f32_16x16x32_bf16 v[94:97], v[62:65], v[222:225], v[94:97]
	v_mfma_f32_16x16x32_bf16 v[90:93], v[78:81], v[222:225], v[90:93]
	v_mfma_f32_16x16x32_bf16 v[138:141], v[130:133], v[162:165], v[138:141]
	v_mfma_f32_16x16x32_bf16 v[134:137], v[154:157], v[162:165], v[134:137]
	v_mfma_f32_16x16x32_bf16 v[118:121], v[130:133], v[170:173], v[118:121]
	v_mfma_f32_16x16x32_bf16 v[114:117], v[154:157], v[170:173], v[114:117]
	v_mfma_f32_16x16x32_bf16 v[102:105], v[130:133], v[178:181], v[102:105]
	v_mfma_f32_16x16x32_bf16 v[98:101], v[154:157], v[178:181], v[98:101]
	v_mfma_f32_16x16x32_bf16 v[86:89], v[130:133], v[218:221], v[86:89]
	v_mfma_f32_16x16x32_bf16 v[82:85], v[154:157], v[218:221], v[82:85]
	v_mfma_f32_16x16x32_bf16 v[138:141], v[142:145], v[166:169], v[138:141]
	v_mfma_f32_16x16x32_bf16 v[134:137], v[158:161], v[166:169], v[134:137]
	v_mfma_f32_16x16x32_bf16 v[118:121], v[142:145], v[174:177], v[118:121]
	v_mfma_f32_16x16x32_bf16 v[114:117], v[158:161], v[174:177], v[114:117]
	v_mfma_f32_16x16x32_bf16 v[102:105], v[142:145], v[182:185], v[102:105]
	v_mfma_f32_16x16x32_bf16 v[98:101], v[158:161], v[182:185], v[98:101]
	v_mfma_f32_16x16x32_bf16 v[86:89], v[142:145], v[222:225], v[86:89]
	v_mfma_f32_16x16x32_bf16 v[82:85], v[158:161], v[222:225], v[82:85]
	s_setprio 0
	s_barrier
	s_add_i32 s0, vcc_lo, s54
	v_lshl_add_u64 v[204:205], v[204:205], 0, s[22:23]
	s_mov_b32 m0, s0
	ds_read_b128 v[162:165], v233 offset:49152
	ds_read_b128 v[166:169], v233 offset:50176
	ds_read_b128 v[170:173], v233 offset:51200
	ds_read_b128 v[174:177], v233 offset:52224
	ds_read_b128 v[178:181], v233 offset:53248
	ds_read_b128 v[182:185], v233 offset:54272
	ds_read_b128 v[218:221], v233 offset:55296
	ds_read_b128 v[222:225], v233 offset:56320
	global_load_lds_dwordx4 v[204:205], off
	s_add_i32 m0, s0, 0x2000
	s_add_u32 s0, s36, 0xb0080
	v_lshl_add_u64 v[204:205], v[226:227], 0, s[22:23]
	s_addc_u32 s1, s37, 0
	s_add_i32 s36, vcc_hi, s54
	global_load_lds_dwordx4 v[204:205], off
	v_lshl_add_u64 v[204:205], s[0:1], 0, v[0:1]
	s_mov_b32 m0, s36
	s_nop 0
	global_load_lds_dwordx4 v[204:205], off
	v_lshl_add_u64 v[204:205], s[0:1], 0, v[186:187]
	s_add_i32 m0, s36, 0x2000
	s_nop 0
	global_load_lds_dwordx4 v[204:205], off
	v_lshl_add_u64 v[204:205], v[234:235], 0, s[22:23]
	s_mov_b32 m0, s82
	s_nop 0
	global_load_lds_dwordx4 v[204:205], off
	v_lshl_add_u64 v[204:205], v[246:247], 0, s[22:23]
	s_mov_b32 m0, s83
	s_nop 0
	global_load_lds_dwordx4 v[204:205], off
	s_waitcnt vmcnt(8)
	s_waitcnt lgkmcnt(0)
	s_barrier
	s_setprio 1
	s_waitcnt lgkmcnt(0)
	v_mfma_f32_16x16x32_bf16 v[70:73], v[58:61], v[162:165], v[70:73]
	v_mfma_f32_16x16x32_bf16 v[66:69], v[74:77], v[162:165], v[66:69]
	v_mfma_f32_16x16x32_bf16 v[46:49], v[58:61], v[170:173], v[46:49]
	v_mfma_f32_16x16x32_bf16 v[42:45], v[74:77], v[170:173], v[42:45]
	v_mfma_f32_16x16x32_bf16 v[30:33], v[58:61], v[178:181], v[30:33]
	v_mfma_f32_16x16x32_bf16 v[26:29], v[74:77], v[178:181], v[26:29]
	v_mfma_f32_16x16x32_bf16 v[14:17], v[58:61], v[218:221], v[14:17]
	v_mfma_f32_16x16x32_bf16 v[10:13], v[74:77], v[218:221], v[10:13]
	v_mfma_f32_16x16x32_bf16 v[70:73], v[62:65], v[166:169], v[70:73]
	v_mfma_f32_16x16x32_bf16 v[66:69], v[78:81], v[166:169], v[66:69]
	v_mfma_f32_16x16x32_bf16 v[46:49], v[62:65], v[174:177], v[46:49]
	v_mfma_f32_16x16x32_bf16 v[42:45], v[78:81], v[174:177], v[42:45]
	v_mfma_f32_16x16x32_bf16 v[30:33], v[62:65], v[182:185], v[30:33]
	v_mfma_f32_16x16x32_bf16 v[26:29], v[78:81], v[182:185], v[26:29]
	v_mfma_f32_16x16x32_bf16 v[14:17], v[62:65], v[222:225], v[14:17]
	v_mfma_f32_16x16x32_bf16 v[10:13], v[78:81], v[222:225], v[10:13]
	v_mfma_f32_16x16x32_bf16 v[54:57], v[130:133], v[162:165], v[54:57]
	v_mfma_f32_16x16x32_bf16 v[50:53], v[154:157], v[162:165], v[50:53]
	v_mfma_f32_16x16x32_bf16 v[38:41], v[130:133], v[170:173], v[38:41]
	v_mfma_f32_16x16x32_bf16 v[34:37], v[154:157], v[170:173], v[34:37]
	v_mfma_f32_16x16x32_bf16 v[22:25], v[130:133], v[178:181], v[22:25]
	v_mfma_f32_16x16x32_bf16 v[18:21], v[154:157], v[178:181], v[18:21]
	v_mfma_f32_16x16x32_bf16 v[6:9], v[130:133], v[218:221], v[6:9]
	v_mfma_f32_16x16x32_bf16 v[2:5], v[154:157], v[218:221], v[2:5]
	v_mfma_f32_16x16x32_bf16 v[54:57], v[142:145], v[166:169], v[54:57]
	v_mfma_f32_16x16x32_bf16 v[50:53], v[158:161], v[166:169], v[50:53]
	v_mfma_f32_16x16x32_bf16 v[38:41], v[142:145], v[174:177], v[38:41]
	v_mfma_f32_16x16x32_bf16 v[34:37], v[158:161], v[174:177], v[34:37]
	v_mfma_f32_16x16x32_bf16 v[22:25], v[142:145], v[182:185], v[22:25]
	v_mfma_f32_16x16x32_bf16 v[18:21], v[158:161], v[182:185], v[18:21]
	v_mfma_f32_16x16x32_bf16 v[6:9], v[142:145], v[222:225], v[6:9]
	v_mfma_f32_16x16x32_bf16 v[2:5], v[158:161], v[222:225], v[2:5]
	s_setprio 0
	s_barrier
	s_add_i32 s87, s87, 2
	s_add_u32 s9, s9, 0x100
	s_addc_u32 s17, s17, 0
	s_cmp_gt_u32 s87, 41
	s_mov_b64 s[0:1], s[34:35]
	s_cbranch_scc0 .LBB0_1315
